# A/B: all per-phase s_setprio flips of the GEMM loops deleted, on top of write-through dwordx4 stores
# speedup vs baseline: 1.0014x; 1.0013x over previous
; #define PG8_STAGE(bufoff, gbase, voff) do { _Pragma("unroll") for (int _i = 0; _i < 2; ++_i) \
;         __builtin_amdgcn_global_load_lds((const unsigned*)((const char*)(gbase) + (voff)[_i]), (PG8_LAS unsigned*)(lds + (bufoff) + ldsw + _i * 8192), 16, 0, 0); } while (0)
; #define PG8_LDA(dst, b, h) do { _Pragma("unroll") for (int m = 0; m < 4; ++m) _Pragma("unroll") for (int k = 0; k < 2; ++k) dst[m][k] = *(const PG8_LAS bf16x8*)(lds + PG8_SA(b, h) + aoff + m * 2048 + k * 1024); } while (0)
; #define PG8_LDB(dst, b, h) do { _Pragma("unroll") for (int n = 0; n < 2; ++n) _Pragma("unroll") for (int k = 0; k < 2; ++k) dst[n][k] = *(const PG8_LAS bf16x8*)(lds + PG8_SB(b, h) + boff + n * 2048 + k * 1024); } while (0)
; #define PG8_MMA(ai, bj, At, Bt) do { __builtin_amdgcn_s_setprio(1); _Pragma("unroll") for (int m = 0; m < 4; ++m) _Pragma("unroll") for (int n = 0; n < 2; ++n) _Pragma("unroll") for (int k = 0; k < 2; ++k) \
;         acc[ai][bj][m][n] = __builtin_amdgcn_mfma_f32_16x16x32_bf16(Bt[n][k], At[m][k], acc[ai][bj][m][n], 0, 0, 0); __builtin_amdgcn_s_setprio(0); } while (0)
; #define PG8_WAIT_V(n) asm volatile("s_waitcnt vmcnt(" #n ")" ::: "memory")
; #define PG8_WAIT_L(n) asm volatile("s_waitcnt lgkmcnt(" #n ")" ::: "memory")
; #define PG8_BAR __builtin_amdgcn_s_barrier()
; #define PG8_SCHED __builtin_amdgcn_sched_barrier(0)
; template <class Epi, class Sched, bool ALIGN_EPI = false, bool SP2 = false>
; __device__ __forceinline__ void gemm_phase(PG8_LAS unsigned char* lds, const Gemm g, const Sched& S, const Epi& E) {
;     ...
;             PG8_LDB(B0, 0, 0); PG8_LDB(B1, 0, 1); PG8_SCHED; PG8_LDA(At, 0, 0); PG8_STAGE(PG8_SA(1, 1), a1 + hstepA, voffA);
;             PG8_WAIT_V(8); PG8_WAIT_L(0); PG8_BAR; PG8_MMA(0, 0, At, B0); PG8_MMA(0, 1, At, B1); PG8_BAR; PG8_SCHED;
;             PG8_LDA(At, 0, 1); PG8_STAGE(PG8_SB(0, 0), b2, voffB); PG8_STAGE(PG8_SB(0, 1), b2 + hstep, voffB); PG8_STAGE(PG8_SA(0, 0), a2, voffA);
.LBB0_620:
	ds_read_b128 v[144:147], v153
	ds_read_b128 v[158:161], v153 offset:1024
	ds_read_b128 v[162:165], v153 offset:2048
	ds_read_b128 v[166:169], v153 offset:3072
	ds_read_b128 v[170:173], v154
	ds_read_b128 v[174:177], v154 offset:1024
	ds_read_b128 v[178:181], v154 offset:2048
	ds_read_b128 v[182:185], v154 offset:3072
	s_add_u32 s28, s26, 0xfff80080
	s_addc_u32 s29, s27, -1
	s_cmp_eq_u32 s54, 28
	s_cselect_b32 s31, s17, s29
	s_cselect_b32 s30, s23, s28
	s_cselect_b32 s29, s15, s53
	s_cselect_b32 s28, s25, s52
	v_lshl_add_u64 v[148:149], s[26:27], 0, v[136:137]
	s_add_i32 m0, s36, 0xc000
	ds_read_b128 v[186:189], v155
	ds_read_b128 v[190:193], v155 offset:1024
	ds_read_b128 v[194:197], v155 offset:2048
	ds_read_b128 v[198:201], v155 offset:3072
	ds_read_b128 v[206:209], v155 offset:4096
	ds_read_b128 v[210:213], v155 offset:5120
	ds_read_b128 v[214:217], v155 offset:6144
	ds_read_b128 v[218:221], v155 offset:7168
	global_load_lds_dwordx4 v[148:149], off
	v_lshl_add_u64 v[148:149], s[26:27], 0, v[138:139]
	s_add_i32 m0, s36, 0xe000
	s_nop 0
	global_load_lds_dwordx4 v[148:149], off
	s_waitcnt vmcnt(8)
	s_waitcnt lgkmcnt(0)
	s_barrier
	s_waitcnt lgkmcnt(0)
	v_mfma_f32_16x16x32_bf16 v[124:127], v[144:147], v[186:189], v[124:127]
	v_mfma_f32_16x16x32_bf16 v[120:123], v[162:165], v[186:189], v[120:123]
	v_mfma_f32_16x16x32_bf16 v[108:111], v[144:147], v[194:197], v[108:111]
	v_mfma_f32_16x16x32_bf16 v[104:107], v[162:165], v[194:197], v[104:107]
	v_mfma_f32_16x16x32_bf16 v[92:95], v[144:147], v[206:209], v[92:95]
	v_mfma_f32_16x16x32_bf16 v[88:91], v[162:165], v[206:209], v[88:91]
	v_mfma_f32_16x16x32_bf16 v[76:79], v[144:147], v[214:217], v[76:79]
	v_mfma_f32_16x16x32_bf16 v[72:75], v[162:165], v[214:217], v[72:75]
	v_mfma_f32_16x16x32_bf16 v[124:127], v[158:161], v[190:193], v[124:127]
	v_mfma_f32_16x16x32_bf16 v[120:123], v[166:169], v[190:193], v[120:123]
	v_mfma_f32_16x16x32_bf16 v[108:111], v[158:161], v[198:201], v[108:111]
	v_mfma_f32_16x16x32_bf16 v[104:107], v[166:169], v[198:201], v[104:107]
	v_mfma_f32_16x16x32_bf16 v[92:95], v[158:161], v[210:213], v[92:95]
	v_mfma_f32_16x16x32_bf16 v[88:91], v[166:169], v[210:213], v[88:91]
	v_mfma_f32_16x16x32_bf16 v[76:79], v[158:161], v[218:221], v[76:79]
	v_mfma_f32_16x16x32_bf16 v[72:75], v[166:169], v[218:221], v[72:75]
	v_mfma_f32_16x16x32_bf16 v[116:119], v[170:173], v[186:189], v[116:119]
	v_mfma_f32_16x16x32_bf16 v[112:115], v[178:181], v[186:189], v[112:115]
	v_mfma_f32_16x16x32_bf16 v[100:103], v[170:173], v[194:197], v[100:103]
	v_mfma_f32_16x16x32_bf16 v[96:99], v[178:181], v[194:197], v[96:99]
	v_mfma_f32_16x16x32_bf16 v[84:87], v[170:173], v[206:209], v[84:87]
	v_mfma_f32_16x16x32_bf16 v[80:83], v[178:181], v[206:209], v[80:83]
	v_mfma_f32_16x16x32_bf16 v[68:71], v[170:173], v[214:217], v[68:71]
	v_mfma_f32_16x16x32_bf16 v[64:67], v[178:181], v[214:217], v[64:67]
	v_mfma_f32_16x16x32_bf16 v[116:119], v[174:177], v[190:193], v[116:119]
	v_mfma_f32_16x16x32_bf16 v[112:115], v[182:185], v[190:193], v[112:115]
	v_mfma_f32_16x16x32_bf16 v[100:103], v[174:177], v[198:201], v[100:103]
	v_mfma_f32_16x16x32_bf16 v[96:99], v[182:185], v[198:201], v[96:99]
	v_mfma_f32_16x16x32_bf16 v[84:87], v[174:177], v[210:213], v[84:87]
	v_mfma_f32_16x16x32_bf16 v[80:83], v[182:185], v[210:213], v[80:83]
	v_mfma_f32_16x16x32_bf16 v[68:71], v[174:177], v[218:221], v[68:71]
	v_mfma_f32_16x16x32_bf16 v[64:67], v[182:185], v[218:221], v[64:67]
	s_barrier
	s_add_i32 s55, s49, s35
	v_lshl_add_u64 v[148:149], s[28:29], 0, v[128:129]
	s_mov_b32 m0, s55
	ds_read_b128 v[186:189], v155 offset:16384
	ds_read_b128 v[190:193], v155 offset:17408
	ds_read_b128 v[194:197], v155 offset:18432
	ds_read_b128 v[198:201], v155 offset:19456
	ds_read_b128 v[206:209], v155 offset:20480
	ds_read_b128 v[210:213], v155 offset:21504
	ds_read_b128 v[214:217], v155 offset:22528
	ds_read_b128 v[218:221], v155 offset:23552
	global_load_lds_dwordx4 v[148:149], off
	s_add_i32 m0, s55, 0x2000
	s_add_u32 s56, s28, 0x80000
	v_lshl_add_u64 v[202:203], s[28:29], 0, v[130:131]
	s_addc_u32 s57, s29, 0
	s_add_i32 s55, s50, s35
	global_load_lds_dwordx4 v[202:203], off
	v_lshl_add_u64 v[222:223], s[56:57], 0, v[128:129]
	s_mov_b32 m0, s55
	v_lshl_add_u64 v[224:225], s[30:31], 0, v[130:131]
	global_load_lds_dwordx4 v[222:223], off
	v_lshl_add_u64 v[222:223], s[56:57], 0, v[130:131]
	s_add_i32 m0, s55, 0x2000
	s_nop 0
	global_load_lds_dwordx4 v[222:223], off
	v_lshl_add_u64 v[222:223], s[30:31], 0, v[128:129]
	s_mov_b32 m0, s36
	s_nop 0
	global_load_lds_dwordx4 v[222:223], off
	s_mov_b32 m0, s37
	s_nop 0
	global_load_lds_dwordx4 v[224:225], off
	s_waitcnt vmcnt(8)
	s_waitcnt lgkmcnt(0)
	s_barrier
; #define PG8_STAGE(bufoff, gbase, voff) do { _Pragma("unroll") for (int _i = 0; _i < 2; ++_i) \
;         __builtin_amdgcn_global_load_lds((const unsigned*)((const char*)(gbase) + (voff)[_i]), (PG8_LAS unsigned*)(lds + (bufoff) + ldsw + _i * 8192), 16, 0, 0); } while (0)
; #define PG8_LDA(dst, b, h) do { _Pragma("unroll") for (int m = 0; m < 4; ++m) _Pragma("unroll") for (int k = 0; k < 2; ++k) dst[m][k] = *(const PG8_LAS bf16x8*)(lds + PG8_SA(b, h) + aoff + m * 2048 + k * 1024); } while (0)
; #define PG8_LDB(dst, b, h) do { _Pragma("unroll") for (int n = 0; n < 2; ++n) _Pragma("unroll") for (int k = 0; k < 2; ++k) dst[n][k] = *(const PG8_LAS bf16x8*)(lds + PG8_SB(b, h) + boff + n * 2048 + k * 1024); } while (0)
; #define PG8_MMA(ai, bj, At, Bt) do { __builtin_amdgcn_s_setprio(1); _Pragma("unroll") for (int m = 0; m < 4; ++m) _Pragma("unroll") for (int n = 0; n < 2; ++n) _Pragma("unroll") for (int k = 0; k < 2; ++k) \
;         acc[ai][bj][m][n] = __builtin_amdgcn_mfma_f32_16x16x32_bf16(Bt[n][k], At[m][k], acc[ai][bj][m][n], 0, 0, 0); __builtin_amdgcn_s_setprio(0); } while (0)
; #define PG8_WAIT_V(n) asm volatile("s_waitcnt vmcnt(" #n ")" ::: "memory")
; #define PG8_WAIT_L(n) asm volatile("s_waitcnt lgkmcnt(" #n ")" ::: "memory")
; #define PG8_BAR __builtin_amdgcn_s_barrier()
; #define PG8_SCHED __builtin_amdgcn_sched_barrier(0)
; template <class Epi, class Sched, bool ALIGN_EPI = false, bool SP2 = false>
; __device__ __forceinline__ void gemm_phase(PG8_LAS unsigned char* lds, const Gemm g, const Sched& S, const Epi& E) {
;     ...
;             PG8_WAIT_V(8); PG8_WAIT_L(0); PG8_BAR; PG8_MMA(1, 0, At, B0); PG8_MMA(1, 1, At, B1); PG8_BAR; PG8_SCHED;
;             PG8_LDB(B0, 1, 0); PG8_LDB(B1, 1, 1); PG8_SCHED; PG8_LDA(At, 1, 0); PG8_STAGE(PG8_SA(0, 1), a2 + hstepA, voffA);
;             PG8_WAIT_V(8); PG8_WAIT_L(0); PG8_BAR; PG8_MMA(0, 0, At, B0); PG8_MMA(0, 1, At, B1); PG8_BAR; PG8_SCHED;
	s_waitcnt lgkmcnt(0)
	v_mfma_f32_16x16x32_bf16 v[60:63], v[144:147], v[186:189], v[60:63]
	v_mfma_f32_16x16x32_bf16 v[56:59], v[162:165], v[186:189], v[56:59]
	v_mfma_f32_16x16x32_bf16 v[44:47], v[144:147], v[194:197], v[44:47]
	v_mfma_f32_16x16x32_bf16 v[40:43], v[162:165], v[194:197], v[40:43]
	v_mfma_f32_16x16x32_bf16 v[28:31], v[144:147], v[206:209], v[28:31]
	v_mfma_f32_16x16x32_bf16 v[24:27], v[162:165], v[206:209], v[24:27]
	v_mfma_f32_16x16x32_bf16 v[12:15], v[144:147], v[214:217], v[12:15]
	v_mfma_f32_16x16x32_bf16 v[8:11], v[162:165], v[214:217], v[8:11]
	v_mfma_f32_16x16x32_bf16 v[60:63], v[158:161], v[190:193], v[60:63]
	v_mfma_f32_16x16x32_bf16 v[56:59], v[166:169], v[190:193], v[56:59]
	v_mfma_f32_16x16x32_bf16 v[44:47], v[158:161], v[198:201], v[44:47]
	v_mfma_f32_16x16x32_bf16 v[40:43], v[166:169], v[198:201], v[40:43]
	v_mfma_f32_16x16x32_bf16 v[28:31], v[158:161], v[210:213], v[28:31]
	v_mfma_f32_16x16x32_bf16 v[24:27], v[166:169], v[210:213], v[24:27]
	v_mfma_f32_16x16x32_bf16 v[12:15], v[158:161], v[218:221], v[12:15]
	v_mfma_f32_16x16x32_bf16 v[8:11], v[166:169], v[218:221], v[8:11]
	v_mfma_f32_16x16x32_bf16 v[52:55], v[170:173], v[186:189], v[52:55]
	v_mfma_f32_16x16x32_bf16 v[48:51], v[178:181], v[186:189], v[48:51]
	v_mfma_f32_16x16x32_bf16 v[36:39], v[170:173], v[194:197], v[36:39]
	v_mfma_f32_16x16x32_bf16 v[32:35], v[178:181], v[194:197], v[32:35]
	v_mfma_f32_16x16x32_bf16 v[20:23], v[170:173], v[206:209], v[20:23]
	v_mfma_f32_16x16x32_bf16 v[16:19], v[178:181], v[206:209], v[16:19]
	v_mfma_f32_16x16x32_bf16 v[4:7], v[170:173], v[214:217], v[4:7]
	v_mfma_f32_16x16x32_bf16 v[0:3], v[178:181], v[214:217], v[0:3]
	v_mfma_f32_16x16x32_bf16 v[52:55], v[174:177], v[190:193], v[52:55]
	v_mfma_f32_16x16x32_bf16 v[48:51], v[182:185], v[190:193], v[48:51]
	v_mfma_f32_16x16x32_bf16 v[36:39], v[174:177], v[198:201], v[36:39]
	v_mfma_f32_16x16x32_bf16 v[32:35], v[182:185], v[198:201], v[32:35]
	v_mfma_f32_16x16x32_bf16 v[20:23], v[174:177], v[210:213], v[20:23]
	v_mfma_f32_16x16x32_bf16 v[16:19], v[182:185], v[210:213], v[16:19]
	v_mfma_f32_16x16x32_bf16 v[4:7], v[174:177], v[218:221], v[4:7]
	v_mfma_f32_16x16x32_bf16 v[0:3], v[182:185], v[218:221], v[0:3]
	s_barrier
	s_add_i32 s55, 0, 0x18000
	v_add_u32_e32 v132, s55, v151
	s_add_i32 s56, 0, 0x1c000
	ds_read_b128 v[144:147], v132
	ds_read_b128 v[158:161], v132 offset:1024
	ds_read_b128 v[162:165], v132 offset:2048
	ds_read_b128 v[166:169], v132 offset:3072
	v_add_u32_e32 v132, s56, v151
	ds_read_b128 v[170:173], v132
	ds_read_b128 v[174:177], v132 offset:1024
	ds_read_b128 v[178:181], v132 offset:2048
	ds_read_b128 v[182:185], v132 offset:3072
	s_add_u32 s30, s30, 0x80000
	s_addc_u32 s31, s31, 0
	s_mov_b32 m0, s38
	v_lshl_add_u64 v[226:227], s[30:31], 0, v[128:129]
	ds_read_b128 v[186:189], v155 offset:32768
	ds_read_b128 v[190:193], v155 offset:33792
	ds_read_b128 v[194:197], v155 offset:34816
	ds_read_b128 v[198:201], v155 offset:35840
	ds_read_b128 v[206:209], v155 offset:36864
	ds_read_b128 v[210:213], v155 offset:37888
	ds_read_b128 v[214:217], v155 offset:38912
	ds_read_b128 v[218:221], v155 offset:39936
	global_load_lds_dwordx4 v[226:227], off
	v_lshl_add_u64 v[226:227], s[30:31], 0, v[130:131]
	s_mov_b32 m0, s2
	s_nop 0
	global_load_lds_dwordx4 v[226:227], off
	s_waitcnt vmcnt(8)
	s_waitcnt lgkmcnt(0)
	s_barrier
	s_waitcnt lgkmcnt(0)
	v_mfma_f32_16x16x32_bf16 v[124:127], v[144:147], v[186:189], v[124:127]
	v_mfma_f32_16x16x32_bf16 v[120:123], v[162:165], v[186:189], v[120:123]
	v_mfma_f32_16x16x32_bf16 v[108:111], v[144:147], v[194:197], v[108:111]
	v_mfma_f32_16x16x32_bf16 v[104:107], v[162:165], v[194:197], v[104:107]
	v_mfma_f32_16x16x32_bf16 v[92:95], v[144:147], v[206:209], v[92:95]
	v_mfma_f32_16x16x32_bf16 v[88:91], v[162:165], v[206:209], v[88:91]
	v_mfma_f32_16x16x32_bf16 v[76:79], v[144:147], v[214:217], v[76:79]
	v_mfma_f32_16x16x32_bf16 v[72:75], v[162:165], v[214:217], v[72:75]
	v_mfma_f32_16x16x32_bf16 v[124:127], v[158:161], v[190:193], v[124:127]
	v_mfma_f32_16x16x32_bf16 v[120:123], v[166:169], v[190:193], v[120:123]
	v_mfma_f32_16x16x32_bf16 v[108:111], v[158:161], v[198:201], v[108:111]
	v_mfma_f32_16x16x32_bf16 v[104:107], v[166:169], v[198:201], v[104:107]
	v_mfma_f32_16x16x32_bf16 v[92:95], v[158:161], v[210:213], v[92:95]
	v_mfma_f32_16x16x32_bf16 v[88:91], v[166:169], v[210:213], v[88:91]
	v_mfma_f32_16x16x32_bf16 v[76:79], v[158:161], v[218:221], v[76:79]
	v_mfma_f32_16x16x32_bf16 v[72:75], v[166:169], v[218:221], v[72:75]
	v_mfma_f32_16x16x32_bf16 v[116:119], v[170:173], v[186:189], v[116:119]
	v_mfma_f32_16x16x32_bf16 v[112:115], v[178:181], v[186:189], v[112:115]
	v_mfma_f32_16x16x32_bf16 v[100:103], v[170:173], v[194:197], v[100:103]
	v_mfma_f32_16x16x32_bf16 v[96:99], v[178:181], v[194:197], v[96:99]
	v_mfma_f32_16x16x32_bf16 v[84:87], v[170:173], v[206:209], v[84:87]
	v_mfma_f32_16x16x32_bf16 v[80:83], v[178:181], v[206:209], v[80:83]
	v_mfma_f32_16x16x32_bf16 v[68:71], v[170:173], v[214:217], v[68:71]
	v_mfma_f32_16x16x32_bf16 v[64:67], v[178:181], v[214:217], v[64:67]
	v_mfma_f32_16x16x32_bf16 v[116:119], v[174:177], v[190:193], v[116:119]
	v_mfma_f32_16x16x32_bf16 v[112:115], v[182:185], v[190:193], v[112:115]
	v_mfma_f32_16x16x32_bf16 v[100:103], v[174:177], v[198:201], v[100:103]
	v_mfma_f32_16x16x32_bf16 v[96:99], v[182:185], v[198:201], v[96:99]
	v_mfma_f32_16x16x32_bf16 v[84:87], v[174:177], v[210:213], v[84:87]
	v_mfma_f32_16x16x32_bf16 v[80:83], v[182:185], v[210:213], v[80:83]
	v_mfma_f32_16x16x32_bf16 v[68:71], v[174:177], v[218:221], v[68:71]
	v_mfma_f32_16x16x32_bf16 v[64:67], v[182:185], v[218:221], v[64:67]
	s_barrier
; #define PG8_STAGE(bufoff, gbase, voff) do { _Pragma("unroll") for (int _i = 0; _i < 2; ++_i) \
;         __builtin_amdgcn_global_load_lds((const unsigned*)((const char*)(gbase) + (voff)[_i]), (PG8_LAS unsigned*)(lds + (bufoff) + ldsw + _i * 8192), 16, 0, 0); } while (0)
; #define PG8_LDA(dst, b, h) do { _Pragma("unroll") for (int m = 0; m < 4; ++m) _Pragma("unroll") for (int k = 0; k < 2; ++k) dst[m][k] = *(const PG8_LAS bf16x8*)(lds + PG8_SA(b, h) + aoff + m * 2048 + k * 1024); } while (0)
; #define PG8_MMA(ai, bj, At, Bt) do { __builtin_amdgcn_s_setprio(1); _Pragma("unroll") for (int m = 0; m < 4; ++m) _Pragma("unroll") for (int n = 0; n < 2; ++n) _Pragma("unroll") for (int k = 0; k < 2; ++k) \
;         acc[ai][bj][m][n] = __builtin_amdgcn_mfma_f32_16x16x32_bf16(Bt[n][k], At[m][k], acc[ai][bj][m][n], 0, 0, 0); __builtin_amdgcn_s_setprio(0); } while (0)
; #define PG8_WAIT_V(n) asm volatile("s_waitcnt vmcnt(" #n ")" ::: "memory")
; #define PG8_WAIT_L(n) asm volatile("s_waitcnt lgkmcnt(" #n ")" ::: "memory")
; #define PG8_BAR __builtin_amdgcn_s_barrier()
; #define PG8_SCHED __builtin_amdgcn_sched_barrier(0)
; template <class Epi, class Sched, bool ALIGN_EPI = false, bool SP2 = false>
; __device__ __forceinline__ void gemm_phase(PG8_LAS unsigned char* lds, const Gemm g, const Sched& S, const Epi& E) {
;     ...
;         for (int t = 0; t < nt; t += 2) {
;             const bool last = (t == nt - 2);
;     ...
;             PG8_LDA(At, 1, 1); PG8_STAGE(PG8_SB(1, 0), b3, voffB); PG8_STAGE(PG8_SB(1, 1), b3 + hstep, voffB); PG8_STAGE(PG8_SA(1, 0), a3, voffA);
;             PG8_WAIT_V(8); PG8_WAIT_L(0); PG8_BAR; PG8_MMA(1, 0, At, B0); PG8_MMA(1, 1, At, B1); PG8_BAR; PG8_SCHED;
	s_add_i32 s30, s55, s35
	v_lshl_add_u64 v[148:149], v[148:149], 0, s[10:11]
	s_mov_b32 m0, s30
	ds_read_b128 v[186:189], v155 offset:49152
	ds_read_b128 v[190:193], v155 offset:50176
	ds_read_b128 v[194:197], v155 offset:51200
	ds_read_b128 v[198:201], v155 offset:52224
	ds_read_b128 v[206:209], v155 offset:53248
	ds_read_b128 v[210:213], v155 offset:54272
	ds_read_b128 v[214:217], v155 offset:55296
	ds_read_b128 v[218:221], v155 offset:56320
	global_load_lds_dwordx4 v[148:149], off
	s_add_i32 m0, s30, 0x2000
	s_add_u32 s28, s28, 0x80080
	v_lshl_add_u64 v[148:149], v[202:203], 0, s[10:11]
	s_addc_u32 s29, s29, 0
	s_add_i32 s30, s56, s35
	global_load_lds_dwordx4 v[148:149], off
	v_lshl_add_u64 v[148:149], s[28:29], 0, v[128:129]
	s_mov_b32 m0, s30
	s_nop 0
	global_load_lds_dwordx4 v[148:149], off
	v_lshl_add_u64 v[148:149], s[28:29], 0, v[130:131]
	s_add_i32 m0, s30, 0x2000
	s_nop 0
	global_load_lds_dwordx4 v[148:149], off
	v_lshl_add_u64 v[148:149], v[222:223], 0, s[10:11]
	s_mov_b32 m0, s44
	s_nop 0
	global_load_lds_dwordx4 v[148:149], off
	v_lshl_add_u64 v[148:149], v[224:225], 0, s[10:11]
	s_mov_b32 m0, s45
	s_nop 0
	global_load_lds_dwordx4 v[148:149], off
	s_waitcnt vmcnt(8)
	s_waitcnt lgkmcnt(0)
	s_barrier
	s_waitcnt lgkmcnt(0)
	v_mfma_f32_16x16x32_bf16 v[60:63], v[144:147], v[186:189], v[60:63]
	v_mfma_f32_16x16x32_bf16 v[56:59], v[162:165], v[186:189], v[56:59]
	v_mfma_f32_16x16x32_bf16 v[44:47], v[144:147], v[194:197], v[44:47]
	v_mfma_f32_16x16x32_bf16 v[40:43], v[162:165], v[194:197], v[40:43]
	v_mfma_f32_16x16x32_bf16 v[28:31], v[144:147], v[206:209], v[28:31]
	v_mfma_f32_16x16x32_bf16 v[24:27], v[162:165], v[206:209], v[24:27]
	v_mfma_f32_16x16x32_bf16 v[12:15], v[144:147], v[214:217], v[12:15]
	v_mfma_f32_16x16x32_bf16 v[8:11], v[162:165], v[214:217], v[8:11]
	v_mfma_f32_16x16x32_bf16 v[60:63], v[158:161], v[190:193], v[60:63]
	v_mfma_f32_16x16x32_bf16 v[56:59], v[166:169], v[190:193], v[56:59]
	v_mfma_f32_16x16x32_bf16 v[44:47], v[158:161], v[198:201], v[44:47]
	v_mfma_f32_16x16x32_bf16 v[40:43], v[166:169], v[198:201], v[40:43]
	v_mfma_f32_16x16x32_bf16 v[28:31], v[158:161], v[210:213], v[28:31]
	v_mfma_f32_16x16x32_bf16 v[24:27], v[166:169], v[210:213], v[24:27]
	v_mfma_f32_16x16x32_bf16 v[12:15], v[158:161], v[218:221], v[12:15]
	v_mfma_f32_16x16x32_bf16 v[8:11], v[166:169], v[218:221], v[8:11]
	v_mfma_f32_16x16x32_bf16 v[52:55], v[170:173], v[186:189], v[52:55]
	v_mfma_f32_16x16x32_bf16 v[48:51], v[178:181], v[186:189], v[48:51]
	v_mfma_f32_16x16x32_bf16 v[36:39], v[170:173], v[194:197], v[36:39]
	v_mfma_f32_16x16x32_bf16 v[32:35], v[178:181], v[194:197], v[32:35]
	v_mfma_f32_16x16x32_bf16 v[20:23], v[170:173], v[206:209], v[20:23]
	v_mfma_f32_16x16x32_bf16 v[16:19], v[178:181], v[206:209], v[16:19]
	v_mfma_f32_16x16x32_bf16 v[4:7], v[170:173], v[214:217], v[4:7]
	v_mfma_f32_16x16x32_bf16 v[0:3], v[178:181], v[214:217], v[0:3]
	v_mfma_f32_16x16x32_bf16 v[52:55], v[174:177], v[190:193], v[52:55]
	v_mfma_f32_16x16x32_bf16 v[48:51], v[182:185], v[190:193], v[48:51]
	v_mfma_f32_16x16x32_bf16 v[36:39], v[174:177], v[198:201], v[36:39]
	v_mfma_f32_16x16x32_bf16 v[32:35], v[182:185], v[198:201], v[32:35]
	v_mfma_f32_16x16x32_bf16 v[20:23], v[174:177], v[210:213], v[20:23]
	v_mfma_f32_16x16x32_bf16 v[16:19], v[182:185], v[210:213], v[16:19]
	v_mfma_f32_16x16x32_bf16 v[4:7], v[174:177], v[218:221], v[4:7]
	v_mfma_f32_16x16x32_bf16 v[0:3], v[182:185], v[218:221], v[0:3]
	s_barrier
	s_add_i32 s54, s54, 2
	s_add_u32 s26, s26, 0x100
	s_addc_u32 s27, s27, 0
	s_add_u32 s52, s52, 0x100
	s_addc_u32 s53, s53, 0
	s_cmp_gt_u32 s54, 29
	s_cbranch_scc0 .LBB0_620
	s_and_b64 vcc, exec, s[12:13]
	s_cbranch_vccz .LBB0_623
	s_barrier

; #define PG8_STAGE(bufoff, gbase, voff) do { _Pragma("unroll") for (int _i = 0; _i < 2; ++_i) \
;         __builtin_amdgcn_global_load_lds((const unsigned*)((const char*)(gbase) + (voff)[_i]), (PG8_LAS unsigned*)(lds + (bufoff) + ldsw + _i * 8192), 16, 0, 0); } while (0)
; #define PG8_LDA(dst, b, h) do { _Pragma("unroll") for (int m = 0; m < 4; ++m) _Pragma("unroll") for (int k = 0; k < 2; ++k) dst[m][k] = *(const PG8_LAS bf16x8*)(lds + PG8_SA(b, h) + aoff + m * 2048 + k * 1024); } while (0)
; #define PG8_LDB(dst, b, h) do { _Pragma("unroll") for (int n = 0; n < 2; ++n) _Pragma("unroll") for (int k = 0; k < 2; ++k) dst[n][k] = *(const PG8_LAS bf16x8*)(lds + PG8_SB(b, h) + boff + n * 2048 + k * 1024); } while (0)
; #define PG8_MMA(ai, bj, At, Bt) do { __builtin_amdgcn_s_setprio(1); _Pragma("unroll") for (int m = 0; m < 4; ++m) _Pragma("unroll") for (int n = 0; n < 2; ++n) _Pragma("unroll") for (int k = 0; k < 2; ++k) \
;         acc[ai][bj][m][n] = __builtin_amdgcn_mfma_f32_16x16x32_bf16(Bt[n][k], At[m][k], acc[ai][bj][m][n], 0, 0, 0); __builtin_amdgcn_s_setprio(0); } while (0)
; #define PG8_WAIT_V(n) asm volatile("s_waitcnt vmcnt(" #n ")" ::: "memory")
; #define PG8_WAIT_L(n) asm volatile("s_waitcnt lgkmcnt(" #n ")" ::: "memory")
; #define PG8_BAR __builtin_amdgcn_s_barrier()
; #define PG8_SCHED __builtin_amdgcn_sched_barrier(0)
; template <class Epi, class Sched, bool ALIGN_EPI = false, bool SP2 = false>
; __device__ __forceinline__ void gemm_phase(PG8_LAS unsigned char* lds, const Gemm g, const Sched& S, const Epi& E) {
;     ...
;             PG8_LDB(B0, 0, 0); PG8_LDB(B1, 0, 1); PG8_SCHED; PG8_LDA(At, 0, 0); PG8_STAGE(PG8_SA(1, 1), a1 + hstepA, voffA);
;             PG8_WAIT_V(8); PG8_WAIT_L(0); PG8_BAR; PG8_MMA(0, 0, At, B0); PG8_MMA(0, 1, At, B1); PG8_BAR; PG8_SCHED;
;             PG8_LDA(At, 0, 1); PG8_STAGE(PG8_SB(0, 0), b2, voffB); PG8_STAGE(PG8_SB(0, 1), b2 + hstep, voffB); PG8_STAGE(PG8_SA(0, 0), a2, voffA);
.LBB0_818:
	ds_read_b128 v[146:149], v153
	ds_read_b128 v[158:161], v153 offset:1024
	ds_read_b128 v[162:165], v153 offset:2048
	ds_read_b128 v[166:169], v153 offset:3072
	ds_read_b128 v[170:173], v154
	ds_read_b128 v[174:177], v154 offset:1024
	ds_read_b128 v[178:181], v154 offset:2048
	ds_read_b128 v[182:185], v154 offset:3072
	s_add_u32 s30, s28, 0xfffe0080
	s_addc_u32 s31, s29, -1
	s_cmp_eq_u32 s53, 4
	s_cselect_b32 s35, s19, s31
	s_cselect_b32 s34, s25, s30
	s_cselect_b32 s31, s17, s52
	s_cselect_b32 s30, s27, s51
	v_lshl_add_u64 v[202:203], s[28:29], 0, v[138:139]
	s_add_i32 m0, s38, 0xc000
	ds_read_b128 v[186:189], v155
	ds_read_b128 v[190:193], v155 offset:1024
	ds_read_b128 v[194:197], v155 offset:2048
	ds_read_b128 v[198:201], v155 offset:3072
	ds_read_b128 v[206:209], v155 offset:4096
	ds_read_b128 v[210:213], v155 offset:5120
	ds_read_b128 v[214:217], v155 offset:6144
	ds_read_b128 v[218:221], v155 offset:7168
	global_load_lds_dwordx4 v[202:203], off
	v_lshl_add_u64 v[202:203], s[28:29], 0, v[140:141]
	s_add_i32 m0, s38, 0xe000
	s_nop 0
	global_load_lds_dwordx4 v[202:203], off
	s_waitcnt vmcnt(8)
	s_waitcnt lgkmcnt(0)
	s_barrier
	s_waitcnt lgkmcnt(0)
	v_mfma_f32_16x16x32_bf16 v[124:127], v[146:149], v[186:189], v[124:127]
	v_mfma_f32_16x16x32_bf16 v[120:123], v[162:165], v[186:189], v[120:123]
	v_mfma_f32_16x16x32_bf16 v[108:111], v[146:149], v[194:197], v[108:111]
	v_mfma_f32_16x16x32_bf16 v[104:107], v[162:165], v[194:197], v[104:107]
	v_mfma_f32_16x16x32_bf16 v[92:95], v[146:149], v[206:209], v[92:95]
	v_mfma_f32_16x16x32_bf16 v[88:91], v[162:165], v[206:209], v[88:91]
	v_mfma_f32_16x16x32_bf16 v[76:79], v[146:149], v[214:217], v[76:79]
	v_mfma_f32_16x16x32_bf16 v[72:75], v[162:165], v[214:217], v[72:75]
	v_mfma_f32_16x16x32_bf16 v[124:127], v[158:161], v[190:193], v[124:127]
	v_mfma_f32_16x16x32_bf16 v[120:123], v[166:169], v[190:193], v[120:123]
	v_mfma_f32_16x16x32_bf16 v[108:111], v[158:161], v[198:201], v[108:111]
	v_mfma_f32_16x16x32_bf16 v[104:107], v[166:169], v[198:201], v[104:107]
	v_mfma_f32_16x16x32_bf16 v[92:95], v[158:161], v[210:213], v[92:95]
	v_mfma_f32_16x16x32_bf16 v[88:91], v[166:169], v[210:213], v[88:91]
	v_mfma_f32_16x16x32_bf16 v[76:79], v[158:161], v[218:221], v[76:79]
	v_mfma_f32_16x16x32_bf16 v[72:75], v[166:169], v[218:221], v[72:75]
	v_mfma_f32_16x16x32_bf16 v[116:119], v[170:173], v[186:189], v[116:119]
	v_mfma_f32_16x16x32_bf16 v[112:115], v[178:181], v[186:189], v[112:115]
	v_mfma_f32_16x16x32_bf16 v[100:103], v[170:173], v[194:197], v[100:103]
	v_mfma_f32_16x16x32_bf16 v[96:99], v[178:181], v[194:197], v[96:99]
	v_mfma_f32_16x16x32_bf16 v[84:87], v[170:173], v[206:209], v[84:87]
	v_mfma_f32_16x16x32_bf16 v[80:83], v[178:181], v[206:209], v[80:83]
	v_mfma_f32_16x16x32_bf16 v[68:71], v[170:173], v[214:217], v[68:71]
	v_mfma_f32_16x16x32_bf16 v[64:67], v[178:181], v[214:217], v[64:67]
	v_mfma_f32_16x16x32_bf16 v[116:119], v[174:177], v[190:193], v[116:119]
	v_mfma_f32_16x16x32_bf16 v[112:115], v[182:185], v[190:193], v[112:115]
	v_mfma_f32_16x16x32_bf16 v[100:103], v[174:177], v[198:201], v[100:103]
	v_mfma_f32_16x16x32_bf16 v[96:99], v[182:185], v[198:201], v[96:99]
	v_mfma_f32_16x16x32_bf16 v[84:87], v[174:177], v[210:213], v[84:87]
	v_mfma_f32_16x16x32_bf16 v[80:83], v[182:185], v[210:213], v[80:83]
	v_mfma_f32_16x16x32_bf16 v[68:71], v[174:177], v[218:221], v[68:71]
	v_mfma_f32_16x16x32_bf16 v[64:67], v[182:185], v[218:221], v[64:67]
	s_barrier
	s_add_i32 s54, s48, s37
	v_lshl_add_u64 v[202:203], s[30:31], 0, v[130:131]
	s_mov_b32 m0, s54
	ds_read_b128 v[186:189], v155 offset:16384
	ds_read_b128 v[190:193], v155 offset:17408
	ds_read_b128 v[194:197], v155 offset:18432
	ds_read_b128 v[198:201], v155 offset:19456
	ds_read_b128 v[206:209], v155 offset:20480
	ds_read_b128 v[210:213], v155 offset:21504
	ds_read_b128 v[214:217], v155 offset:22528
	ds_read_b128 v[218:221], v155 offset:23552
	global_load_lds_dwordx4 v[202:203], off
	s_add_i32 m0, s54, 0x2000
	s_add_u32 s54, s30, 0x20000
	v_lshl_add_u64 v[222:223], s[30:31], 0, v[134:135]
	s_addc_u32 s55, s31, 0
	s_add_i32 s56, s49, s37
	global_load_lds_dwordx4 v[222:223], off
	v_lshl_add_u64 v[224:225], s[54:55], 0, v[130:131]
	s_mov_b32 m0, s56
	v_lshl_add_u64 v[226:227], s[34:35], 0, v[132:133]
	global_load_lds_dwordx4 v[224:225], off
	v_lshl_add_u64 v[224:225], s[54:55], 0, v[134:135]
	s_add_i32 m0, s56, 0x2000
	s_nop 0
	global_load_lds_dwordx4 v[224:225], off
	v_lshl_add_u64 v[224:225], s[34:35], 0, v[128:129]
	s_mov_b32 m0, s38
	s_nop 0
	global_load_lds_dwordx4 v[224:225], off
	s_mov_b32 m0, s39
	s_nop 0
	global_load_lds_dwordx4 v[226:227], off
	s_waitcnt vmcnt(8)
	s_waitcnt lgkmcnt(0)
	s_barrier
; #define PG8_STAGE(bufoff, gbase, voff) do { _Pragma("unroll") for (int _i = 0; _i < 2; ++_i) \
;         __builtin_amdgcn_global_load_lds((const unsigned*)((const char*)(gbase) + (voff)[_i]), (PG8_LAS unsigned*)(lds + (bufoff) + ldsw + _i * 8192), 16, 0, 0); } while (0)
; #define PG8_LDA(dst, b, h) do { _Pragma("unroll") for (int m = 0; m < 4; ++m) _Pragma("unroll") for (int k = 0; k < 2; ++k) dst[m][k] = *(const PG8_LAS bf16x8*)(lds + PG8_SA(b, h) + aoff + m * 2048 + k * 1024); } while (0)
; #define PG8_LDB(dst, b, h) do { _Pragma("unroll") for (int n = 0; n < 2; ++n) _Pragma("unroll") for (int k = 0; k < 2; ++k) dst[n][k] = *(const PG8_LAS bf16x8*)(lds + PG8_SB(b, h) + boff + n * 2048 + k * 1024); } while (0)
; #define PG8_MMA(ai, bj, At, Bt) do { __builtin_amdgcn_s_setprio(1); _Pragma("unroll") for (int m = 0; m < 4; ++m) _Pragma("unroll") for (int n = 0; n < 2; ++n) _Pragma("unroll") for (int k = 0; k < 2; ++k) \
;         acc[ai][bj][m][n] = __builtin_amdgcn_mfma_f32_16x16x32_bf16(Bt[n][k], At[m][k], acc[ai][bj][m][n], 0, 0, 0); __builtin_amdgcn_s_setprio(0); } while (0)
; #define PG8_WAIT_V(n) asm volatile("s_waitcnt vmcnt(" #n ")" ::: "memory")
; #define PG8_WAIT_L(n) asm volatile("s_waitcnt lgkmcnt(" #n ")" ::: "memory")
; #define PG8_BAR __builtin_amdgcn_s_barrier()
; #define PG8_SCHED __builtin_amdgcn_sched_barrier(0)
; template <class Epi, class Sched, bool ALIGN_EPI = false, bool SP2 = false>
; __device__ __forceinline__ void gemm_phase(PG8_LAS unsigned char* lds, const Gemm g, const Sched& S, const Epi& E) {
;     ...
;             PG8_WAIT_V(8); PG8_WAIT_L(0); PG8_BAR; PG8_MMA(1, 0, At, B0); PG8_MMA(1, 1, At, B1); PG8_BAR; PG8_SCHED;
;             PG8_LDB(B0, 1, 0); PG8_LDB(B1, 1, 1); PG8_SCHED; PG8_LDA(At, 1, 0); PG8_STAGE(PG8_SA(0, 1), a2 + hstepA, voffA);
;             PG8_WAIT_V(8); PG8_WAIT_L(0); PG8_BAR; PG8_MMA(0, 0, At, B0); PG8_MMA(0, 1, At, B1); PG8_BAR; PG8_SCHED;
	s_waitcnt lgkmcnt(0)
	v_mfma_f32_16x16x32_bf16 v[60:63], v[146:149], v[186:189], v[60:63]
	v_mfma_f32_16x16x32_bf16 v[56:59], v[162:165], v[186:189], v[56:59]
	v_mfma_f32_16x16x32_bf16 v[44:47], v[146:149], v[194:197], v[44:47]
	v_mfma_f32_16x16x32_bf16 v[40:43], v[162:165], v[194:197], v[40:43]
	v_mfma_f32_16x16x32_bf16 v[28:31], v[146:149], v[206:209], v[28:31]
	v_mfma_f32_16x16x32_bf16 v[24:27], v[162:165], v[206:209], v[24:27]
	v_mfma_f32_16x16x32_bf16 v[12:15], v[146:149], v[214:217], v[12:15]
	v_mfma_f32_16x16x32_bf16 v[8:11], v[162:165], v[214:217], v[8:11]
	v_mfma_f32_16x16x32_bf16 v[60:63], v[158:161], v[190:193], v[60:63]
	v_mfma_f32_16x16x32_bf16 v[56:59], v[166:169], v[190:193], v[56:59]
	v_mfma_f32_16x16x32_bf16 v[44:47], v[158:161], v[198:201], v[44:47]
	v_mfma_f32_16x16x32_bf16 v[40:43], v[166:169], v[198:201], v[40:43]
	v_mfma_f32_16x16x32_bf16 v[28:31], v[158:161], v[210:213], v[28:31]
	v_mfma_f32_16x16x32_bf16 v[24:27], v[166:169], v[210:213], v[24:27]
	v_mfma_f32_16x16x32_bf16 v[12:15], v[158:161], v[218:221], v[12:15]
	v_mfma_f32_16x16x32_bf16 v[8:11], v[166:169], v[218:221], v[8:11]
	v_mfma_f32_16x16x32_bf16 v[52:55], v[170:173], v[186:189], v[52:55]
	v_mfma_f32_16x16x32_bf16 v[48:51], v[178:181], v[186:189], v[48:51]
	v_mfma_f32_16x16x32_bf16 v[36:39], v[170:173], v[194:197], v[36:39]
	v_mfma_f32_16x16x32_bf16 v[32:35], v[178:181], v[194:197], v[32:35]
	v_mfma_f32_16x16x32_bf16 v[20:23], v[170:173], v[206:209], v[20:23]
	v_mfma_f32_16x16x32_bf16 v[16:19], v[178:181], v[206:209], v[16:19]
	v_mfma_f32_16x16x32_bf16 v[4:7], v[170:173], v[214:217], v[4:7]
	v_mfma_f32_16x16x32_bf16 v[0:3], v[178:181], v[214:217], v[0:3]
	v_mfma_f32_16x16x32_bf16 v[52:55], v[174:177], v[190:193], v[52:55]
	v_mfma_f32_16x16x32_bf16 v[48:51], v[182:185], v[190:193], v[48:51]
	v_mfma_f32_16x16x32_bf16 v[36:39], v[174:177], v[198:201], v[36:39]
	v_mfma_f32_16x16x32_bf16 v[32:35], v[182:185], v[198:201], v[32:35]
	v_mfma_f32_16x16x32_bf16 v[20:23], v[174:177], v[210:213], v[20:23]
	v_mfma_f32_16x16x32_bf16 v[16:19], v[182:185], v[210:213], v[16:19]
	v_mfma_f32_16x16x32_bf16 v[4:7], v[174:177], v[218:221], v[4:7]
	v_mfma_f32_16x16x32_bf16 v[0:3], v[182:185], v[218:221], v[0:3]
	s_barrier
	s_add_i32 s54, 0, 0x18000
	s_add_i32 s55, 0, 0x1c000
	v_add_u32_e32 v166, s54, v151
	v_add_u32_e32 v182, s55, v151
	ds_read_b128 v[146:149], v166
	ds_read_b128 v[158:161], v166 offset:1024
	ds_read_b128 v[162:165], v166 offset:2048
	ds_read_b128 v[166:169], v166 offset:3072
	ds_read_b128 v[170:173], v182
	ds_read_b128 v[174:177], v182 offset:1024
	ds_read_b128 v[178:181], v182 offset:2048
	ds_read_b128 v[182:185], v182 offset:3072
	s_add_u32 s34, s34, 0x20000
	s_addc_u32 s35, s35, 0
	s_mov_b32 m0, s40
	v_lshl_add_u64 v[228:229], s[34:35], 0, v[128:129]
	ds_read_b128 v[186:189], v155 offset:32768
	ds_read_b128 v[190:193], v155 offset:33792
	ds_read_b128 v[194:197], v155 offset:34816
	ds_read_b128 v[198:201], v155 offset:35840
	ds_read_b128 v[206:209], v155 offset:36864
	ds_read_b128 v[210:213], v155 offset:37888
	ds_read_b128 v[214:217], v155 offset:38912
	ds_read_b128 v[218:221], v155 offset:39936
	global_load_lds_dwordx4 v[228:229], off
	v_lshl_add_u64 v[228:229], s[34:35], 0, v[132:133]
	s_mov_b32 m0, s41
	s_nop 0
	global_load_lds_dwordx4 v[228:229], off
	s_waitcnt vmcnt(8)
	s_waitcnt lgkmcnt(0)
	s_barrier
	s_waitcnt lgkmcnt(0)
	v_mfma_f32_16x16x32_bf16 v[124:127], v[146:149], v[186:189], v[124:127]
	v_mfma_f32_16x16x32_bf16 v[120:123], v[162:165], v[186:189], v[120:123]
	v_mfma_f32_16x16x32_bf16 v[108:111], v[146:149], v[194:197], v[108:111]
	v_mfma_f32_16x16x32_bf16 v[104:107], v[162:165], v[194:197], v[104:107]
	v_mfma_f32_16x16x32_bf16 v[92:95], v[146:149], v[206:209], v[92:95]
	v_mfma_f32_16x16x32_bf16 v[88:91], v[162:165], v[206:209], v[88:91]
	v_mfma_f32_16x16x32_bf16 v[76:79], v[146:149], v[214:217], v[76:79]
	v_mfma_f32_16x16x32_bf16 v[72:75], v[162:165], v[214:217], v[72:75]
	v_mfma_f32_16x16x32_bf16 v[124:127], v[158:161], v[190:193], v[124:127]
	v_mfma_f32_16x16x32_bf16 v[120:123], v[166:169], v[190:193], v[120:123]
	v_mfma_f32_16x16x32_bf16 v[108:111], v[158:161], v[198:201], v[108:111]
	v_mfma_f32_16x16x32_bf16 v[104:107], v[166:169], v[198:201], v[104:107]
	v_mfma_f32_16x16x32_bf16 v[92:95], v[158:161], v[210:213], v[92:95]
	v_mfma_f32_16x16x32_bf16 v[88:91], v[166:169], v[210:213], v[88:91]
	v_mfma_f32_16x16x32_bf16 v[76:79], v[158:161], v[218:221], v[76:79]
	v_mfma_f32_16x16x32_bf16 v[72:75], v[166:169], v[218:221], v[72:75]
	v_mfma_f32_16x16x32_bf16 v[116:119], v[170:173], v[186:189], v[116:119]
	v_mfma_f32_16x16x32_bf16 v[112:115], v[178:181], v[186:189], v[112:115]
	v_mfma_f32_16x16x32_bf16 v[100:103], v[170:173], v[194:197], v[100:103]
	v_mfma_f32_16x16x32_bf16 v[96:99], v[178:181], v[194:197], v[96:99]
	v_mfma_f32_16x16x32_bf16 v[84:87], v[170:173], v[206:209], v[84:87]
	v_mfma_f32_16x16x32_bf16 v[80:83], v[178:181], v[206:209], v[80:83]
	v_mfma_f32_16x16x32_bf16 v[68:71], v[170:173], v[214:217], v[68:71]
	v_mfma_f32_16x16x32_bf16 v[64:67], v[178:181], v[214:217], v[64:67]
	v_mfma_f32_16x16x32_bf16 v[116:119], v[174:177], v[190:193], v[116:119]
	v_mfma_f32_16x16x32_bf16 v[112:115], v[182:185], v[190:193], v[112:115]
	v_mfma_f32_16x16x32_bf16 v[100:103], v[174:177], v[198:201], v[100:103]
	v_mfma_f32_16x16x32_bf16 v[96:99], v[182:185], v[198:201], v[96:99]
	v_mfma_f32_16x16x32_bf16 v[84:87], v[174:177], v[210:213], v[84:87]
	v_mfma_f32_16x16x32_bf16 v[80:83], v[182:185], v[210:213], v[80:83]
	v_mfma_f32_16x16x32_bf16 v[68:71], v[174:177], v[218:221], v[68:71]
	v_mfma_f32_16x16x32_bf16 v[64:67], v[182:185], v[218:221], v[64:67]
	s_barrier
; #define PG8_STAGE(bufoff, gbase, voff) do { _Pragma("unroll") for (int _i = 0; _i < 2; ++_i) \
;         __builtin_amdgcn_global_load_lds((const unsigned*)((const char*)(gbase) + (voff)[_i]), (PG8_LAS unsigned*)(lds + (bufoff) + ldsw + _i * 8192), 16, 0, 0); } while (0)
; #define PG8_LDA(dst, b, h) do { _Pragma("unroll") for (int m = 0; m < 4; ++m) _Pragma("unroll") for (int k = 0; k < 2; ++k) dst[m][k] = *(const PG8_LAS bf16x8*)(lds + PG8_SA(b, h) + aoff + m * 2048 + k * 1024); } while (0)
; #define PG8_MMA(ai, bj, At, Bt) do { __builtin_amdgcn_s_setprio(1); _Pragma("unroll") for (int m = 0; m < 4; ++m) _Pragma("unroll") for (int n = 0; n < 2; ++n) _Pragma("unroll") for (int k = 0; k < 2; ++k) \
;         acc[ai][bj][m][n] = __builtin_amdgcn_mfma_f32_16x16x32_bf16(Bt[n][k], At[m][k], acc[ai][bj][m][n], 0, 0, 0); __builtin_amdgcn_s_setprio(0); } while (0)
; #define PG8_WAIT_V(n) asm volatile("s_waitcnt vmcnt(" #n ")" ::: "memory")
; #define PG8_WAIT_L(n) asm volatile("s_waitcnt lgkmcnt(" #n ")" ::: "memory")
; #define PG8_BAR __builtin_amdgcn_s_barrier()
; #define PG8_SCHED __builtin_amdgcn_sched_barrier(0)
; template <class Epi, class Sched, bool ALIGN_EPI = false, bool SP2 = false>
; __device__ __forceinline__ void gemm_phase(PG8_LAS unsigned char* lds, const Gemm g, const Sched& S, const Epi& E) {
;     ...
;             PG8_LDA(At, 1, 1); PG8_STAGE(PG8_SB(1, 0), b3, voffB); PG8_STAGE(PG8_SB(1, 1), b3 + hstep, voffB); PG8_STAGE(PG8_SA(1, 0), a3, voffA);
;             PG8_WAIT_V(8); PG8_WAIT_L(0); PG8_BAR; PG8_MMA(1, 0, At, B0); PG8_MMA(1, 1, At, B1); PG8_BAR; PG8_SCHED;
	s_add_i32 s34, s54, s37
	v_lshl_add_u64 v[202:203], v[202:203], 0, s[10:11]
	s_mov_b32 m0, s34
	ds_read_b128 v[186:189], v155 offset:49152
	ds_read_b128 v[190:193], v155 offset:50176
	ds_read_b128 v[194:197], v155 offset:51200
	ds_read_b128 v[198:201], v155 offset:52224
	ds_read_b128 v[206:209], v155 offset:53248
	ds_read_b128 v[210:213], v155 offset:54272
	ds_read_b128 v[214:217], v155 offset:55296
	ds_read_b128 v[218:221], v155 offset:56320
	global_load_lds_dwordx4 v[202:203], off
	s_add_i32 m0, s34, 0x2000
	s_add_u32 s30, s30, 0x20080
	v_lshl_add_u64 v[202:203], v[222:223], 0, s[10:11]
	s_addc_u32 s31, s31, 0
	s_add_i32 s34, s55, s37
	global_load_lds_dwordx4 v[202:203], off
	v_lshl_add_u64 v[202:203], s[30:31], 0, v[130:131]
	s_mov_b32 m0, s34
	s_nop 0
	global_load_lds_dwordx4 v[202:203], off
	v_lshl_add_u64 v[202:203], s[30:31], 0, v[134:135]
	s_add_i32 m0, s34, 0x2000
	s_nop 0
	global_load_lds_dwordx4 v[202:203], off
	v_lshl_add_u64 v[202:203], v[224:225], 0, s[10:11]
	s_mov_b32 m0, s43
	s_nop 0
	global_load_lds_dwordx4 v[202:203], off
	v_lshl_add_u64 v[202:203], v[226:227], 0, s[10:11]
	s_mov_b32 m0, s44
	s_nop 0
	global_load_lds_dwordx4 v[202:203], off
	s_waitcnt vmcnt(8)
	s_waitcnt lgkmcnt(0)
	s_barrier
	s_waitcnt lgkmcnt(0)
	v_mfma_f32_16x16x32_bf16 v[60:63], v[146:149], v[186:189], v[60:63]
	v_mfma_f32_16x16x32_bf16 v[56:59], v[162:165], v[186:189], v[56:59]
	v_mfma_f32_16x16x32_bf16 v[44:47], v[146:149], v[194:197], v[44:47]
	v_mfma_f32_16x16x32_bf16 v[40:43], v[162:165], v[194:197], v[40:43]
	v_mfma_f32_16x16x32_bf16 v[28:31], v[146:149], v[206:209], v[28:31]
	v_mfma_f32_16x16x32_bf16 v[24:27], v[162:165], v[206:209], v[24:27]
	v_mfma_f32_16x16x32_bf16 v[12:15], v[146:149], v[214:217], v[12:15]
	v_mfma_f32_16x16x32_bf16 v[8:11], v[162:165], v[214:217], v[8:11]
	v_mfma_f32_16x16x32_bf16 v[60:63], v[158:161], v[190:193], v[60:63]
	v_mfma_f32_16x16x32_bf16 v[56:59], v[166:169], v[190:193], v[56:59]
	v_mfma_f32_16x16x32_bf16 v[44:47], v[158:161], v[198:201], v[44:47]
	v_mfma_f32_16x16x32_bf16 v[40:43], v[166:169], v[198:201], v[40:43]
	v_mfma_f32_16x16x32_bf16 v[28:31], v[158:161], v[210:213], v[28:31]
	v_mfma_f32_16x16x32_bf16 v[24:27], v[166:169], v[210:213], v[24:27]
	v_mfma_f32_16x16x32_bf16 v[12:15], v[158:161], v[218:221], v[12:15]
	v_mfma_f32_16x16x32_bf16 v[8:11], v[166:169], v[218:221], v[8:11]
	v_mfma_f32_16x16x32_bf16 v[52:55], v[170:173], v[186:189], v[52:55]
	v_mfma_f32_16x16x32_bf16 v[48:51], v[178:181], v[186:189], v[48:51]
	v_mfma_f32_16x16x32_bf16 v[36:39], v[170:173], v[194:197], v[36:39]
	v_mfma_f32_16x16x32_bf16 v[32:35], v[178:181], v[194:197], v[32:35]
	v_mfma_f32_16x16x32_bf16 v[20:23], v[170:173], v[206:209], v[20:23]
	v_mfma_f32_16x16x32_bf16 v[16:19], v[178:181], v[206:209], v[16:19]
	v_mfma_f32_16x16x32_bf16 v[4:7], v[170:173], v[214:217], v[4:7]
	v_mfma_f32_16x16x32_bf16 v[0:3], v[178:181], v[214:217], v[0:3]
	v_mfma_f32_16x16x32_bf16 v[52:55], v[174:177], v[190:193], v[52:55]
	v_mfma_f32_16x16x32_bf16 v[48:51], v[182:185], v[190:193], v[48:51]
	v_mfma_f32_16x16x32_bf16 v[36:39], v[174:177], v[198:201], v[36:39]
	v_mfma_f32_16x16x32_bf16 v[32:35], v[182:185], v[198:201], v[32:35]
	v_mfma_f32_16x16x32_bf16 v[20:23], v[174:177], v[210:213], v[20:23]
	v_mfma_f32_16x16x32_bf16 v[16:19], v[182:185], v[210:213], v[16:19]
	v_mfma_f32_16x16x32_bf16 v[4:7], v[174:177], v[218:221], v[4:7]
	v_mfma_f32_16x16x32_bf16 v[0:3], v[182:185], v[218:221], v[0:3]
	s_barrier
	s_add_i32 s53, s53, 2
	s_add_u32 s28, s28, 0x100
	s_addc_u32 s29, s29, 0
	s_add_u32 s51, s51, 0x100
	s_addc_u32 s52, s52, 0
	s_cmp_gt_u32 s53, 5
	s_cbranch_scc0 .LBB0_818
	s_and_b64 vcc, exec, s[12:13]
	s_cbranch_vccz .LBB0_821
	s_barrier

; #define PG8_STAGE(bufoff, gbase, voff) do { _Pragma("unroll") for (int _i = 0; _i < 2; ++_i) \
;         __builtin_amdgcn_global_load_lds((const unsigned*)((const char*)(gbase) + (voff)[_i]), (PG8_LAS unsigned*)(lds + (bufoff) + ldsw + _i * 8192), 16, 0, 0); } while (0)
; #define PG8_LDA(dst, b, h) do { _Pragma("unroll") for (int m = 0; m < 4; ++m) _Pragma("unroll") for (int k = 0; k < 2; ++k) dst[m][k] = *(const PG8_LAS bf16x8*)(lds + PG8_SA(b, h) + aoff + m * 2048 + k * 1024); } while (0)
; #define PG8_LDB(dst, b, h) do { _Pragma("unroll") for (int n = 0; n < 2; ++n) _Pragma("unroll") for (int k = 0; k < 2; ++k) dst[n][k] = *(const PG8_LAS bf16x8*)(lds + PG8_SB(b, h) + boff + n * 2048 + k * 1024); } while (0)
; #define PG8_MMA(ai, bj, At, Bt) do { __builtin_amdgcn_s_setprio(1); _Pragma("unroll") for (int m = 0; m < 4; ++m) _Pragma("unroll") for (int n = 0; n < 2; ++n) _Pragma("unroll") for (int k = 0; k < 2; ++k) \
;         acc[ai][bj][m][n] = __builtin_amdgcn_mfma_f32_16x16x32_bf16(Bt[n][k], At[m][k], acc[ai][bj][m][n], 0, 0, 0); __builtin_amdgcn_s_setprio(0); } while (0)
; #define PG8_WAIT_V(n) asm volatile("s_waitcnt vmcnt(" #n ")" ::: "memory")
; #define PG8_WAIT_L(n) asm volatile("s_waitcnt lgkmcnt(" #n ")" ::: "memory")
; #define PG8_BAR __builtin_amdgcn_s_barrier()
; #define PG8_SCHED __builtin_amdgcn_sched_barrier(0)
; template <class Epi, class Sched, bool ALIGN_EPI = false, bool SP2 = false>
; __device__ __forceinline__ void gemm_phase(PG8_LAS unsigned char* lds, const Gemm g, const Sched& S, const Epi& E) {
;     ...
;             PG8_LDB(B0, 0, 0); PG8_LDB(B1, 0, 1); PG8_SCHED; PG8_LDA(At, 0, 0); PG8_STAGE(PG8_SA(1, 1), a1 + hstepA, voffA);
;             PG8_WAIT_V(8); PG8_WAIT_L(0); PG8_BAR; PG8_MMA(0, 0, At, B0); PG8_MMA(0, 1, At, B1); PG8_BAR; PG8_SCHED;
;             PG8_LDA(At, 0, 1); PG8_STAGE(PG8_SB(0, 0), b2, voffB); PG8_STAGE(PG8_SB(0, 1), b2 + hstep, voffB); PG8_STAGE(PG8_SA(0, 0), a2, voffA);
.LBB0_860:
	ds_read_b128 v[146:149], v153
	ds_read_b128 v[158:161], v153 offset:1024
	ds_read_b128 v[162:165], v153 offset:2048
	ds_read_b128 v[166:169], v153 offset:3072
	ds_read_b128 v[170:173], v154
	ds_read_b128 v[174:177], v154 offset:1024
	ds_read_b128 v[178:181], v154 offset:2048
	ds_read_b128 v[182:185], v154 offset:3072
	s_add_u32 s28, s26, 0xfffe0080
	s_addc_u32 s29, s27, -1
	s_cmp_eq_u32 s51, 4
	s_cselect_b32 s31, s6, s29
	s_cselect_b32 s30, s7, s28
	s_cselect_b32 s29, s15, s25
	s_cselect_b32 s28, s17, s23
	v_lshl_add_u64 v[202:203], s[26:27], 0, v[138:139]
	s_add_i32 m0, s37, 0xc000
	ds_read_b128 v[186:189], v155
	ds_read_b128 v[190:193], v155 offset:1024
	ds_read_b128 v[194:197], v155 offset:2048
	ds_read_b128 v[198:201], v155 offset:3072
	ds_read_b128 v[206:209], v155 offset:4096
	ds_read_b128 v[210:213], v155 offset:5120
	ds_read_b128 v[214:217], v155 offset:6144
	ds_read_b128 v[218:221], v155 offset:7168
	global_load_lds_dwordx4 v[202:203], off
	v_lshl_add_u64 v[202:203], s[26:27], 0, v[140:141]
	s_add_i32 m0, s37, 0xe000
	s_nop 0
	global_load_lds_dwordx4 v[202:203], off
	s_waitcnt vmcnt(8)
	s_waitcnt lgkmcnt(0)
	s_barrier
	s_waitcnt lgkmcnt(0)
	v_mfma_f32_16x16x32_bf16 v[124:127], v[146:149], v[186:189], v[124:127]
	v_mfma_f32_16x16x32_bf16 v[120:123], v[162:165], v[186:189], v[120:123]
	v_mfma_f32_16x16x32_bf16 v[108:111], v[146:149], v[194:197], v[108:111]
	v_mfma_f32_16x16x32_bf16 v[104:107], v[162:165], v[194:197], v[104:107]
	v_mfma_f32_16x16x32_bf16 v[92:95], v[146:149], v[206:209], v[92:95]
	v_mfma_f32_16x16x32_bf16 v[88:91], v[162:165], v[206:209], v[88:91]
	v_mfma_f32_16x16x32_bf16 v[76:79], v[146:149], v[214:217], v[76:79]
	v_mfma_f32_16x16x32_bf16 v[72:75], v[162:165], v[214:217], v[72:75]
	v_mfma_f32_16x16x32_bf16 v[124:127], v[158:161], v[190:193], v[124:127]
	v_mfma_f32_16x16x32_bf16 v[120:123], v[166:169], v[190:193], v[120:123]
	v_mfma_f32_16x16x32_bf16 v[108:111], v[158:161], v[198:201], v[108:111]
	v_mfma_f32_16x16x32_bf16 v[104:107], v[166:169], v[198:201], v[104:107]
	v_mfma_f32_16x16x32_bf16 v[92:95], v[158:161], v[210:213], v[92:95]
	v_mfma_f32_16x16x32_bf16 v[88:91], v[166:169], v[210:213], v[88:91]
	v_mfma_f32_16x16x32_bf16 v[76:79], v[158:161], v[218:221], v[76:79]
	v_mfma_f32_16x16x32_bf16 v[72:75], v[166:169], v[218:221], v[72:75]
	v_mfma_f32_16x16x32_bf16 v[116:119], v[170:173], v[186:189], v[116:119]
	v_mfma_f32_16x16x32_bf16 v[112:115], v[178:181], v[186:189], v[112:115]
	v_mfma_f32_16x16x32_bf16 v[100:103], v[170:173], v[194:197], v[100:103]
	v_mfma_f32_16x16x32_bf16 v[96:99], v[178:181], v[194:197], v[96:99]
	v_mfma_f32_16x16x32_bf16 v[84:87], v[170:173], v[206:209], v[84:87]
	v_mfma_f32_16x16x32_bf16 v[80:83], v[178:181], v[206:209], v[80:83]
	v_mfma_f32_16x16x32_bf16 v[68:71], v[170:173], v[214:217], v[68:71]
	v_mfma_f32_16x16x32_bf16 v[64:67], v[178:181], v[214:217], v[64:67]
	v_mfma_f32_16x16x32_bf16 v[116:119], v[174:177], v[190:193], v[116:119]
	v_mfma_f32_16x16x32_bf16 v[112:115], v[182:185], v[190:193], v[112:115]
	v_mfma_f32_16x16x32_bf16 v[100:103], v[174:177], v[198:201], v[100:103]
	v_mfma_f32_16x16x32_bf16 v[96:99], v[182:185], v[198:201], v[96:99]
	v_mfma_f32_16x16x32_bf16 v[84:87], v[174:177], v[210:213], v[84:87]
	v_mfma_f32_16x16x32_bf16 v[80:83], v[182:185], v[210:213], v[80:83]
	v_mfma_f32_16x16x32_bf16 v[68:71], v[174:177], v[218:221], v[68:71]
	v_mfma_f32_16x16x32_bf16 v[64:67], v[182:185], v[218:221], v[64:67]
	s_barrier
	s_add_i32 s52, s49, s36
	v_lshl_add_u64 v[202:203], s[28:29], 0, v[130:131]
	s_mov_b32 m0, s52
	ds_read_b128 v[186:189], v155 offset:16384
	ds_read_b128 v[190:193], v155 offset:17408
	ds_read_b128 v[194:197], v155 offset:18432
	ds_read_b128 v[198:201], v155 offset:19456
	ds_read_b128 v[206:209], v155 offset:20480
	ds_read_b128 v[210:213], v155 offset:21504
	ds_read_b128 v[214:217], v155 offset:22528
	ds_read_b128 v[218:221], v155 offset:23552
	global_load_lds_dwordx4 v[202:203], off
	s_add_i32 m0, s52, 0x2000
	s_add_u32 s52, s28, 0x20000
	v_lshl_add_u64 v[222:223], s[28:29], 0, v[134:135]
	s_addc_u32 s53, s29, 0
	s_add_i32 s54, s50, s36
	global_load_lds_dwordx4 v[222:223], off
	v_lshl_add_u64 v[224:225], s[52:53], 0, v[130:131]
	s_mov_b32 m0, s54
	v_lshl_add_u64 v[226:227], s[30:31], 0, v[132:133]
	global_load_lds_dwordx4 v[224:225], off
	v_lshl_add_u64 v[224:225], s[52:53], 0, v[134:135]
	s_add_i32 m0, s54, 0x2000
	s_nop 0
	global_load_lds_dwordx4 v[224:225], off
	v_lshl_add_u64 v[224:225], s[30:31], 0, v[128:129]
	s_mov_b32 m0, s37
	s_nop 0
	global_load_lds_dwordx4 v[224:225], off
	s_mov_b32 m0, s38
	s_nop 0
	global_load_lds_dwordx4 v[226:227], off
	s_waitcnt vmcnt(8)
	s_waitcnt lgkmcnt(0)
	s_barrier
; #define PG8_STAGE(bufoff, gbase, voff) do { _Pragma("unroll") for (int _i = 0; _i < 2; ++_i) \
;         __builtin_amdgcn_global_load_lds((const unsigned*)((const char*)(gbase) + (voff)[_i]), (PG8_LAS unsigned*)(lds + (bufoff) + ldsw + _i * 8192), 16, 0, 0); } while (0)
; #define PG8_LDA(dst, b, h) do { _Pragma("unroll") for (int m = 0; m < 4; ++m) _Pragma("unroll") for (int k = 0; k < 2; ++k) dst[m][k] = *(const PG8_LAS bf16x8*)(lds + PG8_SA(b, h) + aoff + m * 2048 + k * 1024); } while (0)
; #define PG8_LDB(dst, b, h) do { _Pragma("unroll") for (int n = 0; n < 2; ++n) _Pragma("unroll") for (int k = 0; k < 2; ++k) dst[n][k] = *(const PG8_LAS bf16x8*)(lds + PG8_SB(b, h) + boff + n * 2048 + k * 1024); } while (0)
; #define PG8_MMA(ai, bj, At, Bt) do { __builtin_amdgcn_s_setprio(1); _Pragma("unroll") for (int m = 0; m < 4; ++m) _Pragma("unroll") for (int n = 0; n < 2; ++n) _Pragma("unroll") for (int k = 0; k < 2; ++k) \
;         acc[ai][bj][m][n] = __builtin_amdgcn_mfma_f32_16x16x32_bf16(Bt[n][k], At[m][k], acc[ai][bj][m][n], 0, 0, 0); __builtin_amdgcn_s_setprio(0); } while (0)
; #define PG8_WAIT_V(n) asm volatile("s_waitcnt vmcnt(" #n ")" ::: "memory")
; #define PG8_WAIT_L(n) asm volatile("s_waitcnt lgkmcnt(" #n ")" ::: "memory")
; #define PG8_BAR __builtin_amdgcn_s_barrier()
; #define PG8_SCHED __builtin_amdgcn_sched_barrier(0)
; template <class Epi, class Sched, bool ALIGN_EPI = false, bool SP2 = false>
; __device__ __forceinline__ void gemm_phase(PG8_LAS unsigned char* lds, const Gemm g, const Sched& S, const Epi& E) {
;     ...
;             PG8_WAIT_V(8); PG8_WAIT_L(0); PG8_BAR; PG8_MMA(1, 0, At, B0); PG8_MMA(1, 1, At, B1); PG8_BAR; PG8_SCHED;
;             PG8_LDB(B0, 1, 0); PG8_LDB(B1, 1, 1); PG8_SCHED; PG8_LDA(At, 1, 0); PG8_STAGE(PG8_SA(0, 1), a2 + hstepA, voffA);
;             PG8_WAIT_V(8); PG8_WAIT_L(0); PG8_BAR; PG8_MMA(0, 0, At, B0); PG8_MMA(0, 1, At, B1); PG8_BAR; PG8_SCHED;
	s_waitcnt lgkmcnt(0)
	v_mfma_f32_16x16x32_bf16 v[60:63], v[146:149], v[186:189], v[60:63]
	v_mfma_f32_16x16x32_bf16 v[56:59], v[162:165], v[186:189], v[56:59]
	v_mfma_f32_16x16x32_bf16 v[44:47], v[146:149], v[194:197], v[44:47]
	v_mfma_f32_16x16x32_bf16 v[40:43], v[162:165], v[194:197], v[40:43]
	v_mfma_f32_16x16x32_bf16 v[28:31], v[146:149], v[206:209], v[28:31]
	v_mfma_f32_16x16x32_bf16 v[24:27], v[162:165], v[206:209], v[24:27]
	v_mfma_f32_16x16x32_bf16 v[12:15], v[146:149], v[214:217], v[12:15]
	v_mfma_f32_16x16x32_bf16 v[8:11], v[162:165], v[214:217], v[8:11]
	v_mfma_f32_16x16x32_bf16 v[60:63], v[158:161], v[190:193], v[60:63]
	v_mfma_f32_16x16x32_bf16 v[56:59], v[166:169], v[190:193], v[56:59]
	v_mfma_f32_16x16x32_bf16 v[44:47], v[158:161], v[198:201], v[44:47]
	v_mfma_f32_16x16x32_bf16 v[40:43], v[166:169], v[198:201], v[40:43]
	v_mfma_f32_16x16x32_bf16 v[28:31], v[158:161], v[210:213], v[28:31]
	v_mfma_f32_16x16x32_bf16 v[24:27], v[166:169], v[210:213], v[24:27]
	v_mfma_f32_16x16x32_bf16 v[12:15], v[158:161], v[218:221], v[12:15]
	v_mfma_f32_16x16x32_bf16 v[8:11], v[166:169], v[218:221], v[8:11]
	v_mfma_f32_16x16x32_bf16 v[52:55], v[170:173], v[186:189], v[52:55]
	v_mfma_f32_16x16x32_bf16 v[48:51], v[178:181], v[186:189], v[48:51]
	v_mfma_f32_16x16x32_bf16 v[36:39], v[170:173], v[194:197], v[36:39]
	v_mfma_f32_16x16x32_bf16 v[32:35], v[178:181], v[194:197], v[32:35]
	v_mfma_f32_16x16x32_bf16 v[20:23], v[170:173], v[206:209], v[20:23]
	v_mfma_f32_16x16x32_bf16 v[16:19], v[178:181], v[206:209], v[16:19]
	v_mfma_f32_16x16x32_bf16 v[4:7], v[170:173], v[214:217], v[4:7]
	v_mfma_f32_16x16x32_bf16 v[0:3], v[178:181], v[214:217], v[0:3]
	v_mfma_f32_16x16x32_bf16 v[52:55], v[174:177], v[190:193], v[52:55]
	v_mfma_f32_16x16x32_bf16 v[48:51], v[182:185], v[190:193], v[48:51]
	v_mfma_f32_16x16x32_bf16 v[36:39], v[174:177], v[198:201], v[36:39]
	v_mfma_f32_16x16x32_bf16 v[32:35], v[182:185], v[198:201], v[32:35]
	v_mfma_f32_16x16x32_bf16 v[20:23], v[174:177], v[210:213], v[20:23]
	v_mfma_f32_16x16x32_bf16 v[16:19], v[182:185], v[210:213], v[16:19]
	v_mfma_f32_16x16x32_bf16 v[4:7], v[174:177], v[218:221], v[4:7]
	v_mfma_f32_16x16x32_bf16 v[0:3], v[182:185], v[218:221], v[0:3]
	s_barrier
	s_add_i32 s52, 0, 0x18000
	s_add_i32 s53, 0, 0x1c000
	v_add_u32_e32 v166, s52, v151
	v_add_u32_e32 v182, s53, v151
	ds_read_b128 v[146:149], v166
	ds_read_b128 v[158:161], v166 offset:1024
	ds_read_b128 v[162:165], v166 offset:2048
	ds_read_b128 v[166:169], v166 offset:3072
	ds_read_b128 v[170:173], v182
	ds_read_b128 v[174:177], v182 offset:1024
	ds_read_b128 v[178:181], v182 offset:2048
	ds_read_b128 v[182:185], v182 offset:3072
	s_add_u32 s30, s30, 0x20000
	s_addc_u32 s31, s31, 0
	s_mov_b32 m0, s39
	v_lshl_add_u64 v[228:229], s[30:31], 0, v[128:129]
	ds_read_b128 v[186:189], v155 offset:32768
	ds_read_b128 v[190:193], v155 offset:33792
	ds_read_b128 v[194:197], v155 offset:34816
	ds_read_b128 v[198:201], v155 offset:35840
	ds_read_b128 v[206:209], v155 offset:36864
	ds_read_b128 v[210:213], v155 offset:37888
	ds_read_b128 v[214:217], v155 offset:38912
	ds_read_b128 v[218:221], v155 offset:39936
	global_load_lds_dwordx4 v[228:229], off
	v_lshl_add_u64 v[228:229], s[30:31], 0, v[132:133]
	s_mov_b32 m0, s40
	s_nop 0
	global_load_lds_dwordx4 v[228:229], off
	s_waitcnt vmcnt(8)
	s_waitcnt lgkmcnt(0)
	s_barrier
	s_waitcnt lgkmcnt(0)
	v_mfma_f32_16x16x32_bf16 v[124:127], v[146:149], v[186:189], v[124:127]
	v_mfma_f32_16x16x32_bf16 v[120:123], v[162:165], v[186:189], v[120:123]
	v_mfma_f32_16x16x32_bf16 v[108:111], v[146:149], v[194:197], v[108:111]
	v_mfma_f32_16x16x32_bf16 v[104:107], v[162:165], v[194:197], v[104:107]
	v_mfma_f32_16x16x32_bf16 v[92:95], v[146:149], v[206:209], v[92:95]
	v_mfma_f32_16x16x32_bf16 v[88:91], v[162:165], v[206:209], v[88:91]
	v_mfma_f32_16x16x32_bf16 v[76:79], v[146:149], v[214:217], v[76:79]
	v_mfma_f32_16x16x32_bf16 v[72:75], v[162:165], v[214:217], v[72:75]
	v_mfma_f32_16x16x32_bf16 v[124:127], v[158:161], v[190:193], v[124:127]
	v_mfma_f32_16x16x32_bf16 v[120:123], v[166:169], v[190:193], v[120:123]
	v_mfma_f32_16x16x32_bf16 v[108:111], v[158:161], v[198:201], v[108:111]
	v_mfma_f32_16x16x32_bf16 v[104:107], v[166:169], v[198:201], v[104:107]
	v_mfma_f32_16x16x32_bf16 v[92:95], v[158:161], v[210:213], v[92:95]
	v_mfma_f32_16x16x32_bf16 v[88:91], v[166:169], v[210:213], v[88:91]
	v_mfma_f32_16x16x32_bf16 v[76:79], v[158:161], v[218:221], v[76:79]
	v_mfma_f32_16x16x32_bf16 v[72:75], v[166:169], v[218:221], v[72:75]
	v_mfma_f32_16x16x32_bf16 v[116:119], v[170:173], v[186:189], v[116:119]
	v_mfma_f32_16x16x32_bf16 v[112:115], v[178:181], v[186:189], v[112:115]
	v_mfma_f32_16x16x32_bf16 v[100:103], v[170:173], v[194:197], v[100:103]
	v_mfma_f32_16x16x32_bf16 v[96:99], v[178:181], v[194:197], v[96:99]
	v_mfma_f32_16x16x32_bf16 v[84:87], v[170:173], v[206:209], v[84:87]
	v_mfma_f32_16x16x32_bf16 v[80:83], v[178:181], v[206:209], v[80:83]
	v_mfma_f32_16x16x32_bf16 v[68:71], v[170:173], v[214:217], v[68:71]
	v_mfma_f32_16x16x32_bf16 v[64:67], v[178:181], v[214:217], v[64:67]
	v_mfma_f32_16x16x32_bf16 v[116:119], v[174:177], v[190:193], v[116:119]
	v_mfma_f32_16x16x32_bf16 v[112:115], v[182:185], v[190:193], v[112:115]
	v_mfma_f32_16x16x32_bf16 v[100:103], v[174:177], v[198:201], v[100:103]
	v_mfma_f32_16x16x32_bf16 v[96:99], v[182:185], v[198:201], v[96:99]
	v_mfma_f32_16x16x32_bf16 v[84:87], v[174:177], v[210:213], v[84:87]
	v_mfma_f32_16x16x32_bf16 v[80:83], v[182:185], v[210:213], v[80:83]
	v_mfma_f32_16x16x32_bf16 v[68:71], v[174:177], v[218:221], v[68:71]
	v_mfma_f32_16x16x32_bf16 v[64:67], v[182:185], v[218:221], v[64:67]
	s_barrier
; #define PG8_STAGE(bufoff, gbase, voff) do { _Pragma("unroll") for (int _i = 0; _i < 2; ++_i) \
;         __builtin_amdgcn_global_load_lds((const unsigned*)((const char*)(gbase) + (voff)[_i]), (PG8_LAS unsigned*)(lds + (bufoff) + ldsw + _i * 8192), 16, 0, 0); } while (0)
; #define PG8_LDA(dst, b, h) do { _Pragma("unroll") for (int m = 0; m < 4; ++m) _Pragma("unroll") for (int k = 0; k < 2; ++k) dst[m][k] = *(const PG8_LAS bf16x8*)(lds + PG8_SA(b, h) + aoff + m * 2048 + k * 1024); } while (0)
; #define PG8_MMA(ai, bj, At, Bt) do { __builtin_amdgcn_s_setprio(1); _Pragma("unroll") for (int m = 0; m < 4; ++m) _Pragma("unroll") for (int n = 0; n < 2; ++n) _Pragma("unroll") for (int k = 0; k < 2; ++k) \
;         acc[ai][bj][m][n] = __builtin_amdgcn_mfma_f32_16x16x32_bf16(Bt[n][k], At[m][k], acc[ai][bj][m][n], 0, 0, 0); __builtin_amdgcn_s_setprio(0); } while (0)
; #define PG8_WAIT_V(n) asm volatile("s_waitcnt vmcnt(" #n ")" ::: "memory")
; #define PG8_WAIT_L(n) asm volatile("s_waitcnt lgkmcnt(" #n ")" ::: "memory")
; #define PG8_BAR __builtin_amdgcn_s_barrier()
; #define PG8_SCHED __builtin_amdgcn_sched_barrier(0)
; template <class Epi, class Sched, bool ALIGN_EPI = false, bool SP2 = false>
; __device__ __forceinline__ void gemm_phase(PG8_LAS unsigned char* lds, const Gemm g, const Sched& S, const Epi& E) {
;     ...
;             PG8_LDA(At, 1, 1); PG8_STAGE(PG8_SB(1, 0), b3, voffB); PG8_STAGE(PG8_SB(1, 1), b3 + hstep, voffB); PG8_STAGE(PG8_SA(1, 0), a3, voffA);
;             PG8_WAIT_V(8); PG8_WAIT_L(0); PG8_BAR; PG8_MMA(1, 0, At, B0); PG8_MMA(1, 1, At, B1); PG8_BAR; PG8_SCHED;
	s_add_i32 s30, s52, s36
	v_lshl_add_u64 v[202:203], v[202:203], 0, s[10:11]
	s_mov_b32 m0, s30
	ds_read_b128 v[186:189], v155 offset:49152
	ds_read_b128 v[190:193], v155 offset:50176
	ds_read_b128 v[194:197], v155 offset:51200
	ds_read_b128 v[198:201], v155 offset:52224
	ds_read_b128 v[206:209], v155 offset:53248
	ds_read_b128 v[210:213], v155 offset:54272
	ds_read_b128 v[214:217], v155 offset:55296
	ds_read_b128 v[218:221], v155 offset:56320
	global_load_lds_dwordx4 v[202:203], off
	s_add_i32 m0, s30, 0x2000
	s_add_u32 s28, s28, 0x20080
	v_lshl_add_u64 v[202:203], v[222:223], 0, s[10:11]
	s_addc_u32 s29, s29, 0
	s_add_i32 s30, s53, s36
	global_load_lds_dwordx4 v[202:203], off
	v_lshl_add_u64 v[202:203], s[28:29], 0, v[130:131]
	s_mov_b32 m0, s30
	s_nop 0
	global_load_lds_dwordx4 v[202:203], off
	v_lshl_add_u64 v[202:203], s[28:29], 0, v[134:135]
	s_add_i32 m0, s30, 0x2000
	s_nop 0
	global_load_lds_dwordx4 v[202:203], off
	v_lshl_add_u64 v[202:203], v[224:225], 0, s[10:11]
	s_mov_b32 m0, s44
	s_nop 0
	global_load_lds_dwordx4 v[202:203], off
	v_lshl_add_u64 v[202:203], v[226:227], 0, s[10:11]
	s_mov_b32 m0, s45
	s_nop 0
	global_load_lds_dwordx4 v[202:203], off
	s_waitcnt vmcnt(8)
	s_waitcnt lgkmcnt(0)
	s_barrier
	s_waitcnt lgkmcnt(0)
	v_mfma_f32_16x16x32_bf16 v[60:63], v[146:149], v[186:189], v[60:63]
	v_mfma_f32_16x16x32_bf16 v[56:59], v[162:165], v[186:189], v[56:59]
	v_mfma_f32_16x16x32_bf16 v[44:47], v[146:149], v[194:197], v[44:47]
	v_mfma_f32_16x16x32_bf16 v[40:43], v[162:165], v[194:197], v[40:43]
	v_mfma_f32_16x16x32_bf16 v[28:31], v[146:149], v[206:209], v[28:31]
	v_mfma_f32_16x16x32_bf16 v[24:27], v[162:165], v[206:209], v[24:27]
	v_mfma_f32_16x16x32_bf16 v[12:15], v[146:149], v[214:217], v[12:15]
	v_mfma_f32_16x16x32_bf16 v[8:11], v[162:165], v[214:217], v[8:11]
	v_mfma_f32_16x16x32_bf16 v[60:63], v[158:161], v[190:193], v[60:63]
	v_mfma_f32_16x16x32_bf16 v[56:59], v[166:169], v[190:193], v[56:59]
	v_mfma_f32_16x16x32_bf16 v[44:47], v[158:161], v[198:201], v[44:47]
	v_mfma_f32_16x16x32_bf16 v[40:43], v[166:169], v[198:201], v[40:43]
	v_mfma_f32_16x16x32_bf16 v[28:31], v[158:161], v[210:213], v[28:31]
	v_mfma_f32_16x16x32_bf16 v[24:27], v[166:169], v[210:213], v[24:27]
	v_mfma_f32_16x16x32_bf16 v[12:15], v[158:161], v[218:221], v[12:15]
	v_mfma_f32_16x16x32_bf16 v[8:11], v[166:169], v[218:221], v[8:11]
	v_mfma_f32_16x16x32_bf16 v[52:55], v[170:173], v[186:189], v[52:55]
	v_mfma_f32_16x16x32_bf16 v[48:51], v[178:181], v[186:189], v[48:51]
	v_mfma_f32_16x16x32_bf16 v[36:39], v[170:173], v[194:197], v[36:39]
	v_mfma_f32_16x16x32_bf16 v[32:35], v[178:181], v[194:197], v[32:35]
	v_mfma_f32_16x16x32_bf16 v[20:23], v[170:173], v[206:209], v[20:23]
	v_mfma_f32_16x16x32_bf16 v[16:19], v[178:181], v[206:209], v[16:19]
	v_mfma_f32_16x16x32_bf16 v[4:7], v[170:173], v[214:217], v[4:7]
	v_mfma_f32_16x16x32_bf16 v[0:3], v[178:181], v[214:217], v[0:3]
	v_mfma_f32_16x16x32_bf16 v[52:55], v[174:177], v[190:193], v[52:55]
	v_mfma_f32_16x16x32_bf16 v[48:51], v[182:185], v[190:193], v[48:51]
	v_mfma_f32_16x16x32_bf16 v[36:39], v[174:177], v[198:201], v[36:39]
	v_mfma_f32_16x16x32_bf16 v[32:35], v[182:185], v[198:201], v[32:35]
	v_mfma_f32_16x16x32_bf16 v[20:23], v[174:177], v[210:213], v[20:23]
	v_mfma_f32_16x16x32_bf16 v[16:19], v[182:185], v[210:213], v[16:19]
	v_mfma_f32_16x16x32_bf16 v[4:7], v[174:177], v[218:221], v[4:7]
	v_mfma_f32_16x16x32_bf16 v[0:3], v[182:185], v[218:221], v[0:3]
	s_barrier
	s_add_i32 s51, s51, 2
	s_add_u32 s26, s26, 0x100
	s_addc_u32 s27, s27, 0
	s_add_u32 s23, s23, 0x100
	s_addc_u32 s25, s25, 0
	s_cmp_gt_u32 s51, 5
	s_cbranch_scc0 .LBB0_860
	s_and_b64 vcc, exec, s[12:13]
	s_cbranch_vccz .LBB0_863
	s_barrier

; #define PG8_STAGE(bufoff, gbase, voff) do { _Pragma("unroll") for (int _i = 0; _i < 2; ++_i) \
;         __builtin_amdgcn_global_load_lds((const unsigned*)((const char*)(gbase) + (voff)[_i]), (PG8_LAS unsigned*)(lds + (bufoff) + ldsw + _i * 8192), 16, 0, 0); } while (0)
; #define PG8_LDA(dst, b, h) do { _Pragma("unroll") for (int m = 0; m < 4; ++m) _Pragma("unroll") for (int k = 0; k < 2; ++k) dst[m][k] = *(const PG8_LAS bf16x8*)(lds + PG8_SA(b, h) + aoff + m * 2048 + k * 1024); } while (0)
; #define PG8_LDB(dst, b, h) do { _Pragma("unroll") for (int n = 0; n < 2; ++n) _Pragma("unroll") for (int k = 0; k < 2; ++k) dst[n][k] = *(const PG8_LAS bf16x8*)(lds + PG8_SB(b, h) + boff + n * 2048 + k * 1024); } while (0)
; #define PG8_MMA(ai, bj, At, Bt) do { __builtin_amdgcn_s_setprio(1); _Pragma("unroll") for (int m = 0; m < 4; ++m) _Pragma("unroll") for (int n = 0; n < 2; ++n) _Pragma("unroll") for (int k = 0; k < 2; ++k) \
;         acc[ai][bj][m][n] = __builtin_amdgcn_mfma_f32_16x16x32_bf16(Bt[n][k], At[m][k], acc[ai][bj][m][n], 0, 0, 0); __builtin_amdgcn_s_setprio(0); } while (0)
; #define PG8_WAIT_V(n) asm volatile("s_waitcnt vmcnt(" #n ")" ::: "memory")
; #define PG8_WAIT_L(n) asm volatile("s_waitcnt lgkmcnt(" #n ")" ::: "memory")
; #define PG8_BAR __builtin_amdgcn_s_barrier()
; #define PG8_SCHED __builtin_amdgcn_sched_barrier(0)
; template <class Epi, class Sched, bool ALIGN_EPI = false, bool SP2 = false>
; __device__ __forceinline__ void gemm_phase(PG8_LAS unsigned char* lds, const Gemm g, const Sched& S, const Epi& E) {
;     ...
;             PG8_LDB(B0, 0, 0); PG8_LDB(B1, 0, 1); PG8_SCHED; PG8_LDA(At, 0, 0); PG8_STAGE(PG8_SA(1, 1), a1 + hstepA, voffA);
;             PG8_WAIT_V(8); PG8_WAIT_L(0); PG8_BAR; PG8_MMA(0, 0, At, B0); PG8_MMA(0, 1, At, B1); PG8_BAR; PG8_SCHED;
;             PG8_LDA(At, 0, 1); PG8_STAGE(PG8_SB(0, 0), b2, voffB); PG8_STAGE(PG8_SB(0, 1), b2 + hstep, voffB); PG8_STAGE(PG8_SA(0, 0), a2, voffA);
.LBB0_1066:
	ds_read_b128 v[128:131], v167
	ds_read_b128 v[132:135], v167 offset:1024
	ds_read_b128 v[152:155], v167 offset:2048
	ds_read_b128 v[156:159], v167 offset:3072
	ds_read_b128 v[160:163], v168
	ds_read_b128 v[172:175], v168 offset:1024
	ds_read_b128 v[176:179], v168 offset:2048
	ds_read_b128 v[180:183], v168 offset:3072
	s_add_u32 s30, s28, 0xfff80080
	s_addc_u32 s31, s29, -1
	s_cmp_eq_u32 s54, 28
	s_cselect_b32 s35, s6, s31
	s_cselect_b32 s34, s7, s30
	s_cselect_b32 s31, s17, s27
	s_cselect_b32 s30, s19, s25
	v_lshl_add_u64 v[218:219], s[28:29], 0, v[144:145]
	s_add_i32 m0, s39, 0xc000
	ds_read_b128 v[184:187], v169
	ds_read_b128 v[188:191], v169 offset:1024
	ds_read_b128 v[192:195], v169 offset:2048
	ds_read_b128 v[196:199], v169 offset:3072
	ds_read_b128 v[200:203], v169 offset:4096
	ds_read_b128 v[206:209], v169 offset:5120
	ds_read_b128 v[210:213], v169 offset:6144
	ds_read_b128 v[214:217], v169 offset:7168
	global_load_lds_dwordx4 v[218:219], off
	v_lshl_add_u64 v[218:219], s[28:29], 0, v[146:147]
	s_add_i32 m0, s39, 0xe000
	s_nop 0
	global_load_lds_dwordx4 v[218:219], off
	s_waitcnt vmcnt(8)
	s_waitcnt lgkmcnt(0)
	s_barrier
	s_waitcnt lgkmcnt(0)
	v_mfma_f32_16x16x32_bf16 v[124:127], v[128:131], v[184:187], v[124:127]
	v_mfma_f32_16x16x32_bf16 v[120:123], v[152:155], v[184:187], v[120:123]
	v_mfma_f32_16x16x32_bf16 v[108:111], v[128:131], v[192:195], v[108:111]
	v_mfma_f32_16x16x32_bf16 v[104:107], v[152:155], v[192:195], v[104:107]
	v_mfma_f32_16x16x32_bf16 v[92:95], v[128:131], v[200:203], v[92:95]
	v_mfma_f32_16x16x32_bf16 v[88:91], v[152:155], v[200:203], v[88:91]
	v_mfma_f32_16x16x32_bf16 v[76:79], v[128:131], v[210:213], v[76:79]
	v_mfma_f32_16x16x32_bf16 v[72:75], v[152:155], v[210:213], v[72:75]
	v_mfma_f32_16x16x32_bf16 v[124:127], v[132:135], v[188:191], v[124:127]
	v_mfma_f32_16x16x32_bf16 v[120:123], v[156:159], v[188:191], v[120:123]
	v_mfma_f32_16x16x32_bf16 v[108:111], v[132:135], v[196:199], v[108:111]
	v_mfma_f32_16x16x32_bf16 v[104:107], v[156:159], v[196:199], v[104:107]
	v_mfma_f32_16x16x32_bf16 v[92:95], v[132:135], v[206:209], v[92:95]
	v_mfma_f32_16x16x32_bf16 v[88:91], v[156:159], v[206:209], v[88:91]
	v_mfma_f32_16x16x32_bf16 v[76:79], v[132:135], v[214:217], v[76:79]
	v_mfma_f32_16x16x32_bf16 v[72:75], v[156:159], v[214:217], v[72:75]
	v_mfma_f32_16x16x32_bf16 v[116:119], v[160:163], v[184:187], v[116:119]
	v_mfma_f32_16x16x32_bf16 v[112:115], v[176:179], v[184:187], v[112:115]
	v_mfma_f32_16x16x32_bf16 v[100:103], v[160:163], v[192:195], v[100:103]
	v_mfma_f32_16x16x32_bf16 v[96:99], v[176:179], v[192:195], v[96:99]
	v_mfma_f32_16x16x32_bf16 v[84:87], v[160:163], v[200:203], v[84:87]
	v_mfma_f32_16x16x32_bf16 v[80:83], v[176:179], v[200:203], v[80:83]
	v_mfma_f32_16x16x32_bf16 v[68:71], v[160:163], v[210:213], v[68:71]
	v_mfma_f32_16x16x32_bf16 v[64:67], v[176:179], v[210:213], v[64:67]
	v_mfma_f32_16x16x32_bf16 v[116:119], v[172:175], v[188:191], v[116:119]
	v_mfma_f32_16x16x32_bf16 v[112:115], v[180:183], v[188:191], v[112:115]
	v_mfma_f32_16x16x32_bf16 v[100:103], v[172:175], v[196:199], v[100:103]
	v_mfma_f32_16x16x32_bf16 v[96:99], v[180:183], v[196:199], v[96:99]
	v_mfma_f32_16x16x32_bf16 v[84:87], v[172:175], v[206:209], v[84:87]
	v_mfma_f32_16x16x32_bf16 v[80:83], v[180:183], v[206:209], v[80:83]
	v_mfma_f32_16x16x32_bf16 v[68:71], v[172:175], v[214:217], v[68:71]
	v_mfma_f32_16x16x32_bf16 v[64:67], v[180:183], v[214:217], v[64:67]
	s_barrier
	s_add_i32 s55, s52, s38
	v_lshl_add_u64 v[218:219], s[30:31], 0, v[138:139]
	s_mov_b32 m0, s55
	ds_read_b128 v[184:187], v169 offset:16384
	ds_read_b128 v[188:191], v169 offset:17408
	ds_read_b128 v[192:195], v169 offset:18432
	ds_read_b128 v[196:199], v169 offset:19456
	ds_read_b128 v[200:203], v169 offset:20480
	ds_read_b128 v[206:209], v169 offset:21504
	ds_read_b128 v[210:213], v169 offset:22528
	ds_read_b128 v[214:217], v169 offset:23552
	global_load_lds_dwordx4 v[218:219], off
	s_add_i32 m0, s55, 0x2000
	s_add_u32 s56, s30, 0x80000
	v_lshl_add_u64 v[220:221], s[30:31], 0, v[142:143]
	s_addc_u32 s57, s31, 0
	s_add_i32 s55, s53, s38
	global_load_lds_dwordx4 v[220:221], off
	v_lshl_add_u64 v[222:223], s[56:57], 0, v[138:139]
	s_mov_b32 m0, s55
	v_lshl_add_u64 v[224:225], s[34:35], 0, v[140:141]
	global_load_lds_dwordx4 v[222:223], off
	v_lshl_add_u64 v[222:223], s[56:57], 0, v[142:143]
	s_add_i32 m0, s55, 0x2000
	s_nop 0
	global_load_lds_dwordx4 v[222:223], off
	v_lshl_add_u64 v[222:223], s[34:35], 0, v[136:137]
	s_mov_b32 m0, s39
	s_nop 0
	global_load_lds_dwordx4 v[222:223], off
	s_mov_b32 m0, s40
	s_nop 0
	global_load_lds_dwordx4 v[224:225], off
	s_waitcnt vmcnt(8)
	s_waitcnt lgkmcnt(0)
	s_barrier
; #define PG8_STAGE(bufoff, gbase, voff) do { _Pragma("unroll") for (int _i = 0; _i < 2; ++_i) \
;         __builtin_amdgcn_global_load_lds((const unsigned*)((const char*)(gbase) + (voff)[_i]), (PG8_LAS unsigned*)(lds + (bufoff) + ldsw + _i * 8192), 16, 0, 0); } while (0)
; #define PG8_LDA(dst, b, h) do { _Pragma("unroll") for (int m = 0; m < 4; ++m) _Pragma("unroll") for (int k = 0; k < 2; ++k) dst[m][k] = *(const PG8_LAS bf16x8*)(lds + PG8_SA(b, h) + aoff + m * 2048 + k * 1024); } while (0)
; #define PG8_LDB(dst, b, h) do { _Pragma("unroll") for (int n = 0; n < 2; ++n) _Pragma("unroll") for (int k = 0; k < 2; ++k) dst[n][k] = *(const PG8_LAS bf16x8*)(lds + PG8_SB(b, h) + boff + n * 2048 + k * 1024); } while (0)
; #define PG8_MMA(ai, bj, At, Bt) do { __builtin_amdgcn_s_setprio(1); _Pragma("unroll") for (int m = 0; m < 4; ++m) _Pragma("unroll") for (int n = 0; n < 2; ++n) _Pragma("unroll") for (int k = 0; k < 2; ++k) \
;         acc[ai][bj][m][n] = __builtin_amdgcn_mfma_f32_16x16x32_bf16(Bt[n][k], At[m][k], acc[ai][bj][m][n], 0, 0, 0); __builtin_amdgcn_s_setprio(0); } while (0)
; #define PG8_WAIT_V(n) asm volatile("s_waitcnt vmcnt(" #n ")" ::: "memory")
; #define PG8_WAIT_L(n) asm volatile("s_waitcnt lgkmcnt(" #n ")" ::: "memory")
; #define PG8_BAR __builtin_amdgcn_s_barrier()
; #define PG8_SCHED __builtin_amdgcn_sched_barrier(0)
; template <class Epi, class Sched, bool ALIGN_EPI = false, bool SP2 = false>
; __device__ __forceinline__ void gemm_phase(PG8_LAS unsigned char* lds, const Gemm g, const Sched& S, const Epi& E) {
;     ...
;             PG8_WAIT_V(8); PG8_WAIT_L(0); PG8_BAR; PG8_MMA(1, 0, At, B0); PG8_MMA(1, 1, At, B1); PG8_BAR; PG8_SCHED;
;             PG8_LDB(B0, 1, 0); PG8_LDB(B1, 1, 1); PG8_SCHED; PG8_LDA(At, 1, 0); PG8_STAGE(PG8_SA(0, 1), a2 + hstepA, voffA);
;             PG8_WAIT_V(8); PG8_WAIT_L(0); PG8_BAR; PG8_MMA(0, 0, At, B0); PG8_MMA(0, 1, At, B1); PG8_BAR; PG8_SCHED;
	s_waitcnt lgkmcnt(0)
	v_mfma_f32_16x16x32_bf16 v[60:63], v[128:131], v[184:187], v[60:63]
	v_mfma_f32_16x16x32_bf16 v[56:59], v[152:155], v[184:187], v[56:59]
	v_mfma_f32_16x16x32_bf16 v[44:47], v[128:131], v[192:195], v[44:47]
	v_mfma_f32_16x16x32_bf16 v[40:43], v[152:155], v[192:195], v[40:43]
	v_mfma_f32_16x16x32_bf16 v[28:31], v[128:131], v[200:203], v[28:31]
	v_mfma_f32_16x16x32_bf16 v[24:27], v[152:155], v[200:203], v[24:27]
	v_mfma_f32_16x16x32_bf16 v[12:15], v[128:131], v[210:213], v[12:15]
	v_mfma_f32_16x16x32_bf16 v[8:11], v[152:155], v[210:213], v[8:11]
	v_mfma_f32_16x16x32_bf16 v[60:63], v[132:135], v[188:191], v[60:63]
	v_mfma_f32_16x16x32_bf16 v[56:59], v[156:159], v[188:191], v[56:59]
	v_mfma_f32_16x16x32_bf16 v[44:47], v[132:135], v[196:199], v[44:47]
	v_mfma_f32_16x16x32_bf16 v[40:43], v[156:159], v[196:199], v[40:43]
	v_mfma_f32_16x16x32_bf16 v[28:31], v[132:135], v[206:209], v[28:31]
	v_mfma_f32_16x16x32_bf16 v[24:27], v[156:159], v[206:209], v[24:27]
	v_mfma_f32_16x16x32_bf16 v[12:15], v[132:135], v[214:217], v[12:15]
	v_mfma_f32_16x16x32_bf16 v[8:11], v[156:159], v[214:217], v[8:11]
	v_mfma_f32_16x16x32_bf16 v[52:55], v[160:163], v[184:187], v[52:55]
	v_mfma_f32_16x16x32_bf16 v[48:51], v[176:179], v[184:187], v[48:51]
	v_mfma_f32_16x16x32_bf16 v[36:39], v[160:163], v[192:195], v[36:39]
	v_mfma_f32_16x16x32_bf16 v[32:35], v[176:179], v[192:195], v[32:35]
	v_mfma_f32_16x16x32_bf16 v[20:23], v[160:163], v[200:203], v[20:23]
	v_mfma_f32_16x16x32_bf16 v[16:19], v[176:179], v[200:203], v[16:19]
	v_mfma_f32_16x16x32_bf16 v[4:7], v[160:163], v[210:213], v[4:7]
	v_mfma_f32_16x16x32_bf16 v[0:3], v[176:179], v[210:213], v[0:3]
	v_mfma_f32_16x16x32_bf16 v[52:55], v[172:175], v[188:191], v[52:55]
	v_mfma_f32_16x16x32_bf16 v[48:51], v[180:183], v[188:191], v[48:51]
	v_mfma_f32_16x16x32_bf16 v[36:39], v[172:175], v[196:199], v[36:39]
	v_mfma_f32_16x16x32_bf16 v[32:35], v[180:183], v[196:199], v[32:35]
	v_mfma_f32_16x16x32_bf16 v[20:23], v[172:175], v[206:209], v[20:23]
	v_mfma_f32_16x16x32_bf16 v[16:19], v[180:183], v[206:209], v[16:19]
	v_mfma_f32_16x16x32_bf16 v[4:7], v[172:175], v[214:217], v[4:7]
	v_mfma_f32_16x16x32_bf16 v[0:3], v[180:183], v[214:217], v[0:3]
	s_barrier
	s_add_i32 s55, 0, 0x18000
	s_add_i32 s56, 0, 0x1c000
	v_add_u32_e32 v156, s55, v165
	v_add_u32_e32 v171, s56, v165
	ds_read_b128 v[128:131], v156
	ds_read_b128 v[132:135], v156 offset:1024
	ds_read_b128 v[152:155], v156 offset:2048
	ds_read_b128 v[156:159], v156 offset:3072
	ds_read_b128 v[160:163], v171
	ds_read_b128 v[172:175], v171 offset:1024
	ds_read_b128 v[176:179], v171 offset:2048
	ds_read_b128 v[180:183], v171 offset:3072
	s_add_u32 s34, s34, 0x80000
	s_addc_u32 s35, s35, 0
	s_mov_b32 m0, s41
	v_lshl_add_u64 v[226:227], s[34:35], 0, v[136:137]
	ds_read_b128 v[184:187], v169 offset:32768
	ds_read_b128 v[188:191], v169 offset:33792
	ds_read_b128 v[192:195], v169 offset:34816
	ds_read_b128 v[196:199], v169 offset:35840
	ds_read_b128 v[200:203], v169 offset:36864
	ds_read_b128 v[206:209], v169 offset:37888
	ds_read_b128 v[210:213], v169 offset:38912
	ds_read_b128 v[214:217], v169 offset:39936
	global_load_lds_dwordx4 v[226:227], off
	v_lshl_add_u64 v[226:227], s[34:35], 0, v[140:141]
	s_mov_b32 m0, s42
	s_nop 0
	global_load_lds_dwordx4 v[226:227], off
	s_waitcnt vmcnt(8)
	s_waitcnt lgkmcnt(0)
	s_barrier
	s_waitcnt lgkmcnt(0)
	v_mfma_f32_16x16x32_bf16 v[124:127], v[128:131], v[184:187], v[124:127]
	v_mfma_f32_16x16x32_bf16 v[120:123], v[152:155], v[184:187], v[120:123]
	v_mfma_f32_16x16x32_bf16 v[108:111], v[128:131], v[192:195], v[108:111]
	v_mfma_f32_16x16x32_bf16 v[104:107], v[152:155], v[192:195], v[104:107]
	v_mfma_f32_16x16x32_bf16 v[92:95], v[128:131], v[200:203], v[92:95]
	v_mfma_f32_16x16x32_bf16 v[88:91], v[152:155], v[200:203], v[88:91]
	v_mfma_f32_16x16x32_bf16 v[76:79], v[128:131], v[210:213], v[76:79]
	v_mfma_f32_16x16x32_bf16 v[72:75], v[152:155], v[210:213], v[72:75]
	v_mfma_f32_16x16x32_bf16 v[124:127], v[132:135], v[188:191], v[124:127]
	v_mfma_f32_16x16x32_bf16 v[120:123], v[156:159], v[188:191], v[120:123]
	v_mfma_f32_16x16x32_bf16 v[108:111], v[132:135], v[196:199], v[108:111]
	v_mfma_f32_16x16x32_bf16 v[104:107], v[156:159], v[196:199], v[104:107]
	v_mfma_f32_16x16x32_bf16 v[92:95], v[132:135], v[206:209], v[92:95]
	v_mfma_f32_16x16x32_bf16 v[88:91], v[156:159], v[206:209], v[88:91]
	v_mfma_f32_16x16x32_bf16 v[76:79], v[132:135], v[214:217], v[76:79]
	v_mfma_f32_16x16x32_bf16 v[72:75], v[156:159], v[214:217], v[72:75]
	v_mfma_f32_16x16x32_bf16 v[116:119], v[160:163], v[184:187], v[116:119]
	v_mfma_f32_16x16x32_bf16 v[112:115], v[176:179], v[184:187], v[112:115]
	v_mfma_f32_16x16x32_bf16 v[100:103], v[160:163], v[192:195], v[100:103]
	v_mfma_f32_16x16x32_bf16 v[96:99], v[176:179], v[192:195], v[96:99]
	v_mfma_f32_16x16x32_bf16 v[84:87], v[160:163], v[200:203], v[84:87]
	v_mfma_f32_16x16x32_bf16 v[80:83], v[176:179], v[200:203], v[80:83]
	v_mfma_f32_16x16x32_bf16 v[68:71], v[160:163], v[210:213], v[68:71]
	v_mfma_f32_16x16x32_bf16 v[64:67], v[176:179], v[210:213], v[64:67]
	v_mfma_f32_16x16x32_bf16 v[116:119], v[172:175], v[188:191], v[116:119]
	v_mfma_f32_16x16x32_bf16 v[112:115], v[180:183], v[188:191], v[112:115]
	v_mfma_f32_16x16x32_bf16 v[100:103], v[172:175], v[196:199], v[100:103]
	v_mfma_f32_16x16x32_bf16 v[96:99], v[180:183], v[196:199], v[96:99]
	v_mfma_f32_16x16x32_bf16 v[84:87], v[172:175], v[206:209], v[84:87]
	v_mfma_f32_16x16x32_bf16 v[80:83], v[180:183], v[206:209], v[80:83]
	v_mfma_f32_16x16x32_bf16 v[68:71], v[172:175], v[214:217], v[68:71]
	v_mfma_f32_16x16x32_bf16 v[64:67], v[180:183], v[214:217], v[64:67]
	s_barrier
; #define PG8_STAGE(bufoff, gbase, voff) do { _Pragma("unroll") for (int _i = 0; _i < 2; ++_i) \
;         __builtin_amdgcn_global_load_lds((const unsigned*)((const char*)(gbase) + (voff)[_i]), (PG8_LAS unsigned*)(lds + (bufoff) + ldsw + _i * 8192), 16, 0, 0); } while (0)
; #define PG8_LDA(dst, b, h) do { _Pragma("unroll") for (int m = 0; m < 4; ++m) _Pragma("unroll") for (int k = 0; k < 2; ++k) dst[m][k] = *(const PG8_LAS bf16x8*)(lds + PG8_SA(b, h) + aoff + m * 2048 + k * 1024); } while (0)
; #define PG8_MMA(ai, bj, At, Bt) do { __builtin_amdgcn_s_setprio(1); _Pragma("unroll") for (int m = 0; m < 4; ++m) _Pragma("unroll") for (int n = 0; n < 2; ++n) _Pragma("unroll") for (int k = 0; k < 2; ++k) \
;         acc[ai][bj][m][n] = __builtin_amdgcn_mfma_f32_16x16x32_bf16(Bt[n][k], At[m][k], acc[ai][bj][m][n], 0, 0, 0); __builtin_amdgcn_s_setprio(0); } while (0)
; #define PG8_WAIT_V(n) asm volatile("s_waitcnt vmcnt(" #n ")" ::: "memory")
; #define PG8_WAIT_L(n) asm volatile("s_waitcnt lgkmcnt(" #n ")" ::: "memory")
; #define PG8_BAR __builtin_amdgcn_s_barrier()
; #define PG8_SCHED __builtin_amdgcn_sched_barrier(0)
; template <class Epi, class Sched, bool ALIGN_EPI = false, bool SP2 = false>
; __device__ __forceinline__ void gemm_phase(PG8_LAS unsigned char* lds, const Gemm g, const Sched& S, const Epi& E) {
;     ...
;             PG8_LDA(At, 1, 1); PG8_STAGE(PG8_SB(1, 0), b3, voffB); PG8_STAGE(PG8_SB(1, 1), b3 + hstep, voffB); PG8_STAGE(PG8_SA(1, 0), a3, voffA);
;             PG8_WAIT_V(8); PG8_WAIT_L(0); PG8_BAR; PG8_MMA(1, 0, At, B0); PG8_MMA(1, 1, At, B1); PG8_BAR; PG8_SCHED;
	s_add_i32 s34, s55, s38
	v_lshl_add_u64 v[218:219], v[218:219], 0, s[12:13]
	s_mov_b32 m0, s34
	ds_read_b128 v[184:187], v169 offset:49152
	ds_read_b128 v[188:191], v169 offset:50176
	ds_read_b128 v[192:195], v169 offset:51200
	ds_read_b128 v[196:199], v169 offset:52224
	ds_read_b128 v[200:203], v169 offset:53248
	ds_read_b128 v[206:209], v169 offset:54272
	ds_read_b128 v[210:213], v169 offset:55296
	ds_read_b128 v[214:217], v169 offset:56320
	global_load_lds_dwordx4 v[218:219], off
	s_add_i32 m0, s34, 0x2000
	s_add_u32 s30, s30, 0x80080
	v_lshl_add_u64 v[218:219], v[220:221], 0, s[12:13]
	s_addc_u32 s31, s31, 0
	s_add_i32 s34, s56, s38
	global_load_lds_dwordx4 v[218:219], off
	v_lshl_add_u64 v[218:219], s[30:31], 0, v[138:139]
	s_mov_b32 m0, s34
	s_nop 0
	global_load_lds_dwordx4 v[218:219], off
	v_lshl_add_u64 v[218:219], s[30:31], 0, v[142:143]
	s_add_i32 m0, s34, 0x2000
	s_nop 0
	global_load_lds_dwordx4 v[218:219], off
	v_lshl_add_u64 v[218:219], v[222:223], 0, s[12:13]
	s_mov_b32 m0, s47
	s_nop 0
	global_load_lds_dwordx4 v[218:219], off
	v_lshl_add_u64 v[218:219], v[224:225], 0, s[12:13]
	s_mov_b32 m0, s48
	s_nop 0
	global_load_lds_dwordx4 v[218:219], off
	s_waitcnt vmcnt(8)
	s_waitcnt lgkmcnt(0)
	s_barrier
	s_waitcnt lgkmcnt(0)
	v_mfma_f32_16x16x32_bf16 v[60:63], v[128:131], v[184:187], v[60:63]
	v_mfma_f32_16x16x32_bf16 v[56:59], v[152:155], v[184:187], v[56:59]
	v_mfma_f32_16x16x32_bf16 v[44:47], v[128:131], v[192:195], v[44:47]
	v_mfma_f32_16x16x32_bf16 v[40:43], v[152:155], v[192:195], v[40:43]
	v_mfma_f32_16x16x32_bf16 v[28:31], v[128:131], v[200:203], v[28:31]
	v_mfma_f32_16x16x32_bf16 v[24:27], v[152:155], v[200:203], v[24:27]
	v_mfma_f32_16x16x32_bf16 v[12:15], v[128:131], v[210:213], v[12:15]
	v_mfma_f32_16x16x32_bf16 v[8:11], v[152:155], v[210:213], v[8:11]
	v_mfma_f32_16x16x32_bf16 v[60:63], v[132:135], v[188:191], v[60:63]
	v_mfma_f32_16x16x32_bf16 v[56:59], v[156:159], v[188:191], v[56:59]
	v_mfma_f32_16x16x32_bf16 v[44:47], v[132:135], v[196:199], v[44:47]
	v_mfma_f32_16x16x32_bf16 v[40:43], v[156:159], v[196:199], v[40:43]
	v_mfma_f32_16x16x32_bf16 v[28:31], v[132:135], v[206:209], v[28:31]
	v_mfma_f32_16x16x32_bf16 v[24:27], v[156:159], v[206:209], v[24:27]
	v_mfma_f32_16x16x32_bf16 v[12:15], v[132:135], v[214:217], v[12:15]
	v_mfma_f32_16x16x32_bf16 v[8:11], v[156:159], v[214:217], v[8:11]
	v_mfma_f32_16x16x32_bf16 v[52:55], v[160:163], v[184:187], v[52:55]
	v_mfma_f32_16x16x32_bf16 v[48:51], v[176:179], v[184:187], v[48:51]
	v_mfma_f32_16x16x32_bf16 v[36:39], v[160:163], v[192:195], v[36:39]
	v_mfma_f32_16x16x32_bf16 v[32:35], v[176:179], v[192:195], v[32:35]
	v_mfma_f32_16x16x32_bf16 v[20:23], v[160:163], v[200:203], v[20:23]
	v_mfma_f32_16x16x32_bf16 v[16:19], v[176:179], v[200:203], v[16:19]
	v_mfma_f32_16x16x32_bf16 v[4:7], v[160:163], v[210:213], v[4:7]
	v_mfma_f32_16x16x32_bf16 v[0:3], v[176:179], v[210:213], v[0:3]
	v_mfma_f32_16x16x32_bf16 v[52:55], v[172:175], v[188:191], v[52:55]
	v_mfma_f32_16x16x32_bf16 v[48:51], v[180:183], v[188:191], v[48:51]
	v_mfma_f32_16x16x32_bf16 v[36:39], v[172:175], v[196:199], v[36:39]
	v_mfma_f32_16x16x32_bf16 v[32:35], v[180:183], v[196:199], v[32:35]
	v_mfma_f32_16x16x32_bf16 v[20:23], v[172:175], v[206:209], v[20:23]
	v_mfma_f32_16x16x32_bf16 v[16:19], v[180:183], v[206:209], v[16:19]
	v_mfma_f32_16x16x32_bf16 v[4:7], v[172:175], v[214:217], v[4:7]
	v_mfma_f32_16x16x32_bf16 v[0:3], v[180:183], v[214:217], v[0:3]
	s_barrier
	s_add_i32 s54, s54, 2
	s_add_u32 s28, s28, 0x100
	s_addc_u32 s29, s29, 0
	s_add_u32 s25, s25, 0x100
	s_addc_u32 s27, s27, 0
	s_cmp_gt_u32 s54, 29
	s_cbranch_scc0 .LBB0_1066
	s_and_b64 vcc, exec, s[14:15]
	s_cbranch_vccz .LBB0_1069
	s_barrier

; #define PG8_STAGE(bufoff, gbase, voff) do { _Pragma("unroll") for (int _i = 0; _i < 2; ++_i) \
;         __builtin_amdgcn_global_load_lds((const unsigned*)((const char*)(gbase) + (voff)[_i]), (PG8_LAS unsigned*)(lds + (bufoff) + ldsw + _i * 8192), 16, 0, 0); } while (0)
; #define PG8_LDA(dst, b, h) do { _Pragma("unroll") for (int m = 0; m < 4; ++m) _Pragma("unroll") for (int k = 0; k < 2; ++k) dst[m][k] = *(const PG8_LAS bf16x8*)(lds + PG8_SA(b, h) + aoff + m * 2048 + k * 1024); } while (0)
; #define PG8_LDB(dst, b, h) do { _Pragma("unroll") for (int n = 0; n < 2; ++n) _Pragma("unroll") for (int k = 0; k < 2; ++k) dst[n][k] = *(const PG8_LAS bf16x8*)(lds + PG8_SB(b, h) + boff + n * 2048 + k * 1024); } while (0)
; #define PG8_MMA(ai, bj, At, Bt) do { __builtin_amdgcn_s_setprio(1); _Pragma("unroll") for (int m = 0; m < 4; ++m) _Pragma("unroll") for (int n = 0; n < 2; ++n) _Pragma("unroll") for (int k = 0; k < 2; ++k) \
;         acc[ai][bj][m][n] = __builtin_amdgcn_mfma_f32_16x16x32_bf16(Bt[n][k], At[m][k], acc[ai][bj][m][n], 0, 0, 0); __builtin_amdgcn_s_setprio(0); } while (0)
; #define PG8_WAIT_V(n) asm volatile("s_waitcnt vmcnt(" #n ")" ::: "memory")
; #define PG8_WAIT_L(n) asm volatile("s_waitcnt lgkmcnt(" #n ")" ::: "memory")
; #define PG8_BAR __builtin_amdgcn_s_barrier()
; #define PG8_SCHED __builtin_amdgcn_sched_barrier(0)
; template <class Epi, class Sched, bool ALIGN_EPI = false, bool SP2 = false>
; __device__ __forceinline__ void gemm_phase(PG8_LAS unsigned char* lds, const Gemm g, const Sched& S, const Epi& E) {
;     ...
;             PG8_LDB(B0, 0, 0); PG8_LDB(B1, 0, 1); PG8_SCHED; PG8_LDA(At, 0, 0); PG8_STAGE(PG8_SA(1, 1), a1 + hstepA, voffA);
;             PG8_WAIT_V(8); PG8_WAIT_L(0); PG8_BAR; PG8_MMA(0, 0, At, B0); PG8_MMA(0, 1, At, B1); PG8_BAR; PG8_SCHED;
;             PG8_LDA(At, 0, 1); PG8_STAGE(PG8_SB(0, 0), b2, voffB); PG8_STAGE(PG8_SB(0, 1), b2 + hstep, voffB); PG8_STAGE(PG8_SA(0, 0), a2, voffA);
.LBB0_1154:
	ds_read_b128 v[96:99], v209
	ds_read_b128 v[108:111], v209 offset:1024
	ds_read_b128 v[112:115], v209 offset:2048
	ds_read_b128 v[116:119], v209 offset:3072
	ds_read_b128 v[120:123], v210
	ds_read_b128 v[124:127], v210 offset:1024
	ds_read_b128 v[128:131], v210 offset:2048
	ds_read_b128 v[132:135], v210 offset:3072
	s_add_u32 s14, s16, 0x100
	s_addc_u32 s15, s17, 0
	s_cmp_eq_u32 s25, 28
	s_cselect_b32 s21, s53, s15
	s_cselect_b32 s20, s52, s14
	s_cselect_b32 s19, s6, s23
	s_cselect_b32 s18, s7, s22
	v_lshl_add_u64 v[202:203], s[16:17], 0, v[174:175]
	s_add_i32 m0, s60, 0xc000
	ds_read_b128 v[136:139], v211
	ds_read_b128 v[182:185], v211 offset:1024
	ds_read_b128 v[186:189], v211 offset:2048
	ds_read_b128 v[190:193], v211 offset:3072
	ds_read_b128 v[194:197], v211 offset:4096
	ds_read_b128 v[198:201], v211 offset:5120
	ds_read_b128 v[214:217], v211 offset:6144
	ds_read_b128 v[218:221], v211 offset:7168
	global_load_lds_dwordx4 v[202:203], off
	v_lshl_add_u64 v[202:203], s[16:17], 0, v[176:177]
	s_add_i32 m0, s60, 0xe000
	s_nop 0
	global_load_lds_dwordx4 v[202:203], off
	s_waitcnt vmcnt(8)
	s_waitcnt lgkmcnt(0)
	s_barrier
	s_waitcnt lgkmcnt(0)
	v_mfma_f32_16x16x32_bf16 v[160:163], v[96:99], v[136:139], v[160:163]
	v_mfma_f32_16x16x32_bf16 v[60:63], v[112:115], v[136:139], v[60:63]
	v_mfma_f32_16x16x32_bf16 v[156:159], v[96:99], v[186:189], v[156:159]
	v_mfma_f32_16x16x32_bf16 v[56:59], v[112:115], v[186:189], v[56:59]
	v_mfma_f32_16x16x32_bf16 v[152:155], v[96:99], v[194:197], v[152:155]
	v_mfma_f32_16x16x32_bf16 v[52:55], v[112:115], v[194:197], v[52:55]
	v_mfma_f32_16x16x32_bf16 v[144:147], v[96:99], v[214:217], v[144:147]
	v_mfma_f32_16x16x32_bf16 v[44:47], v[112:115], v[214:217], v[44:47]
	v_mfma_f32_16x16x32_bf16 v[160:163], v[108:111], v[182:185], v[160:163]
	v_mfma_f32_16x16x32_bf16 v[60:63], v[116:119], v[182:185], v[60:63]
	v_mfma_f32_16x16x32_bf16 v[156:159], v[108:111], v[190:193], v[156:159]
	v_mfma_f32_16x16x32_bf16 v[56:59], v[116:119], v[190:193], v[56:59]
	v_mfma_f32_16x16x32_bf16 v[152:155], v[108:111], v[198:201], v[152:155]
	v_mfma_f32_16x16x32_bf16 v[52:55], v[116:119], v[198:201], v[52:55]
	v_mfma_f32_16x16x32_bf16 v[144:147], v[108:111], v[218:221], v[144:147]
	v_mfma_f32_16x16x32_bf16 v[44:47], v[116:119], v[218:221], v[44:47]
	v_mfma_f32_16x16x32_bf16 v[148:151], v[120:123], v[136:139], v[148:151]
	v_mfma_f32_16x16x32_bf16 v[48:51], v[128:131], v[136:139], v[48:51]
	v_mfma_f32_16x16x32_bf16 v[40:43], v[128:131], v[186:189], v[40:43]
	v_mfma_f32_16x16x32_bf16 v[104:107], v[120:123], v[194:197], v[104:107]
	v_mfma_f32_16x16x32_bf16 v[36:39], v[128:131], v[194:197], v[36:39]
	v_mfma_f32_16x16x32_bf16 v[100:103], v[120:123], v[214:217], v[100:103]
	v_mfma_f32_16x16x32_bf16 v[32:35], v[128:131], v[214:217], v[32:35]
	v_mfma_f32_16x16x32_bf16 v[148:151], v[124:127], v[182:185], v[148:151]
	v_mfma_f32_16x16x32_bf16 v[48:51], v[132:135], v[182:185], v[48:51]
	v_mfma_f32_16x16x32_bf16 v[136:139], v[120:123], v[186:189], v[140:143]
	v_mfma_f32_16x16x32_bf16 v[40:43], v[132:135], v[190:193], v[40:43]
	v_mfma_f32_16x16x32_bf16 v[104:107], v[124:127], v[198:201], v[104:107]
	v_mfma_f32_16x16x32_bf16 v[36:39], v[132:135], v[198:201], v[36:39]
	v_mfma_f32_16x16x32_bf16 v[100:103], v[124:127], v[218:221], v[100:103]
	v_mfma_f32_16x16x32_bf16 v[32:35], v[132:135], v[218:221], v[32:35]
	v_mfma_f32_16x16x32_bf16 v[136:139], v[124:127], v[190:193], v[136:139]
	s_barrier
	s_add_i32 s16, s78, s59
	v_lshl_add_u64 v[202:203], s[18:19], 0, v[166:167]
	s_mov_b32 m0, s16
	ds_read_b128 v[140:143], v211 offset:16384
	ds_read_b128 v[182:185], v211 offset:17408
	ds_read_b128 v[186:189], v211 offset:18432
	ds_read_b128 v[190:193], v211 offset:19456
	ds_read_b128 v[194:197], v211 offset:20480
	ds_read_b128 v[198:201], v211 offset:21504
	ds_read_b128 v[214:217], v211 offset:22528
	ds_read_b128 v[218:221], v211 offset:23552
	global_load_lds_dwordx4 v[202:203], off
	s_add_i32 m0, s16, 0x2000
	s_add_u32 s16, s18, 0x80000
	v_lshl_add_u64 v[222:223], s[18:19], 0, v[170:171]
	s_addc_u32 s17, s19, 0
	s_add_i32 s26, s79, s59
	global_load_lds_dwordx4 v[222:223], off
	v_lshl_add_u64 v[224:225], s[16:17], 0, v[166:167]
	s_mov_b32 m0, s26
	v_lshl_add_u64 v[226:227], s[20:21], 0, v[168:169]
	global_load_lds_dwordx4 v[224:225], off
	v_lshl_add_u64 v[224:225], s[16:17], 0, v[170:171]
	s_add_i32 m0, s26, 0x2000
	s_nop 0
	global_load_lds_dwordx4 v[224:225], off
	v_lshl_add_u64 v[224:225], s[20:21], 0, v[164:165]
	s_mov_b32 m0, s60
	s_nop 0
	global_load_lds_dwordx4 v[224:225], off
	s_mov_b32 m0, s61
	s_nop 0
	global_load_lds_dwordx4 v[226:227], off
	s_waitcnt vmcnt(8)
	s_waitcnt lgkmcnt(0)
	s_barrier
; #define PG8_STAGE(bufoff, gbase, voff) do { _Pragma("unroll") for (int _i = 0; _i < 2; ++_i) \
;         __builtin_amdgcn_global_load_lds((const unsigned*)((const char*)(gbase) + (voff)[_i]), (PG8_LAS unsigned*)(lds + (bufoff) + ldsw + _i * 8192), 16, 0, 0); } while (0)
; #define PG8_LDA(dst, b, h) do { _Pragma("unroll") for (int m = 0; m < 4; ++m) _Pragma("unroll") for (int k = 0; k < 2; ++k) dst[m][k] = *(const PG8_LAS bf16x8*)(lds + PG8_SA(b, h) + aoff + m * 2048 + k * 1024); } while (0)
; #define PG8_LDB(dst, b, h) do { _Pragma("unroll") for (int n = 0; n < 2; ++n) _Pragma("unroll") for (int k = 0; k < 2; ++k) dst[n][k] = *(const PG8_LAS bf16x8*)(lds + PG8_SB(b, h) + boff + n * 2048 + k * 1024); } while (0)
; #define PG8_MMA(ai, bj, At, Bt) do { __builtin_amdgcn_s_setprio(1); _Pragma("unroll") for (int m = 0; m < 4; ++m) _Pragma("unroll") for (int n = 0; n < 2; ++n) _Pragma("unroll") for (int k = 0; k < 2; ++k) \
;         acc[ai][bj][m][n] = __builtin_amdgcn_mfma_f32_16x16x32_bf16(Bt[n][k], At[m][k], acc[ai][bj][m][n], 0, 0, 0); __builtin_amdgcn_s_setprio(0); } while (0)
; #define PG8_WAIT_V(n) asm volatile("s_waitcnt vmcnt(" #n ")" ::: "memory")
; #define PG8_WAIT_L(n) asm volatile("s_waitcnt lgkmcnt(" #n ")" ::: "memory")
; #define PG8_BAR __builtin_amdgcn_s_barrier()
; #define PG8_SCHED __builtin_amdgcn_sched_barrier(0)
; template <class Epi, class Sched, bool ALIGN_EPI = false, bool SP2 = false>
; __device__ __forceinline__ void gemm_phase(PG8_LAS unsigned char* lds, const Gemm g, const Sched& S, const Epi& E) {
;     ...
;             PG8_WAIT_V(8); PG8_WAIT_L(0); PG8_BAR; PG8_MMA(1, 0, At, B0); PG8_MMA(1, 1, At, B1); PG8_BAR; PG8_SCHED;
;             PG8_LDB(B0, 1, 0); PG8_LDB(B1, 1, 1); PG8_SCHED; PG8_LDA(At, 1, 0); PG8_STAGE(PG8_SA(0, 1), a2 + hstepA, voffA);
;             PG8_WAIT_V(8); PG8_WAIT_L(0); PG8_BAR; PG8_MMA(0, 0, At, B0); PG8_MMA(0, 1, At, B1); PG8_BAR; PG8_SCHED;
	s_waitcnt lgkmcnt(0)
	v_mfma_f32_16x16x32_bf16 v[92:95], v[96:99], v[140:143], v[92:95]
	v_mfma_f32_16x16x32_bf16 v[28:31], v[112:115], v[140:143], v[28:31]
	v_mfma_f32_16x16x32_bf16 v[88:91], v[96:99], v[186:189], v[88:91]
	v_mfma_f32_16x16x32_bf16 v[24:27], v[112:115], v[186:189], v[24:27]
	v_mfma_f32_16x16x32_bf16 v[84:87], v[96:99], v[194:197], v[84:87]
	v_mfma_f32_16x16x32_bf16 v[20:23], v[112:115], v[194:197], v[20:23]
	v_mfma_f32_16x16x32_bf16 v[76:79], v[96:99], v[214:217], v[76:79]
	v_mfma_f32_16x16x32_bf16 v[12:15], v[112:115], v[214:217], v[12:15]
	v_mfma_f32_16x16x32_bf16 v[92:95], v[108:111], v[182:185], v[92:95]
	v_mfma_f32_16x16x32_bf16 v[28:31], v[116:119], v[182:185], v[28:31]
	v_mfma_f32_16x16x32_bf16 v[88:91], v[108:111], v[190:193], v[88:91]
	v_mfma_f32_16x16x32_bf16 v[24:27], v[116:119], v[190:193], v[24:27]
	v_mfma_f32_16x16x32_bf16 v[84:87], v[108:111], v[198:201], v[84:87]
	v_mfma_f32_16x16x32_bf16 v[20:23], v[116:119], v[198:201], v[20:23]
	v_mfma_f32_16x16x32_bf16 v[76:79], v[108:111], v[218:221], v[76:79]
	v_mfma_f32_16x16x32_bf16 v[12:15], v[116:119], v[218:221], v[12:15]
	v_mfma_f32_16x16x32_bf16 v[80:83], v[120:123], v[140:143], v[80:83]
	v_mfma_f32_16x16x32_bf16 v[16:19], v[128:131], v[140:143], v[16:19]
	v_mfma_f32_16x16x32_bf16 v[72:75], v[120:123], v[186:189], v[72:75]
	v_mfma_f32_16x16x32_bf16 v[8:11], v[128:131], v[186:189], v[8:11]
	v_mfma_f32_16x16x32_bf16 v[68:71], v[120:123], v[194:197], v[68:71]
	v_mfma_f32_16x16x32_bf16 v[4:7], v[128:131], v[194:197], v[4:7]
	v_mfma_f32_16x16x32_bf16 v[64:67], v[120:123], v[214:217], v[64:67]
	v_mfma_f32_16x16x32_bf16 v[0:3], v[128:131], v[214:217], v[0:3]
	v_mfma_f32_16x16x32_bf16 v[80:83], v[124:127], v[182:185], v[80:83]
	v_mfma_f32_16x16x32_bf16 v[16:19], v[132:135], v[182:185], v[16:19]
	v_mfma_f32_16x16x32_bf16 v[72:75], v[124:127], v[190:193], v[72:75]
	v_mfma_f32_16x16x32_bf16 v[8:11], v[132:135], v[190:193], v[8:11]
	v_mfma_f32_16x16x32_bf16 v[68:71], v[124:127], v[198:201], v[68:71]
	v_mfma_f32_16x16x32_bf16 v[4:7], v[132:135], v[198:201], v[4:7]
	v_mfma_f32_16x16x32_bf16 v[64:67], v[124:127], v[218:221], v[64:67]
	v_mfma_f32_16x16x32_bf16 v[0:3], v[132:135], v[218:221], v[0:3]
	s_barrier
	s_add_i32 s26, 0, 0x18000
	s_add_i32 s27, 0, 0x1c000
	v_add_u32_e32 v116, s26, v206
	v_add_u32_e32 v132, s27, v206
	ds_read_b128 v[96:99], v116
	ds_read_b128 v[108:111], v116 offset:1024
	ds_read_b128 v[112:115], v116 offset:2048
	ds_read_b128 v[116:119], v116 offset:3072
	ds_read_b128 v[120:123], v132
	ds_read_b128 v[124:127], v132 offset:1024
	ds_read_b128 v[128:131], v132 offset:2048
	ds_read_b128 v[132:135], v132 offset:3072
	s_add_u32 s16, s20, 0x7c000
	s_addc_u32 s17, s21, 0
	s_mov_b32 m0, s62
	v_lshl_add_u64 v[228:229], s[16:17], 0, v[164:165]
	ds_read_b128 v[140:143], v211 offset:32768
	ds_read_b128 v[182:185], v211 offset:33792
	ds_read_b128 v[186:189], v211 offset:34816
	ds_read_b128 v[190:193], v211 offset:35840
	ds_read_b128 v[194:197], v211 offset:36864
	ds_read_b128 v[198:201], v211 offset:37888
	ds_read_b128 v[214:217], v211 offset:38912
	ds_read_b128 v[218:221], v211 offset:39936
	global_load_lds_dwordx4 v[228:229], off
	v_lshl_add_u64 v[228:229], s[16:17], 0, v[168:169]
	s_mov_b32 m0, s63
	s_nop 0
	global_load_lds_dwordx4 v[228:229], off
	s_waitcnt vmcnt(8)
	s_waitcnt lgkmcnt(0)
	s_barrier
	s_waitcnt lgkmcnt(0)
	v_mfma_f32_16x16x32_bf16 v[160:163], v[96:99], v[140:143], v[160:163]
	v_mfma_f32_16x16x32_bf16 v[60:63], v[112:115], v[140:143], v[60:63]
	v_mfma_f32_16x16x32_bf16 v[156:159], v[96:99], v[186:189], v[156:159]
	v_mfma_f32_16x16x32_bf16 v[56:59], v[112:115], v[186:189], v[56:59]
	v_mfma_f32_16x16x32_bf16 v[152:155], v[96:99], v[194:197], v[152:155]
	v_mfma_f32_16x16x32_bf16 v[52:55], v[112:115], v[194:197], v[52:55]
	v_mfma_f32_16x16x32_bf16 v[144:147], v[96:99], v[214:217], v[144:147]
	v_mfma_f32_16x16x32_bf16 v[44:47], v[112:115], v[214:217], v[44:47]
	v_mfma_f32_16x16x32_bf16 v[160:163], v[108:111], v[182:185], v[160:163]
	v_mfma_f32_16x16x32_bf16 v[60:63], v[116:119], v[182:185], v[60:63]
	v_mfma_f32_16x16x32_bf16 v[156:159], v[108:111], v[190:193], v[156:159]
	v_mfma_f32_16x16x32_bf16 v[56:59], v[116:119], v[190:193], v[56:59]
	v_mfma_f32_16x16x32_bf16 v[152:155], v[108:111], v[198:201], v[152:155]
	v_mfma_f32_16x16x32_bf16 v[52:55], v[116:119], v[198:201], v[52:55]
	v_mfma_f32_16x16x32_bf16 v[144:147], v[108:111], v[218:221], v[144:147]
	v_mfma_f32_16x16x32_bf16 v[44:47], v[116:119], v[218:221], v[44:47]
	v_mfma_f32_16x16x32_bf16 v[148:151], v[120:123], v[140:143], v[148:151]
	v_mfma_f32_16x16x32_bf16 v[48:51], v[128:131], v[140:143], v[48:51]
	v_mfma_f32_16x16x32_bf16 v[136:139], v[120:123], v[186:189], v[136:139]
	v_mfma_f32_16x16x32_bf16 v[40:43], v[128:131], v[186:189], v[40:43]
	v_mfma_f32_16x16x32_bf16 v[104:107], v[120:123], v[194:197], v[104:107]
	v_mfma_f32_16x16x32_bf16 v[36:39], v[128:131], v[194:197], v[36:39]
	v_mfma_f32_16x16x32_bf16 v[100:103], v[120:123], v[214:217], v[100:103]
	v_mfma_f32_16x16x32_bf16 v[32:35], v[128:131], v[214:217], v[32:35]
	v_mfma_f32_16x16x32_bf16 v[148:151], v[124:127], v[182:185], v[148:151]
	v_mfma_f32_16x16x32_bf16 v[48:51], v[132:135], v[182:185], v[48:51]
	v_mfma_f32_16x16x32_bf16 v[140:143], v[124:127], v[190:193], v[136:139]
	v_mfma_f32_16x16x32_bf16 v[40:43], v[132:135], v[190:193], v[40:43]
	v_mfma_f32_16x16x32_bf16 v[104:107], v[124:127], v[198:201], v[104:107]
	v_mfma_f32_16x16x32_bf16 v[36:39], v[132:135], v[198:201], v[36:39]
	v_mfma_f32_16x16x32_bf16 v[100:103], v[124:127], v[218:221], v[100:103]
	v_mfma_f32_16x16x32_bf16 v[32:35], v[132:135], v[218:221], v[32:35]
	s_barrier
; #define PG8_STAGE(bufoff, gbase, voff) do { _Pragma("unroll") for (int _i = 0; _i < 2; ++_i) \
;         __builtin_amdgcn_global_load_lds((const unsigned*)((const char*)(gbase) + (voff)[_i]), (PG8_LAS unsigned*)(lds + (bufoff) + ldsw + _i * 8192), 16, 0, 0); } while (0)
; #define PG8_LDA(dst, b, h) do { _Pragma("unroll") for (int m = 0; m < 4; ++m) _Pragma("unroll") for (int k = 0; k < 2; ++k) dst[m][k] = *(const PG8_LAS bf16x8*)(lds + PG8_SA(b, h) + aoff + m * 2048 + k * 1024); } while (0)
; #define PG8_MMA(ai, bj, At, Bt) do { __builtin_amdgcn_s_setprio(1); _Pragma("unroll") for (int m = 0; m < 4; ++m) _Pragma("unroll") for (int n = 0; n < 2; ++n) _Pragma("unroll") for (int k = 0; k < 2; ++k) \
;         acc[ai][bj][m][n] = __builtin_amdgcn_mfma_f32_16x16x32_bf16(Bt[n][k], At[m][k], acc[ai][bj][m][n], 0, 0, 0); __builtin_amdgcn_s_setprio(0); } while (0)
; #define PG8_WAIT_V(n) asm volatile("s_waitcnt vmcnt(" #n ")" ::: "memory")
; #define PG8_WAIT_L(n) asm volatile("s_waitcnt lgkmcnt(" #n ")" ::: "memory")
; #define PG8_BAR __builtin_amdgcn_s_barrier()
; #define PG8_SCHED __builtin_amdgcn_sched_barrier(0)
; template <class Epi, class Sched, bool ALIGN_EPI = false, bool SP2 = false>
; __device__ __forceinline__ void gemm_phase(PG8_LAS unsigned char* lds, const Gemm g, const Sched& S, const Epi& E) {
;     ...
;             PG8_LDA(At, 1, 1); PG8_STAGE(PG8_SB(1, 0), b3, voffB); PG8_STAGE(PG8_SB(1, 1), b3 + hstep, voffB); PG8_STAGE(PG8_SA(1, 0), a3, voffA);
;             PG8_WAIT_V(8); PG8_WAIT_L(0); PG8_BAR; PG8_MMA(1, 0, At, B0); PG8_MMA(1, 1, At, B1); PG8_BAR; PG8_SCHED;
	s_add_i32 s16, s26, s59
	v_lshl_add_u64 v[202:203], v[202:203], 0, s[8:9]
	s_mov_b32 m0, s16
	ds_read_b128 v[136:139], v211 offset:49152
	ds_read_b128 v[182:185], v211 offset:50176
	ds_read_b128 v[186:189], v211 offset:51200
	ds_read_b128 v[190:193], v211 offset:52224
	ds_read_b128 v[194:197], v211 offset:53248
	ds_read_b128 v[198:201], v211 offset:54272
	ds_read_b128 v[214:217], v211 offset:55296
	ds_read_b128 v[218:221], v211 offset:56320
	global_load_lds_dwordx4 v[202:203], off
	s_add_i32 m0, s16, 0x2000
	s_add_u32 s16, s18, 0x80080
	v_lshl_add_u64 v[202:203], v[222:223], 0, s[8:9]
	s_addc_u32 s17, s19, 0
	s_add_i32 s18, s27, s59
	global_load_lds_dwordx4 v[202:203], off
	v_lshl_add_u64 v[202:203], s[16:17], 0, v[166:167]
	s_mov_b32 m0, s18
	s_nop 0
	global_load_lds_dwordx4 v[202:203], off
	v_lshl_add_u64 v[202:203], s[16:17], 0, v[170:171]
	s_add_i32 m0, s18, 0x2000
	s_nop 0
	global_load_lds_dwordx4 v[202:203], off
	v_lshl_add_u64 v[202:203], v[224:225], 0, s[8:9]
	s_mov_b32 m0, s66
	s_nop 0
	global_load_lds_dwordx4 v[202:203], off
	v_lshl_add_u64 v[202:203], v[226:227], 0, s[8:9]
	s_mov_b32 m0, s67
	s_nop 0
	global_load_lds_dwordx4 v[202:203], off
	s_waitcnt vmcnt(8)
	s_waitcnt lgkmcnt(0)
	s_barrier
	s_waitcnt lgkmcnt(0)
	v_mfma_f32_16x16x32_bf16 v[92:95], v[96:99], v[136:139], v[92:95]
	v_mfma_f32_16x16x32_bf16 v[28:31], v[112:115], v[136:139], v[28:31]
	v_mfma_f32_16x16x32_bf16 v[88:91], v[96:99], v[186:189], v[88:91]
	v_mfma_f32_16x16x32_bf16 v[24:27], v[112:115], v[186:189], v[24:27]
	v_mfma_f32_16x16x32_bf16 v[84:87], v[96:99], v[194:197], v[84:87]
	v_mfma_f32_16x16x32_bf16 v[20:23], v[112:115], v[194:197], v[20:23]
	v_mfma_f32_16x16x32_bf16 v[76:79], v[96:99], v[214:217], v[76:79]
	v_mfma_f32_16x16x32_bf16 v[12:15], v[112:115], v[214:217], v[12:15]
	v_mfma_f32_16x16x32_bf16 v[92:95], v[108:111], v[182:185], v[92:95]
	v_mfma_f32_16x16x32_bf16 v[28:31], v[116:119], v[182:185], v[28:31]
	v_mfma_f32_16x16x32_bf16 v[88:91], v[108:111], v[190:193], v[88:91]
	v_mfma_f32_16x16x32_bf16 v[24:27], v[116:119], v[190:193], v[24:27]
	v_mfma_f32_16x16x32_bf16 v[84:87], v[108:111], v[198:201], v[84:87]
	v_mfma_f32_16x16x32_bf16 v[20:23], v[116:119], v[198:201], v[20:23]
	v_mfma_f32_16x16x32_bf16 v[76:79], v[108:111], v[218:221], v[76:79]
	v_mfma_f32_16x16x32_bf16 v[12:15], v[116:119], v[218:221], v[12:15]
	v_mfma_f32_16x16x32_bf16 v[80:83], v[120:123], v[136:139], v[80:83]
	v_mfma_f32_16x16x32_bf16 v[16:19], v[128:131], v[136:139], v[16:19]
	v_mfma_f32_16x16x32_bf16 v[72:75], v[120:123], v[186:189], v[72:75]
	v_mfma_f32_16x16x32_bf16 v[8:11], v[128:131], v[186:189], v[8:11]
	v_mfma_f32_16x16x32_bf16 v[68:71], v[120:123], v[194:197], v[68:71]
	v_mfma_f32_16x16x32_bf16 v[4:7], v[128:131], v[194:197], v[4:7]
	v_mfma_f32_16x16x32_bf16 v[64:67], v[120:123], v[214:217], v[64:67]
	v_mfma_f32_16x16x32_bf16 v[0:3], v[128:131], v[214:217], v[0:3]
	v_mfma_f32_16x16x32_bf16 v[80:83], v[124:127], v[182:185], v[80:83]
	v_mfma_f32_16x16x32_bf16 v[16:19], v[132:135], v[182:185], v[16:19]
	v_mfma_f32_16x16x32_bf16 v[72:75], v[124:127], v[190:193], v[72:75]
	v_mfma_f32_16x16x32_bf16 v[8:11], v[132:135], v[190:193], v[8:11]
	v_mfma_f32_16x16x32_bf16 v[68:71], v[124:127], v[198:201], v[68:71]
	v_mfma_f32_16x16x32_bf16 v[4:7], v[132:135], v[198:201], v[4:7]
	v_mfma_f32_16x16x32_bf16 v[64:67], v[124:127], v[218:221], v[64:67]
	v_mfma_f32_16x16x32_bf16 v[0:3], v[132:135], v[218:221], v[0:3]
	s_barrier
	s_add_i32 s25, s25, 2
	s_add_u32 s22, s22, 0x100
	s_addc_u32 s23, s23, 0
	s_cmp_gt_u32 s25, 29
	s_mov_b64 s[16:17], s[14:15]
	s_cbranch_scc0 .LBB0_1154
	s_and_b64 vcc, exec, s[30:31]
	s_cbranch_vccz .LBB0_1157
	s_barrier

; #define PG8_STAGE(bufoff, gbase, voff) do { _Pragma("unroll") for (int _i = 0; _i < 2; ++_i) \
;         __builtin_amdgcn_global_load_lds((const unsigned*)((const char*)(gbase) + (voff)[_i]), (PG8_LAS unsigned*)(lds + (bufoff) + ldsw + _i * 8192), 16, 0, 0); } while (0)
; #define PG8_LDA(dst, b, h) do { _Pragma("unroll") for (int m = 0; m < 4; ++m) _Pragma("unroll") for (int k = 0; k < 2; ++k) dst[m][k] = *(const PG8_LAS bf16x8*)(lds + PG8_SA(b, h) + aoff + m * 2048 + k * 1024); } while (0)
; #define PG8_LDB(dst, b, h) do { _Pragma("unroll") for (int n = 0; n < 2; ++n) _Pragma("unroll") for (int k = 0; k < 2; ++k) dst[n][k] = *(const PG8_LAS bf16x8*)(lds + PG8_SB(b, h) + boff + n * 2048 + k * 1024); } while (0)
; #define PG8_MMA(ai, bj, At, Bt) do { __builtin_amdgcn_s_setprio(1); _Pragma("unroll") for (int m = 0; m < 4; ++m) _Pragma("unroll") for (int n = 0; n < 2; ++n) _Pragma("unroll") for (int k = 0; k < 2; ++k) \
;         acc[ai][bj][m][n] = __builtin_amdgcn_mfma_f32_16x16x32_bf16(Bt[n][k], At[m][k], acc[ai][bj][m][n], 0, 0, 0); __builtin_amdgcn_s_setprio(0); } while (0)
; #define PG8_WAIT_V(n) asm volatile("s_waitcnt vmcnt(" #n ")" ::: "memory")
; #define PG8_WAIT_L(n) asm volatile("s_waitcnt lgkmcnt(" #n ")" ::: "memory")
; #define PG8_BAR __builtin_amdgcn_s_barrier()
; #define PG8_SCHED __builtin_amdgcn_sched_barrier(0)
; template <class Epi, class Sched, bool ALIGN_EPI = false, bool SP2 = false>
; __device__ __forceinline__ void gemm_phase(PG8_LAS unsigned char* lds, const Gemm g, const Sched& S, const Epi& E) {
;     ...
;             PG8_LDB(B0, 0, 0); PG8_LDB(B1, 0, 1); PG8_SCHED; PG8_LDA(At, 0, 0); PG8_STAGE(PG8_SA(1, 1), a1 + hstepA, voffA);
;             PG8_WAIT_V(8); PG8_WAIT_L(0); PG8_BAR; PG8_MMA(0, 0, At, B0); PG8_MMA(0, 1, At, B1); PG8_BAR; PG8_SCHED;
;             PG8_LDA(At, 0, 1); PG8_STAGE(PG8_SB(0, 0), b2, voffB); PG8_STAGE(PG8_SB(0, 1), b2 + hstep, voffB); PG8_STAGE(PG8_SA(0, 0), a2, voffA);
.LBB0_1298:
	ds_read_b128 v[128:131], v167
	ds_read_b128 v[132:135], v167 offset:1024
	ds_read_b128 v[152:155], v167 offset:2048
	ds_read_b128 v[156:159], v167 offset:3072
	ds_read_b128 v[160:163], v168
	ds_read_b128 v[172:175], v168 offset:1024
	ds_read_b128 v[176:179], v168 offset:2048
	ds_read_b128 v[180:183], v168 offset:3072
	s_add_u32 s24, s22, 0x100
	s_addc_u32 s25, s23, 0
	s_cmpk_eq_i32 s54, 0x54
	s_cselect_b32 s29, s15, s25
	s_cselect_b32 s28, s14, s24
	s_cselect_b32 s27, s21, s53
	s_cselect_b32 s26, s20, s52
	v_lshl_add_u64 v[218:219], s[22:23], 0, v[144:145]
	s_add_i32 m0, s35, 0xc000
	ds_read_b128 v[184:187], v169
	ds_read_b128 v[188:191], v169 offset:1024
	ds_read_b128 v[192:195], v169 offset:2048
	ds_read_b128 v[196:199], v169 offset:3072
	ds_read_b128 v[200:203], v169 offset:4096
	ds_read_b128 v[206:209], v169 offset:5120
	ds_read_b128 v[210:213], v169 offset:6144
	ds_read_b128 v[214:217], v169 offset:7168
	global_load_lds_dwordx4 v[218:219], off
	v_lshl_add_u64 v[218:219], s[22:23], 0, v[146:147]
	s_add_i32 m0, s35, 0xe000
	s_nop 0
	global_load_lds_dwordx4 v[218:219], off
	s_waitcnt vmcnt(8)
	s_waitcnt lgkmcnt(0)
	s_barrier
	s_waitcnt lgkmcnt(0)
	v_mfma_f32_16x16x32_bf16 v[124:127], v[128:131], v[184:187], v[124:127]
	v_mfma_f32_16x16x32_bf16 v[120:123], v[152:155], v[184:187], v[120:123]
	v_mfma_f32_16x16x32_bf16 v[108:111], v[128:131], v[192:195], v[108:111]
	v_mfma_f32_16x16x32_bf16 v[104:107], v[152:155], v[192:195], v[104:107]
	v_mfma_f32_16x16x32_bf16 v[92:95], v[128:131], v[200:203], v[92:95]
	v_mfma_f32_16x16x32_bf16 v[88:91], v[152:155], v[200:203], v[88:91]
	v_mfma_f32_16x16x32_bf16 v[76:79], v[128:131], v[210:213], v[76:79]
	v_mfma_f32_16x16x32_bf16 v[72:75], v[152:155], v[210:213], v[72:75]
	v_mfma_f32_16x16x32_bf16 v[124:127], v[132:135], v[188:191], v[124:127]
	v_mfma_f32_16x16x32_bf16 v[120:123], v[156:159], v[188:191], v[120:123]
	v_mfma_f32_16x16x32_bf16 v[108:111], v[132:135], v[196:199], v[108:111]
	v_mfma_f32_16x16x32_bf16 v[104:107], v[156:159], v[196:199], v[104:107]
	v_mfma_f32_16x16x32_bf16 v[92:95], v[132:135], v[206:209], v[92:95]
	v_mfma_f32_16x16x32_bf16 v[88:91], v[156:159], v[206:209], v[88:91]
	v_mfma_f32_16x16x32_bf16 v[76:79], v[132:135], v[214:217], v[76:79]
	v_mfma_f32_16x16x32_bf16 v[72:75], v[156:159], v[214:217], v[72:75]
	v_mfma_f32_16x16x32_bf16 v[116:119], v[160:163], v[184:187], v[116:119]
	v_mfma_f32_16x16x32_bf16 v[112:115], v[176:179], v[184:187], v[112:115]
	v_mfma_f32_16x16x32_bf16 v[100:103], v[160:163], v[192:195], v[100:103]
	v_mfma_f32_16x16x32_bf16 v[96:99], v[176:179], v[192:195], v[96:99]
	v_mfma_f32_16x16x32_bf16 v[84:87], v[160:163], v[200:203], v[84:87]
	v_mfma_f32_16x16x32_bf16 v[80:83], v[176:179], v[200:203], v[80:83]
	v_mfma_f32_16x16x32_bf16 v[68:71], v[160:163], v[210:213], v[68:71]
	v_mfma_f32_16x16x32_bf16 v[64:67], v[176:179], v[210:213], v[64:67]
	v_mfma_f32_16x16x32_bf16 v[116:119], v[172:175], v[188:191], v[116:119]
	v_mfma_f32_16x16x32_bf16 v[112:115], v[180:183], v[188:191], v[112:115]
	v_mfma_f32_16x16x32_bf16 v[100:103], v[172:175], v[196:199], v[100:103]
	v_mfma_f32_16x16x32_bf16 v[96:99], v[180:183], v[196:199], v[96:99]
	v_mfma_f32_16x16x32_bf16 v[84:87], v[172:175], v[206:209], v[84:87]
	v_mfma_f32_16x16x32_bf16 v[80:83], v[180:183], v[206:209], v[80:83]
	v_mfma_f32_16x16x32_bf16 v[68:71], v[172:175], v[214:217], v[68:71]
	v_mfma_f32_16x16x32_bf16 v[64:67], v[180:183], v[214:217], v[64:67]
	s_barrier
	s_add_i32 s22, s48, s34
	v_lshl_add_u64 v[218:219], s[26:27], 0, v[138:139]
	s_mov_b32 m0, s22
	ds_read_b128 v[184:187], v169 offset:16384
	ds_read_b128 v[188:191], v169 offset:17408
	ds_read_b128 v[192:195], v169 offset:18432
	ds_read_b128 v[196:199], v169 offset:19456
	ds_read_b128 v[200:203], v169 offset:20480
	ds_read_b128 v[206:209], v169 offset:21504
	ds_read_b128 v[210:213], v169 offset:22528
	ds_read_b128 v[214:217], v169 offset:23552
	global_load_lds_dwordx4 v[218:219], off
	s_add_i32 m0, s22, 0x2000
	s_add_u32 s22, s26, 0x160000
	v_lshl_add_u64 v[220:221], s[26:27], 0, v[142:143]
	s_addc_u32 s23, s27, 0
	s_add_i32 s55, s49, s34
	global_load_lds_dwordx4 v[220:221], off
	v_lshl_add_u64 v[222:223], s[22:23], 0, v[138:139]
	s_mov_b32 m0, s55
	v_lshl_add_u64 v[224:225], s[28:29], 0, v[140:141]
	global_load_lds_dwordx4 v[222:223], off
	v_lshl_add_u64 v[222:223], s[22:23], 0, v[142:143]
	s_add_i32 m0, s55, 0x2000
	s_nop 0
	global_load_lds_dwordx4 v[222:223], off
	v_lshl_add_u64 v[222:223], s[28:29], 0, v[136:137]
	s_mov_b32 m0, s35
	s_nop 0
	global_load_lds_dwordx4 v[222:223], off
	s_mov_b32 m0, s36
	s_nop 0
	global_load_lds_dwordx4 v[224:225], off
	s_waitcnt vmcnt(8)
	s_waitcnt lgkmcnt(0)
	s_barrier
; #define PG8_STAGE(bufoff, gbase, voff) do { _Pragma("unroll") for (int _i = 0; _i < 2; ++_i) \
;         __builtin_amdgcn_global_load_lds((const unsigned*)((const char*)(gbase) + (voff)[_i]), (PG8_LAS unsigned*)(lds + (bufoff) + ldsw + _i * 8192), 16, 0, 0); } while (0)
; #define PG8_LDA(dst, b, h) do { _Pragma("unroll") for (int m = 0; m < 4; ++m) _Pragma("unroll") for (int k = 0; k < 2; ++k) dst[m][k] = *(const PG8_LAS bf16x8*)(lds + PG8_SA(b, h) + aoff + m * 2048 + k * 1024); } while (0)
; #define PG8_LDB(dst, b, h) do { _Pragma("unroll") for (int n = 0; n < 2; ++n) _Pragma("unroll") for (int k = 0; k < 2; ++k) dst[n][k] = *(const PG8_LAS bf16x8*)(lds + PG8_SB(b, h) + boff + n * 2048 + k * 1024); } while (0)
; #define PG8_MMA(ai, bj, At, Bt) do { __builtin_amdgcn_s_setprio(1); _Pragma("unroll") for (int m = 0; m < 4; ++m) _Pragma("unroll") for (int n = 0; n < 2; ++n) _Pragma("unroll") for (int k = 0; k < 2; ++k) \
;         acc[ai][bj][m][n] = __builtin_amdgcn_mfma_f32_16x16x32_bf16(Bt[n][k], At[m][k], acc[ai][bj][m][n], 0, 0, 0); __builtin_amdgcn_s_setprio(0); } while (0)
; #define PG8_WAIT_V(n) asm volatile("s_waitcnt vmcnt(" #n ")" ::: "memory")
; #define PG8_WAIT_L(n) asm volatile("s_waitcnt lgkmcnt(" #n ")" ::: "memory")
; #define PG8_BAR __builtin_amdgcn_s_barrier()
; #define PG8_SCHED __builtin_amdgcn_sched_barrier(0)
; template <class Epi, class Sched, bool ALIGN_EPI = false, bool SP2 = false>
; __device__ __forceinline__ void gemm_phase(PG8_LAS unsigned char* lds, const Gemm g, const Sched& S, const Epi& E) {
;     ...
;             PG8_WAIT_V(8); PG8_WAIT_L(0); PG8_BAR; PG8_MMA(1, 0, At, B0); PG8_MMA(1, 1, At, B1); PG8_BAR; PG8_SCHED;
;             PG8_LDB(B0, 1, 0); PG8_LDB(B1, 1, 1); PG8_SCHED; PG8_LDA(At, 1, 0); PG8_STAGE(PG8_SA(0, 1), a2 + hstepA, voffA);
;             PG8_WAIT_V(8); PG8_WAIT_L(0); PG8_BAR; PG8_MMA(0, 0, At, B0); PG8_MMA(0, 1, At, B1); PG8_BAR; PG8_SCHED;
	s_waitcnt lgkmcnt(0)
	v_mfma_f32_16x16x32_bf16 v[60:63], v[128:131], v[184:187], v[60:63]
	v_mfma_f32_16x16x32_bf16 v[56:59], v[152:155], v[184:187], v[56:59]
	v_mfma_f32_16x16x32_bf16 v[44:47], v[128:131], v[192:195], v[44:47]
	v_mfma_f32_16x16x32_bf16 v[40:43], v[152:155], v[192:195], v[40:43]
	v_mfma_f32_16x16x32_bf16 v[28:31], v[128:131], v[200:203], v[28:31]
	v_mfma_f32_16x16x32_bf16 v[24:27], v[152:155], v[200:203], v[24:27]
	v_mfma_f32_16x16x32_bf16 v[12:15], v[128:131], v[210:213], v[12:15]
	v_mfma_f32_16x16x32_bf16 v[8:11], v[152:155], v[210:213], v[8:11]
	v_mfma_f32_16x16x32_bf16 v[60:63], v[132:135], v[188:191], v[60:63]
	v_mfma_f32_16x16x32_bf16 v[56:59], v[156:159], v[188:191], v[56:59]
	v_mfma_f32_16x16x32_bf16 v[44:47], v[132:135], v[196:199], v[44:47]
	v_mfma_f32_16x16x32_bf16 v[40:43], v[156:159], v[196:199], v[40:43]
	v_mfma_f32_16x16x32_bf16 v[28:31], v[132:135], v[206:209], v[28:31]
	v_mfma_f32_16x16x32_bf16 v[24:27], v[156:159], v[206:209], v[24:27]
	v_mfma_f32_16x16x32_bf16 v[12:15], v[132:135], v[214:217], v[12:15]
	v_mfma_f32_16x16x32_bf16 v[8:11], v[156:159], v[214:217], v[8:11]
	v_mfma_f32_16x16x32_bf16 v[52:55], v[160:163], v[184:187], v[52:55]
	v_mfma_f32_16x16x32_bf16 v[48:51], v[176:179], v[184:187], v[48:51]
	v_mfma_f32_16x16x32_bf16 v[36:39], v[160:163], v[192:195], v[36:39]
	v_mfma_f32_16x16x32_bf16 v[32:35], v[176:179], v[192:195], v[32:35]
	v_mfma_f32_16x16x32_bf16 v[20:23], v[160:163], v[200:203], v[20:23]
	v_mfma_f32_16x16x32_bf16 v[16:19], v[176:179], v[200:203], v[16:19]
	v_mfma_f32_16x16x32_bf16 v[4:7], v[160:163], v[210:213], v[4:7]
	v_mfma_f32_16x16x32_bf16 v[0:3], v[176:179], v[210:213], v[0:3]
	v_mfma_f32_16x16x32_bf16 v[52:55], v[172:175], v[188:191], v[52:55]
	v_mfma_f32_16x16x32_bf16 v[48:51], v[180:183], v[188:191], v[48:51]
	v_mfma_f32_16x16x32_bf16 v[36:39], v[172:175], v[196:199], v[36:39]
	v_mfma_f32_16x16x32_bf16 v[32:35], v[180:183], v[196:199], v[32:35]
	v_mfma_f32_16x16x32_bf16 v[20:23], v[172:175], v[206:209], v[20:23]
	v_mfma_f32_16x16x32_bf16 v[16:19], v[180:183], v[206:209], v[16:19]
	v_mfma_f32_16x16x32_bf16 v[4:7], v[172:175], v[214:217], v[4:7]
	v_mfma_f32_16x16x32_bf16 v[0:3], v[180:183], v[214:217], v[0:3]
	s_barrier
	s_add_i32 s55, 0, 0x18000
	s_add_i32 s56, 0, 0x1c000
	v_add_u32_e32 v156, s55, v165
	v_add_u32_e32 v171, s56, v165
	ds_read_b128 v[128:131], v156
	ds_read_b128 v[132:135], v156 offset:1024
	ds_read_b128 v[152:155], v156 offset:2048
	ds_read_b128 v[156:159], v156 offset:3072
	ds_read_b128 v[160:163], v171
	ds_read_b128 v[172:175], v171 offset:1024
	ds_read_b128 v[176:179], v171 offset:2048
	ds_read_b128 v[180:183], v171 offset:3072
	s_add_u32 s22, s28, 0x160000
	s_addc_u32 s23, s29, 0
	s_mov_b32 m0, s37
	v_lshl_add_u64 v[226:227], s[22:23], 0, v[136:137]
	ds_read_b128 v[184:187], v169 offset:32768
	ds_read_b128 v[188:191], v169 offset:33792
	ds_read_b128 v[192:195], v169 offset:34816
	ds_read_b128 v[196:199], v169 offset:35840
	ds_read_b128 v[200:203], v169 offset:36864
	ds_read_b128 v[206:209], v169 offset:37888
	ds_read_b128 v[210:213], v169 offset:38912
	ds_read_b128 v[214:217], v169 offset:39936
	global_load_lds_dwordx4 v[226:227], off
	v_lshl_add_u64 v[226:227], s[22:23], 0, v[140:141]
	s_mov_b32 m0, s38
	s_nop 0
	global_load_lds_dwordx4 v[226:227], off
	s_waitcnt vmcnt(8)
	s_waitcnt lgkmcnt(0)
	s_barrier
	s_waitcnt lgkmcnt(0)
	v_mfma_f32_16x16x32_bf16 v[124:127], v[128:131], v[184:187], v[124:127]
	v_mfma_f32_16x16x32_bf16 v[120:123], v[152:155], v[184:187], v[120:123]
	v_mfma_f32_16x16x32_bf16 v[108:111], v[128:131], v[192:195], v[108:111]
	v_mfma_f32_16x16x32_bf16 v[104:107], v[152:155], v[192:195], v[104:107]
	v_mfma_f32_16x16x32_bf16 v[92:95], v[128:131], v[200:203], v[92:95]
	v_mfma_f32_16x16x32_bf16 v[88:91], v[152:155], v[200:203], v[88:91]
	v_mfma_f32_16x16x32_bf16 v[76:79], v[128:131], v[210:213], v[76:79]
	v_mfma_f32_16x16x32_bf16 v[72:75], v[152:155], v[210:213], v[72:75]
	v_mfma_f32_16x16x32_bf16 v[124:127], v[132:135], v[188:191], v[124:127]
	v_mfma_f32_16x16x32_bf16 v[120:123], v[156:159], v[188:191], v[120:123]
	v_mfma_f32_16x16x32_bf16 v[108:111], v[132:135], v[196:199], v[108:111]
	v_mfma_f32_16x16x32_bf16 v[104:107], v[156:159], v[196:199], v[104:107]
	v_mfma_f32_16x16x32_bf16 v[92:95], v[132:135], v[206:209], v[92:95]
	v_mfma_f32_16x16x32_bf16 v[88:91], v[156:159], v[206:209], v[88:91]
	v_mfma_f32_16x16x32_bf16 v[76:79], v[132:135], v[214:217], v[76:79]
	v_mfma_f32_16x16x32_bf16 v[72:75], v[156:159], v[214:217], v[72:75]
	v_mfma_f32_16x16x32_bf16 v[116:119], v[160:163], v[184:187], v[116:119]
	v_mfma_f32_16x16x32_bf16 v[112:115], v[176:179], v[184:187], v[112:115]
	v_mfma_f32_16x16x32_bf16 v[100:103], v[160:163], v[192:195], v[100:103]
	v_mfma_f32_16x16x32_bf16 v[96:99], v[176:179], v[192:195], v[96:99]
	v_mfma_f32_16x16x32_bf16 v[84:87], v[160:163], v[200:203], v[84:87]
	v_mfma_f32_16x16x32_bf16 v[80:83], v[176:179], v[200:203], v[80:83]
	v_mfma_f32_16x16x32_bf16 v[68:71], v[160:163], v[210:213], v[68:71]
	v_mfma_f32_16x16x32_bf16 v[64:67], v[176:179], v[210:213], v[64:67]
	v_mfma_f32_16x16x32_bf16 v[116:119], v[172:175], v[188:191], v[116:119]
	v_mfma_f32_16x16x32_bf16 v[112:115], v[180:183], v[188:191], v[112:115]
	v_mfma_f32_16x16x32_bf16 v[100:103], v[172:175], v[196:199], v[100:103]
	v_mfma_f32_16x16x32_bf16 v[96:99], v[180:183], v[196:199], v[96:99]
	v_mfma_f32_16x16x32_bf16 v[84:87], v[172:175], v[206:209], v[84:87]
	v_mfma_f32_16x16x32_bf16 v[80:83], v[180:183], v[206:209], v[80:83]
	v_mfma_f32_16x16x32_bf16 v[68:71], v[172:175], v[214:217], v[68:71]
	v_mfma_f32_16x16x32_bf16 v[64:67], v[180:183], v[214:217], v[64:67]
	s_barrier
; #define PG8_STAGE(bufoff, gbase, voff) do { _Pragma("unroll") for (int _i = 0; _i < 2; ++_i) \
;         __builtin_amdgcn_global_load_lds((const unsigned*)((const char*)(gbase) + (voff)[_i]), (PG8_LAS unsigned*)(lds + (bufoff) + ldsw + _i * 8192), 16, 0, 0); } while (0)
; #define PG8_LDA(dst, b, h) do { _Pragma("unroll") for (int m = 0; m < 4; ++m) _Pragma("unroll") for (int k = 0; k < 2; ++k) dst[m][k] = *(const PG8_LAS bf16x8*)(lds + PG8_SA(b, h) + aoff + m * 2048 + k * 1024); } while (0)
; #define PG8_MMA(ai, bj, At, Bt) do { __builtin_amdgcn_s_setprio(1); _Pragma("unroll") for (int m = 0; m < 4; ++m) _Pragma("unroll") for (int n = 0; n < 2; ++n) _Pragma("unroll") for (int k = 0; k < 2; ++k) \
;         acc[ai][bj][m][n] = __builtin_amdgcn_mfma_f32_16x16x32_bf16(Bt[n][k], At[m][k], acc[ai][bj][m][n], 0, 0, 0); __builtin_amdgcn_s_setprio(0); } while (0)
; #define PG8_WAIT_V(n) asm volatile("s_waitcnt vmcnt(" #n ")" ::: "memory")
; #define PG8_WAIT_L(n) asm volatile("s_waitcnt lgkmcnt(" #n ")" ::: "memory")
; #define PG8_BAR __builtin_amdgcn_s_barrier()
; #define PG8_SCHED __builtin_amdgcn_sched_barrier(0)
; template <class Epi, class Sched, bool ALIGN_EPI = false, bool SP2 = false>
; __device__ __forceinline__ void gemm_phase(PG8_LAS unsigned char* lds, const Gemm g, const Sched& S, const Epi& E) {
;     ...
;             PG8_LDA(At, 1, 1); PG8_STAGE(PG8_SB(1, 0), b3, voffB); PG8_STAGE(PG8_SB(1, 1), b3 + hstep, voffB); PG8_STAGE(PG8_SA(1, 0), a3, voffA);
;             PG8_WAIT_V(8); PG8_WAIT_L(0); PG8_BAR; PG8_MMA(1, 0, At, B0); PG8_MMA(1, 1, At, B1); PG8_BAR; PG8_SCHED;
	s_add_i32 s22, s55, s34
	v_lshl_add_u64 v[218:219], v[218:219], 0, s[16:17]
	s_mov_b32 m0, s22
	ds_read_b128 v[184:187], v169 offset:49152
	ds_read_b128 v[188:191], v169 offset:50176
	ds_read_b128 v[192:195], v169 offset:51200
	ds_read_b128 v[196:199], v169 offset:52224
	ds_read_b128 v[200:203], v169 offset:53248
	ds_read_b128 v[206:209], v169 offset:54272
	ds_read_b128 v[210:213], v169 offset:55296
	ds_read_b128 v[214:217], v169 offset:56320
	global_load_lds_dwordx4 v[218:219], off
	s_add_i32 m0, s22, 0x2000
	s_add_u32 s22, s26, 0x160080
	v_lshl_add_u64 v[218:219], v[220:221], 0, s[16:17]
	s_addc_u32 s23, s27, 0
	s_add_i32 s26, s56, s34
	global_load_lds_dwordx4 v[218:219], off
	v_lshl_add_u64 v[218:219], s[22:23], 0, v[138:139]
	s_mov_b32 m0, s26
	s_nop 0
	global_load_lds_dwordx4 v[218:219], off
	v_lshl_add_u64 v[218:219], s[22:23], 0, v[142:143]
	s_add_i32 m0, s26, 0x2000
	s_nop 0
	global_load_lds_dwordx4 v[218:219], off
	v_lshl_add_u64 v[218:219], v[222:223], 0, s[16:17]
	s_mov_b32 m0, s43
	s_nop 0
	global_load_lds_dwordx4 v[218:219], off
	v_lshl_add_u64 v[218:219], v[224:225], 0, s[16:17]
	s_mov_b32 m0, s44
	s_nop 0
	global_load_lds_dwordx4 v[218:219], off
	s_waitcnt vmcnt(8)
	s_waitcnt lgkmcnt(0)
	s_barrier
	s_waitcnt lgkmcnt(0)
	v_mfma_f32_16x16x32_bf16 v[60:63], v[128:131], v[184:187], v[60:63]
	v_mfma_f32_16x16x32_bf16 v[56:59], v[152:155], v[184:187], v[56:59]
	v_mfma_f32_16x16x32_bf16 v[44:47], v[128:131], v[192:195], v[44:47]
	v_mfma_f32_16x16x32_bf16 v[40:43], v[152:155], v[192:195], v[40:43]
	v_mfma_f32_16x16x32_bf16 v[28:31], v[128:131], v[200:203], v[28:31]
	v_mfma_f32_16x16x32_bf16 v[24:27], v[152:155], v[200:203], v[24:27]
	v_mfma_f32_16x16x32_bf16 v[12:15], v[128:131], v[210:213], v[12:15]
	v_mfma_f32_16x16x32_bf16 v[8:11], v[152:155], v[210:213], v[8:11]
	v_mfma_f32_16x16x32_bf16 v[60:63], v[132:135], v[188:191], v[60:63]
	v_mfma_f32_16x16x32_bf16 v[56:59], v[156:159], v[188:191], v[56:59]
	v_mfma_f32_16x16x32_bf16 v[44:47], v[132:135], v[196:199], v[44:47]
	v_mfma_f32_16x16x32_bf16 v[40:43], v[156:159], v[196:199], v[40:43]
	v_mfma_f32_16x16x32_bf16 v[28:31], v[132:135], v[206:209], v[28:31]
	v_mfma_f32_16x16x32_bf16 v[24:27], v[156:159], v[206:209], v[24:27]
	v_mfma_f32_16x16x32_bf16 v[12:15], v[132:135], v[214:217], v[12:15]
	v_mfma_f32_16x16x32_bf16 v[8:11], v[156:159], v[214:217], v[8:11]
	v_mfma_f32_16x16x32_bf16 v[52:55], v[160:163], v[184:187], v[52:55]
	v_mfma_f32_16x16x32_bf16 v[48:51], v[176:179], v[184:187], v[48:51]
	v_mfma_f32_16x16x32_bf16 v[36:39], v[160:163], v[192:195], v[36:39]
	v_mfma_f32_16x16x32_bf16 v[32:35], v[176:179], v[192:195], v[32:35]
	v_mfma_f32_16x16x32_bf16 v[20:23], v[160:163], v[200:203], v[20:23]
	v_mfma_f32_16x16x32_bf16 v[16:19], v[176:179], v[200:203], v[16:19]
	v_mfma_f32_16x16x32_bf16 v[4:7], v[160:163], v[210:213], v[4:7]
	v_mfma_f32_16x16x32_bf16 v[0:3], v[176:179], v[210:213], v[0:3]
	v_mfma_f32_16x16x32_bf16 v[52:55], v[172:175], v[188:191], v[52:55]
	v_mfma_f32_16x16x32_bf16 v[48:51], v[180:183], v[188:191], v[48:51]
	v_mfma_f32_16x16x32_bf16 v[36:39], v[172:175], v[196:199], v[36:39]
	v_mfma_f32_16x16x32_bf16 v[32:35], v[180:183], v[196:199], v[32:35]
	v_mfma_f32_16x16x32_bf16 v[20:23], v[172:175], v[206:209], v[20:23]
	v_mfma_f32_16x16x32_bf16 v[16:19], v[180:183], v[206:209], v[16:19]
	v_mfma_f32_16x16x32_bf16 v[4:7], v[172:175], v[214:217], v[4:7]
	v_mfma_f32_16x16x32_bf16 v[0:3], v[180:183], v[214:217], v[0:3]
	s_barrier
	s_add_i32 s54, s54, 2
	s_add_u32 s52, s52, 0x100
	s_addc_u32 s53, s53, 0
	s_cmpk_gt_u32 s54, 0x55
	s_mov_b64 s[22:23], s[24:25]
	s_cbranch_scc0 .LBB0_1298
	s_and_b64 vcc, exec, s[18:19]
	s_cbranch_vccz .LBB0_1301
	s_barrier

; #define PG8_STAGE(bufoff, gbase, voff) do { _Pragma("unroll") for (int _i = 0; _i < 2; ++_i) \
;         __builtin_amdgcn_global_load_lds((const unsigned*)((const char*)(gbase) + (voff)[_i]), (PG8_LAS unsigned*)(lds + (bufoff) + ldsw + _i * 8192), 16, 0, 0); } while (0)
; #define PG8_LDA(dst, b, h) do { _Pragma("unroll") for (int m = 0; m < 4; ++m) _Pragma("unroll") for (int k = 0; k < 2; ++k) dst[m][k] = *(const PG8_LAS bf16x8*)(lds + PG8_SA(b, h) + aoff + m * 2048 + k * 1024); } while (0)
; #define PG8_LDB(dst, b, h) do { _Pragma("unroll") for (int n = 0; n < 2; ++n) _Pragma("unroll") for (int k = 0; k < 2; ++k) dst[n][k] = *(const PG8_LAS bf16x8*)(lds + PG8_SB(b, h) + boff + n * 2048 + k * 1024); } while (0)
; #define PG8_MMA(ai, bj, At, Bt) do { __builtin_amdgcn_s_setprio(1); _Pragma("unroll") for (int m = 0; m < 4; ++m) _Pragma("unroll") for (int n = 0; n < 2; ++n) _Pragma("unroll") for (int k = 0; k < 2; ++k) \
;         acc[ai][bj][m][n] = __builtin_amdgcn_mfma_f32_16x16x32_bf16(Bt[n][k], At[m][k], acc[ai][bj][m][n], 0, 0, 0); __builtin_amdgcn_s_setprio(0); } while (0)
; #define PG8_WAIT_V(n) asm volatile("s_waitcnt vmcnt(" #n ")" ::: "memory")
; #define PG8_WAIT_L(n) asm volatile("s_waitcnt lgkmcnt(" #n ")" ::: "memory")
; #define PG8_BAR __builtin_amdgcn_s_barrier()
; #define PG8_SCHED __builtin_amdgcn_sched_barrier(0)
; template <class Epi, class Sched, bool ALIGN_EPI = false, bool SP2 = false>
; __device__ __forceinline__ void gemm_phase(PG8_LAS unsigned char* lds, const Gemm g, const Sched& S, const Epi& E) {
;     ...
;             PG8_LDB(B0, 0, 0); PG8_LDB(B1, 0, 1); PG8_SCHED; PG8_LDA(At, 0, 0); PG8_STAGE(PG8_SA(1, 1), a1 + hstepA, voffA);
;             PG8_WAIT_V(8); PG8_WAIT_L(0); PG8_BAR; PG8_MMA(0, 0, At, B0); PG8_MMA(0, 1, At, B1); PG8_BAR; PG8_SCHED;
;             PG8_LDA(At, 0, 1); PG8_STAGE(PG8_SB(0, 0), b2, voffB); PG8_STAGE(PG8_SB(0, 1), b2 + hstep, voffB); PG8_STAGE(PG8_SA(0, 0), a2, voffA);
.LBB0_1382:
	ds_read_b128 v[104:107], v170
	ds_read_b128 v[108:111], v170 offset:1024
	ds_read_b128 v[120:123], v170 offset:2048
	ds_read_b128 v[124:127], v170 offset:3072
	ds_read_b128 v[176:179], v171
	ds_read_b128 v[180:183], v171 offset:1024
	ds_read_b128 v[184:187], v171 offset:2048
	ds_read_b128 v[188:191], v171 offset:3072
	s_add_u32 s30, s12, 0xfff80080
	s_addc_u32 s31, s13, -1
	s_cmp_eq_u32 s55, 28
	s_cselect_b32 s35, s7, s31
	s_cselect_b32 s34, s23, s30
	s_cselect_b32 s31, s21, s54
	s_cselect_b32 s30, s52, s53
	v_lshl_add_u64 v[162:163], s[12:13], 0, v[154:155]
	s_add_i32 m0, s29, 0xc000
	ds_read_b128 v[192:195], v172
	ds_read_b128 v[196:199], v172 offset:1024
	ds_read_b128 v[200:203], v172 offset:2048
	ds_read_b128 v[206:209], v172 offset:3072
	ds_read_b128 v[210:213], v172 offset:4096
	ds_read_b128 v[214:217], v172 offset:5120
	ds_read_b128 v[218:221], v172 offset:6144
	ds_read_b128 v[222:225], v172 offset:7168
	global_load_lds_dwordx4 v[162:163], off
	v_lshl_add_u64 v[162:163], s[12:13], 0, v[156:157]
	s_add_i32 m0, s29, 0xe000
	s_nop 0
	global_load_lds_dwordx4 v[162:163], off
	s_waitcnt vmcnt(8)
	s_waitcnt lgkmcnt(0)
	s_barrier
	s_waitcnt lgkmcnt(0)
	v_mfma_f32_16x16x32_bf16 v[140:143], v[104:107], v[192:195], v[140:143]
	v_mfma_f32_16x16x32_bf16 v[136:139], v[120:123], v[192:195], v[136:139]
	v_mfma_f32_16x16x32_bf16 v[116:119], v[104:107], v[200:203], v[116:119]
	v_mfma_f32_16x16x32_bf16 v[112:115], v[120:123], v[200:203], v[112:115]
	v_mfma_f32_16x16x32_bf16 v[92:95], v[104:107], v[210:213], v[92:95]
	v_mfma_f32_16x16x32_bf16 v[88:91], v[120:123], v[210:213], v[88:91]
	v_mfma_f32_16x16x32_bf16 v[76:79], v[104:107], v[218:221], v[76:79]
	v_mfma_f32_16x16x32_bf16 v[72:75], v[120:123], v[218:221], v[72:75]
	v_mfma_f32_16x16x32_bf16 v[140:143], v[108:111], v[196:199], v[140:143]
	v_mfma_f32_16x16x32_bf16 v[136:139], v[124:127], v[196:199], v[136:139]
	v_mfma_f32_16x16x32_bf16 v[116:119], v[108:111], v[206:209], v[116:119]
	v_mfma_f32_16x16x32_bf16 v[112:115], v[124:127], v[206:209], v[112:115]
	v_mfma_f32_16x16x32_bf16 v[92:95], v[108:111], v[214:217], v[92:95]
	v_mfma_f32_16x16x32_bf16 v[88:91], v[124:127], v[214:217], v[88:91]
	v_mfma_f32_16x16x32_bf16 v[76:79], v[108:111], v[222:225], v[76:79]
	v_mfma_f32_16x16x32_bf16 v[72:75], v[124:127], v[222:225], v[72:75]
	v_mfma_f32_16x16x32_bf16 v[132:135], v[176:179], v[192:195], v[132:135]
	v_mfma_f32_16x16x32_bf16 v[128:131], v[184:187], v[192:195], v[128:131]
	v_mfma_f32_16x16x32_bf16 v[100:103], v[176:179], v[200:203], v[100:103]
	v_mfma_f32_16x16x32_bf16 v[96:99], v[184:187], v[200:203], v[96:99]
	v_mfma_f32_16x16x32_bf16 v[84:87], v[176:179], v[210:213], v[84:87]
	v_mfma_f32_16x16x32_bf16 v[80:83], v[184:187], v[210:213], v[80:83]
	v_mfma_f32_16x16x32_bf16 v[68:71], v[176:179], v[218:221], v[68:71]
	v_mfma_f32_16x16x32_bf16 v[64:67], v[184:187], v[218:221], v[64:67]
	v_mfma_f32_16x16x32_bf16 v[132:135], v[180:183], v[196:199], v[132:135]
	v_mfma_f32_16x16x32_bf16 v[128:131], v[188:191], v[196:199], v[128:131]
	v_mfma_f32_16x16x32_bf16 v[100:103], v[180:183], v[206:209], v[100:103]
	v_mfma_f32_16x16x32_bf16 v[96:99], v[188:191], v[206:209], v[96:99]
	v_mfma_f32_16x16x32_bf16 v[84:87], v[180:183], v[214:217], v[84:87]
	v_mfma_f32_16x16x32_bf16 v[80:83], v[188:191], v[214:217], v[80:83]
	v_mfma_f32_16x16x32_bf16 v[68:71], v[180:183], v[222:225], v[68:71]
	v_mfma_f32_16x16x32_bf16 v[64:67], v[188:191], v[222:225], v[64:67]
	s_barrier
	s_add_i32 s56, s50, s38
	v_lshl_add_u64 v[162:163], s[30:31], 0, v[148:149]
	s_mov_b32 m0, s56
	ds_read_b128 v[192:195], v172 offset:16384
	ds_read_b128 v[196:199], v172 offset:17408
	ds_read_b128 v[200:203], v172 offset:18432
	ds_read_b128 v[206:209], v172 offset:19456
	ds_read_b128 v[210:213], v172 offset:20480
	ds_read_b128 v[214:217], v172 offset:21504
	ds_read_b128 v[218:221], v172 offset:22528
	ds_read_b128 v[222:225], v172 offset:23552
	global_load_lds_dwordx4 v[162:163], off
	s_add_i32 m0, s56, 0x2000
	s_add_u32 s56, s30, 0x80000
	v_lshl_add_u64 v[166:167], s[30:31], 0, v[144:145]
	s_addc_u32 s57, s31, 0
	s_add_i32 s58, s51, s38
	global_load_lds_dwordx4 v[166:167], off
	v_lshl_add_u64 v[226:227], s[56:57], 0, v[148:149]
	s_mov_b32 m0, s58
	v_lshl_add_u64 v[228:229], s[34:35], 0, v[146:147]
	global_load_lds_dwordx4 v[226:227], off
	v_lshl_add_u64 v[226:227], s[56:57], 0, v[144:145]
	s_add_i32 m0, s58, 0x2000
	s_nop 0
	global_load_lds_dwordx4 v[226:227], off
	v_lshl_add_u64 v[226:227], s[34:35], 0, v[150:151]
	s_mov_b32 m0, s29
	s_nop 0
	global_load_lds_dwordx4 v[226:227], off
	s_mov_b32 m0, s40
	s_nop 0
	global_load_lds_dwordx4 v[228:229], off
	s_waitcnt vmcnt(8)
	s_waitcnt lgkmcnt(0)
	s_barrier
; #define PG8_STAGE(bufoff, gbase, voff) do { _Pragma("unroll") for (int _i = 0; _i < 2; ++_i) \
;         __builtin_amdgcn_global_load_lds((const unsigned*)((const char*)(gbase) + (voff)[_i]), (PG8_LAS unsigned*)(lds + (bufoff) + ldsw + _i * 8192), 16, 0, 0); } while (0)
; #define PG8_LDA(dst, b, h) do { _Pragma("unroll") for (int m = 0; m < 4; ++m) _Pragma("unroll") for (int k = 0; k < 2; ++k) dst[m][k] = *(const PG8_LAS bf16x8*)(lds + PG8_SA(b, h) + aoff + m * 2048 + k * 1024); } while (0)
; #define PG8_LDB(dst, b, h) do { _Pragma("unroll") for (int n = 0; n < 2; ++n) _Pragma("unroll") for (int k = 0; k < 2; ++k) dst[n][k] = *(const PG8_LAS bf16x8*)(lds + PG8_SB(b, h) + boff + n * 2048 + k * 1024); } while (0)
; #define PG8_MMA(ai, bj, At, Bt) do { __builtin_amdgcn_s_setprio(1); _Pragma("unroll") for (int m = 0; m < 4; ++m) _Pragma("unroll") for (int n = 0; n < 2; ++n) _Pragma("unroll") for (int k = 0; k < 2; ++k) \
;         acc[ai][bj][m][n] = __builtin_amdgcn_mfma_f32_16x16x32_bf16(Bt[n][k], At[m][k], acc[ai][bj][m][n], 0, 0, 0); __builtin_amdgcn_s_setprio(0); } while (0)
; #define PG8_WAIT_V(n) asm volatile("s_waitcnt vmcnt(" #n ")" ::: "memory")
; #define PG8_WAIT_L(n) asm volatile("s_waitcnt lgkmcnt(" #n ")" ::: "memory")
; #define PG8_BAR __builtin_amdgcn_s_barrier()
; #define PG8_SCHED __builtin_amdgcn_sched_barrier(0)
; template <class Epi, class Sched, bool ALIGN_EPI = false, bool SP2 = false>
; __device__ __forceinline__ void gemm_phase(PG8_LAS unsigned char* lds, const Gemm g, const Sched& S, const Epi& E) {
;     ...
;             PG8_WAIT_V(8); PG8_WAIT_L(0); PG8_BAR; PG8_MMA(1, 0, At, B0); PG8_MMA(1, 1, At, B1); PG8_BAR; PG8_SCHED;
;             PG8_LDB(B0, 1, 0); PG8_LDB(B1, 1, 1); PG8_SCHED; PG8_LDA(At, 1, 0); PG8_STAGE(PG8_SA(0, 1), a2 + hstepA, voffA);
;             PG8_WAIT_V(8); PG8_WAIT_L(0); PG8_BAR; PG8_MMA(0, 0, At, B0); PG8_MMA(0, 1, At, B1); PG8_BAR; PG8_SCHED;
	s_waitcnt lgkmcnt(0)
	v_mfma_f32_16x16x32_bf16 v[60:63], v[104:107], v[192:195], v[60:63]
	v_mfma_f32_16x16x32_bf16 v[56:59], v[120:123], v[192:195], v[56:59]
	v_mfma_f32_16x16x32_bf16 v[44:47], v[104:107], v[200:203], v[44:47]
	v_mfma_f32_16x16x32_bf16 v[40:43], v[120:123], v[200:203], v[40:43]
	v_mfma_f32_16x16x32_bf16 v[28:31], v[104:107], v[210:213], v[28:31]
	v_mfma_f32_16x16x32_bf16 v[24:27], v[120:123], v[210:213], v[24:27]
	v_mfma_f32_16x16x32_bf16 v[12:15], v[104:107], v[218:221], v[12:15]
	v_mfma_f32_16x16x32_bf16 v[8:11], v[120:123], v[218:221], v[8:11]
	v_mfma_f32_16x16x32_bf16 v[60:63], v[108:111], v[196:199], v[60:63]
	v_mfma_f32_16x16x32_bf16 v[56:59], v[124:127], v[196:199], v[56:59]
	v_mfma_f32_16x16x32_bf16 v[44:47], v[108:111], v[206:209], v[44:47]
	v_mfma_f32_16x16x32_bf16 v[40:43], v[124:127], v[206:209], v[40:43]
	v_mfma_f32_16x16x32_bf16 v[28:31], v[108:111], v[214:217], v[28:31]
	v_mfma_f32_16x16x32_bf16 v[24:27], v[124:127], v[214:217], v[24:27]
	v_mfma_f32_16x16x32_bf16 v[12:15], v[108:111], v[222:225], v[12:15]
	v_mfma_f32_16x16x32_bf16 v[8:11], v[124:127], v[222:225], v[8:11]
	v_mfma_f32_16x16x32_bf16 v[52:55], v[176:179], v[192:195], v[52:55]
	v_mfma_f32_16x16x32_bf16 v[48:51], v[184:187], v[192:195], v[48:51]
	v_mfma_f32_16x16x32_bf16 v[36:39], v[176:179], v[200:203], v[36:39]
	v_mfma_f32_16x16x32_bf16 v[32:35], v[184:187], v[200:203], v[32:35]
	v_mfma_f32_16x16x32_bf16 v[20:23], v[176:179], v[210:213], v[20:23]
	v_mfma_f32_16x16x32_bf16 v[16:19], v[184:187], v[210:213], v[16:19]
	v_mfma_f32_16x16x32_bf16 v[4:7], v[176:179], v[218:221], v[4:7]
	v_mfma_f32_16x16x32_bf16 v[0:3], v[184:187], v[218:221], v[0:3]
	v_mfma_f32_16x16x32_bf16 v[52:55], v[180:183], v[196:199], v[52:55]
	v_mfma_f32_16x16x32_bf16 v[48:51], v[188:191], v[196:199], v[48:51]
	v_mfma_f32_16x16x32_bf16 v[36:39], v[180:183], v[206:209], v[36:39]
	v_mfma_f32_16x16x32_bf16 v[32:35], v[188:191], v[206:209], v[32:35]
	v_mfma_f32_16x16x32_bf16 v[20:23], v[180:183], v[214:217], v[20:23]
	v_mfma_f32_16x16x32_bf16 v[16:19], v[188:191], v[214:217], v[16:19]
	v_mfma_f32_16x16x32_bf16 v[4:7], v[180:183], v[222:225], v[4:7]
	v_mfma_f32_16x16x32_bf16 v[0:3], v[188:191], v[222:225], v[0:3]
	s_barrier
	s_add_i32 s56, 0, 0x18000
	s_add_i32 s57, 0, 0x1c000
	v_add_u32_e32 v124, s56, v168
	v_add_u32_e32 v164, s57, v168
	ds_read_b128 v[104:107], v124
	ds_read_b128 v[108:111], v124 offset:1024
	ds_read_b128 v[120:123], v124 offset:2048
	ds_read_b128 v[124:127], v124 offset:3072
	ds_read_b128 v[176:179], v164
	ds_read_b128 v[180:183], v164 offset:1024
	ds_read_b128 v[184:187], v164 offset:2048
	ds_read_b128 v[188:191], v164 offset:3072
	s_add_u32 s34, s34, 0x80000
	s_addc_u32 s35, s35, 0
	s_mov_b32 m0, s41
	v_lshl_add_u64 v[230:231], s[34:35], 0, v[150:151]
	ds_read_b128 v[192:195], v172 offset:32768
	ds_read_b128 v[196:199], v172 offset:33792
	ds_read_b128 v[200:203], v172 offset:34816
	ds_read_b128 v[206:209], v172 offset:35840
	ds_read_b128 v[210:213], v172 offset:36864
	ds_read_b128 v[214:217], v172 offset:37888
	ds_read_b128 v[218:221], v172 offset:38912
	ds_read_b128 v[222:225], v172 offset:39936
	global_load_lds_dwordx4 v[230:231], off
	v_lshl_add_u64 v[230:231], s[34:35], 0, v[146:147]
	s_mov_b32 m0, s42
	s_nop 0
	global_load_lds_dwordx4 v[230:231], off
	s_waitcnt vmcnt(8)
	s_waitcnt lgkmcnt(0)
	s_barrier
	s_waitcnt lgkmcnt(0)
	v_mfma_f32_16x16x32_bf16 v[140:143], v[104:107], v[192:195], v[140:143]
	v_mfma_f32_16x16x32_bf16 v[136:139], v[120:123], v[192:195], v[136:139]
	v_mfma_f32_16x16x32_bf16 v[116:119], v[104:107], v[200:203], v[116:119]
	v_mfma_f32_16x16x32_bf16 v[112:115], v[120:123], v[200:203], v[112:115]
	v_mfma_f32_16x16x32_bf16 v[92:95], v[104:107], v[210:213], v[92:95]
	v_mfma_f32_16x16x32_bf16 v[88:91], v[120:123], v[210:213], v[88:91]
	v_mfma_f32_16x16x32_bf16 v[76:79], v[104:107], v[218:221], v[76:79]
	v_mfma_f32_16x16x32_bf16 v[72:75], v[120:123], v[218:221], v[72:75]
	v_mfma_f32_16x16x32_bf16 v[140:143], v[108:111], v[196:199], v[140:143]
	v_mfma_f32_16x16x32_bf16 v[136:139], v[124:127], v[196:199], v[136:139]
	v_mfma_f32_16x16x32_bf16 v[116:119], v[108:111], v[206:209], v[116:119]
	v_mfma_f32_16x16x32_bf16 v[112:115], v[124:127], v[206:209], v[112:115]
	v_mfma_f32_16x16x32_bf16 v[92:95], v[108:111], v[214:217], v[92:95]
	v_mfma_f32_16x16x32_bf16 v[88:91], v[124:127], v[214:217], v[88:91]
	v_mfma_f32_16x16x32_bf16 v[76:79], v[108:111], v[222:225], v[76:79]
	v_mfma_f32_16x16x32_bf16 v[72:75], v[124:127], v[222:225], v[72:75]
	v_mfma_f32_16x16x32_bf16 v[132:135], v[176:179], v[192:195], v[132:135]
	v_mfma_f32_16x16x32_bf16 v[128:131], v[184:187], v[192:195], v[128:131]
	v_mfma_f32_16x16x32_bf16 v[100:103], v[176:179], v[200:203], v[100:103]
	v_mfma_f32_16x16x32_bf16 v[96:99], v[184:187], v[200:203], v[96:99]
	v_mfma_f32_16x16x32_bf16 v[84:87], v[176:179], v[210:213], v[84:87]
	v_mfma_f32_16x16x32_bf16 v[80:83], v[184:187], v[210:213], v[80:83]
	v_mfma_f32_16x16x32_bf16 v[68:71], v[176:179], v[218:221], v[68:71]
	v_mfma_f32_16x16x32_bf16 v[64:67], v[184:187], v[218:221], v[64:67]
	v_mfma_f32_16x16x32_bf16 v[132:135], v[180:183], v[196:199], v[132:135]
	v_mfma_f32_16x16x32_bf16 v[128:131], v[188:191], v[196:199], v[128:131]
	v_mfma_f32_16x16x32_bf16 v[100:103], v[180:183], v[206:209], v[100:103]
	v_mfma_f32_16x16x32_bf16 v[96:99], v[188:191], v[206:209], v[96:99]
	v_mfma_f32_16x16x32_bf16 v[84:87], v[180:183], v[214:217], v[84:87]
	v_mfma_f32_16x16x32_bf16 v[80:83], v[188:191], v[214:217], v[80:83]
	v_mfma_f32_16x16x32_bf16 v[68:71], v[180:183], v[222:225], v[68:71]
	v_mfma_f32_16x16x32_bf16 v[64:67], v[188:191], v[222:225], v[64:67]
	s_barrier
; #define PG8_STAGE(bufoff, gbase, voff) do { _Pragma("unroll") for (int _i = 0; _i < 2; ++_i) \
;         __builtin_amdgcn_global_load_lds((const unsigned*)((const char*)(gbase) + (voff)[_i]), (PG8_LAS unsigned*)(lds + (bufoff) + ldsw + _i * 8192), 16, 0, 0); } while (0)
; #define PG8_LDA(dst, b, h) do { _Pragma("unroll") for (int m = 0; m < 4; ++m) _Pragma("unroll") for (int k = 0; k < 2; ++k) dst[m][k] = *(const PG8_LAS bf16x8*)(lds + PG8_SA(b, h) + aoff + m * 2048 + k * 1024); } while (0)
; #define PG8_MMA(ai, bj, At, Bt) do { __builtin_amdgcn_s_setprio(1); _Pragma("unroll") for (int m = 0; m < 4; ++m) _Pragma("unroll") for (int n = 0; n < 2; ++n) _Pragma("unroll") for (int k = 0; k < 2; ++k) \
;         acc[ai][bj][m][n] = __builtin_amdgcn_mfma_f32_16x16x32_bf16(Bt[n][k], At[m][k], acc[ai][bj][m][n], 0, 0, 0); __builtin_amdgcn_s_setprio(0); } while (0)
; #define PG8_WAIT_V(n) asm volatile("s_waitcnt vmcnt(" #n ")" ::: "memory")
; #define PG8_WAIT_L(n) asm volatile("s_waitcnt lgkmcnt(" #n ")" ::: "memory")
; #define PG8_BAR __builtin_amdgcn_s_barrier()
; #define PG8_SCHED __builtin_amdgcn_sched_barrier(0)
; template <class Epi, class Sched, bool ALIGN_EPI = false, bool SP2 = false>
; __device__ __forceinline__ void gemm_phase(PG8_LAS unsigned char* lds, const Gemm g, const Sched& S, const Epi& E) {
;     ...
;             PG8_LDA(At, 1, 1); PG8_STAGE(PG8_SB(1, 0), b3, voffB); PG8_STAGE(PG8_SB(1, 1), b3 + hstep, voffB); PG8_STAGE(PG8_SA(1, 0), a3, voffA);
;             PG8_WAIT_V(8); PG8_WAIT_L(0); PG8_BAR; PG8_MMA(1, 0, At, B0); PG8_MMA(1, 1, At, B1); PG8_BAR; PG8_SCHED;
	s_add_i32 s34, s56, s38
	v_lshl_add_u64 v[162:163], v[162:163], 0, s[14:15]
	s_mov_b32 m0, s34
	ds_read_b128 v[192:195], v172 offset:49152
	ds_read_b128 v[196:199], v172 offset:50176
	ds_read_b128 v[200:203], v172 offset:51200
	ds_read_b128 v[206:209], v172 offset:52224
	ds_read_b128 v[210:213], v172 offset:53248
	ds_read_b128 v[214:217], v172 offset:54272
	ds_read_b128 v[218:221], v172 offset:55296
	ds_read_b128 v[222:225], v172 offset:56320
	global_load_lds_dwordx4 v[162:163], off
	s_add_i32 m0, s34, 0x2000
	s_add_u32 s30, s30, 0x80080
	v_lshl_add_u64 v[162:163], v[166:167], 0, s[14:15]
	s_addc_u32 s31, s31, 0
	s_add_i32 s34, s57, s38
	global_load_lds_dwordx4 v[162:163], off
	v_lshl_add_u64 v[162:163], s[30:31], 0, v[148:149]
	s_mov_b32 m0, s34
	s_nop 0
	global_load_lds_dwordx4 v[162:163], off
	v_lshl_add_u64 v[162:163], s[30:31], 0, v[144:145]
	s_add_i32 m0, s34, 0x2000
	s_nop 0
	global_load_lds_dwordx4 v[162:163], off
	v_lshl_add_u64 v[162:163], v[226:227], 0, s[14:15]
	s_mov_b32 m0, s46
	s_nop 0
	global_load_lds_dwordx4 v[162:163], off
	v_lshl_add_u64 v[162:163], v[228:229], 0, s[14:15]
	s_mov_b32 m0, s47
	s_nop 0
	global_load_lds_dwordx4 v[162:163], off
	s_waitcnt vmcnt(8)
	s_waitcnt lgkmcnt(0)
	s_barrier
	s_waitcnt lgkmcnt(0)
	v_mfma_f32_16x16x32_bf16 v[60:63], v[104:107], v[192:195], v[60:63]
	v_mfma_f32_16x16x32_bf16 v[56:59], v[120:123], v[192:195], v[56:59]
	v_mfma_f32_16x16x32_bf16 v[44:47], v[104:107], v[200:203], v[44:47]
	v_mfma_f32_16x16x32_bf16 v[40:43], v[120:123], v[200:203], v[40:43]
	v_mfma_f32_16x16x32_bf16 v[28:31], v[104:107], v[210:213], v[28:31]
	v_mfma_f32_16x16x32_bf16 v[24:27], v[120:123], v[210:213], v[24:27]
	v_mfma_f32_16x16x32_bf16 v[12:15], v[104:107], v[218:221], v[12:15]
	v_mfma_f32_16x16x32_bf16 v[8:11], v[120:123], v[218:221], v[8:11]
	v_mfma_f32_16x16x32_bf16 v[60:63], v[108:111], v[196:199], v[60:63]
	v_mfma_f32_16x16x32_bf16 v[56:59], v[124:127], v[196:199], v[56:59]
	v_mfma_f32_16x16x32_bf16 v[44:47], v[108:111], v[206:209], v[44:47]
	v_mfma_f32_16x16x32_bf16 v[40:43], v[124:127], v[206:209], v[40:43]
	v_mfma_f32_16x16x32_bf16 v[28:31], v[108:111], v[214:217], v[28:31]
	v_mfma_f32_16x16x32_bf16 v[24:27], v[124:127], v[214:217], v[24:27]
	v_mfma_f32_16x16x32_bf16 v[12:15], v[108:111], v[222:225], v[12:15]
	v_mfma_f32_16x16x32_bf16 v[8:11], v[124:127], v[222:225], v[8:11]
	v_mfma_f32_16x16x32_bf16 v[52:55], v[176:179], v[192:195], v[52:55]
	v_mfma_f32_16x16x32_bf16 v[48:51], v[184:187], v[192:195], v[48:51]
	v_mfma_f32_16x16x32_bf16 v[36:39], v[176:179], v[200:203], v[36:39]
	v_mfma_f32_16x16x32_bf16 v[32:35], v[184:187], v[200:203], v[32:35]
	v_mfma_f32_16x16x32_bf16 v[20:23], v[176:179], v[210:213], v[20:23]
	v_mfma_f32_16x16x32_bf16 v[16:19], v[184:187], v[210:213], v[16:19]
	v_mfma_f32_16x16x32_bf16 v[4:7], v[176:179], v[218:221], v[4:7]
	v_mfma_f32_16x16x32_bf16 v[0:3], v[184:187], v[218:221], v[0:3]
	v_mfma_f32_16x16x32_bf16 v[52:55], v[180:183], v[196:199], v[52:55]
	v_mfma_f32_16x16x32_bf16 v[48:51], v[188:191], v[196:199], v[48:51]
	v_mfma_f32_16x16x32_bf16 v[36:39], v[180:183], v[206:209], v[36:39]
	v_mfma_f32_16x16x32_bf16 v[32:35], v[188:191], v[206:209], v[32:35]
	v_mfma_f32_16x16x32_bf16 v[20:23], v[180:183], v[214:217], v[20:23]
	v_mfma_f32_16x16x32_bf16 v[16:19], v[188:191], v[214:217], v[16:19]
	v_mfma_f32_16x16x32_bf16 v[4:7], v[180:183], v[222:225], v[4:7]
	v_mfma_f32_16x16x32_bf16 v[0:3], v[188:191], v[222:225], v[0:3]
	s_barrier
	s_add_i32 s55, s55, 2
	s_add_u32 s12, s12, 0x100
	s_addc_u32 s13, s13, 0
	s_add_u32 s53, s53, 0x100
	s_addc_u32 s54, s54, 0
	s_cmp_gt_u32 s55, 29
	s_cbranch_scc0 .LBB0_1382
	s_and_b64 vcc, exec, s[16:17]
	s_cbranch_vccz .LBB0_1385
	s_barrier

; #define PG8_STAGE(bufoff, gbase, voff) do { _Pragma("unroll") for (int _i = 0; _i < 2; ++_i) \
;         __builtin_amdgcn_global_load_lds((const unsigned*)((const char*)(gbase) + (voff)[_i]), (PG8_LAS unsigned*)(lds + (bufoff) + ldsw + _i * 8192), 16, 0, 0); } while (0)
; #define PG8_LDA(dst, b, h) do { _Pragma("unroll") for (int m = 0; m < 4; ++m) _Pragma("unroll") for (int k = 0; k < 2; ++k) dst[m][k] = *(const PG8_LAS bf16x8*)(lds + PG8_SA(b, h) + aoff + m * 2048 + k * 1024); } while (0)
; #define PG8_LDB(dst, b, h) do { _Pragma("unroll") for (int n = 0; n < 2; ++n) _Pragma("unroll") for (int k = 0; k < 2; ++k) dst[n][k] = *(const PG8_LAS bf16x8*)(lds + PG8_SB(b, h) + boff + n * 2048 + k * 1024); } while (0)
; #define PG8_MMA(ai, bj, At, Bt) do { __builtin_amdgcn_s_setprio(1); _Pragma("unroll") for (int m = 0; m < 4; ++m) _Pragma("unroll") for (int n = 0; n < 2; ++n) _Pragma("unroll") for (int k = 0; k < 2; ++k) \
;         acc[ai][bj][m][n] = __builtin_amdgcn_mfma_f32_16x16x32_bf16(Bt[n][k], At[m][k], acc[ai][bj][m][n], 0, 0, 0); __builtin_amdgcn_s_setprio(0); } while (0)
; #define PG8_WAIT_V(n) asm volatile("s_waitcnt vmcnt(" #n ")" ::: "memory")
; #define PG8_WAIT_L(n) asm volatile("s_waitcnt lgkmcnt(" #n ")" ::: "memory")
; #define PG8_BAR __builtin_amdgcn_s_barrier()
; #define PG8_SCHED __builtin_amdgcn_sched_barrier(0)
; template <class Epi, class Sched, bool ALIGN_EPI = false, bool SP2 = false>
; __device__ __forceinline__ void gemm_phase(PG8_LAS unsigned char* lds, const Gemm g, const Sched& S, const Epi& E) {
;     ...
;             PG8_LDB(B0, 0, 0); PG8_LDB(B1, 0, 1); PG8_SCHED; PG8_LDA(At, 0, 0); PG8_STAGE(PG8_SA(1, 1), a1 + hstepA, voffA);
;             PG8_WAIT_V(8); PG8_WAIT_L(0); PG8_BAR; PG8_MMA(0, 0, At, B0); PG8_MMA(0, 1, At, B1); PG8_BAR; PG8_SCHED;
;             PG8_LDA(At, 0, 1); PG8_STAGE(PG8_SB(0, 0), b2, voffB); PG8_STAGE(PG8_SB(0, 1), b2 + hstep, voffB); PG8_STAGE(PG8_SA(0, 0), a2, voffA);
.LBB0_1697:
	ds_read_b128 v[92:95], v183
	ds_read_b128 v[96:99], v183 offset:1024
	ds_read_b128 v[100:103], v183 offset:2048
	ds_read_b128 v[108:111], v183 offset:3072
	ds_read_b128 v[144:147], v184
	ds_read_b128 v[148:151], v184 offset:1024
	ds_read_b128 v[168:171], v184 offset:2048
	ds_read_b128 v[172:175], v184 offset:3072
	s_add_u32 s40, s14, 0xfff80080
	s_addc_u32 s41, s15, -1
	s_cmp_eq_u32 s62, 28
	s_cselect_b32 s43, s6, s41
	s_cselect_b32 s42, s7, s40
	s_cselect_b32 s41, s27, s61
	s_cselect_b32 s40, s29, s37
	v_lshl_add_u64 v[218:219], s[14:15], 0, v[160:161]
	s_add_i32 m0, s39, 0xc000
	ds_read_b128 v[176:179], v185
	ds_read_b128 v[188:191], v185 offset:1024
	ds_read_b128 v[192:195], v185 offset:2048
	ds_read_b128 v[196:199], v185 offset:3072
	ds_read_b128 v[200:203], v185 offset:4096
	ds_read_b128 v[206:209], v185 offset:5120
	ds_read_b128 v[210:213], v185 offset:6144
	ds_read_b128 v[214:217], v185 offset:7168
	global_load_lds_dwordx4 v[218:219], off
	v_lshl_add_u64 v[218:219], s[14:15], 0, v[162:163]
	s_add_i32 m0, s39, 0xe000
	s_nop 0
	global_load_lds_dwordx4 v[218:219], off
	s_waitcnt vmcnt(8)
	s_waitcnt lgkmcnt(0)
	s_barrier
	s_waitcnt lgkmcnt(0)
	v_mfma_f32_16x16x32_bf16 v[140:143], v[92:95], v[176:179], v[140:143]
	v_mfma_f32_16x16x32_bf16 v[136:139], v[100:103], v[176:179], v[136:139]
	v_mfma_f32_16x16x32_bf16 v[124:127], v[92:95], v[192:195], v[124:127]
	v_mfma_f32_16x16x32_bf16 v[120:123], v[100:103], v[192:195], v[120:123]
	v_mfma_f32_16x16x32_bf16 v[104:107], v[92:95], v[200:203], v[104:107]
	v_mfma_f32_16x16x32_bf16 v[88:91], v[100:103], v[200:203], v[88:91]
	v_mfma_f32_16x16x32_bf16 v[76:79], v[92:95], v[210:213], v[76:79]
	v_mfma_f32_16x16x32_bf16 v[72:75], v[100:103], v[210:213], v[72:75]
	v_mfma_f32_16x16x32_bf16 v[140:143], v[96:99], v[188:191], v[140:143]
	v_mfma_f32_16x16x32_bf16 v[136:139], v[108:111], v[188:191], v[136:139]
	v_mfma_f32_16x16x32_bf16 v[124:127], v[96:99], v[196:199], v[124:127]
	v_mfma_f32_16x16x32_bf16 v[120:123], v[108:111], v[196:199], v[120:123]
	v_mfma_f32_16x16x32_bf16 v[104:107], v[96:99], v[206:209], v[104:107]
	v_mfma_f32_16x16x32_bf16 v[88:91], v[108:111], v[206:209], v[88:91]
	v_mfma_f32_16x16x32_bf16 v[76:79], v[96:99], v[214:217], v[76:79]
	v_mfma_f32_16x16x32_bf16 v[72:75], v[108:111], v[214:217], v[72:75]
	v_mfma_f32_16x16x32_bf16 v[132:135], v[144:147], v[176:179], v[132:135]
	v_mfma_f32_16x16x32_bf16 v[128:131], v[168:171], v[176:179], v[128:131]
	v_mfma_f32_16x16x32_bf16 v[116:119], v[144:147], v[192:195], v[116:119]
	v_mfma_f32_16x16x32_bf16 v[112:115], v[168:171], v[192:195], v[112:115]
	v_mfma_f32_16x16x32_bf16 v[84:87], v[144:147], v[200:203], v[84:87]
	v_mfma_f32_16x16x32_bf16 v[80:83], v[168:171], v[200:203], v[80:83]
	v_mfma_f32_16x16x32_bf16 v[68:71], v[144:147], v[210:213], v[68:71]
	v_mfma_f32_16x16x32_bf16 v[64:67], v[168:171], v[210:213], v[64:67]
	v_mfma_f32_16x16x32_bf16 v[132:135], v[148:151], v[188:191], v[132:135]
	v_mfma_f32_16x16x32_bf16 v[128:131], v[172:175], v[188:191], v[128:131]
	v_mfma_f32_16x16x32_bf16 v[116:119], v[148:151], v[196:199], v[116:119]
	v_mfma_f32_16x16x32_bf16 v[112:115], v[172:175], v[196:199], v[112:115]
	v_mfma_f32_16x16x32_bf16 v[84:87], v[148:151], v[206:209], v[84:87]
	v_mfma_f32_16x16x32_bf16 v[80:83], v[172:175], v[206:209], v[80:83]
	v_mfma_f32_16x16x32_bf16 v[68:71], v[148:151], v[214:217], v[68:71]
	v_mfma_f32_16x16x32_bf16 v[64:67], v[172:175], v[214:217], v[64:67]
	s_barrier
	s_add_i32 s63, s59, s47
	v_lshl_add_u64 v[218:219], s[40:41], 0, v[154:155]
	s_mov_b32 m0, s63
	ds_read_b128 v[176:179], v185 offset:16384
	ds_read_b128 v[188:191], v185 offset:17408
	ds_read_b128 v[192:195], v185 offset:18432
	ds_read_b128 v[196:199], v185 offset:19456
	ds_read_b128 v[200:203], v185 offset:20480
	ds_read_b128 v[206:209], v185 offset:21504
	ds_read_b128 v[210:213], v185 offset:22528
	ds_read_b128 v[214:217], v185 offset:23552
	global_load_lds_dwordx4 v[218:219], off
	s_add_i32 m0, s63, 0x2000
	s_add_u32 s66, s40, 0x80000
	v_lshl_add_u64 v[220:221], s[40:41], 0, v[158:159]
	s_addc_u32 s67, s41, 0
	s_add_i32 s63, s60, s47
	global_load_lds_dwordx4 v[220:221], off
	v_lshl_add_u64 v[222:223], s[66:67], 0, v[154:155]
	s_mov_b32 m0, s63
	v_lshl_add_u64 v[224:225], s[42:43], 0, v[156:157]
	global_load_lds_dwordx4 v[222:223], off
	v_lshl_add_u64 v[222:223], s[66:67], 0, v[158:159]
	s_add_i32 m0, s63, 0x2000
	s_nop 0
	global_load_lds_dwordx4 v[222:223], off
	v_lshl_add_u64 v[222:223], s[42:43], 0, v[152:153]
	s_mov_b32 m0, s39
	s_nop 0
	global_load_lds_dwordx4 v[222:223], off
	s_mov_b32 m0, s2
	s_nop 0
	global_load_lds_dwordx4 v[224:225], off
	s_waitcnt vmcnt(8)
	s_waitcnt lgkmcnt(0)
	s_barrier
; #define PG8_STAGE(bufoff, gbase, voff) do { _Pragma("unroll") for (int _i = 0; _i < 2; ++_i) \
;         __builtin_amdgcn_global_load_lds((const unsigned*)((const char*)(gbase) + (voff)[_i]), (PG8_LAS unsigned*)(lds + (bufoff) + ldsw + _i * 8192), 16, 0, 0); } while (0)
; #define PG8_LDA(dst, b, h) do { _Pragma("unroll") for (int m = 0; m < 4; ++m) _Pragma("unroll") for (int k = 0; k < 2; ++k) dst[m][k] = *(const PG8_LAS bf16x8*)(lds + PG8_SA(b, h) + aoff + m * 2048 + k * 1024); } while (0)
; #define PG8_LDB(dst, b, h) do { _Pragma("unroll") for (int n = 0; n < 2; ++n) _Pragma("unroll") for (int k = 0; k < 2; ++k) dst[n][k] = *(const PG8_LAS bf16x8*)(lds + PG8_SB(b, h) + boff + n * 2048 + k * 1024); } while (0)
; #define PG8_MMA(ai, bj, At, Bt) do { __builtin_amdgcn_s_setprio(1); _Pragma("unroll") for (int m = 0; m < 4; ++m) _Pragma("unroll") for (int n = 0; n < 2; ++n) _Pragma("unroll") for (int k = 0; k < 2; ++k) \
;         acc[ai][bj][m][n] = __builtin_amdgcn_mfma_f32_16x16x32_bf16(Bt[n][k], At[m][k], acc[ai][bj][m][n], 0, 0, 0); __builtin_amdgcn_s_setprio(0); } while (0)
; #define PG8_WAIT_V(n) asm volatile("s_waitcnt vmcnt(" #n ")" ::: "memory")
; #define PG8_WAIT_L(n) asm volatile("s_waitcnt lgkmcnt(" #n ")" ::: "memory")
; #define PG8_BAR __builtin_amdgcn_s_barrier()
; #define PG8_SCHED __builtin_amdgcn_sched_barrier(0)
; template <class Epi, class Sched, bool ALIGN_EPI = false, bool SP2 = false>
; __device__ __forceinline__ void gemm_phase(PG8_LAS unsigned char* lds, const Gemm g, const Sched& S, const Epi& E) {
;     ...
;             PG8_WAIT_V(8); PG8_WAIT_L(0); PG8_BAR; PG8_MMA(1, 0, At, B0); PG8_MMA(1, 1, At, B1); PG8_BAR; PG8_SCHED;
;             PG8_LDB(B0, 1, 0); PG8_LDB(B1, 1, 1); PG8_SCHED; PG8_LDA(At, 1, 0); PG8_STAGE(PG8_SA(0, 1), a2 + hstepA, voffA);
;             PG8_WAIT_V(8); PG8_WAIT_L(0); PG8_BAR; PG8_MMA(0, 0, At, B0); PG8_MMA(0, 1, At, B1); PG8_BAR; PG8_SCHED;
	s_waitcnt lgkmcnt(0)
	v_mfma_f32_16x16x32_bf16 v[60:63], v[92:95], v[176:179], v[60:63]
	v_mfma_f32_16x16x32_bf16 v[56:59], v[100:103], v[176:179], v[56:59]
	v_mfma_f32_16x16x32_bf16 v[44:47], v[92:95], v[192:195], v[44:47]
	v_mfma_f32_16x16x32_bf16 v[40:43], v[100:103], v[192:195], v[40:43]
	v_mfma_f32_16x16x32_bf16 v[28:31], v[92:95], v[200:203], v[28:31]
	v_mfma_f32_16x16x32_bf16 v[24:27], v[100:103], v[200:203], v[24:27]
	v_mfma_f32_16x16x32_bf16 v[12:15], v[92:95], v[210:213], v[12:15]
	v_mfma_f32_16x16x32_bf16 v[8:11], v[100:103], v[210:213], v[8:11]
	v_mfma_f32_16x16x32_bf16 v[60:63], v[96:99], v[188:191], v[60:63]
	v_mfma_f32_16x16x32_bf16 v[56:59], v[108:111], v[188:191], v[56:59]
	v_mfma_f32_16x16x32_bf16 v[44:47], v[96:99], v[196:199], v[44:47]
	v_mfma_f32_16x16x32_bf16 v[40:43], v[108:111], v[196:199], v[40:43]
	v_mfma_f32_16x16x32_bf16 v[28:31], v[96:99], v[206:209], v[28:31]
	v_mfma_f32_16x16x32_bf16 v[24:27], v[108:111], v[206:209], v[24:27]
	v_mfma_f32_16x16x32_bf16 v[12:15], v[96:99], v[214:217], v[12:15]
	v_mfma_f32_16x16x32_bf16 v[8:11], v[108:111], v[214:217], v[8:11]
	v_mfma_f32_16x16x32_bf16 v[52:55], v[144:147], v[176:179], v[52:55]
	v_mfma_f32_16x16x32_bf16 v[48:51], v[168:171], v[176:179], v[48:51]
	v_mfma_f32_16x16x32_bf16 v[36:39], v[144:147], v[192:195], v[36:39]
	v_mfma_f32_16x16x32_bf16 v[32:35], v[168:171], v[192:195], v[32:35]
	v_mfma_f32_16x16x32_bf16 v[20:23], v[144:147], v[200:203], v[20:23]
	v_mfma_f32_16x16x32_bf16 v[16:19], v[168:171], v[200:203], v[16:19]
	v_mfma_f32_16x16x32_bf16 v[4:7], v[144:147], v[210:213], v[4:7]
	v_mfma_f32_16x16x32_bf16 v[0:3], v[168:171], v[210:213], v[0:3]
	v_mfma_f32_16x16x32_bf16 v[52:55], v[148:151], v[188:191], v[52:55]
	v_mfma_f32_16x16x32_bf16 v[48:51], v[172:175], v[188:191], v[48:51]
	v_mfma_f32_16x16x32_bf16 v[36:39], v[148:151], v[196:199], v[36:39]
	v_mfma_f32_16x16x32_bf16 v[32:35], v[172:175], v[196:199], v[32:35]
	v_mfma_f32_16x16x32_bf16 v[20:23], v[148:151], v[206:209], v[20:23]
	v_mfma_f32_16x16x32_bf16 v[16:19], v[172:175], v[206:209], v[16:19]
	v_mfma_f32_16x16x32_bf16 v[4:7], v[148:151], v[214:217], v[4:7]
	v_mfma_f32_16x16x32_bf16 v[0:3], v[172:175], v[214:217], v[0:3]
	s_barrier
	s_add_i32 s63, 0, 0x18000
	s_add_i32 s66, 0, 0x1c000
	v_add_u32_e32 v108, s63, v181
	v_add_u32_e32 v172, s66, v181
	ds_read_b128 v[92:95], v108
	ds_read_b128 v[96:99], v108 offset:1024
	ds_read_b128 v[100:103], v108 offset:2048
	ds_read_b128 v[108:111], v108 offset:3072
	ds_read_b128 v[144:147], v172
	ds_read_b128 v[148:151], v172 offset:1024
	ds_read_b128 v[168:171], v172 offset:2048
	ds_read_b128 v[172:175], v172 offset:3072
	s_add_u32 s42, s42, 0x80000
	s_addc_u32 s43, s43, 0
	s_mov_b32 m0, s48
	v_lshl_add_u64 v[226:227], s[42:43], 0, v[152:153]
	ds_read_b128 v[176:179], v185 offset:32768
	ds_read_b128 v[188:191], v185 offset:33792
	ds_read_b128 v[192:195], v185 offset:34816
	ds_read_b128 v[196:199], v185 offset:35840
	ds_read_b128 v[200:203], v185 offset:36864
	ds_read_b128 v[206:209], v185 offset:37888
	ds_read_b128 v[210:213], v185 offset:38912
	ds_read_b128 v[214:217], v185 offset:39936
	global_load_lds_dwordx4 v[226:227], off
	v_lshl_add_u64 v[226:227], s[42:43], 0, v[156:157]
	s_mov_b32 m0, s49
	s_nop 0
	global_load_lds_dwordx4 v[226:227], off
	s_waitcnt vmcnt(8)
	s_waitcnt lgkmcnt(0)
	s_barrier
	s_waitcnt lgkmcnt(0)
	v_mfma_f32_16x16x32_bf16 v[140:143], v[92:95], v[176:179], v[140:143]
	v_mfma_f32_16x16x32_bf16 v[136:139], v[100:103], v[176:179], v[136:139]
	v_mfma_f32_16x16x32_bf16 v[124:127], v[92:95], v[192:195], v[124:127]
	v_mfma_f32_16x16x32_bf16 v[120:123], v[100:103], v[192:195], v[120:123]
	v_mfma_f32_16x16x32_bf16 v[104:107], v[92:95], v[200:203], v[104:107]
	v_mfma_f32_16x16x32_bf16 v[88:91], v[100:103], v[200:203], v[88:91]
	v_mfma_f32_16x16x32_bf16 v[76:79], v[92:95], v[210:213], v[76:79]
	v_mfma_f32_16x16x32_bf16 v[72:75], v[100:103], v[210:213], v[72:75]
	v_mfma_f32_16x16x32_bf16 v[140:143], v[96:99], v[188:191], v[140:143]
	v_mfma_f32_16x16x32_bf16 v[136:139], v[108:111], v[188:191], v[136:139]
	v_mfma_f32_16x16x32_bf16 v[124:127], v[96:99], v[196:199], v[124:127]
	v_mfma_f32_16x16x32_bf16 v[120:123], v[108:111], v[196:199], v[120:123]
	v_mfma_f32_16x16x32_bf16 v[104:107], v[96:99], v[206:209], v[104:107]
	v_mfma_f32_16x16x32_bf16 v[88:91], v[108:111], v[206:209], v[88:91]
	v_mfma_f32_16x16x32_bf16 v[76:79], v[96:99], v[214:217], v[76:79]
	v_mfma_f32_16x16x32_bf16 v[72:75], v[108:111], v[214:217], v[72:75]
	v_mfma_f32_16x16x32_bf16 v[132:135], v[144:147], v[176:179], v[132:135]
	v_mfma_f32_16x16x32_bf16 v[128:131], v[168:171], v[176:179], v[128:131]
	v_mfma_f32_16x16x32_bf16 v[116:119], v[144:147], v[192:195], v[116:119]
	v_mfma_f32_16x16x32_bf16 v[112:115], v[168:171], v[192:195], v[112:115]
	v_mfma_f32_16x16x32_bf16 v[84:87], v[144:147], v[200:203], v[84:87]
	v_mfma_f32_16x16x32_bf16 v[80:83], v[168:171], v[200:203], v[80:83]
	v_mfma_f32_16x16x32_bf16 v[68:71], v[144:147], v[210:213], v[68:71]
	v_mfma_f32_16x16x32_bf16 v[64:67], v[168:171], v[210:213], v[64:67]
	v_mfma_f32_16x16x32_bf16 v[132:135], v[148:151], v[188:191], v[132:135]
	v_mfma_f32_16x16x32_bf16 v[128:131], v[172:175], v[188:191], v[128:131]
	v_mfma_f32_16x16x32_bf16 v[116:119], v[148:151], v[196:199], v[116:119]
	v_mfma_f32_16x16x32_bf16 v[112:115], v[172:175], v[196:199], v[112:115]
	v_mfma_f32_16x16x32_bf16 v[84:87], v[148:151], v[206:209], v[84:87]
	v_mfma_f32_16x16x32_bf16 v[80:83], v[172:175], v[206:209], v[80:83]
	v_mfma_f32_16x16x32_bf16 v[68:71], v[148:151], v[214:217], v[68:71]
	v_mfma_f32_16x16x32_bf16 v[64:67], v[172:175], v[214:217], v[64:67]
	s_barrier
; #define PG8_STAGE(bufoff, gbase, voff) do { _Pragma("unroll") for (int _i = 0; _i < 2; ++_i) \
;         __builtin_amdgcn_global_load_lds((const unsigned*)((const char*)(gbase) + (voff)[_i]), (PG8_LAS unsigned*)(lds + (bufoff) + ldsw + _i * 8192), 16, 0, 0); } while (0)
; #define PG8_LDA(dst, b, h) do { _Pragma("unroll") for (int m = 0; m < 4; ++m) _Pragma("unroll") for (int k = 0; k < 2; ++k) dst[m][k] = *(const PG8_LAS bf16x8*)(lds + PG8_SA(b, h) + aoff + m * 2048 + k * 1024); } while (0)
; #define PG8_MMA(ai, bj, At, Bt) do { __builtin_amdgcn_s_setprio(1); _Pragma("unroll") for (int m = 0; m < 4; ++m) _Pragma("unroll") for (int n = 0; n < 2; ++n) _Pragma("unroll") for (int k = 0; k < 2; ++k) \
;         acc[ai][bj][m][n] = __builtin_amdgcn_mfma_f32_16x16x32_bf16(Bt[n][k], At[m][k], acc[ai][bj][m][n], 0, 0, 0); __builtin_amdgcn_s_setprio(0); } while (0)
; #define PG8_WAIT_V(n) asm volatile("s_waitcnt vmcnt(" #n ")" ::: "memory")
; #define PG8_WAIT_L(n) asm volatile("s_waitcnt lgkmcnt(" #n ")" ::: "memory")
; #define PG8_BAR __builtin_amdgcn_s_barrier()
; #define PG8_SCHED __builtin_amdgcn_sched_barrier(0)
; template <class Epi, class Sched, bool ALIGN_EPI = false, bool SP2 = false>
; __device__ __forceinline__ void gemm_phase(PG8_LAS unsigned char* lds, const Gemm g, const Sched& S, const Epi& E) {
;     ...
;             PG8_LDA(At, 1, 1); PG8_STAGE(PG8_SB(1, 0), b3, voffB); PG8_STAGE(PG8_SB(1, 1), b3 + hstep, voffB); PG8_STAGE(PG8_SA(1, 0), a3, voffA);
;             PG8_WAIT_V(8); PG8_WAIT_L(0); PG8_BAR; PG8_MMA(1, 0, At, B0); PG8_MMA(1, 1, At, B1); PG8_BAR; PG8_SCHED;
	s_add_i32 s42, s63, s47
	v_lshl_add_u64 v[218:219], v[218:219], 0, s[20:21]
	s_mov_b32 m0, s42
	ds_read_b128 v[176:179], v185 offset:49152
	ds_read_b128 v[188:191], v185 offset:50176
	ds_read_b128 v[192:195], v185 offset:51200
	ds_read_b128 v[196:199], v185 offset:52224
	ds_read_b128 v[200:203], v185 offset:53248
	ds_read_b128 v[206:209], v185 offset:54272
	ds_read_b128 v[210:213], v185 offset:55296
	ds_read_b128 v[214:217], v185 offset:56320
	global_load_lds_dwordx4 v[218:219], off
	s_add_i32 m0, s42, 0x2000
	s_add_u32 s40, s40, 0x80080
	v_lshl_add_u64 v[218:219], v[220:221], 0, s[20:21]
	s_addc_u32 s41, s41, 0
	s_add_i32 s42, s66, s47
	global_load_lds_dwordx4 v[218:219], off
	v_lshl_add_u64 v[218:219], s[40:41], 0, v[154:155]
	s_mov_b32 m0, s42
	s_nop 0
	global_load_lds_dwordx4 v[218:219], off
	v_lshl_add_u64 v[218:219], s[40:41], 0, v[158:159]
	s_add_i32 m0, s42, 0x2000
	s_nop 0
	global_load_lds_dwordx4 v[218:219], off
	v_lshl_add_u64 v[218:219], v[222:223], 0, s[20:21]
	s_mov_b32 m0, s54
	s_nop 0
	global_load_lds_dwordx4 v[218:219], off
	v_lshl_add_u64 v[218:219], v[224:225], 0, s[20:21]
	s_mov_b32 m0, s55
	s_nop 0
	global_load_lds_dwordx4 v[218:219], off
	s_waitcnt vmcnt(8)
	s_waitcnt lgkmcnt(0)
	s_barrier
	s_waitcnt lgkmcnt(0)
	v_mfma_f32_16x16x32_bf16 v[60:63], v[92:95], v[176:179], v[60:63]
	v_mfma_f32_16x16x32_bf16 v[56:59], v[100:103], v[176:179], v[56:59]
	v_mfma_f32_16x16x32_bf16 v[44:47], v[92:95], v[192:195], v[44:47]
	v_mfma_f32_16x16x32_bf16 v[40:43], v[100:103], v[192:195], v[40:43]
	v_mfma_f32_16x16x32_bf16 v[28:31], v[92:95], v[200:203], v[28:31]
	v_mfma_f32_16x16x32_bf16 v[24:27], v[100:103], v[200:203], v[24:27]
	v_mfma_f32_16x16x32_bf16 v[12:15], v[92:95], v[210:213], v[12:15]
	v_mfma_f32_16x16x32_bf16 v[8:11], v[100:103], v[210:213], v[8:11]
	v_mfma_f32_16x16x32_bf16 v[60:63], v[96:99], v[188:191], v[60:63]
	v_mfma_f32_16x16x32_bf16 v[56:59], v[108:111], v[188:191], v[56:59]
	v_mfma_f32_16x16x32_bf16 v[44:47], v[96:99], v[196:199], v[44:47]
	v_mfma_f32_16x16x32_bf16 v[40:43], v[108:111], v[196:199], v[40:43]
	v_mfma_f32_16x16x32_bf16 v[28:31], v[96:99], v[206:209], v[28:31]
	v_mfma_f32_16x16x32_bf16 v[24:27], v[108:111], v[206:209], v[24:27]
	v_mfma_f32_16x16x32_bf16 v[12:15], v[96:99], v[214:217], v[12:15]
	v_mfma_f32_16x16x32_bf16 v[8:11], v[108:111], v[214:217], v[8:11]
	v_mfma_f32_16x16x32_bf16 v[52:55], v[144:147], v[176:179], v[52:55]
	v_mfma_f32_16x16x32_bf16 v[48:51], v[168:171], v[176:179], v[48:51]
	v_mfma_f32_16x16x32_bf16 v[36:39], v[144:147], v[192:195], v[36:39]
	v_mfma_f32_16x16x32_bf16 v[32:35], v[168:171], v[192:195], v[32:35]
	v_mfma_f32_16x16x32_bf16 v[20:23], v[144:147], v[200:203], v[20:23]
	v_mfma_f32_16x16x32_bf16 v[16:19], v[168:171], v[200:203], v[16:19]
	v_mfma_f32_16x16x32_bf16 v[4:7], v[144:147], v[210:213], v[4:7]
	v_mfma_f32_16x16x32_bf16 v[0:3], v[168:171], v[210:213], v[0:3]
	v_mfma_f32_16x16x32_bf16 v[52:55], v[148:151], v[188:191], v[52:55]
	v_mfma_f32_16x16x32_bf16 v[48:51], v[172:175], v[188:191], v[48:51]
	v_mfma_f32_16x16x32_bf16 v[36:39], v[148:151], v[196:199], v[36:39]
	v_mfma_f32_16x16x32_bf16 v[32:35], v[172:175], v[196:199], v[32:35]
	v_mfma_f32_16x16x32_bf16 v[20:23], v[148:151], v[206:209], v[20:23]
	v_mfma_f32_16x16x32_bf16 v[16:19], v[172:175], v[206:209], v[16:19]
	v_mfma_f32_16x16x32_bf16 v[4:7], v[148:151], v[214:217], v[4:7]
	v_mfma_f32_16x16x32_bf16 v[0:3], v[172:175], v[214:217], v[0:3]
	s_barrier
	s_add_i32 s62, s62, 2
	s_add_u32 s14, s14, 0x100
	s_addc_u32 s15, s15, 0
	s_add_u32 s37, s37, 0x100
	s_addc_u32 s61, s61, 0
	s_cmp_gt_u32 s62, 29
	s_cbranch_scc0 .LBB0_1697
	s_and_b64 vcc, exec, s[22:23]
	s_cbranch_vccz .LBB0_1700
	s_barrier

; #define PG8_STAGE(bufoff, gbase, voff) do { _Pragma("unroll") for (int _i = 0; _i < 2; ++_i) \
;         __builtin_amdgcn_global_load_lds((const unsigned*)((const char*)(gbase) + (voff)[_i]), (PG8_LAS unsigned*)(lds + (bufoff) + ldsw + _i * 8192), 16, 0, 0); } while (0)
; #define PG8_LDA(dst, b, h) do { _Pragma("unroll") for (int m = 0; m < 4; ++m) _Pragma("unroll") for (int k = 0; k < 2; ++k) dst[m][k] = *(const PG8_LAS bf16x8*)(lds + PG8_SA(b, h) + aoff + m * 2048 + k * 1024); } while (0)
; #define PG8_LDB(dst, b, h) do { _Pragma("unroll") for (int n = 0; n < 2; ++n) _Pragma("unroll") for (int k = 0; k < 2; ++k) dst[n][k] = *(const PG8_LAS bf16x8*)(lds + PG8_SB(b, h) + boff + n * 2048 + k * 1024); } while (0)
; #define PG8_MMA(ai, bj, At, Bt) do { __builtin_amdgcn_s_setprio(1); _Pragma("unroll") for (int m = 0; m < 4; ++m) _Pragma("unroll") for (int n = 0; n < 2; ++n) _Pragma("unroll") for (int k = 0; k < 2; ++k) \
;         acc[ai][bj][m][n] = __builtin_amdgcn_mfma_f32_16x16x32_bf16(Bt[n][k], At[m][k], acc[ai][bj][m][n], 0, 0, 0); __builtin_amdgcn_s_setprio(0); } while (0)
; #define PG8_WAIT_V(n) asm volatile("s_waitcnt vmcnt(" #n ")" ::: "memory")
; #define PG8_WAIT_L(n) asm volatile("s_waitcnt lgkmcnt(" #n ")" ::: "memory")
; #define PG8_BAR __builtin_amdgcn_s_barrier()
; #define PG8_SCHED __builtin_amdgcn_sched_barrier(0)
; template <class Epi, class Sched, bool ALIGN_EPI = false, bool SP2 = false>
; __device__ __forceinline__ void gemm_phase(PG8_LAS unsigned char* lds, const Gemm g, const Sched& S, const Epi& E) {
;     ...
;             PG8_LDB(B0, 0, 0); PG8_LDB(B1, 0, 1); PG8_SCHED; PG8_LDA(At, 0, 0); PG8_STAGE(PG8_SA(1, 1), a1 + hstepA, voffA);
;             PG8_WAIT_V(8); PG8_WAIT_L(0); PG8_BAR; PG8_MMA(0, 0, At, B0); PG8_MMA(0, 1, At, B1); PG8_BAR; PG8_SCHED;
;             PG8_LDA(At, 0, 1); PG8_STAGE(PG8_SB(0, 0), b2, voffB); PG8_STAGE(PG8_SB(0, 1), b2 + hstep, voffB); PG8_STAGE(PG8_SA(0, 0), a2, voffA);
.LBB0_1793:
	ds_read_b128 v[96:99], v207
	ds_read_b128 v[112:115], v207 offset:1024
	ds_read_b128 v[116:119], v207 offset:2048
	ds_read_b128 v[120:123], v207 offset:3072
	ds_read_b128 v[124:127], v208
	ds_read_b128 v[128:131], v208 offset:1024
	ds_read_b128 v[132:135], v208 offset:2048
	ds_read_b128 v[136:139], v208 offset:3072
	s_add_u32 s14, s16, 0x100
	s_addc_u32 s15, s17, 0
	s_cmp_eq_u32 s25, 28
	s_cselect_b32 s21, s57, s15
	s_cselect_b32 s20, s56, s14
	s_cselect_b32 s19, s6, s23
	s_cselect_b32 s18, s7, s22
	v_lshl_add_u64 v[220:221], s[16:17], 0, v[170:171]
	s_add_i32 m0, s66, 0xc000
	ds_read_b128 v[178:181], v209
	ds_read_b128 v[182:185], v209 offset:1024
	ds_read_b128 v[186:189], v209 offset:2048
	ds_read_b128 v[190:193], v209 offset:3072
	ds_read_b128 v[194:197], v209 offset:4096
	ds_read_b128 v[198:201], v209 offset:5120
	ds_read_b128 v[212:215], v209 offset:6144
	ds_read_b128 v[216:219], v209 offset:7168
	global_load_lds_dwordx4 v[220:221], off
	v_lshl_add_u64 v[220:221], s[16:17], 0, v[172:173]
	s_add_i32 m0, s66, 0xe000
	s_nop 0
	global_load_lds_dwordx4 v[220:221], off
	s_waitcnt vmcnt(8)
	s_waitcnt lgkmcnt(0)
	s_barrier
	s_waitcnt lgkmcnt(0)
	v_mfma_f32_16x16x32_bf16 v[156:159], v[96:99], v[178:181], v[156:159]
	v_mfma_f32_16x16x32_bf16 v[60:63], v[116:119], v[178:181], v[60:63]
	v_mfma_f32_16x16x32_bf16 v[152:155], v[96:99], v[186:189], v[152:155]
	v_mfma_f32_16x16x32_bf16 v[56:59], v[116:119], v[186:189], v[56:59]
	v_mfma_f32_16x16x32_bf16 v[148:151], v[96:99], v[194:197], v[148:151]
	v_mfma_f32_16x16x32_bf16 v[52:55], v[116:119], v[194:197], v[52:55]
	v_mfma_f32_16x16x32_bf16 v[140:143], v[96:99], v[212:215], v[140:143]
	v_mfma_f32_16x16x32_bf16 v[44:47], v[116:119], v[212:215], v[44:47]
	v_mfma_f32_16x16x32_bf16 v[156:159], v[112:115], v[182:185], v[156:159]
	v_mfma_f32_16x16x32_bf16 v[60:63], v[120:123], v[182:185], v[60:63]
	v_mfma_f32_16x16x32_bf16 v[152:155], v[112:115], v[190:193], v[152:155]
	v_mfma_f32_16x16x32_bf16 v[56:59], v[120:123], v[190:193], v[56:59]
	v_mfma_f32_16x16x32_bf16 v[148:151], v[112:115], v[198:201], v[148:151]
	v_mfma_f32_16x16x32_bf16 v[52:55], v[120:123], v[198:201], v[52:55]
	v_mfma_f32_16x16x32_bf16 v[140:143], v[112:115], v[216:219], v[140:143]
	v_mfma_f32_16x16x32_bf16 v[44:47], v[120:123], v[216:219], v[44:47]
	v_mfma_f32_16x16x32_bf16 v[144:147], v[124:127], v[178:181], v[144:147]
	v_mfma_f32_16x16x32_bf16 v[48:51], v[132:135], v[178:181], v[48:51]
	v_mfma_f32_16x16x32_bf16 v[108:111], v[124:127], v[186:189], v[108:111]
	v_mfma_f32_16x16x32_bf16 v[40:43], v[132:135], v[186:189], v[40:43]
	v_mfma_f32_16x16x32_bf16 v[104:107], v[124:127], v[194:197], v[104:107]
	v_mfma_f32_16x16x32_bf16 v[36:39], v[132:135], v[194:197], v[36:39]
	v_mfma_f32_16x16x32_bf16 v[100:103], v[124:127], v[212:215], v[100:103]
	v_mfma_f32_16x16x32_bf16 v[32:35], v[132:135], v[212:215], v[32:35]
	v_mfma_f32_16x16x32_bf16 v[144:147], v[128:131], v[182:185], v[144:147]
	v_mfma_f32_16x16x32_bf16 v[48:51], v[136:139], v[182:185], v[48:51]
	v_mfma_f32_16x16x32_bf16 v[108:111], v[128:131], v[190:193], v[108:111]
	v_mfma_f32_16x16x32_bf16 v[40:43], v[136:139], v[190:193], v[40:43]
	v_mfma_f32_16x16x32_bf16 v[104:107], v[128:131], v[198:201], v[104:107]
	v_mfma_f32_16x16x32_bf16 v[36:39], v[136:139], v[198:201], v[36:39]
	v_mfma_f32_16x16x32_bf16 v[100:103], v[128:131], v[216:219], v[100:103]
	v_mfma_f32_16x16x32_bf16 v[32:35], v[136:139], v[216:219], v[32:35]
	s_barrier
	s_add_i32 s16, s84, s63
	v_lshl_add_u64 v[220:221], s[18:19], 0, v[162:163]
	s_mov_b32 m0, s16
	ds_read_b128 v[178:181], v209 offset:16384
	ds_read_b128 v[182:185], v209 offset:17408
	ds_read_b128 v[186:189], v209 offset:18432
	ds_read_b128 v[190:193], v209 offset:19456
	ds_read_b128 v[194:197], v209 offset:20480
	ds_read_b128 v[198:201], v209 offset:21504
	ds_read_b128 v[212:215], v209 offset:22528
	ds_read_b128 v[216:219], v209 offset:23552
	global_load_lds_dwordx4 v[220:221], off
	s_add_i32 m0, s16, 0x2000
	s_add_u32 s16, s18, 0x80000
	v_lshl_add_u64 v[222:223], s[18:19], 0, v[166:167]
	s_addc_u32 s17, s19, 0
	s_add_i32 s26, s85, s63
	global_load_lds_dwordx4 v[222:223], off
	v_lshl_add_u64 v[224:225], s[16:17], 0, v[162:163]
	s_mov_b32 m0, s26
	v_lshl_add_u64 v[226:227], s[20:21], 0, v[164:165]
	global_load_lds_dwordx4 v[224:225], off
	v_lshl_add_u64 v[224:225], s[16:17], 0, v[166:167]
	s_add_i32 m0, s26, 0x2000
	s_nop 0
	global_load_lds_dwordx4 v[224:225], off
	v_lshl_add_u64 v[224:225], s[20:21], 0, v[160:161]
	s_mov_b32 m0, s66
	s_nop 0
	global_load_lds_dwordx4 v[224:225], off
	s_mov_b32 m0, s67
	s_nop 0
	global_load_lds_dwordx4 v[226:227], off
	s_waitcnt vmcnt(8)
	s_waitcnt lgkmcnt(0)
	s_barrier
; #define PG8_STAGE(bufoff, gbase, voff) do { _Pragma("unroll") for (int _i = 0; _i < 2; ++_i) \
;         __builtin_amdgcn_global_load_lds((const unsigned*)((const char*)(gbase) + (voff)[_i]), (PG8_LAS unsigned*)(lds + (bufoff) + ldsw + _i * 8192), 16, 0, 0); } while (0)
; #define PG8_LDA(dst, b, h) do { _Pragma("unroll") for (int m = 0; m < 4; ++m) _Pragma("unroll") for (int k = 0; k < 2; ++k) dst[m][k] = *(const PG8_LAS bf16x8*)(lds + PG8_SA(b, h) + aoff + m * 2048 + k * 1024); } while (0)
; #define PG8_LDB(dst, b, h) do { _Pragma("unroll") for (int n = 0; n < 2; ++n) _Pragma("unroll") for (int k = 0; k < 2; ++k) dst[n][k] = *(const PG8_LAS bf16x8*)(lds + PG8_SB(b, h) + boff + n * 2048 + k * 1024); } while (0)
; #define PG8_MMA(ai, bj, At, Bt) do { __builtin_amdgcn_s_setprio(1); _Pragma("unroll") for (int m = 0; m < 4; ++m) _Pragma("unroll") for (int n = 0; n < 2; ++n) _Pragma("unroll") for (int k = 0; k < 2; ++k) \
;         acc[ai][bj][m][n] = __builtin_amdgcn_mfma_f32_16x16x32_bf16(Bt[n][k], At[m][k], acc[ai][bj][m][n], 0, 0, 0); __builtin_amdgcn_s_setprio(0); } while (0)
; #define PG8_WAIT_V(n) asm volatile("s_waitcnt vmcnt(" #n ")" ::: "memory")
; #define PG8_WAIT_L(n) asm volatile("s_waitcnt lgkmcnt(" #n ")" ::: "memory")
; #define PG8_BAR __builtin_amdgcn_s_barrier()
; #define PG8_SCHED __builtin_amdgcn_sched_barrier(0)
; template <class Epi, class Sched, bool ALIGN_EPI = false, bool SP2 = false>
; __device__ __forceinline__ void gemm_phase(PG8_LAS unsigned char* lds, const Gemm g, const Sched& S, const Epi& E) {
;     ...
;             PG8_WAIT_V(8); PG8_WAIT_L(0); PG8_BAR; PG8_MMA(1, 0, At, B0); PG8_MMA(1, 1, At, B1); PG8_BAR; PG8_SCHED;
;             PG8_LDB(B0, 1, 0); PG8_LDB(B1, 1, 1); PG8_SCHED; PG8_LDA(At, 1, 0); PG8_STAGE(PG8_SA(0, 1), a2 + hstepA, voffA);
;             PG8_WAIT_V(8); PG8_WAIT_L(0); PG8_BAR; PG8_MMA(0, 0, At, B0); PG8_MMA(0, 1, At, B1); PG8_BAR; PG8_SCHED;
	s_waitcnt lgkmcnt(0)
	v_mfma_f32_16x16x32_bf16 v[92:95], v[96:99], v[178:181], v[92:95]
	v_mfma_f32_16x16x32_bf16 v[28:31], v[116:119], v[178:181], v[28:31]
	v_mfma_f32_16x16x32_bf16 v[88:91], v[96:99], v[186:189], v[88:91]
	v_mfma_f32_16x16x32_bf16 v[24:27], v[116:119], v[186:189], v[24:27]
	v_mfma_f32_16x16x32_bf16 v[84:87], v[96:99], v[194:197], v[84:87]
	v_mfma_f32_16x16x32_bf16 v[20:23], v[116:119], v[194:197], v[20:23]
	v_mfma_f32_16x16x32_bf16 v[76:79], v[96:99], v[212:215], v[76:79]
	v_mfma_f32_16x16x32_bf16 v[12:15], v[116:119], v[212:215], v[12:15]
	v_mfma_f32_16x16x32_bf16 v[92:95], v[112:115], v[182:185], v[92:95]
	v_mfma_f32_16x16x32_bf16 v[28:31], v[120:123], v[182:185], v[28:31]
	v_mfma_f32_16x16x32_bf16 v[88:91], v[112:115], v[190:193], v[88:91]
	v_mfma_f32_16x16x32_bf16 v[24:27], v[120:123], v[190:193], v[24:27]
	v_mfma_f32_16x16x32_bf16 v[84:87], v[112:115], v[198:201], v[84:87]
	v_mfma_f32_16x16x32_bf16 v[20:23], v[120:123], v[198:201], v[20:23]
	v_mfma_f32_16x16x32_bf16 v[76:79], v[112:115], v[216:219], v[76:79]
	v_mfma_f32_16x16x32_bf16 v[12:15], v[120:123], v[216:219], v[12:15]
	v_mfma_f32_16x16x32_bf16 v[80:83], v[124:127], v[178:181], v[80:83]
	v_mfma_f32_16x16x32_bf16 v[16:19], v[132:135], v[178:181], v[16:19]
	v_mfma_f32_16x16x32_bf16 v[72:75], v[124:127], v[186:189], v[72:75]
	v_mfma_f32_16x16x32_bf16 v[8:11], v[132:135], v[186:189], v[8:11]
	v_mfma_f32_16x16x32_bf16 v[68:71], v[124:127], v[194:197], v[68:71]
	v_mfma_f32_16x16x32_bf16 v[4:7], v[132:135], v[194:197], v[4:7]
	v_mfma_f32_16x16x32_bf16 v[64:67], v[124:127], v[212:215], v[64:67]
	v_mfma_f32_16x16x32_bf16 v[0:3], v[132:135], v[212:215], v[0:3]
	v_mfma_f32_16x16x32_bf16 v[80:83], v[128:131], v[182:185], v[80:83]
	v_mfma_f32_16x16x32_bf16 v[16:19], v[136:139], v[182:185], v[16:19]
	v_mfma_f32_16x16x32_bf16 v[72:75], v[128:131], v[190:193], v[72:75]
	v_mfma_f32_16x16x32_bf16 v[8:11], v[136:139], v[190:193], v[8:11]
	v_mfma_f32_16x16x32_bf16 v[68:71], v[128:131], v[198:201], v[68:71]
	v_mfma_f32_16x16x32_bf16 v[4:7], v[136:139], v[198:201], v[4:7]
	v_mfma_f32_16x16x32_bf16 v[64:67], v[128:131], v[216:219], v[64:67]
	v_mfma_f32_16x16x32_bf16 v[0:3], v[136:139], v[216:219], v[0:3]
	s_barrier
	s_add_i32 s26, 0, 0x18000
	s_add_i32 s27, 0, 0x1c000
	v_add_u32_e32 v120, s26, v202
	v_add_u32_e32 v136, s27, v202
	ds_read_b128 v[96:99], v120
	ds_read_b128 v[112:115], v120 offset:1024
	ds_read_b128 v[116:119], v120 offset:2048
	ds_read_b128 v[120:123], v120 offset:3072
	ds_read_b128 v[124:127], v136
	ds_read_b128 v[128:131], v136 offset:1024
	ds_read_b128 v[132:135], v136 offset:2048
	ds_read_b128 v[136:139], v136 offset:3072
	s_add_u32 s16, s20, 0x7c000
	s_addc_u32 s17, s21, 0
	s_mov_b32 m0, s68
	v_lshl_add_u64 v[228:229], s[16:17], 0, v[160:161]
	ds_read_b128 v[178:181], v209 offset:32768
	ds_read_b128 v[182:185], v209 offset:33792
	ds_read_b128 v[186:189], v209 offset:34816
	ds_read_b128 v[190:193], v209 offset:35840
	ds_read_b128 v[194:197], v209 offset:36864
	ds_read_b128 v[198:201], v209 offset:37888
	ds_read_b128 v[212:215], v209 offset:38912
	ds_read_b128 v[216:219], v209 offset:39936
	global_load_lds_dwordx4 v[228:229], off
	v_lshl_add_u64 v[228:229], s[16:17], 0, v[164:165]
	s_mov_b32 m0, s69
	s_nop 0
	global_load_lds_dwordx4 v[228:229], off
	s_waitcnt vmcnt(8)
	s_waitcnt lgkmcnt(0)
	s_barrier
	s_waitcnt lgkmcnt(0)
	v_mfma_f32_16x16x32_bf16 v[156:159], v[96:99], v[178:181], v[156:159]
	v_mfma_f32_16x16x32_bf16 v[60:63], v[116:119], v[178:181], v[60:63]
	v_mfma_f32_16x16x32_bf16 v[152:155], v[96:99], v[186:189], v[152:155]
	v_mfma_f32_16x16x32_bf16 v[56:59], v[116:119], v[186:189], v[56:59]
	v_mfma_f32_16x16x32_bf16 v[148:151], v[96:99], v[194:197], v[148:151]
	v_mfma_f32_16x16x32_bf16 v[52:55], v[116:119], v[194:197], v[52:55]
	v_mfma_f32_16x16x32_bf16 v[140:143], v[96:99], v[212:215], v[140:143]
	v_mfma_f32_16x16x32_bf16 v[44:47], v[116:119], v[212:215], v[44:47]
	v_mfma_f32_16x16x32_bf16 v[156:159], v[112:115], v[182:185], v[156:159]
	v_mfma_f32_16x16x32_bf16 v[60:63], v[120:123], v[182:185], v[60:63]
	v_mfma_f32_16x16x32_bf16 v[152:155], v[112:115], v[190:193], v[152:155]
	v_mfma_f32_16x16x32_bf16 v[56:59], v[120:123], v[190:193], v[56:59]
	v_mfma_f32_16x16x32_bf16 v[148:151], v[112:115], v[198:201], v[148:151]
	v_mfma_f32_16x16x32_bf16 v[52:55], v[120:123], v[198:201], v[52:55]
	v_mfma_f32_16x16x32_bf16 v[140:143], v[112:115], v[216:219], v[140:143]
	v_mfma_f32_16x16x32_bf16 v[44:47], v[120:123], v[216:219], v[44:47]
	v_mfma_f32_16x16x32_bf16 v[144:147], v[124:127], v[178:181], v[144:147]
	v_mfma_f32_16x16x32_bf16 v[48:51], v[132:135], v[178:181], v[48:51]
	v_mfma_f32_16x16x32_bf16 v[108:111], v[124:127], v[186:189], v[108:111]
	v_mfma_f32_16x16x32_bf16 v[40:43], v[132:135], v[186:189], v[40:43]
	v_mfma_f32_16x16x32_bf16 v[104:107], v[124:127], v[194:197], v[104:107]
	v_mfma_f32_16x16x32_bf16 v[36:39], v[132:135], v[194:197], v[36:39]
	v_mfma_f32_16x16x32_bf16 v[100:103], v[124:127], v[212:215], v[100:103]
	v_mfma_f32_16x16x32_bf16 v[32:35], v[132:135], v[212:215], v[32:35]
	v_mfma_f32_16x16x32_bf16 v[144:147], v[128:131], v[182:185], v[144:147]
	v_mfma_f32_16x16x32_bf16 v[48:51], v[136:139], v[182:185], v[48:51]
	v_mfma_f32_16x16x32_bf16 v[108:111], v[128:131], v[190:193], v[108:111]
	v_mfma_f32_16x16x32_bf16 v[40:43], v[136:139], v[190:193], v[40:43]
	v_mfma_f32_16x16x32_bf16 v[104:107], v[128:131], v[198:201], v[104:107]
	v_mfma_f32_16x16x32_bf16 v[36:39], v[136:139], v[198:201], v[36:39]
	v_mfma_f32_16x16x32_bf16 v[100:103], v[128:131], v[216:219], v[100:103]
	v_mfma_f32_16x16x32_bf16 v[32:35], v[136:139], v[216:219], v[32:35]
	s_barrier
; #define PG8_STAGE(bufoff, gbase, voff) do { _Pragma("unroll") for (int _i = 0; _i < 2; ++_i) \
;         __builtin_amdgcn_global_load_lds((const unsigned*)((const char*)(gbase) + (voff)[_i]), (PG8_LAS unsigned*)(lds + (bufoff) + ldsw + _i * 8192), 16, 0, 0); } while (0)
; #define PG8_LDA(dst, b, h) do { _Pragma("unroll") for (int m = 0; m < 4; ++m) _Pragma("unroll") for (int k = 0; k < 2; ++k) dst[m][k] = *(const PG8_LAS bf16x8*)(lds + PG8_SA(b, h) + aoff + m * 2048 + k * 1024); } while (0)
; #define PG8_MMA(ai, bj, At, Bt) do { __builtin_amdgcn_s_setprio(1); _Pragma("unroll") for (int m = 0; m < 4; ++m) _Pragma("unroll") for (int n = 0; n < 2; ++n) _Pragma("unroll") for (int k = 0; k < 2; ++k) \
;         acc[ai][bj][m][n] = __builtin_amdgcn_mfma_f32_16x16x32_bf16(Bt[n][k], At[m][k], acc[ai][bj][m][n], 0, 0, 0); __builtin_amdgcn_s_setprio(0); } while (0)
; #define PG8_WAIT_V(n) asm volatile("s_waitcnt vmcnt(" #n ")" ::: "memory")
; #define PG8_WAIT_L(n) asm volatile("s_waitcnt lgkmcnt(" #n ")" ::: "memory")
; #define PG8_BAR __builtin_amdgcn_s_barrier()
; #define PG8_SCHED __builtin_amdgcn_sched_barrier(0)
; template <class Epi, class Sched, bool ALIGN_EPI = false, bool SP2 = false>
; __device__ __forceinline__ void gemm_phase(PG8_LAS unsigned char* lds, const Gemm g, const Sched& S, const Epi& E) {
;     ...
;             PG8_LDA(At, 1, 1); PG8_STAGE(PG8_SB(1, 0), b3, voffB); PG8_STAGE(PG8_SB(1, 1), b3 + hstep, voffB); PG8_STAGE(PG8_SA(1, 0), a3, voffA);
;             PG8_WAIT_V(8); PG8_WAIT_L(0); PG8_BAR; PG8_MMA(1, 0, At, B0); PG8_MMA(1, 1, At, B1); PG8_BAR; PG8_SCHED;
	s_add_i32 s16, s26, s63
	v_lshl_add_u64 v[220:221], v[220:221], 0, s[38:39]
	s_mov_b32 m0, s16
	ds_read_b128 v[178:181], v209 offset:49152
	ds_read_b128 v[182:185], v209 offset:50176
	ds_read_b128 v[186:189], v209 offset:51200
	ds_read_b128 v[190:193], v209 offset:52224
	ds_read_b128 v[194:197], v209 offset:53248
	ds_read_b128 v[198:201], v209 offset:54272
	ds_read_b128 v[212:215], v209 offset:55296
	ds_read_b128 v[216:219], v209 offset:56320
	global_load_lds_dwordx4 v[220:221], off
	s_add_i32 m0, s16, 0x2000
	s_add_u32 s16, s18, 0x80080
	v_lshl_add_u64 v[220:221], v[222:223], 0, s[38:39]
	s_addc_u32 s17, s19, 0
	s_add_i32 s18, s27, s63
	global_load_lds_dwordx4 v[220:221], off
	v_lshl_add_u64 v[220:221], s[16:17], 0, v[162:163]
	s_mov_b32 m0, s18
	s_nop 0
	global_load_lds_dwordx4 v[220:221], off
	v_lshl_add_u64 v[220:221], s[16:17], 0, v[166:167]
	s_add_i32 m0, s18, 0x2000
	s_nop 0
	global_load_lds_dwordx4 v[220:221], off
	v_lshl_add_u64 v[220:221], v[224:225], 0, s[38:39]
	s_mov_b32 m0, s78
	s_nop 0
	global_load_lds_dwordx4 v[220:221], off
	v_lshl_add_u64 v[220:221], v[226:227], 0, s[38:39]
	s_mov_b32 m0, s79
	s_nop 0
	global_load_lds_dwordx4 v[220:221], off
	s_waitcnt vmcnt(8)
	s_waitcnt lgkmcnt(0)
	s_barrier
	s_waitcnt lgkmcnt(0)
	v_mfma_f32_16x16x32_bf16 v[92:95], v[96:99], v[178:181], v[92:95]
	v_mfma_f32_16x16x32_bf16 v[28:31], v[116:119], v[178:181], v[28:31]
	v_mfma_f32_16x16x32_bf16 v[88:91], v[96:99], v[186:189], v[88:91]
	v_mfma_f32_16x16x32_bf16 v[24:27], v[116:119], v[186:189], v[24:27]
	v_mfma_f32_16x16x32_bf16 v[84:87], v[96:99], v[194:197], v[84:87]
	v_mfma_f32_16x16x32_bf16 v[20:23], v[116:119], v[194:197], v[20:23]
	v_mfma_f32_16x16x32_bf16 v[76:79], v[96:99], v[212:215], v[76:79]
	v_mfma_f32_16x16x32_bf16 v[12:15], v[116:119], v[212:215], v[12:15]
	v_mfma_f32_16x16x32_bf16 v[92:95], v[112:115], v[182:185], v[92:95]
	v_mfma_f32_16x16x32_bf16 v[28:31], v[120:123], v[182:185], v[28:31]
	v_mfma_f32_16x16x32_bf16 v[88:91], v[112:115], v[190:193], v[88:91]
	v_mfma_f32_16x16x32_bf16 v[24:27], v[120:123], v[190:193], v[24:27]
	v_mfma_f32_16x16x32_bf16 v[84:87], v[112:115], v[198:201], v[84:87]
	v_mfma_f32_16x16x32_bf16 v[20:23], v[120:123], v[198:201], v[20:23]
	v_mfma_f32_16x16x32_bf16 v[76:79], v[112:115], v[216:219], v[76:79]
	v_mfma_f32_16x16x32_bf16 v[12:15], v[120:123], v[216:219], v[12:15]
	v_mfma_f32_16x16x32_bf16 v[80:83], v[124:127], v[178:181], v[80:83]
	v_mfma_f32_16x16x32_bf16 v[16:19], v[132:135], v[178:181], v[16:19]
	v_mfma_f32_16x16x32_bf16 v[72:75], v[124:127], v[186:189], v[72:75]
	v_mfma_f32_16x16x32_bf16 v[8:11], v[132:135], v[186:189], v[8:11]
	v_mfma_f32_16x16x32_bf16 v[68:71], v[124:127], v[194:197], v[68:71]
	v_mfma_f32_16x16x32_bf16 v[4:7], v[132:135], v[194:197], v[4:7]
	v_mfma_f32_16x16x32_bf16 v[64:67], v[124:127], v[212:215], v[64:67]
	v_mfma_f32_16x16x32_bf16 v[0:3], v[132:135], v[212:215], v[0:3]
	v_mfma_f32_16x16x32_bf16 v[80:83], v[128:131], v[182:185], v[80:83]
	v_mfma_f32_16x16x32_bf16 v[16:19], v[136:139], v[182:185], v[16:19]
	v_mfma_f32_16x16x32_bf16 v[72:75], v[128:131], v[190:193], v[72:75]
	v_mfma_f32_16x16x32_bf16 v[8:11], v[136:139], v[190:193], v[8:11]
	v_mfma_f32_16x16x32_bf16 v[68:71], v[128:131], v[198:201], v[68:71]
	v_mfma_f32_16x16x32_bf16 v[4:7], v[136:139], v[198:201], v[4:7]
	v_mfma_f32_16x16x32_bf16 v[64:67], v[128:131], v[216:219], v[64:67]
	v_mfma_f32_16x16x32_bf16 v[0:3], v[136:139], v[216:219], v[0:3]
	s_barrier
	s_add_i32 s25, s25, 2
	s_add_u32 s22, s22, 0x100
	s_addc_u32 s23, s23, 0
	s_cmp_gt_u32 s25, 29
	s_mov_b64 s[16:17], s[14:15]
	s_cbranch_scc0 .LBB0_1793
	s_and_b64 vcc, exec, s[40:41]
	s_cbranch_vccz .LBB0_1796
	s_barrier

; #define PG8_STAGE(bufoff, gbase, voff) do { _Pragma("unroll") for (int _i = 0; _i < 2; ++_i) \
;         __builtin_amdgcn_global_load_lds((const unsigned*)((const char*)(gbase) + (voff)[_i]), (PG8_LAS unsigned*)(lds + (bufoff) + ldsw + _i * 8192), 16, 0, 0); } while (0)
; #define PG8_LDA(dst, b, h) do { _Pragma("unroll") for (int m = 0; m < 4; ++m) _Pragma("unroll") for (int k = 0; k < 2; ++k) dst[m][k] = *(const PG8_LAS bf16x8*)(lds + PG8_SA(b, h) + aoff + m * 2048 + k * 1024); } while (0)
; #define PG8_LDB(dst, b, h) do { _Pragma("unroll") for (int n = 0; n < 2; ++n) _Pragma("unroll") for (int k = 0; k < 2; ++k) dst[n][k] = *(const PG8_LAS bf16x8*)(lds + PG8_SB(b, h) + boff + n * 2048 + k * 1024); } while (0)
; #define PG8_MMA(ai, bj, At, Bt) do { __builtin_amdgcn_s_setprio(1); _Pragma("unroll") for (int m = 0; m < 4; ++m) _Pragma("unroll") for (int n = 0; n < 2; ++n) _Pragma("unroll") for (int k = 0; k < 2; ++k) \
;         acc[ai][bj][m][n] = __builtin_amdgcn_mfma_f32_16x16x32_bf16(Bt[n][k], At[m][k], acc[ai][bj][m][n], 0, 0, 0); __builtin_amdgcn_s_setprio(0); } while (0)
; #define PG8_WAIT_V(n) asm volatile("s_waitcnt vmcnt(" #n ")" ::: "memory")
; #define PG8_WAIT_L(n) asm volatile("s_waitcnt lgkmcnt(" #n ")" ::: "memory")
; #define PG8_BAR __builtin_amdgcn_s_barrier()
; #define PG8_SCHED __builtin_amdgcn_sched_barrier(0)
; template <class Epi, class Sched, bool ALIGN_EPI = false, bool SP2 = false>
; __device__ __forceinline__ void gemm_phase(PG8_LAS unsigned char* lds, const Gemm g, const Sched& S, const Epi& E) {
;     ...
;             PG8_LDB(B0, 0, 0); PG8_LDB(B1, 0, 1); PG8_SCHED; PG8_LDA(At, 0, 0); PG8_STAGE(PG8_SA(1, 1), a1 + hstepA, voffA);
;             PG8_WAIT_V(8); PG8_WAIT_L(0); PG8_BAR; PG8_MMA(0, 0, At, B0); PG8_MMA(0, 1, At, B1); PG8_BAR; PG8_SCHED;
;             PG8_LDA(At, 0, 1); PG8_STAGE(PG8_SB(0, 0), b2, voffB); PG8_STAGE(PG8_SB(0, 1), b2 + hstep, voffB); PG8_STAGE(PG8_SA(0, 0), a2, voffA);
.LBB0_1937:
	ds_read_b128 v[128:131], v167
	ds_read_b128 v[132:135], v167 offset:1024
	ds_read_b128 v[152:155], v167 offset:2048
	ds_read_b128 v[156:159], v167 offset:3072
	ds_read_b128 v[160:163], v168
	ds_read_b128 v[172:175], v168 offset:1024
	ds_read_b128 v[176:179], v168 offset:2048
	ds_read_b128 v[180:183], v168 offset:3072
	s_add_u32 s26, s24, 0x100
	s_addc_u32 s27, s25, 0
	s_cmpk_eq_i32 s56, 0x54
	s_cselect_b32 s31, s15, s27
	s_cselect_b32 s30, s14, s26
	s_cselect_b32 s29, s23, s55
	s_cselect_b32 s28, s22, s54
	v_lshl_add_u64 v[218:219], s[24:25], 0, v[144:145]
	s_add_i32 m0, s37, 0xc000
	ds_read_b128 v[184:187], v169
	ds_read_b128 v[188:191], v169 offset:1024
	ds_read_b128 v[192:195], v169 offset:2048
	ds_read_b128 v[196:199], v169 offset:3072
	ds_read_b128 v[200:203], v169 offset:4096
	ds_read_b128 v[206:209], v169 offset:5120
	ds_read_b128 v[210:213], v169 offset:6144
	ds_read_b128 v[214:217], v169 offset:7168
	global_load_lds_dwordx4 v[218:219], off
	v_lshl_add_u64 v[218:219], s[24:25], 0, v[146:147]
	s_add_i32 m0, s37, 0xe000
	s_nop 0
	global_load_lds_dwordx4 v[218:219], off
	s_waitcnt vmcnt(8)
	s_waitcnt lgkmcnt(0)
	s_barrier
	s_waitcnt lgkmcnt(0)
	v_mfma_f32_16x16x32_bf16 v[124:127], v[128:131], v[184:187], v[124:127]
	v_mfma_f32_16x16x32_bf16 v[120:123], v[152:155], v[184:187], v[120:123]
	v_mfma_f32_16x16x32_bf16 v[108:111], v[128:131], v[192:195], v[108:111]
	v_mfma_f32_16x16x32_bf16 v[104:107], v[152:155], v[192:195], v[104:107]
	v_mfma_f32_16x16x32_bf16 v[92:95], v[128:131], v[200:203], v[92:95]
	v_mfma_f32_16x16x32_bf16 v[88:91], v[152:155], v[200:203], v[88:91]
	v_mfma_f32_16x16x32_bf16 v[76:79], v[128:131], v[210:213], v[76:79]
	v_mfma_f32_16x16x32_bf16 v[72:75], v[152:155], v[210:213], v[72:75]
	v_mfma_f32_16x16x32_bf16 v[124:127], v[132:135], v[188:191], v[124:127]
	v_mfma_f32_16x16x32_bf16 v[120:123], v[156:159], v[188:191], v[120:123]
	v_mfma_f32_16x16x32_bf16 v[108:111], v[132:135], v[196:199], v[108:111]
	v_mfma_f32_16x16x32_bf16 v[104:107], v[156:159], v[196:199], v[104:107]
	v_mfma_f32_16x16x32_bf16 v[92:95], v[132:135], v[206:209], v[92:95]
	v_mfma_f32_16x16x32_bf16 v[88:91], v[156:159], v[206:209], v[88:91]
	v_mfma_f32_16x16x32_bf16 v[76:79], v[132:135], v[214:217], v[76:79]
	v_mfma_f32_16x16x32_bf16 v[72:75], v[156:159], v[214:217], v[72:75]
	v_mfma_f32_16x16x32_bf16 v[116:119], v[160:163], v[184:187], v[116:119]
	v_mfma_f32_16x16x32_bf16 v[112:115], v[176:179], v[184:187], v[112:115]
	v_mfma_f32_16x16x32_bf16 v[100:103], v[160:163], v[192:195], v[100:103]
	v_mfma_f32_16x16x32_bf16 v[96:99], v[176:179], v[192:195], v[96:99]
	v_mfma_f32_16x16x32_bf16 v[84:87], v[160:163], v[200:203], v[84:87]
	v_mfma_f32_16x16x32_bf16 v[80:83], v[176:179], v[200:203], v[80:83]
	v_mfma_f32_16x16x32_bf16 v[68:71], v[160:163], v[210:213], v[68:71]
	v_mfma_f32_16x16x32_bf16 v[64:67], v[176:179], v[210:213], v[64:67]
	v_mfma_f32_16x16x32_bf16 v[116:119], v[172:175], v[188:191], v[116:119]
	v_mfma_f32_16x16x32_bf16 v[112:115], v[180:183], v[188:191], v[112:115]
	v_mfma_f32_16x16x32_bf16 v[100:103], v[172:175], v[196:199], v[100:103]
	v_mfma_f32_16x16x32_bf16 v[96:99], v[180:183], v[196:199], v[96:99]
	v_mfma_f32_16x16x32_bf16 v[84:87], v[172:175], v[206:209], v[84:87]
	v_mfma_f32_16x16x32_bf16 v[80:83], v[180:183], v[206:209], v[80:83]
	v_mfma_f32_16x16x32_bf16 v[68:71], v[172:175], v[214:217], v[68:71]
	v_mfma_f32_16x16x32_bf16 v[64:67], v[180:183], v[214:217], v[64:67]
	s_barrier
	s_add_i32 s24, s50, s36
	v_lshl_add_u64 v[218:219], s[28:29], 0, v[138:139]
	s_mov_b32 m0, s24
	ds_read_b128 v[184:187], v169 offset:16384
	ds_read_b128 v[188:191], v169 offset:17408
	ds_read_b128 v[192:195], v169 offset:18432
	ds_read_b128 v[196:199], v169 offset:19456
	ds_read_b128 v[200:203], v169 offset:20480
	ds_read_b128 v[206:209], v169 offset:21504
	ds_read_b128 v[210:213], v169 offset:22528
	ds_read_b128 v[214:217], v169 offset:23552
	global_load_lds_dwordx4 v[218:219], off
	s_add_i32 m0, s24, 0x2000
	s_add_u32 s24, s28, 0x160000
	v_lshl_add_u64 v[220:221], s[28:29], 0, v[142:143]
	s_addc_u32 s25, s29, 0
	s_add_i32 s57, s51, s36
	global_load_lds_dwordx4 v[220:221], off
	v_lshl_add_u64 v[222:223], s[24:25], 0, v[138:139]
	s_mov_b32 m0, s57
	v_lshl_add_u64 v[224:225], s[30:31], 0, v[140:141]
	global_load_lds_dwordx4 v[222:223], off
	v_lshl_add_u64 v[222:223], s[24:25], 0, v[142:143]
	s_add_i32 m0, s57, 0x2000
	s_nop 0
	global_load_lds_dwordx4 v[222:223], off
	v_lshl_add_u64 v[222:223], s[30:31], 0, v[136:137]
	s_mov_b32 m0, s37
	s_nop 0
	global_load_lds_dwordx4 v[222:223], off
	s_mov_b32 m0, s38
	s_nop 0
	global_load_lds_dwordx4 v[224:225], off
	s_waitcnt vmcnt(8)
	s_waitcnt lgkmcnt(0)
	s_barrier
; #define PG8_STAGE(bufoff, gbase, voff) do { _Pragma("unroll") for (int _i = 0; _i < 2; ++_i) \
;         __builtin_amdgcn_global_load_lds((const unsigned*)((const char*)(gbase) + (voff)[_i]), (PG8_LAS unsigned*)(lds + (bufoff) + ldsw + _i * 8192), 16, 0, 0); } while (0)
; #define PG8_LDA(dst, b, h) do { _Pragma("unroll") for (int m = 0; m < 4; ++m) _Pragma("unroll") for (int k = 0; k < 2; ++k) dst[m][k] = *(const PG8_LAS bf16x8*)(lds + PG8_SA(b, h) + aoff + m * 2048 + k * 1024); } while (0)
; #define PG8_LDB(dst, b, h) do { _Pragma("unroll") for (int n = 0; n < 2; ++n) _Pragma("unroll") for (int k = 0; k < 2; ++k) dst[n][k] = *(const PG8_LAS bf16x8*)(lds + PG8_SB(b, h) + boff + n * 2048 + k * 1024); } while (0)
; #define PG8_MMA(ai, bj, At, Bt) do { __builtin_amdgcn_s_setprio(1); _Pragma("unroll") for (int m = 0; m < 4; ++m) _Pragma("unroll") for (int n = 0; n < 2; ++n) _Pragma("unroll") for (int k = 0; k < 2; ++k) \
;         acc[ai][bj][m][n] = __builtin_amdgcn_mfma_f32_16x16x32_bf16(Bt[n][k], At[m][k], acc[ai][bj][m][n], 0, 0, 0); __builtin_amdgcn_s_setprio(0); } while (0)
; #define PG8_WAIT_V(n) asm volatile("s_waitcnt vmcnt(" #n ")" ::: "memory")
; #define PG8_WAIT_L(n) asm volatile("s_waitcnt lgkmcnt(" #n ")" ::: "memory")
; #define PG8_BAR __builtin_amdgcn_s_barrier()
; #define PG8_SCHED __builtin_amdgcn_sched_barrier(0)
; template <class Epi, class Sched, bool ALIGN_EPI = false, bool SP2 = false>
; __device__ __forceinline__ void gemm_phase(PG8_LAS unsigned char* lds, const Gemm g, const Sched& S, const Epi& E) {
;     ...
;             PG8_WAIT_V(8); PG8_WAIT_L(0); PG8_BAR; PG8_MMA(1, 0, At, B0); PG8_MMA(1, 1, At, B1); PG8_BAR; PG8_SCHED;
;             PG8_LDB(B0, 1, 0); PG8_LDB(B1, 1, 1); PG8_SCHED; PG8_LDA(At, 1, 0); PG8_STAGE(PG8_SA(0, 1), a2 + hstepA, voffA);
;             PG8_WAIT_V(8); PG8_WAIT_L(0); PG8_BAR; PG8_MMA(0, 0, At, B0); PG8_MMA(0, 1, At, B1); PG8_BAR; PG8_SCHED;
	s_waitcnt lgkmcnt(0)
	v_mfma_f32_16x16x32_bf16 v[60:63], v[128:131], v[184:187], v[60:63]
	v_mfma_f32_16x16x32_bf16 v[56:59], v[152:155], v[184:187], v[56:59]
	v_mfma_f32_16x16x32_bf16 v[44:47], v[128:131], v[192:195], v[44:47]
	v_mfma_f32_16x16x32_bf16 v[40:43], v[152:155], v[192:195], v[40:43]
	v_mfma_f32_16x16x32_bf16 v[28:31], v[128:131], v[200:203], v[28:31]
	v_mfma_f32_16x16x32_bf16 v[24:27], v[152:155], v[200:203], v[24:27]
	v_mfma_f32_16x16x32_bf16 v[12:15], v[128:131], v[210:213], v[12:15]
	v_mfma_f32_16x16x32_bf16 v[8:11], v[152:155], v[210:213], v[8:11]
	v_mfma_f32_16x16x32_bf16 v[60:63], v[132:135], v[188:191], v[60:63]
	v_mfma_f32_16x16x32_bf16 v[56:59], v[156:159], v[188:191], v[56:59]
	v_mfma_f32_16x16x32_bf16 v[44:47], v[132:135], v[196:199], v[44:47]
	v_mfma_f32_16x16x32_bf16 v[40:43], v[156:159], v[196:199], v[40:43]
	v_mfma_f32_16x16x32_bf16 v[28:31], v[132:135], v[206:209], v[28:31]
	v_mfma_f32_16x16x32_bf16 v[24:27], v[156:159], v[206:209], v[24:27]
	v_mfma_f32_16x16x32_bf16 v[12:15], v[132:135], v[214:217], v[12:15]
	v_mfma_f32_16x16x32_bf16 v[8:11], v[156:159], v[214:217], v[8:11]
	v_mfma_f32_16x16x32_bf16 v[52:55], v[160:163], v[184:187], v[52:55]
	v_mfma_f32_16x16x32_bf16 v[48:51], v[176:179], v[184:187], v[48:51]
	v_mfma_f32_16x16x32_bf16 v[36:39], v[160:163], v[192:195], v[36:39]
	v_mfma_f32_16x16x32_bf16 v[32:35], v[176:179], v[192:195], v[32:35]
	v_mfma_f32_16x16x32_bf16 v[20:23], v[160:163], v[200:203], v[20:23]
	v_mfma_f32_16x16x32_bf16 v[16:19], v[176:179], v[200:203], v[16:19]
	v_mfma_f32_16x16x32_bf16 v[4:7], v[160:163], v[210:213], v[4:7]
	v_mfma_f32_16x16x32_bf16 v[0:3], v[176:179], v[210:213], v[0:3]
	v_mfma_f32_16x16x32_bf16 v[52:55], v[172:175], v[188:191], v[52:55]
	v_mfma_f32_16x16x32_bf16 v[48:51], v[180:183], v[188:191], v[48:51]
	v_mfma_f32_16x16x32_bf16 v[36:39], v[172:175], v[196:199], v[36:39]
	v_mfma_f32_16x16x32_bf16 v[32:35], v[180:183], v[196:199], v[32:35]
	v_mfma_f32_16x16x32_bf16 v[20:23], v[172:175], v[206:209], v[20:23]
	v_mfma_f32_16x16x32_bf16 v[16:19], v[180:183], v[206:209], v[16:19]
	v_mfma_f32_16x16x32_bf16 v[4:7], v[172:175], v[214:217], v[4:7]
	v_mfma_f32_16x16x32_bf16 v[0:3], v[180:183], v[214:217], v[0:3]
	s_barrier
	s_add_i32 s57, 0, 0x18000
	s_add_i32 s58, 0, 0x1c000
	v_add_u32_e32 v156, s57, v165
	v_add_u32_e32 v171, s58, v165
	ds_read_b128 v[128:131], v156
	ds_read_b128 v[132:135], v156 offset:1024
	ds_read_b128 v[152:155], v156 offset:2048
	ds_read_b128 v[156:159], v156 offset:3072
	ds_read_b128 v[160:163], v171
	ds_read_b128 v[172:175], v171 offset:1024
	ds_read_b128 v[176:179], v171 offset:2048
	ds_read_b128 v[180:183], v171 offset:3072
	s_add_u32 s24, s30, 0x160000
	s_addc_u32 s25, s31, 0
	s_mov_b32 m0, s39
	v_lshl_add_u64 v[226:227], s[24:25], 0, v[136:137]
	ds_read_b128 v[184:187], v169 offset:32768
	ds_read_b128 v[188:191], v169 offset:33792
	ds_read_b128 v[192:195], v169 offset:34816
	ds_read_b128 v[196:199], v169 offset:35840
	ds_read_b128 v[200:203], v169 offset:36864
	ds_read_b128 v[206:209], v169 offset:37888
	ds_read_b128 v[210:213], v169 offset:38912
	ds_read_b128 v[214:217], v169 offset:39936
	global_load_lds_dwordx4 v[226:227], off
	v_lshl_add_u64 v[226:227], s[24:25], 0, v[140:141]
	s_mov_b32 m0, s40
	s_nop 0
	global_load_lds_dwordx4 v[226:227], off
	s_waitcnt vmcnt(8)
	s_waitcnt lgkmcnt(0)
	s_barrier
	s_waitcnt lgkmcnt(0)
	v_mfma_f32_16x16x32_bf16 v[124:127], v[128:131], v[184:187], v[124:127]
	v_mfma_f32_16x16x32_bf16 v[120:123], v[152:155], v[184:187], v[120:123]
	v_mfma_f32_16x16x32_bf16 v[108:111], v[128:131], v[192:195], v[108:111]
	v_mfma_f32_16x16x32_bf16 v[104:107], v[152:155], v[192:195], v[104:107]
	v_mfma_f32_16x16x32_bf16 v[92:95], v[128:131], v[200:203], v[92:95]
	v_mfma_f32_16x16x32_bf16 v[88:91], v[152:155], v[200:203], v[88:91]
	v_mfma_f32_16x16x32_bf16 v[76:79], v[128:131], v[210:213], v[76:79]
	v_mfma_f32_16x16x32_bf16 v[72:75], v[152:155], v[210:213], v[72:75]
	v_mfma_f32_16x16x32_bf16 v[124:127], v[132:135], v[188:191], v[124:127]
	v_mfma_f32_16x16x32_bf16 v[120:123], v[156:159], v[188:191], v[120:123]
	v_mfma_f32_16x16x32_bf16 v[108:111], v[132:135], v[196:199], v[108:111]
	v_mfma_f32_16x16x32_bf16 v[104:107], v[156:159], v[196:199], v[104:107]
	v_mfma_f32_16x16x32_bf16 v[92:95], v[132:135], v[206:209], v[92:95]
	v_mfma_f32_16x16x32_bf16 v[88:91], v[156:159], v[206:209], v[88:91]
	v_mfma_f32_16x16x32_bf16 v[76:79], v[132:135], v[214:217], v[76:79]
	v_mfma_f32_16x16x32_bf16 v[72:75], v[156:159], v[214:217], v[72:75]
	v_mfma_f32_16x16x32_bf16 v[116:119], v[160:163], v[184:187], v[116:119]
	v_mfma_f32_16x16x32_bf16 v[112:115], v[176:179], v[184:187], v[112:115]
	v_mfma_f32_16x16x32_bf16 v[100:103], v[160:163], v[192:195], v[100:103]
	v_mfma_f32_16x16x32_bf16 v[96:99], v[176:179], v[192:195], v[96:99]
	v_mfma_f32_16x16x32_bf16 v[84:87], v[160:163], v[200:203], v[84:87]
	v_mfma_f32_16x16x32_bf16 v[80:83], v[176:179], v[200:203], v[80:83]
	v_mfma_f32_16x16x32_bf16 v[68:71], v[160:163], v[210:213], v[68:71]
	v_mfma_f32_16x16x32_bf16 v[64:67], v[176:179], v[210:213], v[64:67]
	v_mfma_f32_16x16x32_bf16 v[116:119], v[172:175], v[188:191], v[116:119]
	v_mfma_f32_16x16x32_bf16 v[112:115], v[180:183], v[188:191], v[112:115]
	v_mfma_f32_16x16x32_bf16 v[100:103], v[172:175], v[196:199], v[100:103]
	v_mfma_f32_16x16x32_bf16 v[96:99], v[180:183], v[196:199], v[96:99]
	v_mfma_f32_16x16x32_bf16 v[84:87], v[172:175], v[206:209], v[84:87]
	v_mfma_f32_16x16x32_bf16 v[80:83], v[180:183], v[206:209], v[80:83]
	v_mfma_f32_16x16x32_bf16 v[68:71], v[172:175], v[214:217], v[68:71]
	v_mfma_f32_16x16x32_bf16 v[64:67], v[180:183], v[214:217], v[64:67]
	s_barrier
; #define PG8_STAGE(bufoff, gbase, voff) do { _Pragma("unroll") for (int _i = 0; _i < 2; ++_i) \
;         __builtin_amdgcn_global_load_lds((const unsigned*)((const char*)(gbase) + (voff)[_i]), (PG8_LAS unsigned*)(lds + (bufoff) + ldsw + _i * 8192), 16, 0, 0); } while (0)
; #define PG8_LDA(dst, b, h) do { _Pragma("unroll") for (int m = 0; m < 4; ++m) _Pragma("unroll") for (int k = 0; k < 2; ++k) dst[m][k] = *(const PG8_LAS bf16x8*)(lds + PG8_SA(b, h) + aoff + m * 2048 + k * 1024); } while (0)
; #define PG8_MMA(ai, bj, At, Bt) do { __builtin_amdgcn_s_setprio(1); _Pragma("unroll") for (int m = 0; m < 4; ++m) _Pragma("unroll") for (int n = 0; n < 2; ++n) _Pragma("unroll") for (int k = 0; k < 2; ++k) \
;         acc[ai][bj][m][n] = __builtin_amdgcn_mfma_f32_16x16x32_bf16(Bt[n][k], At[m][k], acc[ai][bj][m][n], 0, 0, 0); __builtin_amdgcn_s_setprio(0); } while (0)
; #define PG8_WAIT_V(n) asm volatile("s_waitcnt vmcnt(" #n ")" ::: "memory")
; #define PG8_WAIT_L(n) asm volatile("s_waitcnt lgkmcnt(" #n ")" ::: "memory")
; #define PG8_BAR __builtin_amdgcn_s_barrier()
; #define PG8_SCHED __builtin_amdgcn_sched_barrier(0)
; template <class Epi, class Sched, bool ALIGN_EPI = false, bool SP2 = false>
; __device__ __forceinline__ void gemm_phase(PG8_LAS unsigned char* lds, const Gemm g, const Sched& S, const Epi& E) {
;     ...
;             PG8_LDA(At, 1, 1); PG8_STAGE(PG8_SB(1, 0), b3, voffB); PG8_STAGE(PG8_SB(1, 1), b3 + hstep, voffB); PG8_STAGE(PG8_SA(1, 0), a3, voffA);
;             PG8_WAIT_V(8); PG8_WAIT_L(0); PG8_BAR; PG8_MMA(1, 0, At, B0); PG8_MMA(1, 1, At, B1); PG8_BAR; PG8_SCHED;
	s_add_i32 s24, s57, s36
	v_lshl_add_u64 v[218:219], v[218:219], 0, s[18:19]
	s_mov_b32 m0, s24
	ds_read_b128 v[184:187], v169 offset:49152
	ds_read_b128 v[188:191], v169 offset:50176
	ds_read_b128 v[192:195], v169 offset:51200
	ds_read_b128 v[196:199], v169 offset:52224
	ds_read_b128 v[200:203], v169 offset:53248
	ds_read_b128 v[206:209], v169 offset:54272
	ds_read_b128 v[210:213], v169 offset:55296
	ds_read_b128 v[214:217], v169 offset:56320
	global_load_lds_dwordx4 v[218:219], off
	s_add_i32 m0, s24, 0x2000
	s_add_u32 s24, s28, 0x160080
	v_lshl_add_u64 v[218:219], v[220:221], 0, s[18:19]
	s_addc_u32 s25, s29, 0
	s_add_i32 s28, s58, s36
	global_load_lds_dwordx4 v[218:219], off
	v_lshl_add_u64 v[218:219], s[24:25], 0, v[138:139]
	s_mov_b32 m0, s28
	s_nop 0
	global_load_lds_dwordx4 v[218:219], off
	v_lshl_add_u64 v[218:219], s[24:25], 0, v[142:143]
	s_add_i32 m0, s28, 0x2000
	s_nop 0
	global_load_lds_dwordx4 v[218:219], off
	v_lshl_add_u64 v[218:219], v[222:223], 0, s[18:19]
	s_mov_b32 m0, s45
	s_nop 0
	global_load_lds_dwordx4 v[218:219], off
	v_lshl_add_u64 v[218:219], v[224:225], 0, s[18:19]
	s_mov_b32 m0, s46
	s_nop 0
	global_load_lds_dwordx4 v[218:219], off
	s_waitcnt vmcnt(8)
	s_waitcnt lgkmcnt(0)
	s_barrier
	s_waitcnt lgkmcnt(0)
	v_mfma_f32_16x16x32_bf16 v[60:63], v[128:131], v[184:187], v[60:63]
	v_mfma_f32_16x16x32_bf16 v[56:59], v[152:155], v[184:187], v[56:59]
	v_mfma_f32_16x16x32_bf16 v[44:47], v[128:131], v[192:195], v[44:47]
	v_mfma_f32_16x16x32_bf16 v[40:43], v[152:155], v[192:195], v[40:43]
	v_mfma_f32_16x16x32_bf16 v[28:31], v[128:131], v[200:203], v[28:31]
	v_mfma_f32_16x16x32_bf16 v[24:27], v[152:155], v[200:203], v[24:27]
	v_mfma_f32_16x16x32_bf16 v[12:15], v[128:131], v[210:213], v[12:15]
	v_mfma_f32_16x16x32_bf16 v[8:11], v[152:155], v[210:213], v[8:11]
	v_mfma_f32_16x16x32_bf16 v[60:63], v[132:135], v[188:191], v[60:63]
	v_mfma_f32_16x16x32_bf16 v[56:59], v[156:159], v[188:191], v[56:59]
	v_mfma_f32_16x16x32_bf16 v[44:47], v[132:135], v[196:199], v[44:47]
	v_mfma_f32_16x16x32_bf16 v[40:43], v[156:159], v[196:199], v[40:43]
	v_mfma_f32_16x16x32_bf16 v[28:31], v[132:135], v[206:209], v[28:31]
	v_mfma_f32_16x16x32_bf16 v[24:27], v[156:159], v[206:209], v[24:27]
	v_mfma_f32_16x16x32_bf16 v[12:15], v[132:135], v[214:217], v[12:15]
	v_mfma_f32_16x16x32_bf16 v[8:11], v[156:159], v[214:217], v[8:11]
	v_mfma_f32_16x16x32_bf16 v[52:55], v[160:163], v[184:187], v[52:55]
	v_mfma_f32_16x16x32_bf16 v[48:51], v[176:179], v[184:187], v[48:51]
	v_mfma_f32_16x16x32_bf16 v[36:39], v[160:163], v[192:195], v[36:39]
	v_mfma_f32_16x16x32_bf16 v[32:35], v[176:179], v[192:195], v[32:35]
	v_mfma_f32_16x16x32_bf16 v[20:23], v[160:163], v[200:203], v[20:23]
	v_mfma_f32_16x16x32_bf16 v[16:19], v[176:179], v[200:203], v[16:19]
	v_mfma_f32_16x16x32_bf16 v[4:7], v[160:163], v[210:213], v[4:7]
	v_mfma_f32_16x16x32_bf16 v[0:3], v[176:179], v[210:213], v[0:3]
	v_mfma_f32_16x16x32_bf16 v[52:55], v[172:175], v[188:191], v[52:55]
	v_mfma_f32_16x16x32_bf16 v[48:51], v[180:183], v[188:191], v[48:51]
	v_mfma_f32_16x16x32_bf16 v[36:39], v[172:175], v[196:199], v[36:39]
	v_mfma_f32_16x16x32_bf16 v[32:35], v[180:183], v[196:199], v[32:35]
	v_mfma_f32_16x16x32_bf16 v[20:23], v[172:175], v[206:209], v[20:23]
	v_mfma_f32_16x16x32_bf16 v[16:19], v[180:183], v[206:209], v[16:19]
	v_mfma_f32_16x16x32_bf16 v[4:7], v[172:175], v[214:217], v[4:7]
	v_mfma_f32_16x16x32_bf16 v[0:3], v[180:183], v[214:217], v[0:3]
	s_barrier
	s_add_i32 s56, s56, 2
	s_add_u32 s54, s54, 0x100
	s_addc_u32 s55, s55, 0
	s_cmpk_gt_u32 s56, 0x55
	s_mov_b64 s[24:25], s[26:27]
	s_cbranch_scc0 .LBB0_1937
	s_and_b64 vcc, exec, s[20:21]
	s_cbranch_vccz .LBB0_1940
	s_barrier

; #define PG8_STAGE(bufoff, gbase, voff) do { _Pragma("unroll") for (int _i = 0; _i < 2; ++_i) \
;         __builtin_amdgcn_global_load_lds((const unsigned*)((const char*)(gbase) + (voff)[_i]), (PG8_LAS unsigned*)(lds + (bufoff) + ldsw + _i * 8192), 16, 0, 0); } while (0)
; #define PG8_LDA(dst, b, h) do { _Pragma("unroll") for (int m = 0; m < 4; ++m) _Pragma("unroll") for (int k = 0; k < 2; ++k) dst[m][k] = *(const PG8_LAS bf16x8*)(lds + PG8_SA(b, h) + aoff + m * 2048 + k * 1024); } while (0)
; #define PG8_LDB(dst, b, h) do { _Pragma("unroll") for (int n = 0; n < 2; ++n) _Pragma("unroll") for (int k = 0; k < 2; ++k) dst[n][k] = *(const PG8_LAS bf16x8*)(lds + PG8_SB(b, h) + boff + n * 2048 + k * 1024); } while (0)
; #define PG8_MMA(ai, bj, At, Bt) do { __builtin_amdgcn_s_setprio(1); _Pragma("unroll") for (int m = 0; m < 4; ++m) _Pragma("unroll") for (int n = 0; n < 2; ++n) _Pragma("unroll") for (int k = 0; k < 2; ++k) \
;         acc[ai][bj][m][n] = __builtin_amdgcn_mfma_f32_16x16x32_bf16(Bt[n][k], At[m][k], acc[ai][bj][m][n], 0, 0, 0); __builtin_amdgcn_s_setprio(0); } while (0)
; #define PG8_WAIT_V(n) asm volatile("s_waitcnt vmcnt(" #n ")" ::: "memory")
; #define PG8_WAIT_L(n) asm volatile("s_waitcnt lgkmcnt(" #n ")" ::: "memory")
; #define PG8_BAR __builtin_amdgcn_s_barrier()
; #define PG8_SCHED __builtin_amdgcn_sched_barrier(0)
; template <class Epi, class Sched, bool ALIGN_EPI = false, bool SP2 = false>
; __device__ __forceinline__ void gemm_phase(PG8_LAS unsigned char* lds, const Gemm g, const Sched& S, const Epi& E) {
;     ...
;             PG8_LDB(B0, 0, 0); PG8_LDB(B1, 0, 1); PG8_SCHED; PG8_LDA(At, 0, 0); PG8_STAGE(PG8_SA(1, 1), a1 + hstepA, voffA);
;             PG8_WAIT_V(8); PG8_WAIT_L(0); PG8_BAR; PG8_MMA(0, 0, At, B0); PG8_MMA(0, 1, At, B1); PG8_BAR; PG8_SCHED;
;             PG8_LDA(At, 0, 1); PG8_STAGE(PG8_SB(0, 0), b2, voffB); PG8_STAGE(PG8_SB(0, 1), b2 + hstep, voffB); PG8_STAGE(PG8_SA(0, 0), a2, voffA);
.LBB0_2021:
	ds_read_b128 v[160:163], v154
	ds_read_b128 v[164:167], v154 offset:1024
	ds_read_b128 v[168:171], v154 offset:2048
	ds_read_b128 v[172:175], v154 offset:3072
	ds_read_b128 v[176:179], v155
	ds_read_b128 v[180:183], v155 offset:1024
	ds_read_b128 v[184:187], v155 offset:2048
	ds_read_b128 v[188:191], v155 offset:3072
	s_add_u32 s28, s26, 0xfff80080
	s_addc_u32 s29, s27, -1
	s_cmp_eq_u32 s54, 28
	s_cselect_b32 s31, s7, s29
	s_cselect_b32 s30, s19, s28
	s_cselect_b32 s29, s17, s53
	s_cselect_b32 s28, s51, s52
	v_lshl_add_u64 v[146:147], s[26:27], 0, v[138:139]
	s_add_i32 m0, s25, 0xc000
	ds_read_b128 v[192:195], v156
	ds_read_b128 v[196:199], v156 offset:1024
	ds_read_b128 v[200:203], v156 offset:2048
	ds_read_b128 v[206:209], v156 offset:3072
	ds_read_b128 v[210:213], v156 offset:4096
	ds_read_b128 v[214:217], v156 offset:5120
	ds_read_b128 v[218:221], v156 offset:6144
	ds_read_b128 v[222:225], v156 offset:7168
	global_load_lds_dwordx4 v[146:147], off
	v_lshl_add_u64 v[146:147], s[26:27], 0, v[140:141]
	s_add_i32 m0, s25, 0xe000
	s_nop 0
	global_load_lds_dwordx4 v[146:147], off
	s_waitcnt vmcnt(8)
	s_waitcnt lgkmcnt(0)
	s_barrier
	s_waitcnt lgkmcnt(0)
	v_mfma_f32_16x16x32_bf16 v[124:127], v[160:163], v[192:195], v[124:127]
	v_mfma_f32_16x16x32_bf16 v[120:123], v[168:171], v[192:195], v[120:123]
	v_mfma_f32_16x16x32_bf16 v[108:111], v[160:163], v[200:203], v[108:111]
	v_mfma_f32_16x16x32_bf16 v[104:107], v[168:171], v[200:203], v[104:107]
	v_mfma_f32_16x16x32_bf16 v[92:95], v[160:163], v[210:213], v[92:95]
	v_mfma_f32_16x16x32_bf16 v[88:91], v[168:171], v[210:213], v[88:91]
	v_mfma_f32_16x16x32_bf16 v[76:79], v[160:163], v[218:221], v[76:79]
	v_mfma_f32_16x16x32_bf16 v[72:75], v[168:171], v[218:221], v[72:75]
	v_mfma_f32_16x16x32_bf16 v[124:127], v[164:167], v[196:199], v[124:127]
	v_mfma_f32_16x16x32_bf16 v[120:123], v[172:175], v[196:199], v[120:123]
	v_mfma_f32_16x16x32_bf16 v[108:111], v[164:167], v[206:209], v[108:111]
	v_mfma_f32_16x16x32_bf16 v[104:107], v[172:175], v[206:209], v[104:107]
	v_mfma_f32_16x16x32_bf16 v[92:95], v[164:167], v[214:217], v[92:95]
	v_mfma_f32_16x16x32_bf16 v[88:91], v[172:175], v[214:217], v[88:91]
	v_mfma_f32_16x16x32_bf16 v[76:79], v[164:167], v[222:225], v[76:79]
	v_mfma_f32_16x16x32_bf16 v[72:75], v[172:175], v[222:225], v[72:75]
	v_mfma_f32_16x16x32_bf16 v[116:119], v[176:179], v[192:195], v[116:119]
	v_mfma_f32_16x16x32_bf16 v[112:115], v[184:187], v[192:195], v[112:115]
	v_mfma_f32_16x16x32_bf16 v[100:103], v[176:179], v[200:203], v[100:103]
	v_mfma_f32_16x16x32_bf16 v[96:99], v[184:187], v[200:203], v[96:99]
	v_mfma_f32_16x16x32_bf16 v[84:87], v[176:179], v[210:213], v[84:87]
	v_mfma_f32_16x16x32_bf16 v[80:83], v[184:187], v[210:213], v[80:83]
	v_mfma_f32_16x16x32_bf16 v[68:71], v[176:179], v[218:221], v[68:71]
	v_mfma_f32_16x16x32_bf16 v[64:67], v[184:187], v[218:221], v[64:67]
	v_mfma_f32_16x16x32_bf16 v[116:119], v[180:183], v[196:199], v[116:119]
	v_mfma_f32_16x16x32_bf16 v[112:115], v[188:191], v[196:199], v[112:115]
	v_mfma_f32_16x16x32_bf16 v[100:103], v[180:183], v[206:209], v[100:103]
	v_mfma_f32_16x16x32_bf16 v[96:99], v[188:191], v[206:209], v[96:99]
	v_mfma_f32_16x16x32_bf16 v[84:87], v[180:183], v[214:217], v[84:87]
	v_mfma_f32_16x16x32_bf16 v[80:83], v[188:191], v[214:217], v[80:83]
	v_mfma_f32_16x16x32_bf16 v[68:71], v[180:183], v[222:225], v[68:71]
	v_mfma_f32_16x16x32_bf16 v[64:67], v[188:191], v[222:225], v[64:67]
	s_barrier
	s_add_i32 s55, s49, s36
	v_lshl_add_u64 v[146:147], s[28:29], 0, v[132:133]
	s_mov_b32 m0, s55
	ds_read_b128 v[192:195], v156 offset:16384
	ds_read_b128 v[196:199], v156 offset:17408
	ds_read_b128 v[200:203], v156 offset:18432
	ds_read_b128 v[206:209], v156 offset:19456
	ds_read_b128 v[210:213], v156 offset:20480
	ds_read_b128 v[214:217], v156 offset:21504
	ds_read_b128 v[218:221], v156 offset:22528
	ds_read_b128 v[222:225], v156 offset:23552
	global_load_lds_dwordx4 v[146:147], off
	s_add_i32 m0, s55, 0x2000
	s_add_u32 s56, s28, 0x80000
	v_lshl_add_u64 v[150:151], s[28:29], 0, v[128:129]
	s_addc_u32 s57, s29, 0
	s_add_i32 s55, s50, s36
	global_load_lds_dwordx4 v[150:151], off
	v_lshl_add_u64 v[226:227], s[56:57], 0, v[132:133]
	s_mov_b32 m0, s55
	v_lshl_add_u64 v[228:229], s[30:31], 0, v[130:131]
	global_load_lds_dwordx4 v[226:227], off
	v_lshl_add_u64 v[226:227], s[56:57], 0, v[128:129]
	s_add_i32 m0, s55, 0x2000
	s_nop 0
	global_load_lds_dwordx4 v[226:227], off
	v_lshl_add_u64 v[226:227], s[30:31], 0, v[134:135]
	s_mov_b32 m0, s25
	s_nop 0
	global_load_lds_dwordx4 v[226:227], off
	s_mov_b32 m0, s39
	s_nop 0
	global_load_lds_dwordx4 v[228:229], off
	s_waitcnt vmcnt(8)
	s_waitcnt lgkmcnt(0)
	s_barrier
; #define PG8_STAGE(bufoff, gbase, voff) do { _Pragma("unroll") for (int _i = 0; _i < 2; ++_i) \
;         __builtin_amdgcn_global_load_lds((const unsigned*)((const char*)(gbase) + (voff)[_i]), (PG8_LAS unsigned*)(lds + (bufoff) + ldsw + _i * 8192), 16, 0, 0); } while (0)
; #define PG8_LDA(dst, b, h) do { _Pragma("unroll") for (int m = 0; m < 4; ++m) _Pragma("unroll") for (int k = 0; k < 2; ++k) dst[m][k] = *(const PG8_LAS bf16x8*)(lds + PG8_SA(b, h) + aoff + m * 2048 + k * 1024); } while (0)
; #define PG8_LDB(dst, b, h) do { _Pragma("unroll") for (int n = 0; n < 2; ++n) _Pragma("unroll") for (int k = 0; k < 2; ++k) dst[n][k] = *(const PG8_LAS bf16x8*)(lds + PG8_SB(b, h) + boff + n * 2048 + k * 1024); } while (0)
; #define PG8_MMA(ai, bj, At, Bt) do { __builtin_amdgcn_s_setprio(1); _Pragma("unroll") for (int m = 0; m < 4; ++m) _Pragma("unroll") for (int n = 0; n < 2; ++n) _Pragma("unroll") for (int k = 0; k < 2; ++k) \
;         acc[ai][bj][m][n] = __builtin_amdgcn_mfma_f32_16x16x32_bf16(Bt[n][k], At[m][k], acc[ai][bj][m][n], 0, 0, 0); __builtin_amdgcn_s_setprio(0); } while (0)
; #define PG8_WAIT_V(n) asm volatile("s_waitcnt vmcnt(" #n ")" ::: "memory")
; #define PG8_WAIT_L(n) asm volatile("s_waitcnt lgkmcnt(" #n ")" ::: "memory")
; #define PG8_BAR __builtin_amdgcn_s_barrier()
; #define PG8_SCHED __builtin_amdgcn_sched_barrier(0)
; template <class Epi, class Sched, bool ALIGN_EPI = false, bool SP2 = false>
; __device__ __forceinline__ void gemm_phase(PG8_LAS unsigned char* lds, const Gemm g, const Sched& S, const Epi& E) {
;     ...
;             PG8_WAIT_V(8); PG8_WAIT_L(0); PG8_BAR; PG8_MMA(1, 0, At, B0); PG8_MMA(1, 1, At, B1); PG8_BAR; PG8_SCHED;
;             PG8_LDB(B0, 1, 0); PG8_LDB(B1, 1, 1); PG8_SCHED; PG8_LDA(At, 1, 0); PG8_STAGE(PG8_SA(0, 1), a2 + hstepA, voffA);
;             PG8_WAIT_V(8); PG8_WAIT_L(0); PG8_BAR; PG8_MMA(0, 0, At, B0); PG8_MMA(0, 1, At, B1); PG8_BAR; PG8_SCHED;
	s_waitcnt lgkmcnt(0)
	v_mfma_f32_16x16x32_bf16 v[60:63], v[160:163], v[192:195], v[60:63]
	v_mfma_f32_16x16x32_bf16 v[56:59], v[168:171], v[192:195], v[56:59]
	v_mfma_f32_16x16x32_bf16 v[44:47], v[160:163], v[200:203], v[44:47]
	v_mfma_f32_16x16x32_bf16 v[40:43], v[168:171], v[200:203], v[40:43]
	v_mfma_f32_16x16x32_bf16 v[28:31], v[160:163], v[210:213], v[28:31]
	v_mfma_f32_16x16x32_bf16 v[24:27], v[168:171], v[210:213], v[24:27]
	v_mfma_f32_16x16x32_bf16 v[12:15], v[160:163], v[218:221], v[12:15]
	v_mfma_f32_16x16x32_bf16 v[8:11], v[168:171], v[218:221], v[8:11]
	v_mfma_f32_16x16x32_bf16 v[60:63], v[164:167], v[196:199], v[60:63]
	v_mfma_f32_16x16x32_bf16 v[56:59], v[172:175], v[196:199], v[56:59]
	v_mfma_f32_16x16x32_bf16 v[44:47], v[164:167], v[206:209], v[44:47]
	v_mfma_f32_16x16x32_bf16 v[40:43], v[172:175], v[206:209], v[40:43]
	v_mfma_f32_16x16x32_bf16 v[28:31], v[164:167], v[214:217], v[28:31]
	v_mfma_f32_16x16x32_bf16 v[24:27], v[172:175], v[214:217], v[24:27]
	v_mfma_f32_16x16x32_bf16 v[12:15], v[164:167], v[222:225], v[12:15]
	v_mfma_f32_16x16x32_bf16 v[8:11], v[172:175], v[222:225], v[8:11]
	v_mfma_f32_16x16x32_bf16 v[52:55], v[176:179], v[192:195], v[52:55]
	v_mfma_f32_16x16x32_bf16 v[48:51], v[184:187], v[192:195], v[48:51]
	v_mfma_f32_16x16x32_bf16 v[36:39], v[176:179], v[200:203], v[36:39]
	v_mfma_f32_16x16x32_bf16 v[32:35], v[184:187], v[200:203], v[32:35]
	v_mfma_f32_16x16x32_bf16 v[20:23], v[176:179], v[210:213], v[20:23]
	v_mfma_f32_16x16x32_bf16 v[16:19], v[184:187], v[210:213], v[16:19]
	v_mfma_f32_16x16x32_bf16 v[4:7], v[176:179], v[218:221], v[4:7]
	v_mfma_f32_16x16x32_bf16 v[0:3], v[184:187], v[218:221], v[0:3]
	v_mfma_f32_16x16x32_bf16 v[52:55], v[180:183], v[196:199], v[52:55]
	v_mfma_f32_16x16x32_bf16 v[48:51], v[188:191], v[196:199], v[48:51]
	v_mfma_f32_16x16x32_bf16 v[36:39], v[180:183], v[206:209], v[36:39]
	v_mfma_f32_16x16x32_bf16 v[32:35], v[188:191], v[206:209], v[32:35]
	v_mfma_f32_16x16x32_bf16 v[20:23], v[180:183], v[214:217], v[20:23]
	v_mfma_f32_16x16x32_bf16 v[16:19], v[188:191], v[214:217], v[16:19]
	v_mfma_f32_16x16x32_bf16 v[4:7], v[180:183], v[222:225], v[4:7]
	v_mfma_f32_16x16x32_bf16 v[0:3], v[188:191], v[222:225], v[0:3]
	s_barrier
	s_add_i32 s55, 0, 0x18000
	v_add_u32_e32 v148, s55, v152
	s_add_i32 s56, 0, 0x1c000
	ds_read_b128 v[160:163], v148
	ds_read_b128 v[164:167], v148 offset:1024
	ds_read_b128 v[168:171], v148 offset:2048
	ds_read_b128 v[172:175], v148 offset:3072
	v_add_u32_e32 v148, s56, v152
	ds_read_b128 v[176:179], v148
	ds_read_b128 v[180:183], v148 offset:1024
	ds_read_b128 v[184:187], v148 offset:2048
	ds_read_b128 v[188:191], v148 offset:3072
	s_add_u32 s30, s30, 0x80000
	s_addc_u32 s31, s31, 0
	s_mov_b32 m0, s40
	v_lshl_add_u64 v[230:231], s[30:31], 0, v[134:135]
	ds_read_b128 v[192:195], v156 offset:32768
	ds_read_b128 v[196:199], v156 offset:33792
	ds_read_b128 v[200:203], v156 offset:34816
	ds_read_b128 v[206:209], v156 offset:35840
	ds_read_b128 v[210:213], v156 offset:36864
	ds_read_b128 v[214:217], v156 offset:37888
	ds_read_b128 v[218:221], v156 offset:38912
	ds_read_b128 v[222:225], v156 offset:39936
	global_load_lds_dwordx4 v[230:231], off
	v_lshl_add_u64 v[230:231], s[30:31], 0, v[130:131]
	s_mov_b32 m0, s41
	s_nop 0
	global_load_lds_dwordx4 v[230:231], off
	s_waitcnt vmcnt(8)
	s_waitcnt lgkmcnt(0)
	s_barrier
	s_waitcnt lgkmcnt(0)
	v_mfma_f32_16x16x32_bf16 v[124:127], v[160:163], v[192:195], v[124:127]
	v_mfma_f32_16x16x32_bf16 v[120:123], v[168:171], v[192:195], v[120:123]
	v_mfma_f32_16x16x32_bf16 v[108:111], v[160:163], v[200:203], v[108:111]
	v_mfma_f32_16x16x32_bf16 v[104:107], v[168:171], v[200:203], v[104:107]
	v_mfma_f32_16x16x32_bf16 v[92:95], v[160:163], v[210:213], v[92:95]
	v_mfma_f32_16x16x32_bf16 v[88:91], v[168:171], v[210:213], v[88:91]
	v_mfma_f32_16x16x32_bf16 v[76:79], v[160:163], v[218:221], v[76:79]
	v_mfma_f32_16x16x32_bf16 v[72:75], v[168:171], v[218:221], v[72:75]
	v_mfma_f32_16x16x32_bf16 v[124:127], v[164:167], v[196:199], v[124:127]
	v_mfma_f32_16x16x32_bf16 v[120:123], v[172:175], v[196:199], v[120:123]
	v_mfma_f32_16x16x32_bf16 v[108:111], v[164:167], v[206:209], v[108:111]
	v_mfma_f32_16x16x32_bf16 v[104:107], v[172:175], v[206:209], v[104:107]
	v_mfma_f32_16x16x32_bf16 v[92:95], v[164:167], v[214:217], v[92:95]
	v_mfma_f32_16x16x32_bf16 v[88:91], v[172:175], v[214:217], v[88:91]
	v_mfma_f32_16x16x32_bf16 v[76:79], v[164:167], v[222:225], v[76:79]
	v_mfma_f32_16x16x32_bf16 v[72:75], v[172:175], v[222:225], v[72:75]
	v_mfma_f32_16x16x32_bf16 v[116:119], v[176:179], v[192:195], v[116:119]
	v_mfma_f32_16x16x32_bf16 v[112:115], v[184:187], v[192:195], v[112:115]
	v_mfma_f32_16x16x32_bf16 v[100:103], v[176:179], v[200:203], v[100:103]
	v_mfma_f32_16x16x32_bf16 v[96:99], v[184:187], v[200:203], v[96:99]
	v_mfma_f32_16x16x32_bf16 v[84:87], v[176:179], v[210:213], v[84:87]
	v_mfma_f32_16x16x32_bf16 v[80:83], v[184:187], v[210:213], v[80:83]
	v_mfma_f32_16x16x32_bf16 v[68:71], v[176:179], v[218:221], v[68:71]
	v_mfma_f32_16x16x32_bf16 v[64:67], v[184:187], v[218:221], v[64:67]
	v_mfma_f32_16x16x32_bf16 v[116:119], v[180:183], v[196:199], v[116:119]
	v_mfma_f32_16x16x32_bf16 v[112:115], v[188:191], v[196:199], v[112:115]
	v_mfma_f32_16x16x32_bf16 v[100:103], v[180:183], v[206:209], v[100:103]
	v_mfma_f32_16x16x32_bf16 v[96:99], v[188:191], v[206:209], v[96:99]
	v_mfma_f32_16x16x32_bf16 v[84:87], v[180:183], v[214:217], v[84:87]
	v_mfma_f32_16x16x32_bf16 v[80:83], v[188:191], v[214:217], v[80:83]
	v_mfma_f32_16x16x32_bf16 v[68:71], v[180:183], v[222:225], v[68:71]
	v_mfma_f32_16x16x32_bf16 v[64:67], v[188:191], v[222:225], v[64:67]
	s_barrier
; #define PG8_STAGE(bufoff, gbase, voff) do { _Pragma("unroll") for (int _i = 0; _i < 2; ++_i) \
;         __builtin_amdgcn_global_load_lds((const unsigned*)((const char*)(gbase) + (voff)[_i]), (PG8_LAS unsigned*)(lds + (bufoff) + ldsw + _i * 8192), 16, 0, 0); } while (0)
; #define PG8_LDA(dst, b, h) do { _Pragma("unroll") for (int m = 0; m < 4; ++m) _Pragma("unroll") for (int k = 0; k < 2; ++k) dst[m][k] = *(const PG8_LAS bf16x8*)(lds + PG8_SA(b, h) + aoff + m * 2048 + k * 1024); } while (0)
; #define PG8_MMA(ai, bj, At, Bt) do { __builtin_amdgcn_s_setprio(1); _Pragma("unroll") for (int m = 0; m < 4; ++m) _Pragma("unroll") for (int n = 0; n < 2; ++n) _Pragma("unroll") for (int k = 0; k < 2; ++k) \
;         acc[ai][bj][m][n] = __builtin_amdgcn_mfma_f32_16x16x32_bf16(Bt[n][k], At[m][k], acc[ai][bj][m][n], 0, 0, 0); __builtin_amdgcn_s_setprio(0); } while (0)
; #define PG8_WAIT_V(n) asm volatile("s_waitcnt vmcnt(" #n ")" ::: "memory")
; #define PG8_WAIT_L(n) asm volatile("s_waitcnt lgkmcnt(" #n ")" ::: "memory")
; #define PG8_BAR __builtin_amdgcn_s_barrier()
; #define PG8_SCHED __builtin_amdgcn_sched_barrier(0)
; template <class Epi, class Sched, bool ALIGN_EPI = false, bool SP2 = false>
; __device__ __forceinline__ void gemm_phase(PG8_LAS unsigned char* lds, const Gemm g, const Sched& S, const Epi& E) {
;     ...
;             PG8_LDA(At, 1, 1); PG8_STAGE(PG8_SB(1, 0), b3, voffB); PG8_STAGE(PG8_SB(1, 1), b3 + hstep, voffB); PG8_STAGE(PG8_SA(1, 0), a3, voffA);
;             PG8_WAIT_V(8); PG8_WAIT_L(0); PG8_BAR; PG8_MMA(1, 0, At, B0); PG8_MMA(1, 1, At, B1); PG8_BAR; PG8_SCHED;
	s_add_i32 s30, s55, s36
	v_lshl_add_u64 v[146:147], v[146:147], 0, s[12:13]
	s_mov_b32 m0, s30
	ds_read_b128 v[192:195], v156 offset:49152
	ds_read_b128 v[196:199], v156 offset:50176
	ds_read_b128 v[200:203], v156 offset:51200
	ds_read_b128 v[206:209], v156 offset:52224
	ds_read_b128 v[210:213], v156 offset:53248
	ds_read_b128 v[214:217], v156 offset:54272
	ds_read_b128 v[218:221], v156 offset:55296
	ds_read_b128 v[222:225], v156 offset:56320
	global_load_lds_dwordx4 v[146:147], off
	s_add_i32 m0, s30, 0x2000
	s_add_u32 s28, s28, 0x80080
	v_lshl_add_u64 v[146:147], v[150:151], 0, s[12:13]
	s_addc_u32 s29, s29, 0
	s_add_i32 s30, s56, s36
	global_load_lds_dwordx4 v[146:147], off
	v_lshl_add_u64 v[146:147], s[28:29], 0, v[132:133]
	s_mov_b32 m0, s30
	s_nop 0
	global_load_lds_dwordx4 v[146:147], off
	v_lshl_add_u64 v[146:147], s[28:29], 0, v[128:129]
	s_add_i32 m0, s30, 0x2000
	s_nop 0
	global_load_lds_dwordx4 v[146:147], off
	v_lshl_add_u64 v[146:147], v[226:227], 0, s[12:13]
	s_mov_b32 m0, s45
	s_nop 0
	global_load_lds_dwordx4 v[146:147], off
	v_lshl_add_u64 v[146:147], v[228:229], 0, s[12:13]
	s_mov_b32 m0, s46
	s_nop 0
	global_load_lds_dwordx4 v[146:147], off
	s_waitcnt vmcnt(8)
	s_waitcnt lgkmcnt(0)
	s_barrier
	s_waitcnt lgkmcnt(0)
	v_mfma_f32_16x16x32_bf16 v[60:63], v[160:163], v[192:195], v[60:63]
	v_mfma_f32_16x16x32_bf16 v[56:59], v[168:171], v[192:195], v[56:59]
	v_mfma_f32_16x16x32_bf16 v[44:47], v[160:163], v[200:203], v[44:47]
	v_mfma_f32_16x16x32_bf16 v[40:43], v[168:171], v[200:203], v[40:43]
	v_mfma_f32_16x16x32_bf16 v[28:31], v[160:163], v[210:213], v[28:31]
	v_mfma_f32_16x16x32_bf16 v[24:27], v[168:171], v[210:213], v[24:27]
	v_mfma_f32_16x16x32_bf16 v[12:15], v[160:163], v[218:221], v[12:15]
	v_mfma_f32_16x16x32_bf16 v[8:11], v[168:171], v[218:221], v[8:11]
	v_mfma_f32_16x16x32_bf16 v[60:63], v[164:167], v[196:199], v[60:63]
	v_mfma_f32_16x16x32_bf16 v[56:59], v[172:175], v[196:199], v[56:59]
	v_mfma_f32_16x16x32_bf16 v[44:47], v[164:167], v[206:209], v[44:47]
	v_mfma_f32_16x16x32_bf16 v[40:43], v[172:175], v[206:209], v[40:43]
	v_mfma_f32_16x16x32_bf16 v[28:31], v[164:167], v[214:217], v[28:31]
	v_mfma_f32_16x16x32_bf16 v[24:27], v[172:175], v[214:217], v[24:27]
	v_mfma_f32_16x16x32_bf16 v[12:15], v[164:167], v[222:225], v[12:15]
	v_mfma_f32_16x16x32_bf16 v[8:11], v[172:175], v[222:225], v[8:11]
	v_mfma_f32_16x16x32_bf16 v[52:55], v[176:179], v[192:195], v[52:55]
	v_mfma_f32_16x16x32_bf16 v[48:51], v[184:187], v[192:195], v[48:51]
	v_mfma_f32_16x16x32_bf16 v[36:39], v[176:179], v[200:203], v[36:39]
	v_mfma_f32_16x16x32_bf16 v[32:35], v[184:187], v[200:203], v[32:35]
	v_mfma_f32_16x16x32_bf16 v[20:23], v[176:179], v[210:213], v[20:23]
	v_mfma_f32_16x16x32_bf16 v[16:19], v[184:187], v[210:213], v[16:19]
	v_mfma_f32_16x16x32_bf16 v[4:7], v[176:179], v[218:221], v[4:7]
	v_mfma_f32_16x16x32_bf16 v[0:3], v[184:187], v[218:221], v[0:3]
	v_mfma_f32_16x16x32_bf16 v[52:55], v[180:183], v[196:199], v[52:55]
	v_mfma_f32_16x16x32_bf16 v[48:51], v[188:191], v[196:199], v[48:51]
	v_mfma_f32_16x16x32_bf16 v[36:39], v[180:183], v[206:209], v[36:39]
	v_mfma_f32_16x16x32_bf16 v[32:35], v[188:191], v[206:209], v[32:35]
	v_mfma_f32_16x16x32_bf16 v[20:23], v[180:183], v[214:217], v[20:23]
	v_mfma_f32_16x16x32_bf16 v[16:19], v[188:191], v[214:217], v[16:19]
	v_mfma_f32_16x16x32_bf16 v[4:7], v[180:183], v[222:225], v[4:7]
	v_mfma_f32_16x16x32_bf16 v[0:3], v[188:191], v[222:225], v[0:3]
	s_barrier
	s_add_i32 s54, s54, 2
	s_add_u32 s26, s26, 0x100
	s_addc_u32 s27, s27, 0
	s_add_u32 s52, s52, 0x100
	s_addc_u32 s53, s53, 0
	s_cmp_gt_u32 s54, 29
	s_cbranch_scc0 .LBB0_2021
	s_and_b64 vcc, exec, s[14:15]
	s_cbranch_vccz .LBB0_2024
	s_barrier

; #define PG8_STAGE(bufoff, gbase, voff) do { _Pragma("unroll") for (int _i = 0; _i < 2; ++_i) \
;         __builtin_amdgcn_global_load_lds((const unsigned*)((const char*)(gbase) + (voff)[_i]), (PG8_LAS unsigned*)(lds + (bufoff) + ldsw + _i * 8192), 16, 0, 0); } while (0)
; #define PG8_LDA(dst, b, h) do { _Pragma("unroll") for (int m = 0; m < 4; ++m) _Pragma("unroll") for (int k = 0; k < 2; ++k) dst[m][k] = *(const PG8_LAS bf16x8*)(lds + PG8_SA(b, h) + aoff + m * 2048 + k * 1024); } while (0)
; #define PG8_LDB(dst, b, h) do { _Pragma("unroll") for (int n = 0; n < 2; ++n) _Pragma("unroll") for (int k = 0; k < 2; ++k) dst[n][k] = *(const PG8_LAS bf16x8*)(lds + PG8_SB(b, h) + boff + n * 2048 + k * 1024); } while (0)
; #define PG8_MMA(ai, bj, At, Bt) do { __builtin_amdgcn_s_setprio(1); _Pragma("unroll") for (int m = 0; m < 4; ++m) _Pragma("unroll") for (int n = 0; n < 2; ++n) _Pragma("unroll") for (int k = 0; k < 2; ++k) \
;         acc[ai][bj][m][n] = __builtin_amdgcn_mfma_f32_16x16x32_bf16(Bt[n][k], At[m][k], acc[ai][bj][m][n], 0, 0, 0); __builtin_amdgcn_s_setprio(0); } while (0)
; #define PG8_WAIT_V(n) asm volatile("s_waitcnt vmcnt(" #n ")" ::: "memory")
; #define PG8_WAIT_L(n) asm volatile("s_waitcnt lgkmcnt(" #n ")" ::: "memory")
; #define PG8_BAR __builtin_amdgcn_s_barrier()
; #define PG8_SCHED __builtin_amdgcn_sched_barrier(0)
; template <class Epi, class Sched, bool ALIGN_EPI = false, bool SP2 = false>
; __device__ __forceinline__ void gemm_phase(PG8_LAS unsigned char* lds, const Gemm g, const Sched& S, const Epi& E) {
;     ...
;             PG8_LDB(B0, 0, 0); PG8_LDB(B1, 0, 1); PG8_SCHED; PG8_LDA(At, 0, 0); PG8_STAGE(PG8_SA(1, 1), a1 + hstepA, voffA);
;             PG8_WAIT_V(8); PG8_WAIT_L(0); PG8_BAR; PG8_MMA(0, 0, At, B0); PG8_MMA(0, 1, At, B1); PG8_BAR; PG8_SCHED;
;             PG8_LDA(At, 0, 1); PG8_STAGE(PG8_SB(0, 0), b2, voffB); PG8_STAGE(PG8_SB(0, 1), b2 + hstep, voffB); PG8_STAGE(PG8_SA(0, 0), a2, voffA);
.LBB0_2195:
	ds_read_b128 v[128:131], v167
	ds_read_b128 v[132:135], v167 offset:1024
	ds_read_b128 v[152:155], v167 offset:2048
	ds_read_b128 v[156:159], v167 offset:3072
	ds_read_b128 v[160:163], v168
	ds_read_b128 v[170:173], v168 offset:1024
	ds_read_b128 v[174:177], v168 offset:2048
	ds_read_b128 v[178:181], v168 offset:3072
	s_add_u32 s28, s26, 0xfff80080
	s_addc_u32 s29, s27, -1
	s_cmp_eq_u32 s25, 28
	s_cselect_b32 s31, s2, s29
	s_cselect_b32 s30, s6, s28
	s_cselect_b32 s29, s7, s23
	s_cselect_b32 s28, s15, s17
	v_lshl_add_u64 v[218:219], s[26:27], 0, v[144:145]
	s_add_i32 m0, s49, 0xc000
	ds_read_b128 v[182:185], v169
	ds_read_b128 v[186:189], v169 offset:1024
	ds_read_b128 v[190:193], v169 offset:2048
	ds_read_b128 v[194:197], v169 offset:3072
	ds_read_b128 v[198:201], v169 offset:4096
	ds_read_b128 v[206:209], v169 offset:5120
	ds_read_b128 v[210:213], v169 offset:6144
	ds_read_b128 v[214:217], v169 offset:7168
	global_load_lds_dwordx4 v[218:219], off
	v_lshl_add_u64 v[218:219], s[26:27], 0, v[146:147]
	s_add_i32 m0, s49, 0xe000
	s_nop 0
	global_load_lds_dwordx4 v[218:219], off
	s_waitcnt vmcnt(8)
	s_waitcnt lgkmcnt(0)
	s_barrier
	s_waitcnt lgkmcnt(0)
	v_mfma_f32_16x16x32_bf16 v[124:127], v[128:131], v[182:185], v[124:127]
	v_mfma_f32_16x16x32_bf16 v[120:123], v[152:155], v[182:185], v[120:123]
	v_mfma_f32_16x16x32_bf16 v[108:111], v[128:131], v[190:193], v[108:111]
	v_mfma_f32_16x16x32_bf16 v[104:107], v[152:155], v[190:193], v[104:107]
	v_mfma_f32_16x16x32_bf16 v[92:95], v[128:131], v[198:201], v[92:95]
	v_mfma_f32_16x16x32_bf16 v[88:91], v[152:155], v[198:201], v[88:91]
	v_mfma_f32_16x16x32_bf16 v[76:79], v[128:131], v[210:213], v[76:79]
	v_mfma_f32_16x16x32_bf16 v[72:75], v[152:155], v[210:213], v[72:75]
	v_mfma_f32_16x16x32_bf16 v[124:127], v[132:135], v[186:189], v[124:127]
	v_mfma_f32_16x16x32_bf16 v[120:123], v[156:159], v[186:189], v[120:123]
	v_mfma_f32_16x16x32_bf16 v[108:111], v[132:135], v[194:197], v[108:111]
	v_mfma_f32_16x16x32_bf16 v[104:107], v[156:159], v[194:197], v[104:107]
	v_mfma_f32_16x16x32_bf16 v[92:95], v[132:135], v[206:209], v[92:95]
	v_mfma_f32_16x16x32_bf16 v[88:91], v[156:159], v[206:209], v[88:91]
	v_mfma_f32_16x16x32_bf16 v[76:79], v[132:135], v[214:217], v[76:79]
	v_mfma_f32_16x16x32_bf16 v[72:75], v[156:159], v[214:217], v[72:75]
	v_mfma_f32_16x16x32_bf16 v[116:119], v[160:163], v[182:185], v[116:119]
	v_mfma_f32_16x16x32_bf16 v[112:115], v[174:177], v[182:185], v[112:115]
	v_mfma_f32_16x16x32_bf16 v[100:103], v[160:163], v[190:193], v[100:103]
	v_mfma_f32_16x16x32_bf16 v[96:99], v[174:177], v[190:193], v[96:99]
	v_mfma_f32_16x16x32_bf16 v[84:87], v[160:163], v[198:201], v[84:87]
	v_mfma_f32_16x16x32_bf16 v[80:83], v[174:177], v[198:201], v[80:83]
	v_mfma_f32_16x16x32_bf16 v[68:71], v[160:163], v[210:213], v[68:71]
	v_mfma_f32_16x16x32_bf16 v[64:67], v[174:177], v[210:213], v[64:67]
	v_mfma_f32_16x16x32_bf16 v[116:119], v[170:173], v[186:189], v[116:119]
	v_mfma_f32_16x16x32_bf16 v[112:115], v[178:181], v[186:189], v[112:115]
	v_mfma_f32_16x16x32_bf16 v[100:103], v[170:173], v[194:197], v[100:103]
	v_mfma_f32_16x16x32_bf16 v[96:99], v[178:181], v[194:197], v[96:99]
	v_mfma_f32_16x16x32_bf16 v[84:87], v[170:173], v[206:209], v[84:87]
	v_mfma_f32_16x16x32_bf16 v[80:83], v[178:181], v[206:209], v[80:83]
	v_mfma_f32_16x16x32_bf16 v[68:71], v[170:173], v[214:217], v[68:71]
	v_mfma_f32_16x16x32_bf16 v[64:67], v[178:181], v[214:217], v[64:67]
	s_barrier
	s_add_i32 s42, s54, s48
	v_lshl_add_u64 v[218:219], s[28:29], 0, v[138:139]
	s_mov_b32 m0, s42
	ds_read_b128 v[182:185], v169 offset:16384
	ds_read_b128 v[186:189], v169 offset:17408
	ds_read_b128 v[190:193], v169 offset:18432
	ds_read_b128 v[194:197], v169 offset:19456
	ds_read_b128 v[198:201], v169 offset:20480
	ds_read_b128 v[206:209], v169 offset:21504
	ds_read_b128 v[210:213], v169 offset:22528
	ds_read_b128 v[214:217], v169 offset:23552
	global_load_lds_dwordx4 v[218:219], off
	s_add_i32 m0, s42, 0x2000
	s_add_u32 s42, s28, 0x80000
	v_lshl_add_u64 v[220:221], s[28:29], 0, v[142:143]
	s_addc_u32 s43, s29, 0
	s_add_i32 s56, s55, s48
	global_load_lds_dwordx4 v[220:221], off
	v_lshl_add_u64 v[222:223], s[42:43], 0, v[138:139]
	s_mov_b32 m0, s56
	v_lshl_add_u64 v[224:225], s[30:31], 0, v[140:141]
	global_load_lds_dwordx4 v[222:223], off
	v_lshl_add_u64 v[222:223], s[42:43], 0, v[142:143]
	s_add_i32 m0, s56, 0x2000
	s_nop 0
	global_load_lds_dwordx4 v[222:223], off
	v_lshl_add_u64 v[222:223], s[30:31], 0, v[136:137]
	s_mov_b32 m0, s49
	s_nop 0
	global_load_lds_dwordx4 v[222:223], off
	s_mov_b32 m0, s50
	s_nop 0
	global_load_lds_dwordx4 v[224:225], off
	s_waitcnt vmcnt(8)
	s_waitcnt lgkmcnt(0)
	s_barrier
; #define PG8_STAGE(bufoff, gbase, voff) do { _Pragma("unroll") for (int _i = 0; _i < 2; ++_i) \
;         __builtin_amdgcn_global_load_lds((const unsigned*)((const char*)(gbase) + (voff)[_i]), (PG8_LAS unsigned*)(lds + (bufoff) + ldsw + _i * 8192), 16, 0, 0); } while (0)
; #define PG8_LDA(dst, b, h) do { _Pragma("unroll") for (int m = 0; m < 4; ++m) _Pragma("unroll") for (int k = 0; k < 2; ++k) dst[m][k] = *(const PG8_LAS bf16x8*)(lds + PG8_SA(b, h) + aoff + m * 2048 + k * 1024); } while (0)
; #define PG8_LDB(dst, b, h) do { _Pragma("unroll") for (int n = 0; n < 2; ++n) _Pragma("unroll") for (int k = 0; k < 2; ++k) dst[n][k] = *(const PG8_LAS bf16x8*)(lds + PG8_SB(b, h) + boff + n * 2048 + k * 1024); } while (0)
; #define PG8_MMA(ai, bj, At, Bt) do { __builtin_amdgcn_s_setprio(1); _Pragma("unroll") for (int m = 0; m < 4; ++m) _Pragma("unroll") for (int n = 0; n < 2; ++n) _Pragma("unroll") for (int k = 0; k < 2; ++k) \
;         acc[ai][bj][m][n] = __builtin_amdgcn_mfma_f32_16x16x32_bf16(Bt[n][k], At[m][k], acc[ai][bj][m][n], 0, 0, 0); __builtin_amdgcn_s_setprio(0); } while (0)
; #define PG8_WAIT_V(n) asm volatile("s_waitcnt vmcnt(" #n ")" ::: "memory")
; #define PG8_WAIT_L(n) asm volatile("s_waitcnt lgkmcnt(" #n ")" ::: "memory")
; #define PG8_BAR __builtin_amdgcn_s_barrier()
; #define PG8_SCHED __builtin_amdgcn_sched_barrier(0)
; template <class Epi, class Sched, bool ALIGN_EPI = false, bool SP2 = false>
; __device__ __forceinline__ void gemm_phase(PG8_LAS unsigned char* lds, const Gemm g, const Sched& S, const Epi& E) {
;     ...
;             PG8_WAIT_V(8); PG8_WAIT_L(0); PG8_BAR; PG8_MMA(1, 0, At, B0); PG8_MMA(1, 1, At, B1); PG8_BAR; PG8_SCHED;
;             PG8_LDB(B0, 1, 0); PG8_LDB(B1, 1, 1); PG8_SCHED; PG8_LDA(At, 1, 0); PG8_STAGE(PG8_SA(0, 1), a2 + hstepA, voffA);
;             PG8_WAIT_V(8); PG8_WAIT_L(0); PG8_BAR; PG8_MMA(0, 0, At, B0); PG8_MMA(0, 1, At, B1); PG8_BAR; PG8_SCHED;
	s_waitcnt lgkmcnt(0)
	v_mfma_f32_16x16x32_bf16 v[60:63], v[128:131], v[182:185], v[60:63]
	v_mfma_f32_16x16x32_bf16 v[56:59], v[152:155], v[182:185], v[56:59]
	v_mfma_f32_16x16x32_bf16 v[44:47], v[128:131], v[190:193], v[44:47]
	v_mfma_f32_16x16x32_bf16 v[40:43], v[152:155], v[190:193], v[40:43]
	v_mfma_f32_16x16x32_bf16 v[28:31], v[128:131], v[198:201], v[28:31]
	v_mfma_f32_16x16x32_bf16 v[24:27], v[152:155], v[198:201], v[24:27]
	v_mfma_f32_16x16x32_bf16 v[12:15], v[128:131], v[210:213], v[12:15]
	v_mfma_f32_16x16x32_bf16 v[8:11], v[152:155], v[210:213], v[8:11]
	v_mfma_f32_16x16x32_bf16 v[60:63], v[132:135], v[186:189], v[60:63]
	v_mfma_f32_16x16x32_bf16 v[56:59], v[156:159], v[186:189], v[56:59]
	v_mfma_f32_16x16x32_bf16 v[44:47], v[132:135], v[194:197], v[44:47]
	v_mfma_f32_16x16x32_bf16 v[40:43], v[156:159], v[194:197], v[40:43]
	v_mfma_f32_16x16x32_bf16 v[28:31], v[132:135], v[206:209], v[28:31]
	v_mfma_f32_16x16x32_bf16 v[24:27], v[156:159], v[206:209], v[24:27]
	v_mfma_f32_16x16x32_bf16 v[12:15], v[132:135], v[214:217], v[12:15]
	v_mfma_f32_16x16x32_bf16 v[8:11], v[156:159], v[214:217], v[8:11]
	v_mfma_f32_16x16x32_bf16 v[52:55], v[160:163], v[182:185], v[52:55]
	v_mfma_f32_16x16x32_bf16 v[48:51], v[174:177], v[182:185], v[48:51]
	v_mfma_f32_16x16x32_bf16 v[36:39], v[160:163], v[190:193], v[36:39]
	v_mfma_f32_16x16x32_bf16 v[32:35], v[174:177], v[190:193], v[32:35]
	v_mfma_f32_16x16x32_bf16 v[20:23], v[160:163], v[198:201], v[20:23]
	v_mfma_f32_16x16x32_bf16 v[16:19], v[174:177], v[198:201], v[16:19]
	v_mfma_f32_16x16x32_bf16 v[4:7], v[160:163], v[210:213], v[4:7]
	v_mfma_f32_16x16x32_bf16 v[0:3], v[174:177], v[210:213], v[0:3]
	v_mfma_f32_16x16x32_bf16 v[52:55], v[170:173], v[186:189], v[52:55]
	v_mfma_f32_16x16x32_bf16 v[48:51], v[178:181], v[186:189], v[48:51]
	v_mfma_f32_16x16x32_bf16 v[36:39], v[170:173], v[194:197], v[36:39]
	v_mfma_f32_16x16x32_bf16 v[32:35], v[178:181], v[194:197], v[32:35]
	v_mfma_f32_16x16x32_bf16 v[20:23], v[170:173], v[206:209], v[20:23]
	v_mfma_f32_16x16x32_bf16 v[16:19], v[178:181], v[206:209], v[16:19]
	v_mfma_f32_16x16x32_bf16 v[4:7], v[170:173], v[214:217], v[4:7]
	v_mfma_f32_16x16x32_bf16 v[0:3], v[178:181], v[214:217], v[0:3]
	s_barrier
	s_add_i32 s42, 0, 0x18000
	s_add_i32 s43, 0, 0x1c000
	v_add_u32_e32 v156, s42, v165
	v_add_u32_e32 v178, s43, v165
	ds_read_b128 v[128:131], v156
	ds_read_b128 v[132:135], v156 offset:1024
	ds_read_b128 v[152:155], v156 offset:2048
	ds_read_b128 v[156:159], v156 offset:3072
	ds_read_b128 v[160:163], v178
	ds_read_b128 v[170:173], v178 offset:1024
	ds_read_b128 v[174:177], v178 offset:2048
	ds_read_b128 v[178:181], v178 offset:3072
	s_add_u32 s30, s30, 0x80000
	s_addc_u32 s31, s31, 0
	s_mov_b32 m0, s51
	v_lshl_add_u64 v[226:227], s[30:31], 0, v[136:137]
	ds_read_b128 v[182:185], v169 offset:32768
	ds_read_b128 v[186:189], v169 offset:33792
	ds_read_b128 v[190:193], v169 offset:34816
	ds_read_b128 v[194:197], v169 offset:35840
	ds_read_b128 v[198:201], v169 offset:36864
	ds_read_b128 v[206:209], v169 offset:37888
	ds_read_b128 v[210:213], v169 offset:38912
	ds_read_b128 v[214:217], v169 offset:39936
	global_load_lds_dwordx4 v[226:227], off
	v_lshl_add_u64 v[226:227], s[30:31], 0, v[140:141]
	s_mov_b32 m0, s52
	s_nop 0
	global_load_lds_dwordx4 v[226:227], off
	s_waitcnt vmcnt(8)
	s_waitcnt lgkmcnt(0)
	s_barrier
	s_waitcnt lgkmcnt(0)
	v_mfma_f32_16x16x32_bf16 v[124:127], v[128:131], v[182:185], v[124:127]
	v_mfma_f32_16x16x32_bf16 v[120:123], v[152:155], v[182:185], v[120:123]
	v_mfma_f32_16x16x32_bf16 v[108:111], v[128:131], v[190:193], v[108:111]
	v_mfma_f32_16x16x32_bf16 v[104:107], v[152:155], v[190:193], v[104:107]
	v_mfma_f32_16x16x32_bf16 v[92:95], v[128:131], v[198:201], v[92:95]
	v_mfma_f32_16x16x32_bf16 v[88:91], v[152:155], v[198:201], v[88:91]
	v_mfma_f32_16x16x32_bf16 v[76:79], v[128:131], v[210:213], v[76:79]
	v_mfma_f32_16x16x32_bf16 v[72:75], v[152:155], v[210:213], v[72:75]
	v_mfma_f32_16x16x32_bf16 v[124:127], v[132:135], v[186:189], v[124:127]
	v_mfma_f32_16x16x32_bf16 v[120:123], v[156:159], v[186:189], v[120:123]
	v_mfma_f32_16x16x32_bf16 v[108:111], v[132:135], v[194:197], v[108:111]
	v_mfma_f32_16x16x32_bf16 v[104:107], v[156:159], v[194:197], v[104:107]
	v_mfma_f32_16x16x32_bf16 v[92:95], v[132:135], v[206:209], v[92:95]
	v_mfma_f32_16x16x32_bf16 v[88:91], v[156:159], v[206:209], v[88:91]
	v_mfma_f32_16x16x32_bf16 v[76:79], v[132:135], v[214:217], v[76:79]
	v_mfma_f32_16x16x32_bf16 v[72:75], v[156:159], v[214:217], v[72:75]
	v_mfma_f32_16x16x32_bf16 v[116:119], v[160:163], v[182:185], v[116:119]
	v_mfma_f32_16x16x32_bf16 v[112:115], v[174:177], v[182:185], v[112:115]
	v_mfma_f32_16x16x32_bf16 v[100:103], v[160:163], v[190:193], v[100:103]
	v_mfma_f32_16x16x32_bf16 v[96:99], v[174:177], v[190:193], v[96:99]
	v_mfma_f32_16x16x32_bf16 v[84:87], v[160:163], v[198:201], v[84:87]
	v_mfma_f32_16x16x32_bf16 v[80:83], v[174:177], v[198:201], v[80:83]
	v_mfma_f32_16x16x32_bf16 v[68:71], v[160:163], v[210:213], v[68:71]
	v_mfma_f32_16x16x32_bf16 v[64:67], v[174:177], v[210:213], v[64:67]
	v_mfma_f32_16x16x32_bf16 v[116:119], v[170:173], v[186:189], v[116:119]
	v_mfma_f32_16x16x32_bf16 v[112:115], v[178:181], v[186:189], v[112:115]
	v_mfma_f32_16x16x32_bf16 v[100:103], v[170:173], v[194:197], v[100:103]
	v_mfma_f32_16x16x32_bf16 v[96:99], v[178:181], v[194:197], v[96:99]
	v_mfma_f32_16x16x32_bf16 v[84:87], v[170:173], v[206:209], v[84:87]
	v_mfma_f32_16x16x32_bf16 v[80:83], v[178:181], v[206:209], v[80:83]
	v_mfma_f32_16x16x32_bf16 v[68:71], v[170:173], v[214:217], v[68:71]
	v_mfma_f32_16x16x32_bf16 v[64:67], v[178:181], v[214:217], v[64:67]
	s_barrier
; #define PG8_STAGE(bufoff, gbase, voff) do { _Pragma("unroll") for (int _i = 0; _i < 2; ++_i) \
;         __builtin_amdgcn_global_load_lds((const unsigned*)((const char*)(gbase) + (voff)[_i]), (PG8_LAS unsigned*)(lds + (bufoff) + ldsw + _i * 8192), 16, 0, 0); } while (0)
; #define PG8_LDA(dst, b, h) do { _Pragma("unroll") for (int m = 0; m < 4; ++m) _Pragma("unroll") for (int k = 0; k < 2; ++k) dst[m][k] = *(const PG8_LAS bf16x8*)(lds + PG8_SA(b, h) + aoff + m * 2048 + k * 1024); } while (0)
; #define PG8_MMA(ai, bj, At, Bt) do { __builtin_amdgcn_s_setprio(1); _Pragma("unroll") for (int m = 0; m < 4; ++m) _Pragma("unroll") for (int n = 0; n < 2; ++n) _Pragma("unroll") for (int k = 0; k < 2; ++k) \
;         acc[ai][bj][m][n] = __builtin_amdgcn_mfma_f32_16x16x32_bf16(Bt[n][k], At[m][k], acc[ai][bj][m][n], 0, 0, 0); __builtin_amdgcn_s_setprio(0); } while (0)
; #define PG8_WAIT_V(n) asm volatile("s_waitcnt vmcnt(" #n ")" ::: "memory")
; #define PG8_WAIT_L(n) asm volatile("s_waitcnt lgkmcnt(" #n ")" ::: "memory")
; #define PG8_BAR __builtin_amdgcn_s_barrier()
; #define PG8_SCHED __builtin_amdgcn_sched_barrier(0)
; template <class Epi, class Sched, bool ALIGN_EPI = false, bool SP2 = false>
; __device__ __forceinline__ void gemm_phase(PG8_LAS unsigned char* lds, const Gemm g, const Sched& S, const Epi& E) {
;     ...
;             PG8_LDA(At, 1, 1); PG8_STAGE(PG8_SB(1, 0), b3, voffB); PG8_STAGE(PG8_SB(1, 1), b3 + hstep, voffB); PG8_STAGE(PG8_SA(1, 0), a3, voffA);
;             PG8_WAIT_V(8); PG8_WAIT_L(0); PG8_BAR; PG8_MMA(1, 0, At, B0); PG8_MMA(1, 1, At, B1); PG8_BAR; PG8_SCHED;
	s_add_i32 s30, s42, s48
	v_lshl_add_u64 v[218:219], v[218:219], 0, s[0:1]
	s_mov_b32 m0, s30
	ds_read_b128 v[182:185], v169 offset:49152
	ds_read_b128 v[186:189], v169 offset:50176
	ds_read_b128 v[190:193], v169 offset:51200
	ds_read_b128 v[194:197], v169 offset:52224
	ds_read_b128 v[198:201], v169 offset:53248
	ds_read_b128 v[206:209], v169 offset:54272
	ds_read_b128 v[210:213], v169 offset:55296
	ds_read_b128 v[214:217], v169 offset:56320
	global_load_lds_dwordx4 v[218:219], off
	s_add_i32 m0, s30, 0x2000
	s_add_u32 s28, s28, 0x80080
	v_lshl_add_u64 v[218:219], v[220:221], 0, s[0:1]
	s_addc_u32 s29, s29, 0
	s_add_i32 s30, s43, s48
	global_load_lds_dwordx4 v[218:219], off
	v_lshl_add_u64 v[218:219], s[28:29], 0, v[138:139]
	s_mov_b32 m0, s30
	s_nop 0
	global_load_lds_dwordx4 v[218:219], off
	v_lshl_add_u64 v[218:219], s[28:29], 0, v[142:143]
	s_add_i32 m0, s30, 0x2000
	s_nop 0
	global_load_lds_dwordx4 v[218:219], off
	v_lshl_add_u64 v[218:219], v[222:223], 0, s[0:1]
	s_mov_b32 m0, s39
	s_nop 0
	global_load_lds_dwordx4 v[218:219], off
	v_lshl_add_u64 v[218:219], v[224:225], 0, s[0:1]
	s_mov_b32 m0, s40
	s_nop 0
	global_load_lds_dwordx4 v[218:219], off
	s_waitcnt vmcnt(8)
	s_waitcnt lgkmcnt(0)
	s_barrier
	s_waitcnt lgkmcnt(0)
	v_mfma_f32_16x16x32_bf16 v[60:63], v[128:131], v[182:185], v[60:63]
	v_mfma_f32_16x16x32_bf16 v[56:59], v[152:155], v[182:185], v[56:59]
	v_mfma_f32_16x16x32_bf16 v[44:47], v[128:131], v[190:193], v[44:47]
	v_mfma_f32_16x16x32_bf16 v[40:43], v[152:155], v[190:193], v[40:43]
	v_mfma_f32_16x16x32_bf16 v[28:31], v[128:131], v[198:201], v[28:31]
	v_mfma_f32_16x16x32_bf16 v[24:27], v[152:155], v[198:201], v[24:27]
	v_mfma_f32_16x16x32_bf16 v[12:15], v[128:131], v[210:213], v[12:15]
	v_mfma_f32_16x16x32_bf16 v[8:11], v[152:155], v[210:213], v[8:11]
	v_mfma_f32_16x16x32_bf16 v[60:63], v[132:135], v[186:189], v[60:63]
	v_mfma_f32_16x16x32_bf16 v[56:59], v[156:159], v[186:189], v[56:59]
	v_mfma_f32_16x16x32_bf16 v[44:47], v[132:135], v[194:197], v[44:47]
	v_mfma_f32_16x16x32_bf16 v[40:43], v[156:159], v[194:197], v[40:43]
	v_mfma_f32_16x16x32_bf16 v[28:31], v[132:135], v[206:209], v[28:31]
	v_mfma_f32_16x16x32_bf16 v[24:27], v[156:159], v[206:209], v[24:27]
	v_mfma_f32_16x16x32_bf16 v[12:15], v[132:135], v[214:217], v[12:15]
	v_mfma_f32_16x16x32_bf16 v[8:11], v[156:159], v[214:217], v[8:11]
	v_mfma_f32_16x16x32_bf16 v[52:55], v[160:163], v[182:185], v[52:55]
	v_mfma_f32_16x16x32_bf16 v[48:51], v[174:177], v[182:185], v[48:51]
	v_mfma_f32_16x16x32_bf16 v[36:39], v[160:163], v[190:193], v[36:39]
	v_mfma_f32_16x16x32_bf16 v[32:35], v[174:177], v[190:193], v[32:35]
	v_mfma_f32_16x16x32_bf16 v[20:23], v[160:163], v[198:201], v[20:23]
	v_mfma_f32_16x16x32_bf16 v[16:19], v[174:177], v[198:201], v[16:19]
	v_mfma_f32_16x16x32_bf16 v[4:7], v[160:163], v[210:213], v[4:7]
	v_mfma_f32_16x16x32_bf16 v[0:3], v[174:177], v[210:213], v[0:3]
	v_mfma_f32_16x16x32_bf16 v[52:55], v[170:173], v[186:189], v[52:55]
	v_mfma_f32_16x16x32_bf16 v[48:51], v[178:181], v[186:189], v[48:51]
	v_mfma_f32_16x16x32_bf16 v[36:39], v[170:173], v[194:197], v[36:39]
	v_mfma_f32_16x16x32_bf16 v[32:35], v[178:181], v[194:197], v[32:35]
	v_mfma_f32_16x16x32_bf16 v[20:23], v[170:173], v[206:209], v[20:23]
	v_mfma_f32_16x16x32_bf16 v[16:19], v[178:181], v[206:209], v[16:19]
	v_mfma_f32_16x16x32_bf16 v[4:7], v[170:173], v[214:217], v[4:7]
	v_mfma_f32_16x16x32_bf16 v[0:3], v[178:181], v[214:217], v[0:3]
	s_barrier
	s_add_i32 s25, s25, 2
	s_add_u32 s26, s26, 0x100
	s_addc_u32 s27, s27, 0
	s_add_u32 s17, s17, 0x100
	s_addc_u32 s23, s23, 0
	s_cmp_gt_u32 s25, 29
	s_cbranch_scc0 .LBB0_2195
	s_and_b64 vcc, exec, s[12:13]
	s_cbranch_vccz .LBB0_2198
	s_barrier

; #define PG8_STAGE(bufoff, gbase, voff) do { _Pragma("unroll") for (int _i = 0; _i < 2; ++_i) \
;         __builtin_amdgcn_global_load_lds((const unsigned*)((const char*)(gbase) + (voff)[_i]), (PG8_LAS unsigned*)(lds + (bufoff) + ldsw + _i * 8192), 16, 0, 0); } while (0)
; #define PG8_LDA(dst, b, h) do { _Pragma("unroll") for (int m = 0; m < 4; ++m) _Pragma("unroll") for (int k = 0; k < 2; ++k) dst[m][k] = *(const PG8_LAS bf16x8*)(lds + PG8_SA(b, h) + aoff + m * 2048 + k * 1024); } while (0)
; #define PG8_LDB(dst, b, h) do { _Pragma("unroll") for (int n = 0; n < 2; ++n) _Pragma("unroll") for (int k = 0; k < 2; ++k) dst[n][k] = *(const PG8_LAS bf16x8*)(lds + PG8_SB(b, h) + boff + n * 2048 + k * 1024); } while (0)
; #define PG8_MMA(ai, bj, At, Bt) do { __builtin_amdgcn_s_setprio(1); _Pragma("unroll") for (int m = 0; m < 4; ++m) _Pragma("unroll") for (int n = 0; n < 2; ++n) _Pragma("unroll") for (int k = 0; k < 2; ++k) \
;         acc[ai][bj][m][n] = __builtin_amdgcn_mfma_f32_16x16x32_bf16(Bt[n][k], At[m][k], acc[ai][bj][m][n], 0, 0, 0); __builtin_amdgcn_s_setprio(0); } while (0)
; #define PG8_WAIT_V(n) asm volatile("s_waitcnt vmcnt(" #n ")" ::: "memory")
; #define PG8_WAIT_L(n) asm volatile("s_waitcnt lgkmcnt(" #n ")" ::: "memory")
; #define PG8_BAR __builtin_amdgcn_s_barrier()
; #define PG8_SCHED __builtin_amdgcn_sched_barrier(0)
; template <class Epi, class Sched, bool ALIGN_EPI = false, bool SP2 = false>
; __device__ __forceinline__ void gemm_phase(PG8_LAS unsigned char* lds, const Gemm g, const Sched& S, const Epi& E) {
;     ...
;             PG8_LDB(B0, 0, 0); PG8_LDB(B1, 0, 1); PG8_SCHED; PG8_LDA(At, 0, 0); PG8_STAGE(PG8_SA(1, 1), a1 + hstepA, voffA);
;             PG8_WAIT_V(8); PG8_WAIT_L(0); PG8_BAR; PG8_MMA(0, 0, At, B0); PG8_MMA(0, 1, At, B1); PG8_BAR; PG8_SCHED;
;             PG8_LDA(At, 0, 1); PG8_STAGE(PG8_SB(0, 0), b2, voffB); PG8_STAGE(PG8_SB(0, 1), b2 + hstep, voffB); PG8_STAGE(PG8_SA(0, 0), a2, voffA);
.LBB0_2283:
	ds_read_b128 v[128:131], v207
	ds_read_b128 v[132:135], v207 offset:1024
	ds_read_b128 v[136:139], v207 offset:2048
	ds_read_b128 v[140:143], v207 offset:3072
	ds_read_b128 v[144:147], v208
	ds_read_b128 v[148:151], v208 offset:1024
	ds_read_b128 v[152:155], v208 offset:2048
	ds_read_b128 v[156:159], v208 offset:3072
	s_add_u32 s26, s24, 0x100
	s_addc_u32 s27, s25, 0
	s_cmp_eq_u32 s33, 28
	s_cselect_b32 s31, s77, s27
	s_cselect_b32 s30, s76, s26
	s_cselect_b32 s29, s1, s7
	s_cselect_b32 s28, s3, s6
	v_lshl_add_u64 v[220:221], s[24:25], 0, v[170:171]
	s_add_i32 m0, s81, 0xc000
	ds_read_b128 v[178:181], v209
	ds_read_b128 v[182:185], v209 offset:1024
	ds_read_b128 v[186:189], v209 offset:2048
	ds_read_b128 v[190:193], v209 offset:3072
	ds_read_b128 v[194:197], v209 offset:4096
	ds_read_b128 v[198:201], v209 offset:5120
	ds_read_b128 v[212:215], v209 offset:6144
	ds_read_b128 v[216:219], v209 offset:7168
	global_load_lds_dwordx4 v[220:221], off
	v_lshl_add_u64 v[220:221], s[24:25], 0, v[172:173]
	s_add_i32 m0, s81, 0xe000
	s_nop 0
	global_load_lds_dwordx4 v[220:221], off
	s_waitcnt vmcnt(8)
	s_waitcnt lgkmcnt(0)
	s_barrier
	s_waitcnt lgkmcnt(0)
	v_mfma_f32_16x16x32_bf16 v[124:127], v[128:131], v[178:181], v[124:127]
	v_mfma_f32_16x16x32_bf16 v[60:63], v[136:139], v[178:181], v[60:63]
	v_mfma_f32_16x16x32_bf16 v[120:123], v[128:131], v[186:189], v[120:123]
	v_mfma_f32_16x16x32_bf16 v[56:59], v[136:139], v[186:189], v[56:59]
	v_mfma_f32_16x16x32_bf16 v[116:119], v[128:131], v[194:197], v[116:119]
	v_mfma_f32_16x16x32_bf16 v[52:55], v[136:139], v[194:197], v[52:55]
	v_mfma_f32_16x16x32_bf16 v[108:111], v[128:131], v[212:215], v[108:111]
	v_mfma_f32_16x16x32_bf16 v[44:47], v[136:139], v[212:215], v[44:47]
	v_mfma_f32_16x16x32_bf16 v[124:127], v[132:135], v[182:185], v[124:127]
	v_mfma_f32_16x16x32_bf16 v[60:63], v[140:143], v[182:185], v[60:63]
	v_mfma_f32_16x16x32_bf16 v[120:123], v[132:135], v[190:193], v[120:123]
	v_mfma_f32_16x16x32_bf16 v[56:59], v[140:143], v[190:193], v[56:59]
	v_mfma_f32_16x16x32_bf16 v[116:119], v[132:135], v[198:201], v[116:119]
	v_mfma_f32_16x16x32_bf16 v[52:55], v[140:143], v[198:201], v[52:55]
	v_mfma_f32_16x16x32_bf16 v[108:111], v[132:135], v[216:219], v[108:111]
	v_mfma_f32_16x16x32_bf16 v[44:47], v[140:143], v[216:219], v[44:47]
	v_mfma_f32_16x16x32_bf16 v[112:115], v[144:147], v[178:181], v[112:115]
	v_mfma_f32_16x16x32_bf16 v[48:51], v[152:155], v[178:181], v[48:51]
	v_mfma_f32_16x16x32_bf16 v[104:107], v[144:147], v[186:189], v[104:107]
	v_mfma_f32_16x16x32_bf16 v[40:43], v[152:155], v[186:189], v[40:43]
	v_mfma_f32_16x16x32_bf16 v[100:103], v[144:147], v[194:197], v[100:103]
	v_mfma_f32_16x16x32_bf16 v[36:39], v[152:155], v[194:197], v[36:39]
	v_mfma_f32_16x16x32_bf16 v[96:99], v[144:147], v[212:215], v[96:99]
	v_mfma_f32_16x16x32_bf16 v[32:35], v[152:155], v[212:215], v[32:35]
	v_mfma_f32_16x16x32_bf16 v[112:115], v[148:151], v[182:185], v[112:115]
	v_mfma_f32_16x16x32_bf16 v[48:51], v[156:159], v[182:185], v[48:51]
	v_mfma_f32_16x16x32_bf16 v[104:107], v[148:151], v[190:193], v[104:107]
	v_mfma_f32_16x16x32_bf16 v[40:43], v[156:159], v[190:193], v[40:43]
	v_mfma_f32_16x16x32_bf16 v[100:103], v[148:151], v[198:201], v[100:103]
	v_mfma_f32_16x16x32_bf16 v[36:39], v[156:159], v[198:201], v[36:39]
	v_mfma_f32_16x16x32_bf16 v[96:99], v[148:151], v[216:219], v[96:99]
	v_mfma_f32_16x16x32_bf16 v[32:35], v[156:159], v[216:219], v[32:35]
	s_barrier
	s_add_i32 s24, s90, s80
	v_lshl_add_u64 v[220:221], s[28:29], 0, v[162:163]
	s_mov_b32 m0, s24
	ds_read_b128 v[178:181], v209 offset:16384
	ds_read_b128 v[182:185], v209 offset:17408
	ds_read_b128 v[186:189], v209 offset:18432
	ds_read_b128 v[190:193], v209 offset:19456
	ds_read_b128 v[194:197], v209 offset:20480
	ds_read_b128 v[198:201], v209 offset:21504
	ds_read_b128 v[212:215], v209 offset:22528
	ds_read_b128 v[216:219], v209 offset:23552
	global_load_lds_dwordx4 v[220:221], off
	s_add_i32 m0, s24, 0x2000
	s_add_u32 s24, s28, 0x80000
	v_lshl_add_u64 v[222:223], s[28:29], 0, v[166:167]
	s_addc_u32 s25, s29, 0
	s_add_i32 s38, s91, s80
	global_load_lds_dwordx4 v[222:223], off
	v_lshl_add_u64 v[224:225], s[24:25], 0, v[162:163]
	s_mov_b32 m0, s38
	v_lshl_add_u64 v[226:227], s[30:31], 0, v[164:165]
	global_load_lds_dwordx4 v[224:225], off
	v_lshl_add_u64 v[224:225], s[24:25], 0, v[166:167]
	s_add_i32 m0, s38, 0x2000
	s_nop 0
	global_load_lds_dwordx4 v[224:225], off
	v_lshl_add_u64 v[224:225], s[30:31], 0, v[160:161]
	s_mov_b32 m0, s81
	s_nop 0
	global_load_lds_dwordx4 v[224:225], off
	s_mov_b32 m0, s82
	s_nop 0
	global_load_lds_dwordx4 v[226:227], off
	s_waitcnt vmcnt(8)
	s_waitcnt lgkmcnt(0)
	s_barrier
; #define PG8_STAGE(bufoff, gbase, voff) do { _Pragma("unroll") for (int _i = 0; _i < 2; ++_i) \
;         __builtin_amdgcn_global_load_lds((const unsigned*)((const char*)(gbase) + (voff)[_i]), (PG8_LAS unsigned*)(lds + (bufoff) + ldsw + _i * 8192), 16, 0, 0); } while (0)
; #define PG8_LDA(dst, b, h) do { _Pragma("unroll") for (int m = 0; m < 4; ++m) _Pragma("unroll") for (int k = 0; k < 2; ++k) dst[m][k] = *(const PG8_LAS bf16x8*)(lds + PG8_SA(b, h) + aoff + m * 2048 + k * 1024); } while (0)
; #define PG8_LDB(dst, b, h) do { _Pragma("unroll") for (int n = 0; n < 2; ++n) _Pragma("unroll") for (int k = 0; k < 2; ++k) dst[n][k] = *(const PG8_LAS bf16x8*)(lds + PG8_SB(b, h) + boff + n * 2048 + k * 1024); } while (0)
; #define PG8_MMA(ai, bj, At, Bt) do { __builtin_amdgcn_s_setprio(1); _Pragma("unroll") for (int m = 0; m < 4; ++m) _Pragma("unroll") for (int n = 0; n < 2; ++n) _Pragma("unroll") for (int k = 0; k < 2; ++k) \
;         acc[ai][bj][m][n] = __builtin_amdgcn_mfma_f32_16x16x32_bf16(Bt[n][k], At[m][k], acc[ai][bj][m][n], 0, 0, 0); __builtin_amdgcn_s_setprio(0); } while (0)
; #define PG8_WAIT_V(n) asm volatile("s_waitcnt vmcnt(" #n ")" ::: "memory")
; #define PG8_WAIT_L(n) asm volatile("s_waitcnt lgkmcnt(" #n ")" ::: "memory")
; #define PG8_BAR __builtin_amdgcn_s_barrier()
; #define PG8_SCHED __builtin_amdgcn_sched_barrier(0)
; template <class Epi, class Sched, bool ALIGN_EPI = false, bool SP2 = false>
; __device__ __forceinline__ void gemm_phase(PG8_LAS unsigned char* lds, const Gemm g, const Sched& S, const Epi& E) {
;     ...
;             PG8_WAIT_V(8); PG8_WAIT_L(0); PG8_BAR; PG8_MMA(1, 0, At, B0); PG8_MMA(1, 1, At, B1); PG8_BAR; PG8_SCHED;
;             PG8_LDB(B0, 1, 0); PG8_LDB(B1, 1, 1); PG8_SCHED; PG8_LDA(At, 1, 0); PG8_STAGE(PG8_SA(0, 1), a2 + hstepA, voffA);
;             PG8_WAIT_V(8); PG8_WAIT_L(0); PG8_BAR; PG8_MMA(0, 0, At, B0); PG8_MMA(0, 1, At, B1); PG8_BAR; PG8_SCHED;
	s_waitcnt lgkmcnt(0)
	v_mfma_f32_16x16x32_bf16 v[92:95], v[128:131], v[178:181], v[92:95]
	v_mfma_f32_16x16x32_bf16 v[28:31], v[136:139], v[178:181], v[28:31]
	v_mfma_f32_16x16x32_bf16 v[88:91], v[128:131], v[186:189], v[88:91]
	v_mfma_f32_16x16x32_bf16 v[24:27], v[136:139], v[186:189], v[24:27]
	v_mfma_f32_16x16x32_bf16 v[84:87], v[128:131], v[194:197], v[84:87]
	v_mfma_f32_16x16x32_bf16 v[20:23], v[136:139], v[194:197], v[20:23]
	v_mfma_f32_16x16x32_bf16 v[76:79], v[128:131], v[212:215], v[76:79]
	v_mfma_f32_16x16x32_bf16 v[12:15], v[136:139], v[212:215], v[12:15]
	v_mfma_f32_16x16x32_bf16 v[92:95], v[132:135], v[182:185], v[92:95]
	v_mfma_f32_16x16x32_bf16 v[28:31], v[140:143], v[182:185], v[28:31]
	v_mfma_f32_16x16x32_bf16 v[88:91], v[132:135], v[190:193], v[88:91]
	v_mfma_f32_16x16x32_bf16 v[24:27], v[140:143], v[190:193], v[24:27]
	v_mfma_f32_16x16x32_bf16 v[84:87], v[132:135], v[198:201], v[84:87]
	v_mfma_f32_16x16x32_bf16 v[20:23], v[140:143], v[198:201], v[20:23]
	v_mfma_f32_16x16x32_bf16 v[76:79], v[132:135], v[216:219], v[76:79]
	v_mfma_f32_16x16x32_bf16 v[12:15], v[140:143], v[216:219], v[12:15]
	v_mfma_f32_16x16x32_bf16 v[80:83], v[144:147], v[178:181], v[80:83]
	v_mfma_f32_16x16x32_bf16 v[16:19], v[152:155], v[178:181], v[16:19]
	v_mfma_f32_16x16x32_bf16 v[72:75], v[144:147], v[186:189], v[72:75]
	v_mfma_f32_16x16x32_bf16 v[8:11], v[152:155], v[186:189], v[8:11]
	v_mfma_f32_16x16x32_bf16 v[68:71], v[144:147], v[194:197], v[68:71]
	v_mfma_f32_16x16x32_bf16 v[4:7], v[152:155], v[194:197], v[4:7]
	v_mfma_f32_16x16x32_bf16 v[64:67], v[144:147], v[212:215], v[64:67]
	v_mfma_f32_16x16x32_bf16 v[0:3], v[152:155], v[212:215], v[0:3]
	v_mfma_f32_16x16x32_bf16 v[80:83], v[148:151], v[182:185], v[80:83]
	v_mfma_f32_16x16x32_bf16 v[16:19], v[156:159], v[182:185], v[16:19]
	v_mfma_f32_16x16x32_bf16 v[72:75], v[148:151], v[190:193], v[72:75]
	v_mfma_f32_16x16x32_bf16 v[8:11], v[156:159], v[190:193], v[8:11]
	v_mfma_f32_16x16x32_bf16 v[68:71], v[148:151], v[198:201], v[68:71]
	v_mfma_f32_16x16x32_bf16 v[4:7], v[156:159], v[198:201], v[4:7]
	v_mfma_f32_16x16x32_bf16 v[64:67], v[148:151], v[216:219], v[64:67]
	v_mfma_f32_16x16x32_bf16 v[0:3], v[156:159], v[216:219], v[0:3]
	s_barrier
	s_add_i32 s38, 0, 0x18000
	s_add_i32 s39, 0, 0x1c000
	v_add_u32_e32 v140, s38, v203
	v_add_u32_e32 v156, s39, v203
	ds_read_b128 v[128:131], v140
	ds_read_b128 v[132:135], v140 offset:1024
	ds_read_b128 v[136:139], v140 offset:2048
	ds_read_b128 v[140:143], v140 offset:3072
	ds_read_b128 v[144:147], v156
	ds_read_b128 v[148:151], v156 offset:1024
	ds_read_b128 v[152:155], v156 offset:2048
	ds_read_b128 v[156:159], v156 offset:3072
	s_add_u32 s24, s30, 0x7c000
	s_addc_u32 s25, s31, 0
	s_mov_b32 m0, s83
	v_lshl_add_u64 v[228:229], s[24:25], 0, v[160:161]
	ds_read_b128 v[178:181], v209 offset:32768
	ds_read_b128 v[182:185], v209 offset:33792
	ds_read_b128 v[186:189], v209 offset:34816
	ds_read_b128 v[190:193], v209 offset:35840
	ds_read_b128 v[194:197], v209 offset:36864
	ds_read_b128 v[198:201], v209 offset:37888
	ds_read_b128 v[212:215], v209 offset:38912
	ds_read_b128 v[216:219], v209 offset:39936
	global_load_lds_dwordx4 v[228:229], off
	v_lshl_add_u64 v[228:229], s[24:25], 0, v[164:165]
	s_mov_b32 m0, s84
	s_nop 0
	global_load_lds_dwordx4 v[228:229], off
	s_waitcnt vmcnt(8)
	s_waitcnt lgkmcnt(0)
	s_barrier
	s_waitcnt lgkmcnt(0)
	v_mfma_f32_16x16x32_bf16 v[124:127], v[128:131], v[178:181], v[124:127]
	v_mfma_f32_16x16x32_bf16 v[60:63], v[136:139], v[178:181], v[60:63]
	v_mfma_f32_16x16x32_bf16 v[120:123], v[128:131], v[186:189], v[120:123]
	v_mfma_f32_16x16x32_bf16 v[56:59], v[136:139], v[186:189], v[56:59]
	v_mfma_f32_16x16x32_bf16 v[116:119], v[128:131], v[194:197], v[116:119]
	v_mfma_f32_16x16x32_bf16 v[52:55], v[136:139], v[194:197], v[52:55]
	v_mfma_f32_16x16x32_bf16 v[108:111], v[128:131], v[212:215], v[108:111]
	v_mfma_f32_16x16x32_bf16 v[44:47], v[136:139], v[212:215], v[44:47]
	v_mfma_f32_16x16x32_bf16 v[124:127], v[132:135], v[182:185], v[124:127]
	v_mfma_f32_16x16x32_bf16 v[60:63], v[140:143], v[182:185], v[60:63]
	v_mfma_f32_16x16x32_bf16 v[120:123], v[132:135], v[190:193], v[120:123]
	v_mfma_f32_16x16x32_bf16 v[56:59], v[140:143], v[190:193], v[56:59]
	v_mfma_f32_16x16x32_bf16 v[116:119], v[132:135], v[198:201], v[116:119]
	v_mfma_f32_16x16x32_bf16 v[52:55], v[140:143], v[198:201], v[52:55]
	v_mfma_f32_16x16x32_bf16 v[108:111], v[132:135], v[216:219], v[108:111]
	v_mfma_f32_16x16x32_bf16 v[44:47], v[140:143], v[216:219], v[44:47]
	v_mfma_f32_16x16x32_bf16 v[112:115], v[144:147], v[178:181], v[112:115]
	v_mfma_f32_16x16x32_bf16 v[48:51], v[152:155], v[178:181], v[48:51]
	v_mfma_f32_16x16x32_bf16 v[104:107], v[144:147], v[186:189], v[104:107]
	v_mfma_f32_16x16x32_bf16 v[40:43], v[152:155], v[186:189], v[40:43]
	v_mfma_f32_16x16x32_bf16 v[100:103], v[144:147], v[194:197], v[100:103]
	v_mfma_f32_16x16x32_bf16 v[36:39], v[152:155], v[194:197], v[36:39]
	v_mfma_f32_16x16x32_bf16 v[96:99], v[144:147], v[212:215], v[96:99]
	v_mfma_f32_16x16x32_bf16 v[32:35], v[152:155], v[212:215], v[32:35]
	v_mfma_f32_16x16x32_bf16 v[112:115], v[148:151], v[182:185], v[112:115]
	v_mfma_f32_16x16x32_bf16 v[48:51], v[156:159], v[182:185], v[48:51]
	v_mfma_f32_16x16x32_bf16 v[104:107], v[148:151], v[190:193], v[104:107]
	v_mfma_f32_16x16x32_bf16 v[40:43], v[156:159], v[190:193], v[40:43]
	v_mfma_f32_16x16x32_bf16 v[100:103], v[148:151], v[198:201], v[100:103]
	v_mfma_f32_16x16x32_bf16 v[36:39], v[156:159], v[198:201], v[36:39]
	v_mfma_f32_16x16x32_bf16 v[96:99], v[148:151], v[216:219], v[96:99]
	v_mfma_f32_16x16x32_bf16 v[32:35], v[156:159], v[216:219], v[32:35]
	s_barrier
; #define PG8_STAGE(bufoff, gbase, voff) do { _Pragma("unroll") for (int _i = 0; _i < 2; ++_i) \
;         __builtin_amdgcn_global_load_lds((const unsigned*)((const char*)(gbase) + (voff)[_i]), (PG8_LAS unsigned*)(lds + (bufoff) + ldsw + _i * 8192), 16, 0, 0); } while (0)
; #define PG8_LDA(dst, b, h) do { _Pragma("unroll") for (int m = 0; m < 4; ++m) _Pragma("unroll") for (int k = 0; k < 2; ++k) dst[m][k] = *(const PG8_LAS bf16x8*)(lds + PG8_SA(b, h) + aoff + m * 2048 + k * 1024); } while (0)
; #define PG8_MMA(ai, bj, At, Bt) do { __builtin_amdgcn_s_setprio(1); _Pragma("unroll") for (int m = 0; m < 4; ++m) _Pragma("unroll") for (int n = 0; n < 2; ++n) _Pragma("unroll") for (int k = 0; k < 2; ++k) \
;         acc[ai][bj][m][n] = __builtin_amdgcn_mfma_f32_16x16x32_bf16(Bt[n][k], At[m][k], acc[ai][bj][m][n], 0, 0, 0); __builtin_amdgcn_s_setprio(0); } while (0)
; #define PG8_WAIT_V(n) asm volatile("s_waitcnt vmcnt(" #n ")" ::: "memory")
; #define PG8_WAIT_L(n) asm volatile("s_waitcnt lgkmcnt(" #n ")" ::: "memory")
; #define PG8_BAR __builtin_amdgcn_s_barrier()
; #define PG8_SCHED __builtin_amdgcn_sched_barrier(0)
; template <class Epi, class Sched, bool ALIGN_EPI = false, bool SP2 = false>
; __device__ __forceinline__ void gemm_phase(PG8_LAS unsigned char* lds, const Gemm g, const Sched& S, const Epi& E) {
;     ...
;             PG8_LDA(At, 1, 1); PG8_STAGE(PG8_SB(1, 0), b3, voffB); PG8_STAGE(PG8_SB(1, 1), b3 + hstep, voffB); PG8_STAGE(PG8_SA(1, 0), a3, voffA);
;             PG8_WAIT_V(8); PG8_WAIT_L(0); PG8_BAR; PG8_MMA(1, 0, At, B0); PG8_MMA(1, 1, At, B1); PG8_BAR; PG8_SCHED;
	s_add_i32 s24, s38, s80
	v_lshl_add_u64 v[220:221], v[220:221], 0, s[20:21]
	s_mov_b32 m0, s24
	ds_read_b128 v[178:181], v209 offset:49152
	ds_read_b128 v[182:185], v209 offset:50176
	ds_read_b128 v[186:189], v209 offset:51200
	ds_read_b128 v[190:193], v209 offset:52224
	ds_read_b128 v[194:197], v209 offset:53248
	ds_read_b128 v[198:201], v209 offset:54272
	ds_read_b128 v[212:215], v209 offset:55296
	ds_read_b128 v[216:219], v209 offset:56320
	global_load_lds_dwordx4 v[220:221], off
	s_add_i32 m0, s24, 0x2000
	s_add_u32 s24, s28, 0x80080
	v_lshl_add_u64 v[220:221], v[222:223], 0, s[20:21]
	s_addc_u32 s25, s29, 0
	s_add_i32 s28, s39, s80
	global_load_lds_dwordx4 v[220:221], off
	v_lshl_add_u64 v[220:221], s[24:25], 0, v[162:163]
	s_mov_b32 m0, s28
	s_nop 0
	global_load_lds_dwordx4 v[220:221], off
	v_lshl_add_u64 v[220:221], s[24:25], 0, v[166:167]
	s_add_i32 m0, s28, 0x2000
	s_nop 0
	global_load_lds_dwordx4 v[220:221], off
	v_lshl_add_u64 v[220:221], v[224:225], 0, s[20:21]
	s_mov_b32 m0, s87
	s_nop 0
	global_load_lds_dwordx4 v[220:221], off
	v_lshl_add_u64 v[220:221], v[226:227], 0, s[20:21]
	s_mov_b32 m0, s88
	s_nop 0
	global_load_lds_dwordx4 v[220:221], off
	s_waitcnt vmcnt(8)
	s_waitcnt lgkmcnt(0)
	s_barrier
	s_waitcnt lgkmcnt(0)
	v_mfma_f32_16x16x32_bf16 v[92:95], v[128:131], v[178:181], v[92:95]
	v_mfma_f32_16x16x32_bf16 v[28:31], v[136:139], v[178:181], v[28:31]
	v_mfma_f32_16x16x32_bf16 v[88:91], v[128:131], v[186:189], v[88:91]
	v_mfma_f32_16x16x32_bf16 v[24:27], v[136:139], v[186:189], v[24:27]
	v_mfma_f32_16x16x32_bf16 v[84:87], v[128:131], v[194:197], v[84:87]
	v_mfma_f32_16x16x32_bf16 v[20:23], v[136:139], v[194:197], v[20:23]
	v_mfma_f32_16x16x32_bf16 v[76:79], v[128:131], v[212:215], v[76:79]
	v_mfma_f32_16x16x32_bf16 v[12:15], v[136:139], v[212:215], v[12:15]
	v_mfma_f32_16x16x32_bf16 v[92:95], v[132:135], v[182:185], v[92:95]
	v_mfma_f32_16x16x32_bf16 v[28:31], v[140:143], v[182:185], v[28:31]
	v_mfma_f32_16x16x32_bf16 v[88:91], v[132:135], v[190:193], v[88:91]
	v_mfma_f32_16x16x32_bf16 v[24:27], v[140:143], v[190:193], v[24:27]
	v_mfma_f32_16x16x32_bf16 v[84:87], v[132:135], v[198:201], v[84:87]
	v_mfma_f32_16x16x32_bf16 v[20:23], v[140:143], v[198:201], v[20:23]
	v_mfma_f32_16x16x32_bf16 v[76:79], v[132:135], v[216:219], v[76:79]
	v_mfma_f32_16x16x32_bf16 v[12:15], v[140:143], v[216:219], v[12:15]
	v_mfma_f32_16x16x32_bf16 v[80:83], v[144:147], v[178:181], v[80:83]
	v_mfma_f32_16x16x32_bf16 v[16:19], v[152:155], v[178:181], v[16:19]
	v_mfma_f32_16x16x32_bf16 v[72:75], v[144:147], v[186:189], v[72:75]
	v_mfma_f32_16x16x32_bf16 v[8:11], v[152:155], v[186:189], v[8:11]
	v_mfma_f32_16x16x32_bf16 v[68:71], v[144:147], v[194:197], v[68:71]
	v_mfma_f32_16x16x32_bf16 v[4:7], v[152:155], v[194:197], v[4:7]
	v_mfma_f32_16x16x32_bf16 v[64:67], v[144:147], v[212:215], v[64:67]
	v_mfma_f32_16x16x32_bf16 v[0:3], v[152:155], v[212:215], v[0:3]
	v_mfma_f32_16x16x32_bf16 v[80:83], v[148:151], v[182:185], v[80:83]
	v_mfma_f32_16x16x32_bf16 v[16:19], v[156:159], v[182:185], v[16:19]
	v_mfma_f32_16x16x32_bf16 v[72:75], v[148:151], v[190:193], v[72:75]
	v_mfma_f32_16x16x32_bf16 v[8:11], v[156:159], v[190:193], v[8:11]
	v_mfma_f32_16x16x32_bf16 v[68:71], v[148:151], v[198:201], v[68:71]
	v_mfma_f32_16x16x32_bf16 v[4:7], v[156:159], v[198:201], v[4:7]
	v_mfma_f32_16x16x32_bf16 v[64:67], v[148:151], v[216:219], v[64:67]
	v_mfma_f32_16x16x32_bf16 v[0:3], v[156:159], v[216:219], v[0:3]
	s_barrier
	s_add_i32 s33, s33, 2
	s_add_u32 s6, s6, 0x100
	s_addc_u32 s7, s7, 0
	s_cmp_gt_u32 s33, 29
	s_mov_b64 s[24:25], s[26:27]
	s_cbranch_scc0 .LBB0_2283
	s_and_b64 vcc, exec, s[22:23]
	s_cbranch_vccz .LBB0_2286
	s_barrier

; #define PG8_STAGE(bufoff, gbase, voff) do { _Pragma("unroll") for (int _i = 0; _i < 2; ++_i) \
;         __builtin_amdgcn_global_load_lds((const unsigned*)((const char*)(gbase) + (voff)[_i]), (PG8_LAS unsigned*)(lds + (bufoff) + ldsw + _i * 8192), 16, 0, 0); } while (0)
; #define PG8_LDA(dst, b, h) do { _Pragma("unroll") for (int m = 0; m < 4; ++m) _Pragma("unroll") for (int k = 0; k < 2; ++k) dst[m][k] = *(const PG8_LAS bf16x8*)(lds + PG8_SA(b, h) + aoff + m * 2048 + k * 1024); } while (0)
; #define PG8_LDB(dst, b, h) do { _Pragma("unroll") for (int n = 0; n < 2; ++n) _Pragma("unroll") for (int k = 0; k < 2; ++k) dst[n][k] = *(const PG8_LAS bf16x8*)(lds + PG8_SB(b, h) + boff + n * 2048 + k * 1024); } while (0)
; #define PG8_MMA(ai, bj, At, Bt) do { __builtin_amdgcn_s_setprio(1); _Pragma("unroll") for (int m = 0; m < 4; ++m) _Pragma("unroll") for (int n = 0; n < 2; ++n) _Pragma("unroll") for (int k = 0; k < 2; ++k) \
;         acc[ai][bj][m][n] = __builtin_amdgcn_mfma_f32_16x16x32_bf16(Bt[n][k], At[m][k], acc[ai][bj][m][n], 0, 0, 0); __builtin_amdgcn_s_setprio(0); } while (0)
; #define PG8_WAIT_V(n) asm volatile("s_waitcnt vmcnt(" #n ")" ::: "memory")
; #define PG8_WAIT_L(n) asm volatile("s_waitcnt lgkmcnt(" #n ")" ::: "memory")
; #define PG8_BAR __builtin_amdgcn_s_barrier()
; #define PG8_SCHED __builtin_amdgcn_sched_barrier(0)
; template <class Epi, class Sched, bool ALIGN_EPI = false, bool SP2 = false>
; __device__ __forceinline__ void gemm_phase(PG8_LAS unsigned char* lds, const Gemm g, const Sched& S, const Epi& E) {
;     ...
;             PG8_LDB(B0, 0, 0); PG8_LDB(B1, 0, 1); PG8_SCHED; PG8_LDA(At, 0, 0); PG8_STAGE(PG8_SA(1, 1), a1 + hstepA, voffA);
;             PG8_WAIT_V(8); PG8_WAIT_L(0); PG8_BAR; PG8_MMA(0, 0, At, B0); PG8_MMA(0, 1, At, B1); PG8_BAR; PG8_SCHED;
;             PG8_LDA(At, 0, 1); PG8_STAGE(PG8_SB(0, 0), b2, voffB); PG8_STAGE(PG8_SB(0, 1), b2 + hstep, voffB); PG8_STAGE(PG8_SA(0, 0), a2, voffA);
.LBB0_2427:
	ds_read_b128 v[128:131], v167
	ds_read_b128 v[132:135], v167 offset:1024
	ds_read_b128 v[152:155], v167 offset:2048
	ds_read_b128 v[156:159], v167 offset:3072
	ds_read_b128 v[160:163], v168
	ds_read_b128 v[170:173], v168 offset:1024
	ds_read_b128 v[174:177], v168 offset:2048
	ds_read_b128 v[178:181], v168 offset:3072
	s_add_u32 s18, s16, 0x100
	s_addc_u32 s19, s17, 0
	s_cmpk_eq_i32 s48, 0x54
	s_cselect_b32 s23, s13, s19
	s_cselect_b32 s22, s12, s18
	s_cselect_b32 s21, s15, s43
	s_cselect_b32 s20, s14, s42
	v_lshl_add_u64 v[218:219], s[16:17], 0, v[144:145]
	s_add_i32 m0, s29, 0xc000
	ds_read_b128 v[182:185], v169
	ds_read_b128 v[186:189], v169 offset:1024
	ds_read_b128 v[190:193], v169 offset:2048
	ds_read_b128 v[194:197], v169 offset:3072
	ds_read_b128 v[198:201], v169 offset:4096
	ds_read_b128 v[206:209], v169 offset:5120
	ds_read_b128 v[210:213], v169 offset:6144
	ds_read_b128 v[214:217], v169 offset:7168
	global_load_lds_dwordx4 v[218:219], off
	v_lshl_add_u64 v[218:219], s[16:17], 0, v[146:147]
	s_add_i32 m0, s29, 0xe000
	s_nop 0
	global_load_lds_dwordx4 v[218:219], off
	s_waitcnt vmcnt(8)
	s_waitcnt lgkmcnt(0)
	s_barrier
	s_waitcnt lgkmcnt(0)
	v_mfma_f32_16x16x32_bf16 v[124:127], v[128:131], v[182:185], v[124:127]
	v_mfma_f32_16x16x32_bf16 v[120:123], v[152:155], v[182:185], v[120:123]
	v_mfma_f32_16x16x32_bf16 v[108:111], v[128:131], v[190:193], v[108:111]
	v_mfma_f32_16x16x32_bf16 v[104:107], v[152:155], v[190:193], v[104:107]
	v_mfma_f32_16x16x32_bf16 v[92:95], v[128:131], v[198:201], v[92:95]
	v_mfma_f32_16x16x32_bf16 v[88:91], v[152:155], v[198:201], v[88:91]
	v_mfma_f32_16x16x32_bf16 v[76:79], v[128:131], v[210:213], v[76:79]
	v_mfma_f32_16x16x32_bf16 v[72:75], v[152:155], v[210:213], v[72:75]
	v_mfma_f32_16x16x32_bf16 v[124:127], v[132:135], v[186:189], v[124:127]
	v_mfma_f32_16x16x32_bf16 v[120:123], v[156:159], v[186:189], v[120:123]
	v_mfma_f32_16x16x32_bf16 v[108:111], v[132:135], v[194:197], v[108:111]
	v_mfma_f32_16x16x32_bf16 v[104:107], v[156:159], v[194:197], v[104:107]
	v_mfma_f32_16x16x32_bf16 v[92:95], v[132:135], v[206:209], v[92:95]
	v_mfma_f32_16x16x32_bf16 v[88:91], v[156:159], v[206:209], v[88:91]
	v_mfma_f32_16x16x32_bf16 v[76:79], v[132:135], v[214:217], v[76:79]
	v_mfma_f32_16x16x32_bf16 v[72:75], v[156:159], v[214:217], v[72:75]
	v_mfma_f32_16x16x32_bf16 v[116:119], v[160:163], v[182:185], v[116:119]
	v_mfma_f32_16x16x32_bf16 v[112:115], v[174:177], v[182:185], v[112:115]
	v_mfma_f32_16x16x32_bf16 v[100:103], v[160:163], v[190:193], v[100:103]
	v_mfma_f32_16x16x32_bf16 v[96:99], v[174:177], v[190:193], v[96:99]
	v_mfma_f32_16x16x32_bf16 v[84:87], v[160:163], v[198:201], v[84:87]
	v_mfma_f32_16x16x32_bf16 v[80:83], v[174:177], v[198:201], v[80:83]
	v_mfma_f32_16x16x32_bf16 v[68:71], v[160:163], v[210:213], v[68:71]
	v_mfma_f32_16x16x32_bf16 v[64:67], v[174:177], v[210:213], v[64:67]
	v_mfma_f32_16x16x32_bf16 v[116:119], v[170:173], v[186:189], v[116:119]
	v_mfma_f32_16x16x32_bf16 v[112:115], v[178:181], v[186:189], v[112:115]
	v_mfma_f32_16x16x32_bf16 v[100:103], v[170:173], v[194:197], v[100:103]
	v_mfma_f32_16x16x32_bf16 v[96:99], v[178:181], v[194:197], v[96:99]
	v_mfma_f32_16x16x32_bf16 v[84:87], v[170:173], v[206:209], v[84:87]
	v_mfma_f32_16x16x32_bf16 v[80:83], v[178:181], v[206:209], v[80:83]
	v_mfma_f32_16x16x32_bf16 v[68:71], v[170:173], v[214:217], v[68:71]
	v_mfma_f32_16x16x32_bf16 v[64:67], v[178:181], v[214:217], v[64:67]
	s_barrier
	s_add_i32 s16, s39, s28
	v_lshl_add_u64 v[218:219], s[20:21], 0, v[138:139]
	s_mov_b32 m0, s16
	ds_read_b128 v[182:185], v169 offset:16384
	ds_read_b128 v[186:189], v169 offset:17408
	ds_read_b128 v[190:193], v169 offset:18432
	ds_read_b128 v[194:197], v169 offset:19456
	ds_read_b128 v[198:201], v169 offset:20480
	ds_read_b128 v[206:209], v169 offset:21504
	ds_read_b128 v[210:213], v169 offset:22528
	ds_read_b128 v[214:217], v169 offset:23552
	global_load_lds_dwordx4 v[218:219], off
	s_add_i32 m0, s16, 0x2000
	s_add_u32 s16, s20, 0x160000
	v_lshl_add_u64 v[220:221], s[20:21], 0, v[142:143]
	s_addc_u32 s17, s21, 0
	s_add_i32 s49, s40, s28
	global_load_lds_dwordx4 v[220:221], off
	v_lshl_add_u64 v[222:223], s[16:17], 0, v[138:139]
	s_mov_b32 m0, s49
	v_lshl_add_u64 v[224:225], s[22:23], 0, v[140:141]
	global_load_lds_dwordx4 v[222:223], off
	v_lshl_add_u64 v[222:223], s[16:17], 0, v[142:143]
	s_add_i32 m0, s49, 0x2000
	s_nop 0
	global_load_lds_dwordx4 v[222:223], off
	v_lshl_add_u64 v[222:223], s[22:23], 0, v[136:137]
	s_mov_b32 m0, s29
	s_nop 0
	global_load_lds_dwordx4 v[222:223], off
	s_mov_b32 m0, s30
	s_nop 0
	global_load_lds_dwordx4 v[224:225], off
	s_waitcnt vmcnt(8)
	s_waitcnt lgkmcnt(0)
	s_barrier
; #define PG8_STAGE(bufoff, gbase, voff) do { _Pragma("unroll") for (int _i = 0; _i < 2; ++_i) \
;         __builtin_amdgcn_global_load_lds((const unsigned*)((const char*)(gbase) + (voff)[_i]), (PG8_LAS unsigned*)(lds + (bufoff) + ldsw + _i * 8192), 16, 0, 0); } while (0)
; #define PG8_LDA(dst, b, h) do { _Pragma("unroll") for (int m = 0; m < 4; ++m) _Pragma("unroll") for (int k = 0; k < 2; ++k) dst[m][k] = *(const PG8_LAS bf16x8*)(lds + PG8_SA(b, h) + aoff + m * 2048 + k * 1024); } while (0)
; #define PG8_LDB(dst, b, h) do { _Pragma("unroll") for (int n = 0; n < 2; ++n) _Pragma("unroll") for (int k = 0; k < 2; ++k) dst[n][k] = *(const PG8_LAS bf16x8*)(lds + PG8_SB(b, h) + boff + n * 2048 + k * 1024); } while (0)
; #define PG8_MMA(ai, bj, At, Bt) do { __builtin_amdgcn_s_setprio(1); _Pragma("unroll") for (int m = 0; m < 4; ++m) _Pragma("unroll") for (int n = 0; n < 2; ++n) _Pragma("unroll") for (int k = 0; k < 2; ++k) \
;         acc[ai][bj][m][n] = __builtin_amdgcn_mfma_f32_16x16x32_bf16(Bt[n][k], At[m][k], acc[ai][bj][m][n], 0, 0, 0); __builtin_amdgcn_s_setprio(0); } while (0)
; #define PG8_WAIT_V(n) asm volatile("s_waitcnt vmcnt(" #n ")" ::: "memory")
; #define PG8_WAIT_L(n) asm volatile("s_waitcnt lgkmcnt(" #n ")" ::: "memory")
; #define PG8_BAR __builtin_amdgcn_s_barrier()
; #define PG8_SCHED __builtin_amdgcn_sched_barrier(0)
; template <class Epi, class Sched, bool ALIGN_EPI = false, bool SP2 = false>
; __device__ __forceinline__ void gemm_phase(PG8_LAS unsigned char* lds, const Gemm g, const Sched& S, const Epi& E) {
;     ...
;             PG8_WAIT_V(8); PG8_WAIT_L(0); PG8_BAR; PG8_MMA(1, 0, At, B0); PG8_MMA(1, 1, At, B1); PG8_BAR; PG8_SCHED;
;             PG8_LDB(B0, 1, 0); PG8_LDB(B1, 1, 1); PG8_SCHED; PG8_LDA(At, 1, 0); PG8_STAGE(PG8_SA(0, 1), a2 + hstepA, voffA);
;             PG8_WAIT_V(8); PG8_WAIT_L(0); PG8_BAR; PG8_MMA(0, 0, At, B0); PG8_MMA(0, 1, At, B1); PG8_BAR; PG8_SCHED;
	s_waitcnt lgkmcnt(0)
	v_mfma_f32_16x16x32_bf16 v[60:63], v[128:131], v[182:185], v[60:63]
	v_mfma_f32_16x16x32_bf16 v[56:59], v[152:155], v[182:185], v[56:59]
	v_mfma_f32_16x16x32_bf16 v[44:47], v[128:131], v[190:193], v[44:47]
	v_mfma_f32_16x16x32_bf16 v[40:43], v[152:155], v[190:193], v[40:43]
	v_mfma_f32_16x16x32_bf16 v[28:31], v[128:131], v[198:201], v[28:31]
	v_mfma_f32_16x16x32_bf16 v[24:27], v[152:155], v[198:201], v[24:27]
	v_mfma_f32_16x16x32_bf16 v[12:15], v[128:131], v[210:213], v[12:15]
	v_mfma_f32_16x16x32_bf16 v[8:11], v[152:155], v[210:213], v[8:11]
	v_mfma_f32_16x16x32_bf16 v[60:63], v[132:135], v[186:189], v[60:63]
	v_mfma_f32_16x16x32_bf16 v[56:59], v[156:159], v[186:189], v[56:59]
	v_mfma_f32_16x16x32_bf16 v[44:47], v[132:135], v[194:197], v[44:47]
	v_mfma_f32_16x16x32_bf16 v[40:43], v[156:159], v[194:197], v[40:43]
	v_mfma_f32_16x16x32_bf16 v[28:31], v[132:135], v[206:209], v[28:31]
	v_mfma_f32_16x16x32_bf16 v[24:27], v[156:159], v[206:209], v[24:27]
	v_mfma_f32_16x16x32_bf16 v[12:15], v[132:135], v[214:217], v[12:15]
	v_mfma_f32_16x16x32_bf16 v[8:11], v[156:159], v[214:217], v[8:11]
	v_mfma_f32_16x16x32_bf16 v[52:55], v[160:163], v[182:185], v[52:55]
	v_mfma_f32_16x16x32_bf16 v[48:51], v[174:177], v[182:185], v[48:51]
	v_mfma_f32_16x16x32_bf16 v[36:39], v[160:163], v[190:193], v[36:39]
	v_mfma_f32_16x16x32_bf16 v[32:35], v[174:177], v[190:193], v[32:35]
	v_mfma_f32_16x16x32_bf16 v[20:23], v[160:163], v[198:201], v[20:23]
	v_mfma_f32_16x16x32_bf16 v[16:19], v[174:177], v[198:201], v[16:19]
	v_mfma_f32_16x16x32_bf16 v[4:7], v[160:163], v[210:213], v[4:7]
	v_mfma_f32_16x16x32_bf16 v[0:3], v[174:177], v[210:213], v[0:3]
	v_mfma_f32_16x16x32_bf16 v[52:55], v[170:173], v[186:189], v[52:55]
	v_mfma_f32_16x16x32_bf16 v[48:51], v[178:181], v[186:189], v[48:51]
	v_mfma_f32_16x16x32_bf16 v[36:39], v[170:173], v[194:197], v[36:39]
	v_mfma_f32_16x16x32_bf16 v[32:35], v[178:181], v[194:197], v[32:35]
	v_mfma_f32_16x16x32_bf16 v[20:23], v[170:173], v[206:209], v[20:23]
	v_mfma_f32_16x16x32_bf16 v[16:19], v[178:181], v[206:209], v[16:19]
	v_mfma_f32_16x16x32_bf16 v[4:7], v[170:173], v[214:217], v[4:7]
	v_mfma_f32_16x16x32_bf16 v[0:3], v[178:181], v[214:217], v[0:3]
	s_barrier
	s_add_i32 s49, 0, 0x18000
	s_add_i32 s51, 0, 0x1c000
	v_add_u32_e32 v156, s49, v165
	v_add_u32_e32 v178, s51, v165
	ds_read_b128 v[128:131], v156
	ds_read_b128 v[132:135], v156 offset:1024
	ds_read_b128 v[152:155], v156 offset:2048
	ds_read_b128 v[156:159], v156 offset:3072
	ds_read_b128 v[160:163], v178
	ds_read_b128 v[170:173], v178 offset:1024
	ds_read_b128 v[174:177], v178 offset:2048
	ds_read_b128 v[178:181], v178 offset:3072
	s_add_u32 s16, s22, 0x160000
	s_addc_u32 s17, s23, 0
	s_mov_b32 m0, s31
	v_lshl_add_u64 v[226:227], s[16:17], 0, v[136:137]
	ds_read_b128 v[182:185], v169 offset:32768
	ds_read_b128 v[186:189], v169 offset:33792
	ds_read_b128 v[190:193], v169 offset:34816
	ds_read_b128 v[194:197], v169 offset:35840
	ds_read_b128 v[198:201], v169 offset:36864
	ds_read_b128 v[206:209], v169 offset:37888
	ds_read_b128 v[210:213], v169 offset:38912
	ds_read_b128 v[214:217], v169 offset:39936
	global_load_lds_dwordx4 v[226:227], off
	v_lshl_add_u64 v[226:227], s[16:17], 0, v[140:141]
	s_mov_b32 m0, s34
	s_nop 0
	global_load_lds_dwordx4 v[226:227], off
	s_waitcnt vmcnt(8)
	s_waitcnt lgkmcnt(0)
	s_barrier
	s_waitcnt lgkmcnt(0)
	v_mfma_f32_16x16x32_bf16 v[124:127], v[128:131], v[182:185], v[124:127]
	v_mfma_f32_16x16x32_bf16 v[120:123], v[152:155], v[182:185], v[120:123]
	v_mfma_f32_16x16x32_bf16 v[108:111], v[128:131], v[190:193], v[108:111]
	v_mfma_f32_16x16x32_bf16 v[104:107], v[152:155], v[190:193], v[104:107]
	v_mfma_f32_16x16x32_bf16 v[92:95], v[128:131], v[198:201], v[92:95]
	v_mfma_f32_16x16x32_bf16 v[88:91], v[152:155], v[198:201], v[88:91]
	v_mfma_f32_16x16x32_bf16 v[76:79], v[128:131], v[210:213], v[76:79]
	v_mfma_f32_16x16x32_bf16 v[72:75], v[152:155], v[210:213], v[72:75]
	v_mfma_f32_16x16x32_bf16 v[124:127], v[132:135], v[186:189], v[124:127]
	v_mfma_f32_16x16x32_bf16 v[120:123], v[156:159], v[186:189], v[120:123]
	v_mfma_f32_16x16x32_bf16 v[108:111], v[132:135], v[194:197], v[108:111]
	v_mfma_f32_16x16x32_bf16 v[104:107], v[156:159], v[194:197], v[104:107]
	v_mfma_f32_16x16x32_bf16 v[92:95], v[132:135], v[206:209], v[92:95]
	v_mfma_f32_16x16x32_bf16 v[88:91], v[156:159], v[206:209], v[88:91]
	v_mfma_f32_16x16x32_bf16 v[76:79], v[132:135], v[214:217], v[76:79]
	v_mfma_f32_16x16x32_bf16 v[72:75], v[156:159], v[214:217], v[72:75]
	v_mfma_f32_16x16x32_bf16 v[116:119], v[160:163], v[182:185], v[116:119]
	v_mfma_f32_16x16x32_bf16 v[112:115], v[174:177], v[182:185], v[112:115]
	v_mfma_f32_16x16x32_bf16 v[100:103], v[160:163], v[190:193], v[100:103]
	v_mfma_f32_16x16x32_bf16 v[96:99], v[174:177], v[190:193], v[96:99]
	v_mfma_f32_16x16x32_bf16 v[84:87], v[160:163], v[198:201], v[84:87]
	v_mfma_f32_16x16x32_bf16 v[80:83], v[174:177], v[198:201], v[80:83]
	v_mfma_f32_16x16x32_bf16 v[68:71], v[160:163], v[210:213], v[68:71]
	v_mfma_f32_16x16x32_bf16 v[64:67], v[174:177], v[210:213], v[64:67]
	v_mfma_f32_16x16x32_bf16 v[116:119], v[170:173], v[186:189], v[116:119]
	v_mfma_f32_16x16x32_bf16 v[112:115], v[178:181], v[186:189], v[112:115]
	v_mfma_f32_16x16x32_bf16 v[100:103], v[170:173], v[194:197], v[100:103]
	v_mfma_f32_16x16x32_bf16 v[96:99], v[178:181], v[194:197], v[96:99]
	v_mfma_f32_16x16x32_bf16 v[84:87], v[170:173], v[206:209], v[84:87]
	v_mfma_f32_16x16x32_bf16 v[80:83], v[178:181], v[206:209], v[80:83]
	v_mfma_f32_16x16x32_bf16 v[68:71], v[170:173], v[214:217], v[68:71]
	v_mfma_f32_16x16x32_bf16 v[64:67], v[178:181], v[214:217], v[64:67]
	s_barrier
; #define PG8_STAGE(bufoff, gbase, voff) do { _Pragma("unroll") for (int _i = 0; _i < 2; ++_i) \
;         __builtin_amdgcn_global_load_lds((const unsigned*)((const char*)(gbase) + (voff)[_i]), (PG8_LAS unsigned*)(lds + (bufoff) + ldsw + _i * 8192), 16, 0, 0); } while (0)
; #define PG8_LDA(dst, b, h) do { _Pragma("unroll") for (int m = 0; m < 4; ++m) _Pragma("unroll") for (int k = 0; k < 2; ++k) dst[m][k] = *(const PG8_LAS bf16x8*)(lds + PG8_SA(b, h) + aoff + m * 2048 + k * 1024); } while (0)
; #define PG8_MMA(ai, bj, At, Bt) do { __builtin_amdgcn_s_setprio(1); _Pragma("unroll") for (int m = 0; m < 4; ++m) _Pragma("unroll") for (int n = 0; n < 2; ++n) _Pragma("unroll") for (int k = 0; k < 2; ++k) \
;         acc[ai][bj][m][n] = __builtin_amdgcn_mfma_f32_16x16x32_bf16(Bt[n][k], At[m][k], acc[ai][bj][m][n], 0, 0, 0); __builtin_amdgcn_s_setprio(0); } while (0)
; #define PG8_WAIT_V(n) asm volatile("s_waitcnt vmcnt(" #n ")" ::: "memory")
; #define PG8_WAIT_L(n) asm volatile("s_waitcnt lgkmcnt(" #n ")" ::: "memory")
; #define PG8_BAR __builtin_amdgcn_s_barrier()
; #define PG8_SCHED __builtin_amdgcn_sched_barrier(0)
; template <class Epi, class Sched, bool ALIGN_EPI = false, bool SP2 = false>
; __device__ __forceinline__ void gemm_phase(PG8_LAS unsigned char* lds, const Gemm g, const Sched& S, const Epi& E) {
;     ...
;             PG8_LDA(At, 1, 1); PG8_STAGE(PG8_SB(1, 0), b3, voffB); PG8_STAGE(PG8_SB(1, 1), b3 + hstep, voffB); PG8_STAGE(PG8_SA(1, 0), a3, voffA);
;             PG8_WAIT_V(8); PG8_WAIT_L(0); PG8_BAR; PG8_MMA(1, 0, At, B0); PG8_MMA(1, 1, At, B1); PG8_BAR; PG8_SCHED;
	s_add_i32 s16, s49, s28
	v_lshl_add_u64 v[218:219], v[218:219], 0, s[0:1]
	s_mov_b32 m0, s16
	ds_read_b128 v[182:185], v169 offset:49152
	ds_read_b128 v[186:189], v169 offset:50176
	ds_read_b128 v[190:193], v169 offset:51200
	ds_read_b128 v[194:197], v169 offset:52224
	ds_read_b128 v[198:201], v169 offset:53248
	ds_read_b128 v[206:209], v169 offset:54272
	ds_read_b128 v[210:213], v169 offset:55296
	ds_read_b128 v[214:217], v169 offset:56320
	global_load_lds_dwordx4 v[218:219], off
	s_add_i32 m0, s16, 0x2000
	s_add_u32 s16, s20, 0x160080
	v_lshl_add_u64 v[218:219], v[220:221], 0, s[0:1]
	s_addc_u32 s17, s21, 0
	s_add_i32 s20, s51, s28
	global_load_lds_dwordx4 v[218:219], off
	v_lshl_add_u64 v[218:219], s[16:17], 0, v[138:139]
	s_mov_b32 m0, s20
	s_nop 0
	global_load_lds_dwordx4 v[218:219], off
	v_lshl_add_u64 v[218:219], s[16:17], 0, v[142:143]
	s_add_i32 m0, s20, 0x2000
	s_nop 0
	global_load_lds_dwordx4 v[218:219], off
	v_lshl_add_u64 v[218:219], v[222:223], 0, s[0:1]
	s_mov_b32 m0, s3
	s_nop 0
	global_load_lds_dwordx4 v[218:219], off
	v_lshl_add_u64 v[218:219], v[224:225], 0, s[0:1]
	s_mov_b32 m0, s33
	s_nop 0
	global_load_lds_dwordx4 v[218:219], off
	s_waitcnt vmcnt(8)
	s_waitcnt lgkmcnt(0)
	s_barrier
	s_waitcnt lgkmcnt(0)
	v_mfma_f32_16x16x32_bf16 v[60:63], v[128:131], v[182:185], v[60:63]
	v_mfma_f32_16x16x32_bf16 v[56:59], v[152:155], v[182:185], v[56:59]
	v_mfma_f32_16x16x32_bf16 v[44:47], v[128:131], v[190:193], v[44:47]
	v_mfma_f32_16x16x32_bf16 v[40:43], v[152:155], v[190:193], v[40:43]
	v_mfma_f32_16x16x32_bf16 v[28:31], v[128:131], v[198:201], v[28:31]
	v_mfma_f32_16x16x32_bf16 v[24:27], v[152:155], v[198:201], v[24:27]
	v_mfma_f32_16x16x32_bf16 v[12:15], v[128:131], v[210:213], v[12:15]
	v_mfma_f32_16x16x32_bf16 v[8:11], v[152:155], v[210:213], v[8:11]
	v_mfma_f32_16x16x32_bf16 v[60:63], v[132:135], v[186:189], v[60:63]
	v_mfma_f32_16x16x32_bf16 v[56:59], v[156:159], v[186:189], v[56:59]
	v_mfma_f32_16x16x32_bf16 v[44:47], v[132:135], v[194:197], v[44:47]
	v_mfma_f32_16x16x32_bf16 v[40:43], v[156:159], v[194:197], v[40:43]
	v_mfma_f32_16x16x32_bf16 v[28:31], v[132:135], v[206:209], v[28:31]
	v_mfma_f32_16x16x32_bf16 v[24:27], v[156:159], v[206:209], v[24:27]
	v_mfma_f32_16x16x32_bf16 v[12:15], v[132:135], v[214:217], v[12:15]
	v_mfma_f32_16x16x32_bf16 v[8:11], v[156:159], v[214:217], v[8:11]
	v_mfma_f32_16x16x32_bf16 v[52:55], v[160:163], v[182:185], v[52:55]
	v_mfma_f32_16x16x32_bf16 v[48:51], v[174:177], v[182:185], v[48:51]
	v_mfma_f32_16x16x32_bf16 v[36:39], v[160:163], v[190:193], v[36:39]
	v_mfma_f32_16x16x32_bf16 v[32:35], v[174:177], v[190:193], v[32:35]
	v_mfma_f32_16x16x32_bf16 v[20:23], v[160:163], v[198:201], v[20:23]
	v_mfma_f32_16x16x32_bf16 v[16:19], v[174:177], v[198:201], v[16:19]
	v_mfma_f32_16x16x32_bf16 v[4:7], v[160:163], v[210:213], v[4:7]
	v_mfma_f32_16x16x32_bf16 v[0:3], v[174:177], v[210:213], v[0:3]
	v_mfma_f32_16x16x32_bf16 v[52:55], v[170:173], v[186:189], v[52:55]
	v_mfma_f32_16x16x32_bf16 v[48:51], v[178:181], v[186:189], v[48:51]
	v_mfma_f32_16x16x32_bf16 v[36:39], v[170:173], v[194:197], v[36:39]
	v_mfma_f32_16x16x32_bf16 v[32:35], v[178:181], v[194:197], v[32:35]
	v_mfma_f32_16x16x32_bf16 v[20:23], v[170:173], v[206:209], v[20:23]
	v_mfma_f32_16x16x32_bf16 v[16:19], v[178:181], v[206:209], v[16:19]
	v_mfma_f32_16x16x32_bf16 v[4:7], v[170:173], v[214:217], v[4:7]
	v_mfma_f32_16x16x32_bf16 v[0:3], v[178:181], v[214:217], v[0:3]
	s_barrier
	s_add_i32 s48, s48, 2
	s_add_u32 s42, s42, 0x100
	s_addc_u32 s43, s43, 0
	s_cmpk_gt_u32 s48, 0x55
	s_mov_b64 s[16:17], s[18:19]
	s_cbranch_scc0 .LBB0_2427
	s_and_b64 vcc, exec, s[10:11]
	s_cbranch_vccz .LBB0_2430
	s_barrier

; #define PG8_STAGE(bufoff, gbase, voff) do { _Pragma("unroll") for (int _i = 0; _i < 2; ++_i) \
;         __builtin_amdgcn_global_load_lds((const unsigned*)((const char*)(gbase) + (voff)[_i]), (PG8_LAS unsigned*)(lds + (bufoff) + ldsw + _i * 8192), 16, 0, 0); } while (0)
; #define PG8_LDA(dst, b, h) do { _Pragma("unroll") for (int m = 0; m < 4; ++m) _Pragma("unroll") for (int k = 0; k < 2; ++k) dst[m][k] = *(const PG8_LAS bf16x8*)(lds + PG8_SA(b, h) + aoff + m * 2048 + k * 1024); } while (0)
; #define PG8_LDB(dst, b, h) do { _Pragma("unroll") for (int n = 0; n < 2; ++n) _Pragma("unroll") for (int k = 0; k < 2; ++k) dst[n][k] = *(const PG8_LAS bf16x8*)(lds + PG8_SB(b, h) + boff + n * 2048 + k * 1024); } while (0)
; #define PG8_MMA(ai, bj, At, Bt) do { __builtin_amdgcn_s_setprio(1); _Pragma("unroll") for (int m = 0; m < 4; ++m) _Pragma("unroll") for (int n = 0; n < 2; ++n) _Pragma("unroll") for (int k = 0; k < 2; ++k) \
;         acc[ai][bj][m][n] = __builtin_amdgcn_mfma_f32_16x16x32_bf16(Bt[n][k], At[m][k], acc[ai][bj][m][n], 0, 0, 0); __builtin_amdgcn_s_setprio(0); } while (0)
; #define PG8_WAIT_V(n) asm volatile("s_waitcnt vmcnt(" #n ")" ::: "memory")
; #define PG8_WAIT_L(n) asm volatile("s_waitcnt lgkmcnt(" #n ")" ::: "memory")
; #define PG8_BAR __builtin_amdgcn_s_barrier()
; #define PG8_SCHED __builtin_amdgcn_sched_barrier(0)
; template <class Epi, class Sched, bool ALIGN_EPI = false, bool SP2 = false>
; __device__ __forceinline__ void gemm_phase(PG8_LAS unsigned char* lds, const Gemm g, const Sched& S, const Epi& E) {
;     ...
;             PG8_LDB(B0, 0, 0); PG8_LDB(B1, 0, 1); PG8_SCHED; PG8_LDA(At, 0, 0); PG8_STAGE(PG8_SA(1, 1), a1 + hstepA, voffA);
;             PG8_WAIT_V(8); PG8_WAIT_L(0); PG8_BAR; PG8_MMA(0, 0, At, B0); PG8_MMA(0, 1, At, B1); PG8_BAR; PG8_SCHED;
;             PG8_LDA(At, 0, 1); PG8_STAGE(PG8_SB(0, 0), b2, voffB); PG8_STAGE(PG8_SB(0, 1), b2 + hstep, voffB); PG8_STAGE(PG8_SA(0, 0), a2, voffA);
.LBB0_2511:
	ds_read_b128 v[148:151], v154
	ds_read_b128 v[160:163], v154 offset:1024
	ds_read_b128 v[164:167], v154 offset:2048
	ds_read_b128 v[168:171], v154 offset:3072
	ds_read_b128 v[172:175], v155
	ds_read_b128 v[176:179], v155 offset:1024
	ds_read_b128 v[180:183], v155 offset:2048
	ds_read_b128 v[184:187], v155 offset:3072
	s_add_u32 s22, s20, 0xfff80080
	s_addc_u32 s23, s21, -1
	s_cmp_eq_u32 s33, 28
	s_cselect_b32 s25, s2, s23
	s_cselect_b32 s24, s3, s22
	s_cselect_b32 s23, s6, s15
	s_cselect_b32 s22, s7, s13
	v_lshl_add_u64 v[200:201], s[20:21], 0, v[138:139]
	s_add_i32 m0, s34, 0xc000
	ds_read_b128 v[188:191], v156
	ds_read_b128 v[192:195], v156 offset:1024
	ds_read_b128 v[196:199], v156 offset:2048
	ds_read_b128 v[206:209], v156 offset:3072
	ds_read_b128 v[210:213], v156 offset:4096
	ds_read_b128 v[214:217], v156 offset:5120
	ds_read_b128 v[218:221], v156 offset:6144
	ds_read_b128 v[222:225], v156 offset:7168
	global_load_lds_dwordx4 v[200:201], off
	v_lshl_add_u64 v[200:201], s[20:21], 0, v[140:141]
	s_add_i32 m0, s34, 0xe000
	s_nop 0
	global_load_lds_dwordx4 v[200:201], off
	s_waitcnt vmcnt(8)
	s_waitcnt lgkmcnt(0)
	s_barrier
	s_waitcnt lgkmcnt(0)
	v_mfma_f32_16x16x32_bf16 v[124:127], v[148:151], v[188:191], v[124:127]
	v_mfma_f32_16x16x32_bf16 v[120:123], v[164:167], v[188:191], v[120:123]
	v_mfma_f32_16x16x32_bf16 v[108:111], v[148:151], v[196:199], v[108:111]
	v_mfma_f32_16x16x32_bf16 v[104:107], v[164:167], v[196:199], v[104:107]
	v_mfma_f32_16x16x32_bf16 v[92:95], v[148:151], v[210:213], v[92:95]
	v_mfma_f32_16x16x32_bf16 v[88:91], v[164:167], v[210:213], v[88:91]
	v_mfma_f32_16x16x32_bf16 v[76:79], v[148:151], v[218:221], v[76:79]
	v_mfma_f32_16x16x32_bf16 v[72:75], v[164:167], v[218:221], v[72:75]
	v_mfma_f32_16x16x32_bf16 v[124:127], v[160:163], v[192:195], v[124:127]
	v_mfma_f32_16x16x32_bf16 v[120:123], v[168:171], v[192:195], v[120:123]
	v_mfma_f32_16x16x32_bf16 v[108:111], v[160:163], v[206:209], v[108:111]
	v_mfma_f32_16x16x32_bf16 v[104:107], v[168:171], v[206:209], v[104:107]
	v_mfma_f32_16x16x32_bf16 v[92:95], v[160:163], v[214:217], v[92:95]
	v_mfma_f32_16x16x32_bf16 v[88:91], v[168:171], v[214:217], v[88:91]
	v_mfma_f32_16x16x32_bf16 v[76:79], v[160:163], v[222:225], v[76:79]
	v_mfma_f32_16x16x32_bf16 v[72:75], v[168:171], v[222:225], v[72:75]
	v_mfma_f32_16x16x32_bf16 v[116:119], v[172:175], v[188:191], v[116:119]
	v_mfma_f32_16x16x32_bf16 v[112:115], v[180:183], v[188:191], v[112:115]
	v_mfma_f32_16x16x32_bf16 v[100:103], v[172:175], v[196:199], v[100:103]
	v_mfma_f32_16x16x32_bf16 v[96:99], v[180:183], v[196:199], v[96:99]
	v_mfma_f32_16x16x32_bf16 v[84:87], v[172:175], v[210:213], v[84:87]
	v_mfma_f32_16x16x32_bf16 v[80:83], v[180:183], v[210:213], v[80:83]
	v_mfma_f32_16x16x32_bf16 v[68:71], v[172:175], v[218:221], v[68:71]
	v_mfma_f32_16x16x32_bf16 v[64:67], v[180:183], v[218:221], v[64:67]
	v_mfma_f32_16x16x32_bf16 v[116:119], v[176:179], v[192:195], v[116:119]
	v_mfma_f32_16x16x32_bf16 v[112:115], v[184:187], v[192:195], v[112:115]
	v_mfma_f32_16x16x32_bf16 v[100:103], v[176:179], v[206:209], v[100:103]
	v_mfma_f32_16x16x32_bf16 v[96:99], v[184:187], v[206:209], v[96:99]
	v_mfma_f32_16x16x32_bf16 v[84:87], v[176:179], v[214:217], v[84:87]
	v_mfma_f32_16x16x32_bf16 v[80:83], v[184:187], v[214:217], v[80:83]
	v_mfma_f32_16x16x32_bf16 v[68:71], v[176:179], v[222:225], v[68:71]
	v_mfma_f32_16x16x32_bf16 v[64:67], v[184:187], v[222:225], v[64:67]
	s_barrier
	s_add_i32 s38, s52, s30
	v_lshl_add_u64 v[200:201], s[22:23], 0, v[132:133]
	s_mov_b32 m0, s38
	ds_read_b128 v[188:191], v156 offset:16384
	ds_read_b128 v[192:195], v156 offset:17408
	ds_read_b128 v[196:199], v156 offset:18432
	ds_read_b128 v[206:209], v156 offset:19456
	ds_read_b128 v[210:213], v156 offset:20480
	ds_read_b128 v[214:217], v156 offset:21504
	ds_read_b128 v[218:221], v156 offset:22528
	ds_read_b128 v[222:225], v156 offset:23552
	global_load_lds_dwordx4 v[200:201], off
	s_add_i32 m0, s38, 0x2000
	s_add_u32 s38, s22, 0x80000
	v_lshl_add_u64 v[226:227], s[22:23], 0, v[128:129]
	s_addc_u32 s39, s23, 0
	s_add_i32 s40, s53, s30
	global_load_lds_dwordx4 v[226:227], off
	v_lshl_add_u64 v[228:229], s[38:39], 0, v[132:133]
	s_mov_b32 m0, s40
	v_lshl_add_u64 v[230:231], s[24:25], 0, v[130:131]
	global_load_lds_dwordx4 v[228:229], off
	v_lshl_add_u64 v[228:229], s[38:39], 0, v[128:129]
	s_add_i32 m0, s40, 0x2000
	s_nop 0
	global_load_lds_dwordx4 v[228:229], off
	v_lshl_add_u64 v[228:229], s[24:25], 0, v[134:135]
	s_mov_b32 m0, s34
	s_nop 0
	global_load_lds_dwordx4 v[228:229], off
	s_mov_b32 m0, s35
	s_nop 0
	global_load_lds_dwordx4 v[230:231], off
	s_waitcnt vmcnt(8)
	s_waitcnt lgkmcnt(0)
	s_barrier
; #define PG8_STAGE(bufoff, gbase, voff) do { _Pragma("unroll") for (int _i = 0; _i < 2; ++_i) \
;         __builtin_amdgcn_global_load_lds((const unsigned*)((const char*)(gbase) + (voff)[_i]), (PG8_LAS unsigned*)(lds + (bufoff) + ldsw + _i * 8192), 16, 0, 0); } while (0)
; #define PG8_LDA(dst, b, h) do { _Pragma("unroll") for (int m = 0; m < 4; ++m) _Pragma("unroll") for (int k = 0; k < 2; ++k) dst[m][k] = *(const PG8_LAS bf16x8*)(lds + PG8_SA(b, h) + aoff + m * 2048 + k * 1024); } while (0)
; #define PG8_LDB(dst, b, h) do { _Pragma("unroll") for (int n = 0; n < 2; ++n) _Pragma("unroll") for (int k = 0; k < 2; ++k) dst[n][k] = *(const PG8_LAS bf16x8*)(lds + PG8_SB(b, h) + boff + n * 2048 + k * 1024); } while (0)
; #define PG8_MMA(ai, bj, At, Bt) do { __builtin_amdgcn_s_setprio(1); _Pragma("unroll") for (int m = 0; m < 4; ++m) _Pragma("unroll") for (int n = 0; n < 2; ++n) _Pragma("unroll") for (int k = 0; k < 2; ++k) \
;         acc[ai][bj][m][n] = __builtin_amdgcn_mfma_f32_16x16x32_bf16(Bt[n][k], At[m][k], acc[ai][bj][m][n], 0, 0, 0); __builtin_amdgcn_s_setprio(0); } while (0)
; #define PG8_WAIT_V(n) asm volatile("s_waitcnt vmcnt(" #n ")" ::: "memory")
; #define PG8_WAIT_L(n) asm volatile("s_waitcnt lgkmcnt(" #n ")" ::: "memory")
; #define PG8_BAR __builtin_amdgcn_s_barrier()
; #define PG8_SCHED __builtin_amdgcn_sched_barrier(0)
; template <class Epi, class Sched, bool ALIGN_EPI = false, bool SP2 = false>
; __device__ __forceinline__ void gemm_phase(PG8_LAS unsigned char* lds, const Gemm g, const Sched& S, const Epi& E) {
;     ...
;             PG8_WAIT_V(8); PG8_WAIT_L(0); PG8_BAR; PG8_MMA(1, 0, At, B0); PG8_MMA(1, 1, At, B1); PG8_BAR; PG8_SCHED;
;             PG8_LDB(B0, 1, 0); PG8_LDB(B1, 1, 1); PG8_SCHED; PG8_LDA(At, 1, 0); PG8_STAGE(PG8_SA(0, 1), a2 + hstepA, voffA);
;             PG8_WAIT_V(8); PG8_WAIT_L(0); PG8_BAR; PG8_MMA(0, 0, At, B0); PG8_MMA(0, 1, At, B1); PG8_BAR; PG8_SCHED;
	s_waitcnt lgkmcnt(0)
	v_mfma_f32_16x16x32_bf16 v[60:63], v[148:151], v[188:191], v[60:63]
	v_mfma_f32_16x16x32_bf16 v[56:59], v[164:167], v[188:191], v[56:59]
	v_mfma_f32_16x16x32_bf16 v[44:47], v[148:151], v[196:199], v[44:47]
	v_mfma_f32_16x16x32_bf16 v[40:43], v[164:167], v[196:199], v[40:43]
	v_mfma_f32_16x16x32_bf16 v[28:31], v[148:151], v[210:213], v[28:31]
	v_mfma_f32_16x16x32_bf16 v[24:27], v[164:167], v[210:213], v[24:27]
	v_mfma_f32_16x16x32_bf16 v[12:15], v[148:151], v[218:221], v[12:15]
	v_mfma_f32_16x16x32_bf16 v[8:11], v[164:167], v[218:221], v[8:11]
	v_mfma_f32_16x16x32_bf16 v[60:63], v[160:163], v[192:195], v[60:63]
	v_mfma_f32_16x16x32_bf16 v[56:59], v[168:171], v[192:195], v[56:59]
	v_mfma_f32_16x16x32_bf16 v[44:47], v[160:163], v[206:209], v[44:47]
	v_mfma_f32_16x16x32_bf16 v[40:43], v[168:171], v[206:209], v[40:43]
	v_mfma_f32_16x16x32_bf16 v[28:31], v[160:163], v[214:217], v[28:31]
	v_mfma_f32_16x16x32_bf16 v[24:27], v[168:171], v[214:217], v[24:27]
	v_mfma_f32_16x16x32_bf16 v[12:15], v[160:163], v[222:225], v[12:15]
	v_mfma_f32_16x16x32_bf16 v[8:11], v[168:171], v[222:225], v[8:11]
	v_mfma_f32_16x16x32_bf16 v[52:55], v[172:175], v[188:191], v[52:55]
	v_mfma_f32_16x16x32_bf16 v[48:51], v[180:183], v[188:191], v[48:51]
	v_mfma_f32_16x16x32_bf16 v[36:39], v[172:175], v[196:199], v[36:39]
	v_mfma_f32_16x16x32_bf16 v[32:35], v[180:183], v[196:199], v[32:35]
	v_mfma_f32_16x16x32_bf16 v[20:23], v[172:175], v[210:213], v[20:23]
	v_mfma_f32_16x16x32_bf16 v[16:19], v[180:183], v[210:213], v[16:19]
	v_mfma_f32_16x16x32_bf16 v[4:7], v[172:175], v[218:221], v[4:7]
	v_mfma_f32_16x16x32_bf16 v[0:3], v[180:183], v[218:221], v[0:3]
	v_mfma_f32_16x16x32_bf16 v[52:55], v[176:179], v[192:195], v[52:55]
	v_mfma_f32_16x16x32_bf16 v[48:51], v[184:187], v[192:195], v[48:51]
	v_mfma_f32_16x16x32_bf16 v[36:39], v[176:179], v[206:209], v[36:39]
	v_mfma_f32_16x16x32_bf16 v[32:35], v[184:187], v[206:209], v[32:35]
	v_mfma_f32_16x16x32_bf16 v[20:23], v[176:179], v[214:217], v[20:23]
	v_mfma_f32_16x16x32_bf16 v[16:19], v[184:187], v[214:217], v[16:19]
	v_mfma_f32_16x16x32_bf16 v[4:7], v[176:179], v[222:225], v[4:7]
	v_mfma_f32_16x16x32_bf16 v[0:3], v[184:187], v[222:225], v[0:3]
	s_barrier
	s_add_i32 s38, 0, 0x18000
	v_add_u32_e32 v146, s38, v152
	s_add_i32 s39, 0, 0x1c000
	ds_read_b128 v[148:151], v146
	ds_read_b128 v[160:163], v146 offset:1024
	ds_read_b128 v[164:167], v146 offset:2048
	ds_read_b128 v[168:171], v146 offset:3072
	v_add_u32_e32 v146, s39, v152
	ds_read_b128 v[172:175], v146
	ds_read_b128 v[176:179], v146 offset:1024
	ds_read_b128 v[180:183], v146 offset:2048
	ds_read_b128 v[184:187], v146 offset:3072
	s_add_u32 s24, s24, 0x80000
	s_addc_u32 s25, s25, 0
	s_mov_b32 m0, s36
	v_lshl_add_u64 v[232:233], s[24:25], 0, v[134:135]
	ds_read_b128 v[188:191], v156 offset:32768
	ds_read_b128 v[192:195], v156 offset:33792
	ds_read_b128 v[196:199], v156 offset:34816
	ds_read_b128 v[206:209], v156 offset:35840
	ds_read_b128 v[210:213], v156 offset:36864
	ds_read_b128 v[214:217], v156 offset:37888
	ds_read_b128 v[218:221], v156 offset:38912
	ds_read_b128 v[222:225], v156 offset:39936
	global_load_lds_dwordx4 v[232:233], off
	v_lshl_add_u64 v[232:233], s[24:25], 0, v[130:131]
	s_mov_b32 m0, s37
	s_nop 0
	global_load_lds_dwordx4 v[232:233], off
	s_waitcnt vmcnt(8)
	s_waitcnt lgkmcnt(0)
	s_barrier
	s_waitcnt lgkmcnt(0)
	v_mfma_f32_16x16x32_bf16 v[124:127], v[148:151], v[188:191], v[124:127]
	v_mfma_f32_16x16x32_bf16 v[120:123], v[164:167], v[188:191], v[120:123]
	v_mfma_f32_16x16x32_bf16 v[108:111], v[148:151], v[196:199], v[108:111]
	v_mfma_f32_16x16x32_bf16 v[104:107], v[164:167], v[196:199], v[104:107]
	v_mfma_f32_16x16x32_bf16 v[92:95], v[148:151], v[210:213], v[92:95]
	v_mfma_f32_16x16x32_bf16 v[88:91], v[164:167], v[210:213], v[88:91]
	v_mfma_f32_16x16x32_bf16 v[76:79], v[148:151], v[218:221], v[76:79]
	v_mfma_f32_16x16x32_bf16 v[72:75], v[164:167], v[218:221], v[72:75]
	v_mfma_f32_16x16x32_bf16 v[124:127], v[160:163], v[192:195], v[124:127]
	v_mfma_f32_16x16x32_bf16 v[120:123], v[168:171], v[192:195], v[120:123]
	v_mfma_f32_16x16x32_bf16 v[108:111], v[160:163], v[206:209], v[108:111]
	v_mfma_f32_16x16x32_bf16 v[104:107], v[168:171], v[206:209], v[104:107]
	v_mfma_f32_16x16x32_bf16 v[92:95], v[160:163], v[214:217], v[92:95]
	v_mfma_f32_16x16x32_bf16 v[88:91], v[168:171], v[214:217], v[88:91]
	v_mfma_f32_16x16x32_bf16 v[76:79], v[160:163], v[222:225], v[76:79]
	v_mfma_f32_16x16x32_bf16 v[72:75], v[168:171], v[222:225], v[72:75]
	v_mfma_f32_16x16x32_bf16 v[116:119], v[172:175], v[188:191], v[116:119]
	v_mfma_f32_16x16x32_bf16 v[112:115], v[180:183], v[188:191], v[112:115]
	v_mfma_f32_16x16x32_bf16 v[100:103], v[172:175], v[196:199], v[100:103]
	v_mfma_f32_16x16x32_bf16 v[96:99], v[180:183], v[196:199], v[96:99]
	v_mfma_f32_16x16x32_bf16 v[84:87], v[172:175], v[210:213], v[84:87]
	v_mfma_f32_16x16x32_bf16 v[80:83], v[180:183], v[210:213], v[80:83]
	v_mfma_f32_16x16x32_bf16 v[68:71], v[172:175], v[218:221], v[68:71]
	v_mfma_f32_16x16x32_bf16 v[64:67], v[180:183], v[218:221], v[64:67]
	v_mfma_f32_16x16x32_bf16 v[116:119], v[176:179], v[192:195], v[116:119]
	v_mfma_f32_16x16x32_bf16 v[112:115], v[184:187], v[192:195], v[112:115]
	v_mfma_f32_16x16x32_bf16 v[100:103], v[176:179], v[206:209], v[100:103]
	v_mfma_f32_16x16x32_bf16 v[96:99], v[184:187], v[206:209], v[96:99]
	v_mfma_f32_16x16x32_bf16 v[84:87], v[176:179], v[214:217], v[84:87]
	v_mfma_f32_16x16x32_bf16 v[80:83], v[184:187], v[214:217], v[80:83]
	v_mfma_f32_16x16x32_bf16 v[68:71], v[176:179], v[222:225], v[68:71]
	v_mfma_f32_16x16x32_bf16 v[64:67], v[184:187], v[222:225], v[64:67]
	s_barrier
; #define PG8_STAGE(bufoff, gbase, voff) do { _Pragma("unroll") for (int _i = 0; _i < 2; ++_i) \
;         __builtin_amdgcn_global_load_lds((const unsigned*)((const char*)(gbase) + (voff)[_i]), (PG8_LAS unsigned*)(lds + (bufoff) + ldsw + _i * 8192), 16, 0, 0); } while (0)
; #define PG8_LDA(dst, b, h) do { _Pragma("unroll") for (int m = 0; m < 4; ++m) _Pragma("unroll") for (int k = 0; k < 2; ++k) dst[m][k] = *(const PG8_LAS bf16x8*)(lds + PG8_SA(b, h) + aoff + m * 2048 + k * 1024); } while (0)
; #define PG8_MMA(ai, bj, At, Bt) do { __builtin_amdgcn_s_setprio(1); _Pragma("unroll") for (int m = 0; m < 4; ++m) _Pragma("unroll") for (int n = 0; n < 2; ++n) _Pragma("unroll") for (int k = 0; k < 2; ++k) \
;         acc[ai][bj][m][n] = __builtin_amdgcn_mfma_f32_16x16x32_bf16(Bt[n][k], At[m][k], acc[ai][bj][m][n], 0, 0, 0); __builtin_amdgcn_s_setprio(0); } while (0)
; #define PG8_WAIT_V(n) asm volatile("s_waitcnt vmcnt(" #n ")" ::: "memory")
; #define PG8_WAIT_L(n) asm volatile("s_waitcnt lgkmcnt(" #n ")" ::: "memory")
; #define PG8_BAR __builtin_amdgcn_s_barrier()
; #define PG8_SCHED __builtin_amdgcn_sched_barrier(0)
; template <class Epi, class Sched, bool ALIGN_EPI = false, bool SP2 = false>
; __device__ __forceinline__ void gemm_phase(PG8_LAS unsigned char* lds, const Gemm g, const Sched& S, const Epi& E) {
;     ...
;             PG8_LDA(At, 1, 1); PG8_STAGE(PG8_SB(1, 0), b3, voffB); PG8_STAGE(PG8_SB(1, 1), b3 + hstep, voffB); PG8_STAGE(PG8_SA(1, 0), a3, voffA);
;             PG8_WAIT_V(8); PG8_WAIT_L(0); PG8_BAR; PG8_MMA(1, 0, At, B0); PG8_MMA(1, 1, At, B1); PG8_BAR; PG8_SCHED;
	s_add_i32 s24, s38, s30
	v_lshl_add_u64 v[200:201], v[200:201], 0, s[8:9]
	s_mov_b32 m0, s24
	ds_read_b128 v[188:191], v156 offset:49152
	ds_read_b128 v[192:195], v156 offset:50176
	ds_read_b128 v[196:199], v156 offset:51200
	ds_read_b128 v[206:209], v156 offset:52224
	ds_read_b128 v[210:213], v156 offset:53248
	ds_read_b128 v[214:217], v156 offset:54272
	ds_read_b128 v[218:221], v156 offset:55296
	ds_read_b128 v[222:225], v156 offset:56320
	global_load_lds_dwordx4 v[200:201], off
	s_add_i32 m0, s24, 0x2000
	s_add_u32 s22, s22, 0x80080
	v_lshl_add_u64 v[200:201], v[226:227], 0, s[8:9]
	s_addc_u32 s23, s23, 0
	s_add_i32 s24, s39, s30
	global_load_lds_dwordx4 v[200:201], off
	v_lshl_add_u64 v[200:201], s[22:23], 0, v[132:133]
	s_mov_b32 m0, s24
	s_nop 0
	global_load_lds_dwordx4 v[200:201], off
	v_lshl_add_u64 v[200:201], s[22:23], 0, v[128:129]
	s_add_i32 m0, s24, 0x2000
	s_nop 0
	global_load_lds_dwordx4 v[200:201], off
	v_lshl_add_u64 v[200:201], v[228:229], 0, s[8:9]
	s_mov_b32 m0, s49
	s_nop 0
	global_load_lds_dwordx4 v[200:201], off
	v_lshl_add_u64 v[200:201], v[230:231], 0, s[8:9]
	s_mov_b32 m0, s50
	s_nop 0
	global_load_lds_dwordx4 v[200:201], off
	s_waitcnt vmcnt(8)
	s_waitcnt lgkmcnt(0)
	s_barrier
	s_waitcnt lgkmcnt(0)
	v_mfma_f32_16x16x32_bf16 v[60:63], v[148:151], v[188:191], v[60:63]
	v_mfma_f32_16x16x32_bf16 v[56:59], v[164:167], v[188:191], v[56:59]
	v_mfma_f32_16x16x32_bf16 v[44:47], v[148:151], v[196:199], v[44:47]
	v_mfma_f32_16x16x32_bf16 v[40:43], v[164:167], v[196:199], v[40:43]
	v_mfma_f32_16x16x32_bf16 v[28:31], v[148:151], v[210:213], v[28:31]
	v_mfma_f32_16x16x32_bf16 v[24:27], v[164:167], v[210:213], v[24:27]
	v_mfma_f32_16x16x32_bf16 v[12:15], v[148:151], v[218:221], v[12:15]
	v_mfma_f32_16x16x32_bf16 v[8:11], v[164:167], v[218:221], v[8:11]
	v_mfma_f32_16x16x32_bf16 v[60:63], v[160:163], v[192:195], v[60:63]
	v_mfma_f32_16x16x32_bf16 v[56:59], v[168:171], v[192:195], v[56:59]
	v_mfma_f32_16x16x32_bf16 v[44:47], v[160:163], v[206:209], v[44:47]
	v_mfma_f32_16x16x32_bf16 v[40:43], v[168:171], v[206:209], v[40:43]
	v_mfma_f32_16x16x32_bf16 v[28:31], v[160:163], v[214:217], v[28:31]
	v_mfma_f32_16x16x32_bf16 v[24:27], v[168:171], v[214:217], v[24:27]
	v_mfma_f32_16x16x32_bf16 v[12:15], v[160:163], v[222:225], v[12:15]
	v_mfma_f32_16x16x32_bf16 v[8:11], v[168:171], v[222:225], v[8:11]
	v_mfma_f32_16x16x32_bf16 v[52:55], v[172:175], v[188:191], v[52:55]
	v_mfma_f32_16x16x32_bf16 v[48:51], v[180:183], v[188:191], v[48:51]
	v_mfma_f32_16x16x32_bf16 v[36:39], v[172:175], v[196:199], v[36:39]
	v_mfma_f32_16x16x32_bf16 v[32:35], v[180:183], v[196:199], v[32:35]
	v_mfma_f32_16x16x32_bf16 v[20:23], v[172:175], v[210:213], v[20:23]
	v_mfma_f32_16x16x32_bf16 v[16:19], v[180:183], v[210:213], v[16:19]
	v_mfma_f32_16x16x32_bf16 v[4:7], v[172:175], v[218:221], v[4:7]
	v_mfma_f32_16x16x32_bf16 v[0:3], v[180:183], v[218:221], v[0:3]
	v_mfma_f32_16x16x32_bf16 v[52:55], v[176:179], v[192:195], v[52:55]
	v_mfma_f32_16x16x32_bf16 v[48:51], v[184:187], v[192:195], v[48:51]
	v_mfma_f32_16x16x32_bf16 v[36:39], v[176:179], v[206:209], v[36:39]
	v_mfma_f32_16x16x32_bf16 v[32:35], v[184:187], v[206:209], v[32:35]
	v_mfma_f32_16x16x32_bf16 v[20:23], v[176:179], v[214:217], v[20:23]
	v_mfma_f32_16x16x32_bf16 v[16:19], v[184:187], v[214:217], v[16:19]
	v_mfma_f32_16x16x32_bf16 v[4:7], v[176:179], v[222:225], v[4:7]
	v_mfma_f32_16x16x32_bf16 v[0:3], v[184:187], v[222:225], v[0:3]
	s_barrier
	s_add_i32 s33, s33, 2
	s_add_u32 s20, s20, 0x100
	s_addc_u32 s21, s21, 0
	s_add_u32 s13, s13, 0x100
	s_addc_u32 s15, s15, 0
	s_cmp_gt_u32 s33, 29
	s_cbranch_scc0 .LBB0_2511
	s_and_b64 vcc, exec, s[10:11]
	s_cbranch_vccz .LBB0_2514
	s_barrier

; #define PG8_STAGE(bufoff, gbase, voff) do { _Pragma("unroll") for (int _i = 0; _i < 2; ++_i) \
;         __builtin_amdgcn_global_load_lds((const unsigned*)((const char*)(gbase) + (voff)[_i]), (PG8_LAS unsigned*)(lds + (bufoff) + ldsw + _i * 8192), 16, 0, 0); } while (0)
; #define PG8_LDA(dst, b, h) do { _Pragma("unroll") for (int m = 0; m < 4; ++m) _Pragma("unroll") for (int k = 0; k < 2; ++k) dst[m][k] = *(const PG8_LAS bf16x8*)(lds + PG8_SA(b, h) + aoff + m * 2048 + k * 1024); } while (0)
; #define PG8_LDB(dst, b, h) do { _Pragma("unroll") for (int n = 0; n < 2; ++n) _Pragma("unroll") for (int k = 0; k < 2; ++k) dst[n][k] = *(const PG8_LAS bf16x8*)(lds + PG8_SB(b, h) + boff + n * 2048 + k * 1024); } while (0)
; #define PG8_MMA(ai, bj, At, Bt) do { __builtin_amdgcn_s_setprio(1); _Pragma("unroll") for (int m = 0; m < 4; ++m) _Pragma("unroll") for (int n = 0; n < 2; ++n) _Pragma("unroll") for (int k = 0; k < 2; ++k) \
;         acc[ai][bj][m][n] = __builtin_amdgcn_mfma_f32_16x16x32_bf16(Bt[n][k], At[m][k], acc[ai][bj][m][n], 0, 0, 0); __builtin_amdgcn_s_setprio(0); } while (0)
; #define PG8_WAIT_V(n) asm volatile("s_waitcnt vmcnt(" #n ")" ::: "memory")
; #define PG8_WAIT_L(n) asm volatile("s_waitcnt lgkmcnt(" #n ")" ::: "memory")
; #define PG8_BAR __builtin_amdgcn_s_barrier()
; #define PG8_SCHED __builtin_amdgcn_sched_barrier(0)
; template <class Epi, class Sched, bool ALIGN_EPI = false, bool SP2 = false>
; __device__ __forceinline__ void gemm_phase(PG8_LAS unsigned char* lds, const Gemm g, const Sched& S, const Epi& E) {
;     ...
;             PG8_LDB(B0, 0, 0); PG8_LDB(B1, 0, 1); PG8_SCHED; PG8_LDA(At, 0, 0); PG8_STAGE(PG8_SA(1, 1), a1 + hstepA, voffA);
;             PG8_WAIT_V(8); PG8_WAIT_L(0); PG8_BAR; PG8_MMA(0, 0, At, B0); PG8_MMA(0, 1, At, B1); PG8_BAR; PG8_SCHED;
;             PG8_LDA(At, 0, 1); PG8_STAGE(PG8_SB(0, 0), b2, voffB); PG8_STAGE(PG8_SB(0, 1), b2 + hstep, voffB); PG8_STAGE(PG8_SA(0, 0), a2, voffA);
.LBB0_2846:
	ds_read_b128 v[128:131], v167
	ds_read_b128 v[132:135], v167 offset:1024
	ds_read_b128 v[152:155], v167 offset:2048
	ds_read_b128 v[156:159], v167 offset:3072
	ds_read_b128 v[160:163], v168
	ds_read_b128 v[170:173], v168 offset:1024
	ds_read_b128 v[174:177], v168 offset:2048
	ds_read_b128 v[178:181], v168 offset:3072
	s_add_u32 s26, s24, 0xfff80080
	s_addc_u32 s27, s25, -1
	s_cmp_eq_u32 s43, 28
	s_cselect_b32 s29, s2, s27
	s_cselect_b32 s28, s15, s26
	s_cselect_b32 s27, s13, s42
	s_cselect_b32 s26, s21, s23
	v_lshl_add_u64 v[218:219], s[24:25], 0, v[144:145]
	s_add_i32 m0, s37, 0xc000
	ds_read_b128 v[182:185], v169
	ds_read_b128 v[186:189], v169 offset:1024
	ds_read_b128 v[190:193], v169 offset:2048
	ds_read_b128 v[194:197], v169 offset:3072
	ds_read_b128 v[198:201], v169 offset:4096
	ds_read_b128 v[206:209], v169 offset:5120
	ds_read_b128 v[210:213], v169 offset:6144
	ds_read_b128 v[214:217], v169 offset:7168
	global_load_lds_dwordx4 v[218:219], off
	v_lshl_add_u64 v[218:219], s[24:25], 0, v[146:147]
	s_add_i32 m0, s37, 0xe000
	s_nop 0
	global_load_lds_dwordx4 v[218:219], off
	s_waitcnt vmcnt(8)
	s_waitcnt lgkmcnt(0)
	s_barrier
	s_waitcnt lgkmcnt(0)
	v_mfma_f32_16x16x32_bf16 v[124:127], v[128:131], v[182:185], v[124:127]
	v_mfma_f32_16x16x32_bf16 v[120:123], v[152:155], v[182:185], v[120:123]
	v_mfma_f32_16x16x32_bf16 v[108:111], v[128:131], v[190:193], v[108:111]
	v_mfma_f32_16x16x32_bf16 v[104:107], v[152:155], v[190:193], v[104:107]
	v_mfma_f32_16x16x32_bf16 v[92:95], v[128:131], v[198:201], v[92:95]
	v_mfma_f32_16x16x32_bf16 v[88:91], v[152:155], v[198:201], v[88:91]
	v_mfma_f32_16x16x32_bf16 v[76:79], v[128:131], v[210:213], v[76:79]
	v_mfma_f32_16x16x32_bf16 v[72:75], v[152:155], v[210:213], v[72:75]
	v_mfma_f32_16x16x32_bf16 v[124:127], v[132:135], v[186:189], v[124:127]
	v_mfma_f32_16x16x32_bf16 v[120:123], v[156:159], v[186:189], v[120:123]
	v_mfma_f32_16x16x32_bf16 v[108:111], v[132:135], v[194:197], v[108:111]
	v_mfma_f32_16x16x32_bf16 v[104:107], v[156:159], v[194:197], v[104:107]
	v_mfma_f32_16x16x32_bf16 v[92:95], v[132:135], v[206:209], v[92:95]
	v_mfma_f32_16x16x32_bf16 v[88:91], v[156:159], v[206:209], v[88:91]
	v_mfma_f32_16x16x32_bf16 v[76:79], v[132:135], v[214:217], v[76:79]
	v_mfma_f32_16x16x32_bf16 v[72:75], v[156:159], v[214:217], v[72:75]
	v_mfma_f32_16x16x32_bf16 v[116:119], v[160:163], v[182:185], v[116:119]
	v_mfma_f32_16x16x32_bf16 v[112:115], v[174:177], v[182:185], v[112:115]
	v_mfma_f32_16x16x32_bf16 v[100:103], v[160:163], v[190:193], v[100:103]
	v_mfma_f32_16x16x32_bf16 v[96:99], v[174:177], v[190:193], v[96:99]
	v_mfma_f32_16x16x32_bf16 v[84:87], v[160:163], v[198:201], v[84:87]
	v_mfma_f32_16x16x32_bf16 v[80:83], v[174:177], v[198:201], v[80:83]
	v_mfma_f32_16x16x32_bf16 v[68:71], v[160:163], v[210:213], v[68:71]
	v_mfma_f32_16x16x32_bf16 v[64:67], v[174:177], v[210:213], v[64:67]
	v_mfma_f32_16x16x32_bf16 v[116:119], v[170:173], v[186:189], v[116:119]
	v_mfma_f32_16x16x32_bf16 v[112:115], v[178:181], v[186:189], v[112:115]
	v_mfma_f32_16x16x32_bf16 v[100:103], v[170:173], v[194:197], v[100:103]
	v_mfma_f32_16x16x32_bf16 v[96:99], v[178:181], v[194:197], v[96:99]
	v_mfma_f32_16x16x32_bf16 v[84:87], v[170:173], v[206:209], v[84:87]
	v_mfma_f32_16x16x32_bf16 v[80:83], v[178:181], v[206:209], v[80:83]
	v_mfma_f32_16x16x32_bf16 v[68:71], v[170:173], v[214:217], v[68:71]
	v_mfma_f32_16x16x32_bf16 v[64:67], v[178:181], v[214:217], v[64:67]
	s_barrier
	s_add_i32 s52, s50, s36
	v_lshl_add_u64 v[218:219], s[26:27], 0, v[138:139]
	s_mov_b32 m0, s52
	ds_read_b128 v[182:185], v169 offset:16384
	ds_read_b128 v[186:189], v169 offset:17408
	ds_read_b128 v[190:193], v169 offset:18432
	ds_read_b128 v[194:197], v169 offset:19456
	ds_read_b128 v[198:201], v169 offset:20480
	ds_read_b128 v[206:209], v169 offset:21504
	ds_read_b128 v[210:213], v169 offset:22528
	ds_read_b128 v[214:217], v169 offset:23552
	global_load_lds_dwordx4 v[218:219], off
	s_add_i32 m0, s52, 0x2000
	s_add_u32 s52, s26, 0x80000
	v_lshl_add_u64 v[220:221], s[26:27], 0, v[142:143]
	s_addc_u32 s53, s27, 0
	s_add_i32 s54, s51, s36
	global_load_lds_dwordx4 v[220:221], off
	v_lshl_add_u64 v[222:223], s[52:53], 0, v[138:139]
	s_mov_b32 m0, s54
	v_lshl_add_u64 v[224:225], s[28:29], 0, v[140:141]
	global_load_lds_dwordx4 v[222:223], off
	v_lshl_add_u64 v[222:223], s[52:53], 0, v[142:143]
	s_add_i32 m0, s54, 0x2000
	s_nop 0
	global_load_lds_dwordx4 v[222:223], off
	v_lshl_add_u64 v[222:223], s[28:29], 0, v[136:137]
	s_mov_b32 m0, s37
	s_nop 0
	global_load_lds_dwordx4 v[222:223], off
	s_mov_b32 m0, s46
	s_nop 0
	global_load_lds_dwordx4 v[224:225], off
	s_waitcnt vmcnt(8)
	s_waitcnt lgkmcnt(0)
	s_barrier
; #define PG8_STAGE(bufoff, gbase, voff) do { _Pragma("unroll") for (int _i = 0; _i < 2; ++_i) \
;         __builtin_amdgcn_global_load_lds((const unsigned*)((const char*)(gbase) + (voff)[_i]), (PG8_LAS unsigned*)(lds + (bufoff) + ldsw + _i * 8192), 16, 0, 0); } while (0)
; #define PG8_LDA(dst, b, h) do { _Pragma("unroll") for (int m = 0; m < 4; ++m) _Pragma("unroll") for (int k = 0; k < 2; ++k) dst[m][k] = *(const PG8_LAS bf16x8*)(lds + PG8_SA(b, h) + aoff + m * 2048 + k * 1024); } while (0)
; #define PG8_LDB(dst, b, h) do { _Pragma("unroll") for (int n = 0; n < 2; ++n) _Pragma("unroll") for (int k = 0; k < 2; ++k) dst[n][k] = *(const PG8_LAS bf16x8*)(lds + PG8_SB(b, h) + boff + n * 2048 + k * 1024); } while (0)
; #define PG8_MMA(ai, bj, At, Bt) do { __builtin_amdgcn_s_setprio(1); _Pragma("unroll") for (int m = 0; m < 4; ++m) _Pragma("unroll") for (int n = 0; n < 2; ++n) _Pragma("unroll") for (int k = 0; k < 2; ++k) \
;         acc[ai][bj][m][n] = __builtin_amdgcn_mfma_f32_16x16x32_bf16(Bt[n][k], At[m][k], acc[ai][bj][m][n], 0, 0, 0); __builtin_amdgcn_s_setprio(0); } while (0)
; #define PG8_WAIT_V(n) asm volatile("s_waitcnt vmcnt(" #n ")" ::: "memory")
; #define PG8_WAIT_L(n) asm volatile("s_waitcnt lgkmcnt(" #n ")" ::: "memory")
; #define PG8_BAR __builtin_amdgcn_s_barrier()
; #define PG8_SCHED __builtin_amdgcn_sched_barrier(0)
; template <class Epi, class Sched, bool ALIGN_EPI = false, bool SP2 = false>
; __device__ __forceinline__ void gemm_phase(PG8_LAS unsigned char* lds, const Gemm g, const Sched& S, const Epi& E) {
;     ...
;             PG8_WAIT_V(8); PG8_WAIT_L(0); PG8_BAR; PG8_MMA(1, 0, At, B0); PG8_MMA(1, 1, At, B1); PG8_BAR; PG8_SCHED;
;             PG8_LDB(B0, 1, 0); PG8_LDB(B1, 1, 1); PG8_SCHED; PG8_LDA(At, 1, 0); PG8_STAGE(PG8_SA(0, 1), a2 + hstepA, voffA);
;             PG8_WAIT_V(8); PG8_WAIT_L(0); PG8_BAR; PG8_MMA(0, 0, At, B0); PG8_MMA(0, 1, At, B1); PG8_BAR; PG8_SCHED;
	s_waitcnt lgkmcnt(0)
	v_mfma_f32_16x16x32_bf16 v[60:63], v[128:131], v[182:185], v[60:63]
	v_mfma_f32_16x16x32_bf16 v[56:59], v[152:155], v[182:185], v[56:59]
	v_mfma_f32_16x16x32_bf16 v[44:47], v[128:131], v[190:193], v[44:47]
	v_mfma_f32_16x16x32_bf16 v[40:43], v[152:155], v[190:193], v[40:43]
	v_mfma_f32_16x16x32_bf16 v[28:31], v[128:131], v[198:201], v[28:31]
	v_mfma_f32_16x16x32_bf16 v[24:27], v[152:155], v[198:201], v[24:27]
	v_mfma_f32_16x16x32_bf16 v[12:15], v[128:131], v[210:213], v[12:15]
	v_mfma_f32_16x16x32_bf16 v[8:11], v[152:155], v[210:213], v[8:11]
	v_mfma_f32_16x16x32_bf16 v[60:63], v[132:135], v[186:189], v[60:63]
	v_mfma_f32_16x16x32_bf16 v[56:59], v[156:159], v[186:189], v[56:59]
	v_mfma_f32_16x16x32_bf16 v[44:47], v[132:135], v[194:197], v[44:47]
	v_mfma_f32_16x16x32_bf16 v[40:43], v[156:159], v[194:197], v[40:43]
	v_mfma_f32_16x16x32_bf16 v[28:31], v[132:135], v[206:209], v[28:31]
	v_mfma_f32_16x16x32_bf16 v[24:27], v[156:159], v[206:209], v[24:27]
	v_mfma_f32_16x16x32_bf16 v[12:15], v[132:135], v[214:217], v[12:15]
	v_mfma_f32_16x16x32_bf16 v[8:11], v[156:159], v[214:217], v[8:11]
	v_mfma_f32_16x16x32_bf16 v[52:55], v[160:163], v[182:185], v[52:55]
	v_mfma_f32_16x16x32_bf16 v[48:51], v[174:177], v[182:185], v[48:51]
	v_mfma_f32_16x16x32_bf16 v[36:39], v[160:163], v[190:193], v[36:39]
	v_mfma_f32_16x16x32_bf16 v[32:35], v[174:177], v[190:193], v[32:35]
	v_mfma_f32_16x16x32_bf16 v[20:23], v[160:163], v[198:201], v[20:23]
	v_mfma_f32_16x16x32_bf16 v[16:19], v[174:177], v[198:201], v[16:19]
	v_mfma_f32_16x16x32_bf16 v[4:7], v[160:163], v[210:213], v[4:7]
	v_mfma_f32_16x16x32_bf16 v[0:3], v[174:177], v[210:213], v[0:3]
	v_mfma_f32_16x16x32_bf16 v[52:55], v[170:173], v[186:189], v[52:55]
	v_mfma_f32_16x16x32_bf16 v[48:51], v[178:181], v[186:189], v[48:51]
	v_mfma_f32_16x16x32_bf16 v[36:39], v[170:173], v[194:197], v[36:39]
	v_mfma_f32_16x16x32_bf16 v[32:35], v[178:181], v[194:197], v[32:35]
	v_mfma_f32_16x16x32_bf16 v[20:23], v[170:173], v[206:209], v[20:23]
	v_mfma_f32_16x16x32_bf16 v[16:19], v[178:181], v[206:209], v[16:19]
	v_mfma_f32_16x16x32_bf16 v[4:7], v[170:173], v[214:217], v[4:7]
	v_mfma_f32_16x16x32_bf16 v[0:3], v[178:181], v[214:217], v[0:3]
	s_barrier
	s_add_i32 s52, 0, 0x18000
	s_add_i32 s53, 0, 0x1c000
	v_add_u32_e32 v156, s52, v165
	v_add_u32_e32 v178, s53, v165
	ds_read_b128 v[128:131], v156
	ds_read_b128 v[132:135], v156 offset:1024
	ds_read_b128 v[152:155], v156 offset:2048
	ds_read_b128 v[156:159], v156 offset:3072
	ds_read_b128 v[160:163], v178
	ds_read_b128 v[170:173], v178 offset:1024
	ds_read_b128 v[174:177], v178 offset:2048
	ds_read_b128 v[178:181], v178 offset:3072
	s_add_u32 s28, s28, 0x80000
	s_addc_u32 s29, s29, 0
	s_mov_b32 m0, s47
	v_lshl_add_u64 v[226:227], s[28:29], 0, v[136:137]
	ds_read_b128 v[182:185], v169 offset:32768
	ds_read_b128 v[186:189], v169 offset:33792
	ds_read_b128 v[190:193], v169 offset:34816
	ds_read_b128 v[194:197], v169 offset:35840
	ds_read_b128 v[198:201], v169 offset:36864
	ds_read_b128 v[206:209], v169 offset:37888
	ds_read_b128 v[210:213], v169 offset:38912
	ds_read_b128 v[214:217], v169 offset:39936
	global_load_lds_dwordx4 v[226:227], off
	v_lshl_add_u64 v[226:227], s[28:29], 0, v[140:141]
	s_mov_b32 m0, s48
	s_nop 0
	global_load_lds_dwordx4 v[226:227], off
	s_waitcnt vmcnt(8)
	s_waitcnt lgkmcnt(0)
	s_barrier
	s_waitcnt lgkmcnt(0)
	v_mfma_f32_16x16x32_bf16 v[124:127], v[128:131], v[182:185], v[124:127]
	v_mfma_f32_16x16x32_bf16 v[120:123], v[152:155], v[182:185], v[120:123]
	v_mfma_f32_16x16x32_bf16 v[108:111], v[128:131], v[190:193], v[108:111]
	v_mfma_f32_16x16x32_bf16 v[104:107], v[152:155], v[190:193], v[104:107]
	v_mfma_f32_16x16x32_bf16 v[92:95], v[128:131], v[198:201], v[92:95]
	v_mfma_f32_16x16x32_bf16 v[88:91], v[152:155], v[198:201], v[88:91]
	v_mfma_f32_16x16x32_bf16 v[76:79], v[128:131], v[210:213], v[76:79]
	v_mfma_f32_16x16x32_bf16 v[72:75], v[152:155], v[210:213], v[72:75]
	v_mfma_f32_16x16x32_bf16 v[124:127], v[132:135], v[186:189], v[124:127]
	v_mfma_f32_16x16x32_bf16 v[120:123], v[156:159], v[186:189], v[120:123]
	v_mfma_f32_16x16x32_bf16 v[108:111], v[132:135], v[194:197], v[108:111]
	v_mfma_f32_16x16x32_bf16 v[104:107], v[156:159], v[194:197], v[104:107]
	v_mfma_f32_16x16x32_bf16 v[92:95], v[132:135], v[206:209], v[92:95]
	v_mfma_f32_16x16x32_bf16 v[88:91], v[156:159], v[206:209], v[88:91]
	v_mfma_f32_16x16x32_bf16 v[76:79], v[132:135], v[214:217], v[76:79]
	v_mfma_f32_16x16x32_bf16 v[72:75], v[156:159], v[214:217], v[72:75]
	v_mfma_f32_16x16x32_bf16 v[116:119], v[160:163], v[182:185], v[116:119]
	v_mfma_f32_16x16x32_bf16 v[112:115], v[174:177], v[182:185], v[112:115]
	v_mfma_f32_16x16x32_bf16 v[100:103], v[160:163], v[190:193], v[100:103]
	v_mfma_f32_16x16x32_bf16 v[96:99], v[174:177], v[190:193], v[96:99]
	v_mfma_f32_16x16x32_bf16 v[84:87], v[160:163], v[198:201], v[84:87]
	v_mfma_f32_16x16x32_bf16 v[80:83], v[174:177], v[198:201], v[80:83]
	v_mfma_f32_16x16x32_bf16 v[68:71], v[160:163], v[210:213], v[68:71]
	v_mfma_f32_16x16x32_bf16 v[64:67], v[174:177], v[210:213], v[64:67]
	v_mfma_f32_16x16x32_bf16 v[116:119], v[170:173], v[186:189], v[116:119]
	v_mfma_f32_16x16x32_bf16 v[112:115], v[178:181], v[186:189], v[112:115]
	v_mfma_f32_16x16x32_bf16 v[100:103], v[170:173], v[194:197], v[100:103]
	v_mfma_f32_16x16x32_bf16 v[96:99], v[178:181], v[194:197], v[96:99]
	v_mfma_f32_16x16x32_bf16 v[84:87], v[170:173], v[206:209], v[84:87]
	v_mfma_f32_16x16x32_bf16 v[80:83], v[178:181], v[206:209], v[80:83]
	v_mfma_f32_16x16x32_bf16 v[68:71], v[170:173], v[214:217], v[68:71]
	v_mfma_f32_16x16x32_bf16 v[64:67], v[178:181], v[214:217], v[64:67]
	s_barrier
; #define PG8_STAGE(bufoff, gbase, voff) do { _Pragma("unroll") for (int _i = 0; _i < 2; ++_i) \
;         __builtin_amdgcn_global_load_lds((const unsigned*)((const char*)(gbase) + (voff)[_i]), (PG8_LAS unsigned*)(lds + (bufoff) + ldsw + _i * 8192), 16, 0, 0); } while (0)
; #define PG8_LDA(dst, b, h) do { _Pragma("unroll") for (int m = 0; m < 4; ++m) _Pragma("unroll") for (int k = 0; k < 2; ++k) dst[m][k] = *(const PG8_LAS bf16x8*)(lds + PG8_SA(b, h) + aoff + m * 2048 + k * 1024); } while (0)
; #define PG8_MMA(ai, bj, At, Bt) do { __builtin_amdgcn_s_setprio(1); _Pragma("unroll") for (int m = 0; m < 4; ++m) _Pragma("unroll") for (int n = 0; n < 2; ++n) _Pragma("unroll") for (int k = 0; k < 2; ++k) \
;         acc[ai][bj][m][n] = __builtin_amdgcn_mfma_f32_16x16x32_bf16(Bt[n][k], At[m][k], acc[ai][bj][m][n], 0, 0, 0); __builtin_amdgcn_s_setprio(0); } while (0)
; #define PG8_WAIT_V(n) asm volatile("s_waitcnt vmcnt(" #n ")" ::: "memory")
; #define PG8_WAIT_L(n) asm volatile("s_waitcnt lgkmcnt(" #n ")" ::: "memory")
; #define PG8_BAR __builtin_amdgcn_s_barrier()
; #define PG8_SCHED __builtin_amdgcn_sched_barrier(0)
; template <class Epi, class Sched, bool ALIGN_EPI = false, bool SP2 = false>
; __device__ __forceinline__ void gemm_phase(PG8_LAS unsigned char* lds, const Gemm g, const Sched& S, const Epi& E) {
;     ...
;             PG8_LDA(At, 1, 1); PG8_STAGE(PG8_SB(1, 0), b3, voffB); PG8_STAGE(PG8_SB(1, 1), b3 + hstep, voffB); PG8_STAGE(PG8_SA(1, 0), a3, voffA);
;             PG8_WAIT_V(8); PG8_WAIT_L(0); PG8_BAR; PG8_MMA(1, 0, At, B0); PG8_MMA(1, 1, At, B1); PG8_BAR; PG8_SCHED;
	s_add_i32 s28, s52, s36
	v_lshl_add_u64 v[218:219], v[218:219], 0, s[0:1]
	s_mov_b32 m0, s28
	ds_read_b128 v[182:185], v169 offset:49152
	ds_read_b128 v[186:189], v169 offset:50176
	ds_read_b128 v[190:193], v169 offset:51200
	ds_read_b128 v[194:197], v169 offset:52224
	ds_read_b128 v[198:201], v169 offset:53248
	ds_read_b128 v[206:209], v169 offset:54272
	ds_read_b128 v[210:213], v169 offset:55296
	ds_read_b128 v[214:217], v169 offset:56320
	global_load_lds_dwordx4 v[218:219], off
	s_add_i32 m0, s28, 0x2000
	s_add_u32 s26, s26, 0x80080
	v_lshl_add_u64 v[218:219], v[220:221], 0, s[0:1]
	s_addc_u32 s27, s27, 0
	s_add_i32 s28, s53, s36
	global_load_lds_dwordx4 v[218:219], off
	v_lshl_add_u64 v[218:219], s[26:27], 0, v[138:139]
	s_mov_b32 m0, s28
	s_nop 0
	global_load_lds_dwordx4 v[218:219], off
	v_lshl_add_u64 v[218:219], s[26:27], 0, v[142:143]
	s_add_i32 m0, s28, 0x2000
	s_nop 0
	global_load_lds_dwordx4 v[218:219], off
	v_lshl_add_u64 v[218:219], v[222:223], 0, s[0:1]
	s_mov_b32 m0, s39
	s_nop 0
	global_load_lds_dwordx4 v[218:219], off
	v_lshl_add_u64 v[218:219], v[224:225], 0, s[0:1]
	s_mov_b32 m0, s40
	s_nop 0
	global_load_lds_dwordx4 v[218:219], off
	s_waitcnt vmcnt(8)
	s_waitcnt lgkmcnt(0)
	s_barrier
	s_waitcnt lgkmcnt(0)
	v_mfma_f32_16x16x32_bf16 v[60:63], v[128:131], v[182:185], v[60:63]
	v_mfma_f32_16x16x32_bf16 v[56:59], v[152:155], v[182:185], v[56:59]
	v_mfma_f32_16x16x32_bf16 v[44:47], v[128:131], v[190:193], v[44:47]
	v_mfma_f32_16x16x32_bf16 v[40:43], v[152:155], v[190:193], v[40:43]
	v_mfma_f32_16x16x32_bf16 v[28:31], v[128:131], v[198:201], v[28:31]
	v_mfma_f32_16x16x32_bf16 v[24:27], v[152:155], v[198:201], v[24:27]
	v_mfma_f32_16x16x32_bf16 v[12:15], v[128:131], v[210:213], v[12:15]
	v_mfma_f32_16x16x32_bf16 v[8:11], v[152:155], v[210:213], v[8:11]
	v_mfma_f32_16x16x32_bf16 v[60:63], v[132:135], v[186:189], v[60:63]
	v_mfma_f32_16x16x32_bf16 v[56:59], v[156:159], v[186:189], v[56:59]
	v_mfma_f32_16x16x32_bf16 v[44:47], v[132:135], v[194:197], v[44:47]
	v_mfma_f32_16x16x32_bf16 v[40:43], v[156:159], v[194:197], v[40:43]
	v_mfma_f32_16x16x32_bf16 v[28:31], v[132:135], v[206:209], v[28:31]
	v_mfma_f32_16x16x32_bf16 v[24:27], v[156:159], v[206:209], v[24:27]
	v_mfma_f32_16x16x32_bf16 v[12:15], v[132:135], v[214:217], v[12:15]
	v_mfma_f32_16x16x32_bf16 v[8:11], v[156:159], v[214:217], v[8:11]
	v_mfma_f32_16x16x32_bf16 v[52:55], v[160:163], v[182:185], v[52:55]
	v_mfma_f32_16x16x32_bf16 v[48:51], v[174:177], v[182:185], v[48:51]
	v_mfma_f32_16x16x32_bf16 v[36:39], v[160:163], v[190:193], v[36:39]
	v_mfma_f32_16x16x32_bf16 v[32:35], v[174:177], v[190:193], v[32:35]
	v_mfma_f32_16x16x32_bf16 v[20:23], v[160:163], v[198:201], v[20:23]
	v_mfma_f32_16x16x32_bf16 v[16:19], v[174:177], v[198:201], v[16:19]
	v_mfma_f32_16x16x32_bf16 v[4:7], v[160:163], v[210:213], v[4:7]
	v_mfma_f32_16x16x32_bf16 v[0:3], v[174:177], v[210:213], v[0:3]
	v_mfma_f32_16x16x32_bf16 v[52:55], v[170:173], v[186:189], v[52:55]
	v_mfma_f32_16x16x32_bf16 v[48:51], v[178:181], v[186:189], v[48:51]
	v_mfma_f32_16x16x32_bf16 v[36:39], v[170:173], v[194:197], v[36:39]
	v_mfma_f32_16x16x32_bf16 v[32:35], v[178:181], v[194:197], v[32:35]
	v_mfma_f32_16x16x32_bf16 v[20:23], v[170:173], v[206:209], v[20:23]
	v_mfma_f32_16x16x32_bf16 v[16:19], v[178:181], v[206:209], v[16:19]
	v_mfma_f32_16x16x32_bf16 v[4:7], v[170:173], v[214:217], v[4:7]
	v_mfma_f32_16x16x32_bf16 v[0:3], v[178:181], v[214:217], v[0:3]
	s_barrier
	s_add_i32 s43, s43, 2
	s_add_u32 s24, s24, 0x100
	s_addc_u32 s25, s25, 0
	s_add_u32 s23, s23, 0x100
	s_addc_u32 s42, s42, 0
	s_cmp_gt_u32 s43, 29
	s_cbranch_scc0 .LBB0_2846
	s_and_b64 vcc, exec, s[10:11]
	s_cbranch_vccz .LBB0_2849
	s_barrier

; #define PG8_STAGE(bufoff, gbase, voff) do { _Pragma("unroll") for (int _i = 0; _i < 2; ++_i) \
;         __builtin_amdgcn_global_load_lds((const unsigned*)((const char*)(gbase) + (voff)[_i]), (PG8_LAS unsigned*)(lds + (bufoff) + ldsw + _i * 8192), 16, 0, 0); } while (0)
; #define PG8_LDA(dst, b, h) do { _Pragma("unroll") for (int m = 0; m < 4; ++m) _Pragma("unroll") for (int k = 0; k < 2; ++k) dst[m][k] = *(const PG8_LAS bf16x8*)(lds + PG8_SA(b, h) + aoff + m * 2048 + k * 1024); } while (0)
; #define PG8_LDB(dst, b, h) do { _Pragma("unroll") for (int n = 0; n < 2; ++n) _Pragma("unroll") for (int k = 0; k < 2; ++k) dst[n][k] = *(const PG8_LAS bf16x8*)(lds + PG8_SB(b, h) + boff + n * 2048 + k * 1024); } while (0)
; #define PG8_MMA(ai, bj, At, Bt) do { __builtin_amdgcn_s_setprio(1); _Pragma("unroll") for (int m = 0; m < 4; ++m) _Pragma("unroll") for (int n = 0; n < 2; ++n) _Pragma("unroll") for (int k = 0; k < 2; ++k) \
;         acc[ai][bj][m][n] = __builtin_amdgcn_mfma_f32_16x16x32_bf16(Bt[n][k], At[m][k], acc[ai][bj][m][n], 0, 0, 0); __builtin_amdgcn_s_setprio(0); } while (0)
; #define PG8_WAIT_V(n) asm volatile("s_waitcnt vmcnt(" #n ")" ::: "memory")
; #define PG8_WAIT_L(n) asm volatile("s_waitcnt lgkmcnt(" #n ")" ::: "memory")
; #define PG8_BAR __builtin_amdgcn_s_barrier()
; #define PG8_SCHED __builtin_amdgcn_sched_barrier(0)
; template <class Epi, class Sched, bool ALIGN_EPI = false, bool SP2 = false>
; __device__ __forceinline__ void gemm_phase(PG8_LAS unsigned char* lds, const Gemm g, const Sched& S, const Epi& E) {
;     ...
;             PG8_LDB(B0, 0, 0); PG8_LDB(B1, 0, 1); PG8_SCHED; PG8_LDA(At, 0, 0); PG8_STAGE(PG8_SA(1, 1), a1 + hstepA, voffA);
;             PG8_WAIT_V(8); PG8_WAIT_L(0); PG8_BAR; PG8_MMA(0, 0, At, B0); PG8_MMA(0, 1, At, B1); PG8_BAR; PG8_SCHED;
;             PG8_LDA(At, 0, 1); PG8_STAGE(PG8_SB(0, 0), b2, voffB); PG8_STAGE(PG8_SB(0, 1), b2 + hstep, voffB); PG8_STAGE(PG8_SA(0, 0), a2, voffA);
.LBB0_2934:
	ds_read_b128 v[128:131], v207
	ds_read_b128 v[132:135], v207 offset:1024
	ds_read_b128 v[136:139], v207 offset:2048
	ds_read_b128 v[140:143], v207 offset:3072
	ds_read_b128 v[144:147], v208
	ds_read_b128 v[148:151], v208 offset:1024
	ds_read_b128 v[152:155], v208 offset:2048
	ds_read_b128 v[156:159], v208 offset:3072
	s_add_u32 s26, s24, 0x100
	s_addc_u32 s27, s25, 0
	s_cmp_eq_u32 s39, 28
	s_cselect_b32 s31, s71, s27
	s_cselect_b32 s30, s70, s26
	s_cselect_b32 s29, s1, s38
	s_cselect_b32 s28, s3, s33
	v_lshl_add_u64 v[220:221], s[24:25], 0, v[170:171]
	s_add_i32 m0, s75, 0xc000
	ds_read_b128 v[178:181], v209
	ds_read_b128 v[182:185], v209 offset:1024
	ds_read_b128 v[186:189], v209 offset:2048
	ds_read_b128 v[190:193], v209 offset:3072
	ds_read_b128 v[194:197], v209 offset:4096
	ds_read_b128 v[198:201], v209 offset:5120
	ds_read_b128 v[212:215], v209 offset:6144
	ds_read_b128 v[216:219], v209 offset:7168
	global_load_lds_dwordx4 v[220:221], off
	v_lshl_add_u64 v[220:221], s[24:25], 0, v[172:173]
	s_add_i32 m0, s75, 0xe000
	s_nop 0
	global_load_lds_dwordx4 v[220:221], off
	s_waitcnt vmcnt(8)
	s_waitcnt lgkmcnt(0)
	s_barrier
	s_waitcnt lgkmcnt(0)
	v_mfma_f32_16x16x32_bf16 v[124:127], v[128:131], v[178:181], v[124:127]
	v_mfma_f32_16x16x32_bf16 v[60:63], v[136:139], v[178:181], v[60:63]
	v_mfma_f32_16x16x32_bf16 v[120:123], v[128:131], v[186:189], v[120:123]
	v_mfma_f32_16x16x32_bf16 v[56:59], v[136:139], v[186:189], v[56:59]
	v_mfma_f32_16x16x32_bf16 v[116:119], v[128:131], v[194:197], v[116:119]
	v_mfma_f32_16x16x32_bf16 v[52:55], v[136:139], v[194:197], v[52:55]
	v_mfma_f32_16x16x32_bf16 v[108:111], v[128:131], v[212:215], v[108:111]
	v_mfma_f32_16x16x32_bf16 v[44:47], v[136:139], v[212:215], v[44:47]
	v_mfma_f32_16x16x32_bf16 v[124:127], v[132:135], v[182:185], v[124:127]
	v_mfma_f32_16x16x32_bf16 v[60:63], v[140:143], v[182:185], v[60:63]
	v_mfma_f32_16x16x32_bf16 v[120:123], v[132:135], v[190:193], v[120:123]
	v_mfma_f32_16x16x32_bf16 v[56:59], v[140:143], v[190:193], v[56:59]
	v_mfma_f32_16x16x32_bf16 v[116:119], v[132:135], v[198:201], v[116:119]
	v_mfma_f32_16x16x32_bf16 v[52:55], v[140:143], v[198:201], v[52:55]
	v_mfma_f32_16x16x32_bf16 v[108:111], v[132:135], v[216:219], v[108:111]
	v_mfma_f32_16x16x32_bf16 v[44:47], v[140:143], v[216:219], v[44:47]
	v_mfma_f32_16x16x32_bf16 v[112:115], v[144:147], v[178:181], v[112:115]
	v_mfma_f32_16x16x32_bf16 v[48:51], v[152:155], v[178:181], v[48:51]
	v_mfma_f32_16x16x32_bf16 v[104:107], v[144:147], v[186:189], v[104:107]
	v_mfma_f32_16x16x32_bf16 v[40:43], v[152:155], v[186:189], v[40:43]
	v_mfma_f32_16x16x32_bf16 v[100:103], v[144:147], v[194:197], v[100:103]
	v_mfma_f32_16x16x32_bf16 v[36:39], v[152:155], v[194:197], v[36:39]
	v_mfma_f32_16x16x32_bf16 v[96:99], v[144:147], v[212:215], v[96:99]
	v_mfma_f32_16x16x32_bf16 v[32:35], v[152:155], v[212:215], v[32:35]
	v_mfma_f32_16x16x32_bf16 v[112:115], v[148:151], v[182:185], v[112:115]
	v_mfma_f32_16x16x32_bf16 v[48:51], v[156:159], v[182:185], v[48:51]
	v_mfma_f32_16x16x32_bf16 v[104:107], v[148:151], v[190:193], v[104:107]
	v_mfma_f32_16x16x32_bf16 v[40:43], v[156:159], v[190:193], v[40:43]
	v_mfma_f32_16x16x32_bf16 v[100:103], v[148:151], v[198:201], v[100:103]
	v_mfma_f32_16x16x32_bf16 v[36:39], v[156:159], v[198:201], v[36:39]
	v_mfma_f32_16x16x32_bf16 v[96:99], v[148:151], v[216:219], v[96:99]
	v_mfma_f32_16x16x32_bf16 v[32:35], v[156:159], v[216:219], v[32:35]
	s_barrier
	s_add_i32 s24, s84, s74
	v_lshl_add_u64 v[220:221], s[28:29], 0, v[162:163]
	s_mov_b32 m0, s24
	ds_read_b128 v[178:181], v209 offset:16384
	ds_read_b128 v[182:185], v209 offset:17408
	ds_read_b128 v[186:189], v209 offset:18432
	ds_read_b128 v[190:193], v209 offset:19456
	ds_read_b128 v[194:197], v209 offset:20480
	ds_read_b128 v[198:201], v209 offset:21504
	ds_read_b128 v[212:215], v209 offset:22528
	ds_read_b128 v[216:219], v209 offset:23552
	global_load_lds_dwordx4 v[220:221], off
	s_add_i32 m0, s24, 0x2000
	s_add_u32 s24, s28, 0x80000
	v_lshl_add_u64 v[222:223], s[28:29], 0, v[166:167]
	s_addc_u32 s25, s29, 0
	s_add_i32 s40, s85, s74
	global_load_lds_dwordx4 v[222:223], off
	v_lshl_add_u64 v[224:225], s[24:25], 0, v[162:163]
	s_mov_b32 m0, s40
	v_lshl_add_u64 v[226:227], s[30:31], 0, v[164:165]
	global_load_lds_dwordx4 v[224:225], off
	v_lshl_add_u64 v[224:225], s[24:25], 0, v[166:167]
	s_add_i32 m0, s40, 0x2000
	s_nop 0
	global_load_lds_dwordx4 v[224:225], off
	v_lshl_add_u64 v[224:225], s[30:31], 0, v[160:161]
	s_mov_b32 m0, s75
	s_nop 0
	global_load_lds_dwordx4 v[224:225], off
	s_mov_b32 m0, s76
	s_nop 0
	global_load_lds_dwordx4 v[226:227], off
	s_waitcnt vmcnt(8)
	s_waitcnt lgkmcnt(0)
	s_barrier
; #define PG8_STAGE(bufoff, gbase, voff) do { _Pragma("unroll") for (int _i = 0; _i < 2; ++_i) \
;         __builtin_amdgcn_global_load_lds((const unsigned*)((const char*)(gbase) + (voff)[_i]), (PG8_LAS unsigned*)(lds + (bufoff) + ldsw + _i * 8192), 16, 0, 0); } while (0)
; #define PG8_LDA(dst, b, h) do { _Pragma("unroll") for (int m = 0; m < 4; ++m) _Pragma("unroll") for (int k = 0; k < 2; ++k) dst[m][k] = *(const PG8_LAS bf16x8*)(lds + PG8_SA(b, h) + aoff + m * 2048 + k * 1024); } while (0)
; #define PG8_LDB(dst, b, h) do { _Pragma("unroll") for (int n = 0; n < 2; ++n) _Pragma("unroll") for (int k = 0; k < 2; ++k) dst[n][k] = *(const PG8_LAS bf16x8*)(lds + PG8_SB(b, h) + boff + n * 2048 + k * 1024); } while (0)
; #define PG8_MMA(ai, bj, At, Bt) do { __builtin_amdgcn_s_setprio(1); _Pragma("unroll") for (int m = 0; m < 4; ++m) _Pragma("unroll") for (int n = 0; n < 2; ++n) _Pragma("unroll") for (int k = 0; k < 2; ++k) \
;         acc[ai][bj][m][n] = __builtin_amdgcn_mfma_f32_16x16x32_bf16(Bt[n][k], At[m][k], acc[ai][bj][m][n], 0, 0, 0); __builtin_amdgcn_s_setprio(0); } while (0)
; #define PG8_WAIT_V(n) asm volatile("s_waitcnt vmcnt(" #n ")" ::: "memory")
; #define PG8_WAIT_L(n) asm volatile("s_waitcnt lgkmcnt(" #n ")" ::: "memory")
; #define PG8_BAR __builtin_amdgcn_s_barrier()
; #define PG8_SCHED __builtin_amdgcn_sched_barrier(0)
; template <class Epi, class Sched, bool ALIGN_EPI = false, bool SP2 = false>
; __device__ __forceinline__ void gemm_phase(PG8_LAS unsigned char* lds, const Gemm g, const Sched& S, const Epi& E) {
;     ...
;             PG8_WAIT_V(8); PG8_WAIT_L(0); PG8_BAR; PG8_MMA(1, 0, At, B0); PG8_MMA(1, 1, At, B1); PG8_BAR; PG8_SCHED;
;             PG8_LDB(B0, 1, 0); PG8_LDB(B1, 1, 1); PG8_SCHED; PG8_LDA(At, 1, 0); PG8_STAGE(PG8_SA(0, 1), a2 + hstepA, voffA);
;             PG8_WAIT_V(8); PG8_WAIT_L(0); PG8_BAR; PG8_MMA(0, 0, At, B0); PG8_MMA(0, 1, At, B1); PG8_BAR; PG8_SCHED;
	s_waitcnt lgkmcnt(0)
	v_mfma_f32_16x16x32_bf16 v[92:95], v[128:131], v[178:181], v[92:95]
	v_mfma_f32_16x16x32_bf16 v[28:31], v[136:139], v[178:181], v[28:31]
	v_mfma_f32_16x16x32_bf16 v[88:91], v[128:131], v[186:189], v[88:91]
	v_mfma_f32_16x16x32_bf16 v[24:27], v[136:139], v[186:189], v[24:27]
	v_mfma_f32_16x16x32_bf16 v[84:87], v[128:131], v[194:197], v[84:87]
	v_mfma_f32_16x16x32_bf16 v[20:23], v[136:139], v[194:197], v[20:23]
	v_mfma_f32_16x16x32_bf16 v[76:79], v[128:131], v[212:215], v[76:79]
	v_mfma_f32_16x16x32_bf16 v[12:15], v[136:139], v[212:215], v[12:15]
	v_mfma_f32_16x16x32_bf16 v[92:95], v[132:135], v[182:185], v[92:95]
	v_mfma_f32_16x16x32_bf16 v[28:31], v[140:143], v[182:185], v[28:31]
	v_mfma_f32_16x16x32_bf16 v[88:91], v[132:135], v[190:193], v[88:91]
	v_mfma_f32_16x16x32_bf16 v[24:27], v[140:143], v[190:193], v[24:27]
	v_mfma_f32_16x16x32_bf16 v[84:87], v[132:135], v[198:201], v[84:87]
	v_mfma_f32_16x16x32_bf16 v[20:23], v[140:143], v[198:201], v[20:23]
	v_mfma_f32_16x16x32_bf16 v[76:79], v[132:135], v[216:219], v[76:79]
	v_mfma_f32_16x16x32_bf16 v[12:15], v[140:143], v[216:219], v[12:15]
	v_mfma_f32_16x16x32_bf16 v[80:83], v[144:147], v[178:181], v[80:83]
	v_mfma_f32_16x16x32_bf16 v[16:19], v[152:155], v[178:181], v[16:19]
	v_mfma_f32_16x16x32_bf16 v[72:75], v[144:147], v[186:189], v[72:75]
	v_mfma_f32_16x16x32_bf16 v[8:11], v[152:155], v[186:189], v[8:11]
	v_mfma_f32_16x16x32_bf16 v[68:71], v[144:147], v[194:197], v[68:71]
	v_mfma_f32_16x16x32_bf16 v[4:7], v[152:155], v[194:197], v[4:7]
	v_mfma_f32_16x16x32_bf16 v[64:67], v[144:147], v[212:215], v[64:67]
	v_mfma_f32_16x16x32_bf16 v[0:3], v[152:155], v[212:215], v[0:3]
	v_mfma_f32_16x16x32_bf16 v[80:83], v[148:151], v[182:185], v[80:83]
	v_mfma_f32_16x16x32_bf16 v[16:19], v[156:159], v[182:185], v[16:19]
	v_mfma_f32_16x16x32_bf16 v[72:75], v[148:151], v[190:193], v[72:75]
	v_mfma_f32_16x16x32_bf16 v[8:11], v[156:159], v[190:193], v[8:11]
	v_mfma_f32_16x16x32_bf16 v[68:71], v[148:151], v[198:201], v[68:71]
	v_mfma_f32_16x16x32_bf16 v[4:7], v[156:159], v[198:201], v[4:7]
	v_mfma_f32_16x16x32_bf16 v[64:67], v[148:151], v[216:219], v[64:67]
	v_mfma_f32_16x16x32_bf16 v[0:3], v[156:159], v[216:219], v[0:3]
	s_barrier
	s_add_i32 s40, 0, 0x18000
	s_add_i32 s41, 0, 0x1c000
	v_add_u32_e32 v140, s40, v203
	v_add_u32_e32 v156, s41, v203
	ds_read_b128 v[128:131], v140
	ds_read_b128 v[132:135], v140 offset:1024
	ds_read_b128 v[136:139], v140 offset:2048
	ds_read_b128 v[140:143], v140 offset:3072
	ds_read_b128 v[144:147], v156
	ds_read_b128 v[148:151], v156 offset:1024
	ds_read_b128 v[152:155], v156 offset:2048
	ds_read_b128 v[156:159], v156 offset:3072
	s_add_u32 s24, s30, 0x7c000
	s_addc_u32 s25, s31, 0
	s_mov_b32 m0, s77
	v_lshl_add_u64 v[228:229], s[24:25], 0, v[160:161]
	ds_read_b128 v[178:181], v209 offset:32768
	ds_read_b128 v[182:185], v209 offset:33792
	ds_read_b128 v[186:189], v209 offset:34816
	ds_read_b128 v[190:193], v209 offset:35840
	ds_read_b128 v[194:197], v209 offset:36864
	ds_read_b128 v[198:201], v209 offset:37888
	ds_read_b128 v[212:215], v209 offset:38912
	ds_read_b128 v[216:219], v209 offset:39936
	global_load_lds_dwordx4 v[228:229], off
	v_lshl_add_u64 v[228:229], s[24:25], 0, v[164:165]
	s_mov_b32 m0, s78
	s_nop 0
	global_load_lds_dwordx4 v[228:229], off
	s_waitcnt vmcnt(8)
	s_waitcnt lgkmcnt(0)
	s_barrier
	s_waitcnt lgkmcnt(0)
	v_mfma_f32_16x16x32_bf16 v[124:127], v[128:131], v[178:181], v[124:127]
	v_mfma_f32_16x16x32_bf16 v[60:63], v[136:139], v[178:181], v[60:63]
	v_mfma_f32_16x16x32_bf16 v[120:123], v[128:131], v[186:189], v[120:123]
	v_mfma_f32_16x16x32_bf16 v[56:59], v[136:139], v[186:189], v[56:59]
	v_mfma_f32_16x16x32_bf16 v[116:119], v[128:131], v[194:197], v[116:119]
	v_mfma_f32_16x16x32_bf16 v[52:55], v[136:139], v[194:197], v[52:55]
	v_mfma_f32_16x16x32_bf16 v[108:111], v[128:131], v[212:215], v[108:111]
	v_mfma_f32_16x16x32_bf16 v[44:47], v[136:139], v[212:215], v[44:47]
	v_mfma_f32_16x16x32_bf16 v[124:127], v[132:135], v[182:185], v[124:127]
	v_mfma_f32_16x16x32_bf16 v[60:63], v[140:143], v[182:185], v[60:63]
	v_mfma_f32_16x16x32_bf16 v[120:123], v[132:135], v[190:193], v[120:123]
	v_mfma_f32_16x16x32_bf16 v[56:59], v[140:143], v[190:193], v[56:59]
	v_mfma_f32_16x16x32_bf16 v[116:119], v[132:135], v[198:201], v[116:119]
	v_mfma_f32_16x16x32_bf16 v[52:55], v[140:143], v[198:201], v[52:55]
	v_mfma_f32_16x16x32_bf16 v[108:111], v[132:135], v[216:219], v[108:111]
	v_mfma_f32_16x16x32_bf16 v[44:47], v[140:143], v[216:219], v[44:47]
	v_mfma_f32_16x16x32_bf16 v[112:115], v[144:147], v[178:181], v[112:115]
	v_mfma_f32_16x16x32_bf16 v[48:51], v[152:155], v[178:181], v[48:51]
	v_mfma_f32_16x16x32_bf16 v[104:107], v[144:147], v[186:189], v[104:107]
	v_mfma_f32_16x16x32_bf16 v[40:43], v[152:155], v[186:189], v[40:43]
	v_mfma_f32_16x16x32_bf16 v[100:103], v[144:147], v[194:197], v[100:103]
	v_mfma_f32_16x16x32_bf16 v[36:39], v[152:155], v[194:197], v[36:39]
	v_mfma_f32_16x16x32_bf16 v[96:99], v[144:147], v[212:215], v[96:99]
	v_mfma_f32_16x16x32_bf16 v[32:35], v[152:155], v[212:215], v[32:35]
	v_mfma_f32_16x16x32_bf16 v[112:115], v[148:151], v[182:185], v[112:115]
	v_mfma_f32_16x16x32_bf16 v[48:51], v[156:159], v[182:185], v[48:51]
	v_mfma_f32_16x16x32_bf16 v[104:107], v[148:151], v[190:193], v[104:107]
	v_mfma_f32_16x16x32_bf16 v[40:43], v[156:159], v[190:193], v[40:43]
	v_mfma_f32_16x16x32_bf16 v[100:103], v[148:151], v[198:201], v[100:103]
	v_mfma_f32_16x16x32_bf16 v[36:39], v[156:159], v[198:201], v[36:39]
	v_mfma_f32_16x16x32_bf16 v[96:99], v[148:151], v[216:219], v[96:99]
	v_mfma_f32_16x16x32_bf16 v[32:35], v[156:159], v[216:219], v[32:35]
	s_barrier
; #define PG8_STAGE(bufoff, gbase, voff) do { _Pragma("unroll") for (int _i = 0; _i < 2; ++_i) \
;         __builtin_amdgcn_global_load_lds((const unsigned*)((const char*)(gbase) + (voff)[_i]), (PG8_LAS unsigned*)(lds + (bufoff) + ldsw + _i * 8192), 16, 0, 0); } while (0)
; #define PG8_LDA(dst, b, h) do { _Pragma("unroll") for (int m = 0; m < 4; ++m) _Pragma("unroll") for (int k = 0; k < 2; ++k) dst[m][k] = *(const PG8_LAS bf16x8*)(lds + PG8_SA(b, h) + aoff + m * 2048 + k * 1024); } while (0)
; #define PG8_MMA(ai, bj, At, Bt) do { __builtin_amdgcn_s_setprio(1); _Pragma("unroll") for (int m = 0; m < 4; ++m) _Pragma("unroll") for (int n = 0; n < 2; ++n) _Pragma("unroll") for (int k = 0; k < 2; ++k) \
;         acc[ai][bj][m][n] = __builtin_amdgcn_mfma_f32_16x16x32_bf16(Bt[n][k], At[m][k], acc[ai][bj][m][n], 0, 0, 0); __builtin_amdgcn_s_setprio(0); } while (0)
; #define PG8_WAIT_V(n) asm volatile("s_waitcnt vmcnt(" #n ")" ::: "memory")
; #define PG8_WAIT_L(n) asm volatile("s_waitcnt lgkmcnt(" #n ")" ::: "memory")
; #define PG8_BAR __builtin_amdgcn_s_barrier()
; #define PG8_SCHED __builtin_amdgcn_sched_barrier(0)
; template <class Epi, class Sched, bool ALIGN_EPI = false, bool SP2 = false>
; __device__ __forceinline__ void gemm_phase(PG8_LAS unsigned char* lds, const Gemm g, const Sched& S, const Epi& E) {
;     ...
;             PG8_LDA(At, 1, 1); PG8_STAGE(PG8_SB(1, 0), b3, voffB); PG8_STAGE(PG8_SB(1, 1), b3 + hstep, voffB); PG8_STAGE(PG8_SA(1, 0), a3, voffA);
;             PG8_WAIT_V(8); PG8_WAIT_L(0); PG8_BAR; PG8_MMA(1, 0, At, B0); PG8_MMA(1, 1, At, B1); PG8_BAR; PG8_SCHED;
	s_add_i32 s24, s40, s74
	v_lshl_add_u64 v[220:221], v[220:221], 0, s[18:19]
	s_mov_b32 m0, s24
	ds_read_b128 v[178:181], v209 offset:49152
	ds_read_b128 v[182:185], v209 offset:50176
	ds_read_b128 v[186:189], v209 offset:51200
	ds_read_b128 v[190:193], v209 offset:52224
	ds_read_b128 v[194:197], v209 offset:53248
	ds_read_b128 v[198:201], v209 offset:54272
	ds_read_b128 v[212:215], v209 offset:55296
	ds_read_b128 v[216:219], v209 offset:56320
	global_load_lds_dwordx4 v[220:221], off
	s_add_i32 m0, s24, 0x2000
	s_add_u32 s24, s28, 0x80080
	v_lshl_add_u64 v[220:221], v[222:223], 0, s[18:19]
	s_addc_u32 s25, s29, 0
	s_add_i32 s28, s41, s74
	global_load_lds_dwordx4 v[220:221], off
	v_lshl_add_u64 v[220:221], s[24:25], 0, v[162:163]
	s_mov_b32 m0, s28
	s_nop 0
	global_load_lds_dwordx4 v[220:221], off
	v_lshl_add_u64 v[220:221], s[24:25], 0, v[166:167]
	s_add_i32 m0, s28, 0x2000
	s_nop 0
	global_load_lds_dwordx4 v[220:221], off
	v_lshl_add_u64 v[220:221], v[224:225], 0, s[18:19]
	s_mov_b32 m0, s81
	s_nop 0
	global_load_lds_dwordx4 v[220:221], off
	v_lshl_add_u64 v[220:221], v[226:227], 0, s[18:19]
	s_mov_b32 m0, s82
	s_nop 0
	global_load_lds_dwordx4 v[220:221], off
	s_waitcnt vmcnt(8)
	s_waitcnt lgkmcnt(0)
	s_barrier
	s_waitcnt lgkmcnt(0)
	v_mfma_f32_16x16x32_bf16 v[92:95], v[128:131], v[178:181], v[92:95]
	v_mfma_f32_16x16x32_bf16 v[28:31], v[136:139], v[178:181], v[28:31]
	v_mfma_f32_16x16x32_bf16 v[88:91], v[128:131], v[186:189], v[88:91]
	v_mfma_f32_16x16x32_bf16 v[24:27], v[136:139], v[186:189], v[24:27]
	v_mfma_f32_16x16x32_bf16 v[84:87], v[128:131], v[194:197], v[84:87]
	v_mfma_f32_16x16x32_bf16 v[20:23], v[136:139], v[194:197], v[20:23]
	v_mfma_f32_16x16x32_bf16 v[76:79], v[128:131], v[212:215], v[76:79]
	v_mfma_f32_16x16x32_bf16 v[12:15], v[136:139], v[212:215], v[12:15]
	v_mfma_f32_16x16x32_bf16 v[92:95], v[132:135], v[182:185], v[92:95]
	v_mfma_f32_16x16x32_bf16 v[28:31], v[140:143], v[182:185], v[28:31]
	v_mfma_f32_16x16x32_bf16 v[88:91], v[132:135], v[190:193], v[88:91]
	v_mfma_f32_16x16x32_bf16 v[24:27], v[140:143], v[190:193], v[24:27]
	v_mfma_f32_16x16x32_bf16 v[84:87], v[132:135], v[198:201], v[84:87]
	v_mfma_f32_16x16x32_bf16 v[20:23], v[140:143], v[198:201], v[20:23]
	v_mfma_f32_16x16x32_bf16 v[76:79], v[132:135], v[216:219], v[76:79]
	v_mfma_f32_16x16x32_bf16 v[12:15], v[140:143], v[216:219], v[12:15]
	v_mfma_f32_16x16x32_bf16 v[80:83], v[144:147], v[178:181], v[80:83]
	v_mfma_f32_16x16x32_bf16 v[16:19], v[152:155], v[178:181], v[16:19]
	v_mfma_f32_16x16x32_bf16 v[72:75], v[144:147], v[186:189], v[72:75]
	v_mfma_f32_16x16x32_bf16 v[8:11], v[152:155], v[186:189], v[8:11]
	v_mfma_f32_16x16x32_bf16 v[68:71], v[144:147], v[194:197], v[68:71]
	v_mfma_f32_16x16x32_bf16 v[4:7], v[152:155], v[194:197], v[4:7]
	v_mfma_f32_16x16x32_bf16 v[64:67], v[144:147], v[212:215], v[64:67]
	v_mfma_f32_16x16x32_bf16 v[0:3], v[152:155], v[212:215], v[0:3]
	v_mfma_f32_16x16x32_bf16 v[80:83], v[148:151], v[182:185], v[80:83]
	v_mfma_f32_16x16x32_bf16 v[16:19], v[156:159], v[182:185], v[16:19]
	v_mfma_f32_16x16x32_bf16 v[72:75], v[148:151], v[190:193], v[72:75]
	v_mfma_f32_16x16x32_bf16 v[8:11], v[156:159], v[190:193], v[8:11]
	v_mfma_f32_16x16x32_bf16 v[68:71], v[148:151], v[198:201], v[68:71]
	v_mfma_f32_16x16x32_bf16 v[4:7], v[156:159], v[198:201], v[4:7]
	v_mfma_f32_16x16x32_bf16 v[64:67], v[148:151], v[216:219], v[64:67]
	v_mfma_f32_16x16x32_bf16 v[0:3], v[156:159], v[216:219], v[0:3]
	s_barrier
	s_add_i32 s39, s39, 2
	s_add_u32 s33, s33, 0x100
	s_addc_u32 s38, s38, 0
	s_cmp_gt_u32 s39, 29
	s_mov_b64 s[24:25], s[26:27]
	s_cbranch_scc0 .LBB0_2934
	s_and_b64 vcc, exec, s[20:21]
	s_cbranch_vccz .LBB0_2937
	s_barrier

; #define PG8_STAGE(bufoff, gbase, voff) do { _Pragma("unroll") for (int _i = 0; _i < 2; ++_i) \
;         __builtin_amdgcn_global_load_lds((const unsigned*)((const char*)(gbase) + (voff)[_i]), (PG8_LAS unsigned*)(lds + (bufoff) + ldsw + _i * 8192), 16, 0, 0); } while (0)
; #define PG8_LDA(dst, b, h) do { _Pragma("unroll") for (int m = 0; m < 4; ++m) _Pragma("unroll") for (int k = 0; k < 2; ++k) dst[m][k] = *(const PG8_LAS bf16x8*)(lds + PG8_SA(b, h) + aoff + m * 2048 + k * 1024); } while (0)
; #define PG8_LDB(dst, b, h) do { _Pragma("unroll") for (int n = 0; n < 2; ++n) _Pragma("unroll") for (int k = 0; k < 2; ++k) dst[n][k] = *(const PG8_LAS bf16x8*)(lds + PG8_SB(b, h) + boff + n * 2048 + k * 1024); } while (0)
; #define PG8_MMA(ai, bj, At, Bt) do { __builtin_amdgcn_s_setprio(1); _Pragma("unroll") for (int m = 0; m < 4; ++m) _Pragma("unroll") for (int n = 0; n < 2; ++n) _Pragma("unroll") for (int k = 0; k < 2; ++k) \
;         acc[ai][bj][m][n] = __builtin_amdgcn_mfma_f32_16x16x32_bf16(Bt[n][k], At[m][k], acc[ai][bj][m][n], 0, 0, 0); __builtin_amdgcn_s_setprio(0); } while (0)
; #define PG8_WAIT_V(n) asm volatile("s_waitcnt vmcnt(" #n ")" ::: "memory")
; #define PG8_WAIT_L(n) asm volatile("s_waitcnt lgkmcnt(" #n ")" ::: "memory")
; #define PG8_BAR __builtin_amdgcn_s_barrier()
; #define PG8_SCHED __builtin_amdgcn_sched_barrier(0)
; template <class Epi, class Sched, bool ALIGN_EPI = false, bool SP2 = false>
; __device__ __forceinline__ void gemm_phase(PG8_LAS unsigned char* lds, const Gemm g, const Sched& S, const Epi& E) {
;     ...
;             PG8_LDB(B0, 0, 0); PG8_LDB(B1, 0, 1); PG8_SCHED; PG8_LDA(At, 0, 0); PG8_STAGE(PG8_SA(1, 1), a1 + hstepA, voffA);
;             PG8_WAIT_V(8); PG8_WAIT_L(0); PG8_BAR; PG8_MMA(0, 0, At, B0); PG8_MMA(0, 1, At, B1); PG8_BAR; PG8_SCHED;
;             PG8_LDA(At, 0, 1); PG8_STAGE(PG8_SB(0, 0), b2, voffB); PG8_STAGE(PG8_SB(0, 1), b2 + hstep, voffB); PG8_STAGE(PG8_SA(0, 0), a2, voffA);
.LBB0_3040:
	ds_read_b128 v[128:131], v167
	ds_read_b128 v[132:135], v167 offset:1024
	ds_read_b128 v[152:155], v167 offset:2048
	ds_read_b128 v[156:159], v167 offset:3072
	ds_read_b128 v[160:163], v168
	ds_read_b128 v[170:173], v168 offset:1024
	ds_read_b128 v[174:177], v168 offset:2048
	ds_read_b128 v[178:181], v168 offset:3072
	s_add_u32 s20, s18, 0x100
	s_addc_u32 s21, s19, 0
	s_cmpk_eq_i32 s49, 0x54
	s_cselect_b32 s25, s9, s21
	s_cselect_b32 s24, s8, s20
	s_cselect_b32 s23, s17, s48
	s_cselect_b32 s22, s16, s47
	v_lshl_add_u64 v[218:219], s[18:19], 0, v[144:145]
	s_add_i32 m0, s31, 0xc000
	ds_read_b128 v[182:185], v169
	ds_read_b128 v[186:189], v169 offset:1024
	ds_read_b128 v[190:193], v169 offset:2048
	ds_read_b128 v[194:197], v169 offset:3072
	ds_read_b128 v[198:201], v169 offset:4096
	ds_read_b128 v[206:209], v169 offset:5120
	ds_read_b128 v[210:213], v169 offset:6144
	ds_read_b128 v[214:217], v169 offset:7168
	global_load_lds_dwordx4 v[218:219], off
	v_lshl_add_u64 v[218:219], s[18:19], 0, v[146:147]
	s_add_i32 m0, s31, 0xe000
	s_nop 0
	global_load_lds_dwordx4 v[218:219], off
	s_waitcnt vmcnt(8)
	s_waitcnt lgkmcnt(0)
	s_barrier
	s_waitcnt lgkmcnt(0)
	v_mfma_f32_16x16x32_bf16 v[124:127], v[128:131], v[182:185], v[124:127]
	v_mfma_f32_16x16x32_bf16 v[120:123], v[152:155], v[182:185], v[120:123]
	v_mfma_f32_16x16x32_bf16 v[108:111], v[128:131], v[190:193], v[108:111]
	v_mfma_f32_16x16x32_bf16 v[104:107], v[152:155], v[190:193], v[104:107]
	v_mfma_f32_16x16x32_bf16 v[92:95], v[128:131], v[198:201], v[92:95]
	v_mfma_f32_16x16x32_bf16 v[88:91], v[152:155], v[198:201], v[88:91]
	v_mfma_f32_16x16x32_bf16 v[76:79], v[128:131], v[210:213], v[76:79]
	v_mfma_f32_16x16x32_bf16 v[72:75], v[152:155], v[210:213], v[72:75]
	v_mfma_f32_16x16x32_bf16 v[124:127], v[132:135], v[186:189], v[124:127]
	v_mfma_f32_16x16x32_bf16 v[120:123], v[156:159], v[186:189], v[120:123]
	v_mfma_f32_16x16x32_bf16 v[108:111], v[132:135], v[194:197], v[108:111]
	v_mfma_f32_16x16x32_bf16 v[104:107], v[156:159], v[194:197], v[104:107]
	v_mfma_f32_16x16x32_bf16 v[92:95], v[132:135], v[206:209], v[92:95]
	v_mfma_f32_16x16x32_bf16 v[88:91], v[156:159], v[206:209], v[88:91]
	v_mfma_f32_16x16x32_bf16 v[76:79], v[132:135], v[214:217], v[76:79]
	v_mfma_f32_16x16x32_bf16 v[72:75], v[156:159], v[214:217], v[72:75]
	v_mfma_f32_16x16x32_bf16 v[116:119], v[160:163], v[182:185], v[116:119]
	v_mfma_f32_16x16x32_bf16 v[112:115], v[174:177], v[182:185], v[112:115]
	v_mfma_f32_16x16x32_bf16 v[100:103], v[160:163], v[190:193], v[100:103]
	v_mfma_f32_16x16x32_bf16 v[96:99], v[174:177], v[190:193], v[96:99]
	v_mfma_f32_16x16x32_bf16 v[84:87], v[160:163], v[198:201], v[84:87]
	v_mfma_f32_16x16x32_bf16 v[80:83], v[174:177], v[198:201], v[80:83]
	v_mfma_f32_16x16x32_bf16 v[68:71], v[160:163], v[210:213], v[68:71]
	v_mfma_f32_16x16x32_bf16 v[64:67], v[174:177], v[210:213], v[64:67]
	v_mfma_f32_16x16x32_bf16 v[116:119], v[170:173], v[186:189], v[116:119]
	v_mfma_f32_16x16x32_bf16 v[112:115], v[178:181], v[186:189], v[112:115]
	v_mfma_f32_16x16x32_bf16 v[100:103], v[170:173], v[194:197], v[100:103]
	v_mfma_f32_16x16x32_bf16 v[96:99], v[178:181], v[194:197], v[96:99]
	v_mfma_f32_16x16x32_bf16 v[84:87], v[170:173], v[206:209], v[84:87]
	v_mfma_f32_16x16x32_bf16 v[80:83], v[178:181], v[206:209], v[80:83]
	v_mfma_f32_16x16x32_bf16 v[68:71], v[170:173], v[214:217], v[68:71]
	v_mfma_f32_16x16x32_bf16 v[64:67], v[178:181], v[214:217], v[64:67]
	s_barrier
	s_add_i32 s18, s39, s30
	v_lshl_add_u64 v[218:219], s[22:23], 0, v[138:139]
	s_mov_b32 m0, s18
	ds_read_b128 v[182:185], v169 offset:16384
	ds_read_b128 v[186:189], v169 offset:17408
	ds_read_b128 v[190:193], v169 offset:18432
	ds_read_b128 v[194:197], v169 offset:19456
	ds_read_b128 v[198:201], v169 offset:20480
	ds_read_b128 v[206:209], v169 offset:21504
	ds_read_b128 v[210:213], v169 offset:22528
	ds_read_b128 v[214:217], v169 offset:23552
	global_load_lds_dwordx4 v[218:219], off
	s_add_i32 m0, s18, 0x2000
	s_add_u32 s18, s22, 0x160000
	v_lshl_add_u64 v[220:221], s[22:23], 0, v[142:143]
	s_addc_u32 s19, s23, 0
	s_add_i32 s50, s40, s30
	global_load_lds_dwordx4 v[220:221], off
	v_lshl_add_u64 v[222:223], s[18:19], 0, v[138:139]
	s_mov_b32 m0, s50
	v_lshl_add_u64 v[224:225], s[24:25], 0, v[140:141]
	global_load_lds_dwordx4 v[222:223], off
	v_lshl_add_u64 v[222:223], s[18:19], 0, v[142:143]
	s_add_i32 m0, s50, 0x2000
	s_nop 0
	global_load_lds_dwordx4 v[222:223], off
	v_lshl_add_u64 v[222:223], s[24:25], 0, v[136:137]
	s_mov_b32 m0, s31
	s_nop 0
	global_load_lds_dwordx4 v[222:223], off
	s_mov_b32 m0, s34
	s_nop 0
	global_load_lds_dwordx4 v[224:225], off
	s_waitcnt vmcnt(8)
	s_waitcnt lgkmcnt(0)
	s_barrier
; #define PG8_STAGE(bufoff, gbase, voff) do { _Pragma("unroll") for (int _i = 0; _i < 2; ++_i) \
;         __builtin_amdgcn_global_load_lds((const unsigned*)((const char*)(gbase) + (voff)[_i]), (PG8_LAS unsigned*)(lds + (bufoff) + ldsw + _i * 8192), 16, 0, 0); } while (0)
; #define PG8_LDA(dst, b, h) do { _Pragma("unroll") for (int m = 0; m < 4; ++m) _Pragma("unroll") for (int k = 0; k < 2; ++k) dst[m][k] = *(const PG8_LAS bf16x8*)(lds + PG8_SA(b, h) + aoff + m * 2048 + k * 1024); } while (0)
; #define PG8_LDB(dst, b, h) do { _Pragma("unroll") for (int n = 0; n < 2; ++n) _Pragma("unroll") for (int k = 0; k < 2; ++k) dst[n][k] = *(const PG8_LAS bf16x8*)(lds + PG8_SB(b, h) + boff + n * 2048 + k * 1024); } while (0)
; #define PG8_MMA(ai, bj, At, Bt) do { __builtin_amdgcn_s_setprio(1); _Pragma("unroll") for (int m = 0; m < 4; ++m) _Pragma("unroll") for (int n = 0; n < 2; ++n) _Pragma("unroll") for (int k = 0; k < 2; ++k) \
;         acc[ai][bj][m][n] = __builtin_amdgcn_mfma_f32_16x16x32_bf16(Bt[n][k], At[m][k], acc[ai][bj][m][n], 0, 0, 0); __builtin_amdgcn_s_setprio(0); } while (0)
; #define PG8_WAIT_V(n) asm volatile("s_waitcnt vmcnt(" #n ")" ::: "memory")
; #define PG8_WAIT_L(n) asm volatile("s_waitcnt lgkmcnt(" #n ")" ::: "memory")
; #define PG8_BAR __builtin_amdgcn_s_barrier()
; #define PG8_SCHED __builtin_amdgcn_sched_barrier(0)
; template <class Epi, class Sched, bool ALIGN_EPI = false, bool SP2 = false>
; __device__ __forceinline__ void gemm_phase(PG8_LAS unsigned char* lds, const Gemm g, const Sched& S, const Epi& E) {
;     ...
;             PG8_WAIT_V(8); PG8_WAIT_L(0); PG8_BAR; PG8_MMA(1, 0, At, B0); PG8_MMA(1, 1, At, B1); PG8_BAR; PG8_SCHED;
;             PG8_LDB(B0, 1, 0); PG8_LDB(B1, 1, 1); PG8_SCHED; PG8_LDA(At, 1, 0); PG8_STAGE(PG8_SA(0, 1), a2 + hstepA, voffA);
;             PG8_WAIT_V(8); PG8_WAIT_L(0); PG8_BAR; PG8_MMA(0, 0, At, B0); PG8_MMA(0, 1, At, B1); PG8_BAR; PG8_SCHED;
	s_waitcnt lgkmcnt(0)
	v_mfma_f32_16x16x32_bf16 v[60:63], v[128:131], v[182:185], v[60:63]
	v_mfma_f32_16x16x32_bf16 v[56:59], v[152:155], v[182:185], v[56:59]
	v_mfma_f32_16x16x32_bf16 v[44:47], v[128:131], v[190:193], v[44:47]
	v_mfma_f32_16x16x32_bf16 v[40:43], v[152:155], v[190:193], v[40:43]
	v_mfma_f32_16x16x32_bf16 v[28:31], v[128:131], v[198:201], v[28:31]
	v_mfma_f32_16x16x32_bf16 v[24:27], v[152:155], v[198:201], v[24:27]
	v_mfma_f32_16x16x32_bf16 v[12:15], v[128:131], v[210:213], v[12:15]
	v_mfma_f32_16x16x32_bf16 v[8:11], v[152:155], v[210:213], v[8:11]
	v_mfma_f32_16x16x32_bf16 v[60:63], v[132:135], v[186:189], v[60:63]
	v_mfma_f32_16x16x32_bf16 v[56:59], v[156:159], v[186:189], v[56:59]
	v_mfma_f32_16x16x32_bf16 v[44:47], v[132:135], v[194:197], v[44:47]
	v_mfma_f32_16x16x32_bf16 v[40:43], v[156:159], v[194:197], v[40:43]
	v_mfma_f32_16x16x32_bf16 v[28:31], v[132:135], v[206:209], v[28:31]
	v_mfma_f32_16x16x32_bf16 v[24:27], v[156:159], v[206:209], v[24:27]
	v_mfma_f32_16x16x32_bf16 v[12:15], v[132:135], v[214:217], v[12:15]
	v_mfma_f32_16x16x32_bf16 v[8:11], v[156:159], v[214:217], v[8:11]
	v_mfma_f32_16x16x32_bf16 v[52:55], v[160:163], v[182:185], v[52:55]
	v_mfma_f32_16x16x32_bf16 v[48:51], v[174:177], v[182:185], v[48:51]
	v_mfma_f32_16x16x32_bf16 v[36:39], v[160:163], v[190:193], v[36:39]
	v_mfma_f32_16x16x32_bf16 v[32:35], v[174:177], v[190:193], v[32:35]
	v_mfma_f32_16x16x32_bf16 v[20:23], v[160:163], v[198:201], v[20:23]
	v_mfma_f32_16x16x32_bf16 v[16:19], v[174:177], v[198:201], v[16:19]
	v_mfma_f32_16x16x32_bf16 v[4:7], v[160:163], v[210:213], v[4:7]
	v_mfma_f32_16x16x32_bf16 v[0:3], v[174:177], v[210:213], v[0:3]
	v_mfma_f32_16x16x32_bf16 v[52:55], v[170:173], v[186:189], v[52:55]
	v_mfma_f32_16x16x32_bf16 v[48:51], v[178:181], v[186:189], v[48:51]
	v_mfma_f32_16x16x32_bf16 v[36:39], v[170:173], v[194:197], v[36:39]
	v_mfma_f32_16x16x32_bf16 v[32:35], v[178:181], v[194:197], v[32:35]
	v_mfma_f32_16x16x32_bf16 v[20:23], v[170:173], v[206:209], v[20:23]
	v_mfma_f32_16x16x32_bf16 v[16:19], v[178:181], v[206:209], v[16:19]
	v_mfma_f32_16x16x32_bf16 v[4:7], v[170:173], v[214:217], v[4:7]
	v_mfma_f32_16x16x32_bf16 v[0:3], v[178:181], v[214:217], v[0:3]
	s_barrier
	s_add_i32 s50, 0, 0x18000
	s_add_i32 s51, 0, 0x1c000
	v_add_u32_e32 v156, s50, v165
	v_add_u32_e32 v178, s51, v165
	ds_read_b128 v[128:131], v156
	ds_read_b128 v[132:135], v156 offset:1024
	ds_read_b128 v[152:155], v156 offset:2048
	ds_read_b128 v[156:159], v156 offset:3072
	ds_read_b128 v[160:163], v178
	ds_read_b128 v[170:173], v178 offset:1024
	ds_read_b128 v[174:177], v178 offset:2048
	ds_read_b128 v[178:181], v178 offset:3072
	s_add_u32 s18, s24, 0x160000
	s_addc_u32 s19, s25, 0
	s_mov_b32 m0, s35
	v_lshl_add_u64 v[226:227], s[18:19], 0, v[136:137]
	ds_read_b128 v[182:185], v169 offset:32768
	ds_read_b128 v[186:189], v169 offset:33792
	ds_read_b128 v[190:193], v169 offset:34816
	ds_read_b128 v[194:197], v169 offset:35840
	ds_read_b128 v[198:201], v169 offset:36864
	ds_read_b128 v[206:209], v169 offset:37888
	ds_read_b128 v[210:213], v169 offset:38912
	ds_read_b128 v[214:217], v169 offset:39936
	global_load_lds_dwordx4 v[226:227], off
	v_lshl_add_u64 v[226:227], s[18:19], 0, v[140:141]
	s_mov_b32 m0, s36
	s_nop 0
	global_load_lds_dwordx4 v[226:227], off
	s_waitcnt vmcnt(8)
	s_waitcnt lgkmcnt(0)
	s_barrier
	s_waitcnt lgkmcnt(0)
	v_mfma_f32_16x16x32_bf16 v[124:127], v[128:131], v[182:185], v[124:127]
	v_mfma_f32_16x16x32_bf16 v[120:123], v[152:155], v[182:185], v[120:123]
	v_mfma_f32_16x16x32_bf16 v[108:111], v[128:131], v[190:193], v[108:111]
	v_mfma_f32_16x16x32_bf16 v[104:107], v[152:155], v[190:193], v[104:107]
	v_mfma_f32_16x16x32_bf16 v[92:95], v[128:131], v[198:201], v[92:95]
	v_mfma_f32_16x16x32_bf16 v[88:91], v[152:155], v[198:201], v[88:91]
	v_mfma_f32_16x16x32_bf16 v[76:79], v[128:131], v[210:213], v[76:79]
	v_mfma_f32_16x16x32_bf16 v[72:75], v[152:155], v[210:213], v[72:75]
	v_mfma_f32_16x16x32_bf16 v[124:127], v[132:135], v[186:189], v[124:127]
	v_mfma_f32_16x16x32_bf16 v[120:123], v[156:159], v[186:189], v[120:123]
	v_mfma_f32_16x16x32_bf16 v[108:111], v[132:135], v[194:197], v[108:111]
	v_mfma_f32_16x16x32_bf16 v[104:107], v[156:159], v[194:197], v[104:107]
	v_mfma_f32_16x16x32_bf16 v[92:95], v[132:135], v[206:209], v[92:95]
	v_mfma_f32_16x16x32_bf16 v[88:91], v[156:159], v[206:209], v[88:91]
	v_mfma_f32_16x16x32_bf16 v[76:79], v[132:135], v[214:217], v[76:79]
	v_mfma_f32_16x16x32_bf16 v[72:75], v[156:159], v[214:217], v[72:75]
	v_mfma_f32_16x16x32_bf16 v[116:119], v[160:163], v[182:185], v[116:119]
	v_mfma_f32_16x16x32_bf16 v[112:115], v[174:177], v[182:185], v[112:115]
	v_mfma_f32_16x16x32_bf16 v[100:103], v[160:163], v[190:193], v[100:103]
	v_mfma_f32_16x16x32_bf16 v[96:99], v[174:177], v[190:193], v[96:99]
	v_mfma_f32_16x16x32_bf16 v[84:87], v[160:163], v[198:201], v[84:87]
	v_mfma_f32_16x16x32_bf16 v[80:83], v[174:177], v[198:201], v[80:83]
	v_mfma_f32_16x16x32_bf16 v[68:71], v[160:163], v[210:213], v[68:71]
	v_mfma_f32_16x16x32_bf16 v[64:67], v[174:177], v[210:213], v[64:67]
	v_mfma_f32_16x16x32_bf16 v[116:119], v[170:173], v[186:189], v[116:119]
	v_mfma_f32_16x16x32_bf16 v[112:115], v[178:181], v[186:189], v[112:115]
	v_mfma_f32_16x16x32_bf16 v[100:103], v[170:173], v[194:197], v[100:103]
	v_mfma_f32_16x16x32_bf16 v[96:99], v[178:181], v[194:197], v[96:99]
	v_mfma_f32_16x16x32_bf16 v[84:87], v[170:173], v[206:209], v[84:87]
	v_mfma_f32_16x16x32_bf16 v[80:83], v[178:181], v[206:209], v[80:83]
	v_mfma_f32_16x16x32_bf16 v[68:71], v[170:173], v[214:217], v[68:71]
	v_mfma_f32_16x16x32_bf16 v[64:67], v[178:181], v[214:217], v[64:67]
	s_barrier
; #define PG8_STAGE(bufoff, gbase, voff) do { _Pragma("unroll") for (int _i = 0; _i < 2; ++_i) \
;         __builtin_amdgcn_global_load_lds((const unsigned*)((const char*)(gbase) + (voff)[_i]), (PG8_LAS unsigned*)(lds + (bufoff) + ldsw + _i * 8192), 16, 0, 0); } while (0)
; #define PG8_LDA(dst, b, h) do { _Pragma("unroll") for (int m = 0; m < 4; ++m) _Pragma("unroll") for (int k = 0; k < 2; ++k) dst[m][k] = *(const PG8_LAS bf16x8*)(lds + PG8_SA(b, h) + aoff + m * 2048 + k * 1024); } while (0)
; #define PG8_MMA(ai, bj, At, Bt) do { __builtin_amdgcn_s_setprio(1); _Pragma("unroll") for (int m = 0; m < 4; ++m) _Pragma("unroll") for (int n = 0; n < 2; ++n) _Pragma("unroll") for (int k = 0; k < 2; ++k) \
;         acc[ai][bj][m][n] = __builtin_amdgcn_mfma_f32_16x16x32_bf16(Bt[n][k], At[m][k], acc[ai][bj][m][n], 0, 0, 0); __builtin_amdgcn_s_setprio(0); } while (0)
; #define PG8_WAIT_V(n) asm volatile("s_waitcnt vmcnt(" #n ")" ::: "memory")
; #define PG8_WAIT_L(n) asm volatile("s_waitcnt lgkmcnt(" #n ")" ::: "memory")
; #define PG8_BAR __builtin_amdgcn_s_barrier()
; #define PG8_SCHED __builtin_amdgcn_sched_barrier(0)
; template <class Epi, class Sched, bool ALIGN_EPI = false, bool SP2 = false>
; __device__ __forceinline__ void gemm_phase(PG8_LAS unsigned char* lds, const Gemm g, const Sched& S, const Epi& E) {
;     ...
;             PG8_LDA(At, 1, 1); PG8_STAGE(PG8_SB(1, 0), b3, voffB); PG8_STAGE(PG8_SB(1, 1), b3 + hstep, voffB); PG8_STAGE(PG8_SA(1, 0), a3, voffA);
;             PG8_WAIT_V(8); PG8_WAIT_L(0); PG8_BAR; PG8_MMA(1, 0, At, B0); PG8_MMA(1, 1, At, B1); PG8_BAR; PG8_SCHED;
	s_add_i32 s18, s50, s30
	v_lshl_add_u64 v[218:219], v[218:219], 0, s[0:1]
	s_mov_b32 m0, s18
	ds_read_b128 v[182:185], v169 offset:49152
	ds_read_b128 v[186:189], v169 offset:50176
	ds_read_b128 v[190:193], v169 offset:51200
	ds_read_b128 v[194:197], v169 offset:52224
	ds_read_b128 v[198:201], v169 offset:53248
	ds_read_b128 v[206:209], v169 offset:54272
	ds_read_b128 v[210:213], v169 offset:55296
	ds_read_b128 v[214:217], v169 offset:56320
	global_load_lds_dwordx4 v[218:219], off
	s_add_i32 m0, s18, 0x2000
	s_add_u32 s18, s22, 0x160080
	v_lshl_add_u64 v[218:219], v[220:221], 0, s[0:1]
	s_addc_u32 s19, s23, 0
	s_add_i32 s22, s51, s30
	global_load_lds_dwordx4 v[218:219], off
	v_lshl_add_u64 v[218:219], s[18:19], 0, v[138:139]
	s_mov_b32 m0, s22
	s_nop 0
	global_load_lds_dwordx4 v[218:219], off
	v_lshl_add_u64 v[218:219], s[18:19], 0, v[142:143]
	s_add_i32 m0, s22, 0x2000
	s_nop 0
	global_load_lds_dwordx4 v[218:219], off
	v_lshl_add_u64 v[218:219], v[222:223], 0, s[0:1]
	s_mov_b32 m0, s3
	s_nop 0
	global_load_lds_dwordx4 v[218:219], off
	v_lshl_add_u64 v[218:219], v[224:225], 0, s[0:1]
	s_mov_b32 m0, s33
	s_nop 0
	global_load_lds_dwordx4 v[218:219], off
	s_waitcnt vmcnt(8)
	s_waitcnt lgkmcnt(0)
	s_barrier
	s_waitcnt lgkmcnt(0)
	v_mfma_f32_16x16x32_bf16 v[60:63], v[128:131], v[182:185], v[60:63]
	v_mfma_f32_16x16x32_bf16 v[56:59], v[152:155], v[182:185], v[56:59]
	v_mfma_f32_16x16x32_bf16 v[44:47], v[128:131], v[190:193], v[44:47]
	v_mfma_f32_16x16x32_bf16 v[40:43], v[152:155], v[190:193], v[40:43]
	v_mfma_f32_16x16x32_bf16 v[28:31], v[128:131], v[198:201], v[28:31]
	v_mfma_f32_16x16x32_bf16 v[24:27], v[152:155], v[198:201], v[24:27]
	v_mfma_f32_16x16x32_bf16 v[12:15], v[128:131], v[210:213], v[12:15]
	v_mfma_f32_16x16x32_bf16 v[8:11], v[152:155], v[210:213], v[8:11]
	v_mfma_f32_16x16x32_bf16 v[60:63], v[132:135], v[186:189], v[60:63]
	v_mfma_f32_16x16x32_bf16 v[56:59], v[156:159], v[186:189], v[56:59]
	v_mfma_f32_16x16x32_bf16 v[44:47], v[132:135], v[194:197], v[44:47]
	v_mfma_f32_16x16x32_bf16 v[40:43], v[156:159], v[194:197], v[40:43]
	v_mfma_f32_16x16x32_bf16 v[28:31], v[132:135], v[206:209], v[28:31]
	v_mfma_f32_16x16x32_bf16 v[24:27], v[156:159], v[206:209], v[24:27]
	v_mfma_f32_16x16x32_bf16 v[12:15], v[132:135], v[214:217], v[12:15]
	v_mfma_f32_16x16x32_bf16 v[8:11], v[156:159], v[214:217], v[8:11]
	v_mfma_f32_16x16x32_bf16 v[52:55], v[160:163], v[182:185], v[52:55]
	v_mfma_f32_16x16x32_bf16 v[48:51], v[174:177], v[182:185], v[48:51]
	v_mfma_f32_16x16x32_bf16 v[36:39], v[160:163], v[190:193], v[36:39]
	v_mfma_f32_16x16x32_bf16 v[32:35], v[174:177], v[190:193], v[32:35]
	v_mfma_f32_16x16x32_bf16 v[20:23], v[160:163], v[198:201], v[20:23]
	v_mfma_f32_16x16x32_bf16 v[16:19], v[174:177], v[198:201], v[16:19]
	v_mfma_f32_16x16x32_bf16 v[4:7], v[160:163], v[210:213], v[4:7]
	v_mfma_f32_16x16x32_bf16 v[0:3], v[174:177], v[210:213], v[0:3]
	v_mfma_f32_16x16x32_bf16 v[52:55], v[170:173], v[186:189], v[52:55]
	v_mfma_f32_16x16x32_bf16 v[48:51], v[178:181], v[186:189], v[48:51]
	v_mfma_f32_16x16x32_bf16 v[36:39], v[170:173], v[194:197], v[36:39]
	v_mfma_f32_16x16x32_bf16 v[32:35], v[178:181], v[194:197], v[32:35]
	v_mfma_f32_16x16x32_bf16 v[20:23], v[170:173], v[206:209], v[20:23]
	v_mfma_f32_16x16x32_bf16 v[16:19], v[178:181], v[206:209], v[16:19]
	v_mfma_f32_16x16x32_bf16 v[4:7], v[170:173], v[214:217], v[4:7]
	v_mfma_f32_16x16x32_bf16 v[0:3], v[178:181], v[214:217], v[0:3]
	s_barrier
	s_add_i32 s49, s49, 2
	s_add_u32 s47, s47, 0x100
	s_addc_u32 s48, s48, 0
	s_cmpk_gt_u32 s49, 0x55
	s_mov_b64 s[18:19], s[20:21]
	s_cbranch_scc0 .LBB0_3040
	s_and_b64 vcc, exec, s[14:15]
	s_cbranch_vccz .LBB0_3043
	s_barrier
